# v5 + K-loop MFMA order: accumulator pairs back to back and serpentine so neighbouring MFMAs share one operand
# speedup vs baseline: 1.0126x; 1.0089x over previous
; #define PG8_STAGE(bufoff, gbase, voff) do { _Pragma("unroll") for (int _i = 0; _i < 2; ++_i) \
;         __builtin_amdgcn_global_load_lds((const unsigned*)((const char*)(gbase) + (voff)[_i]), (PG8_LAS unsigned*)(lds + (bufoff) + ldsw + _i * 8192), 16, 0, 0); } while (0)
; #define PG8_LDA(dst, b, h) do { _Pragma("unroll") for (int m = 0; m < 4; ++m) _Pragma("unroll") for (int k = 0; k < 2; ++k) dst[m][k] = *(const PG8_LAS bf16x8*)(lds + PG8_SA(b, h) + aoff + m * 2048 + k * 1024); } while (0)
; #define PG8_LDB(dst, b, h) do { _Pragma("unroll") for (int n = 0; n < 2; ++n) _Pragma("unroll") for (int k = 0; k < 2; ++k) dst[n][k] = *(const PG8_LAS bf16x8*)(lds + PG8_SB(b, h) + boff + n * 2048 + k * 1024); } while (0)
; #define PG8_MMA(ai, bj, At, Bt) do { __builtin_amdgcn_s_setprio(1); _Pragma("unroll") for (int m = 0; m < 4; ++m) _Pragma("unroll") for (int n = 0; n < 2; ++n) _Pragma("unroll") for (int k = 0; k < 2; ++k) \
;         acc[ai][bj][m][n] = __builtin_amdgcn_mfma_f32_16x16x32_bf16(Bt[n][k], At[m][k], acc[ai][bj][m][n], 0, 0, 0); __builtin_amdgcn_s_setprio(0); } while (0)
; #define PG8_WAIT_V(n) asm volatile("s_waitcnt vmcnt(" #n ")" ::: "memory")
; #define PG8_WAIT_L(n) asm volatile("s_waitcnt lgkmcnt(" #n ")" ::: "memory")
; #define PG8_BAR __builtin_amdgcn_s_barrier()
; #define PG8_SCHED __builtin_amdgcn_sched_barrier(0)
; template <class Epi, class Sched, bool ALIGN_EPI = false, bool SP2 = false, bool APERM = false  >
; __device__ __forceinline__ void gemm_phase(PG8_LAS unsigned char* lds, const Gemm g, const Sched& S, const Epi& E, const int wid  ) {
;     ...
;             const bool last = (t == nt - 2);
;             const char* a1 = cA + (size_t)(t + 1) * kstep;
;             const char* a2 = last ? nA : cA + (size_t)(t + 2) * kstep; const char* b2 = last ? nB : cB + (size_t)(t + 2) * kstep;
;             const char* a3 = a2 + kstep; const char* b3 = b2 + kstep;
;             if (last && has_next) S.a_ready(nxt);
;             if constexpr (SP2) {
;             PG8_LDB(B0, 0, 0); PG8_LDB(B1, 0, 1); PG8_SCHED; PG8_LDA(At, 0, 0); PG8_STAGE(PG8_SA(1, 1), a1 + hstep, voffA);
;             PG8_WAIT_V(8); PG8_WAIT_L(0); PG8_BAR; PG8_MMA(0, 0, At, B0); PG8_MMA(0, 1, At, B1); PG8_BAR; PG8_SCHED;
;             PG8_LDA(At, 0, 1); PG8_STAGE(PG8_SB(0, 0), b2, voffB); PG8_STAGE(PG8_SB(0, 1), b2 + hstep, voffB); PG8_STAGE(PG8_SA(0, 0), a2, voffA);
.LBB0_84:
	v_add_u32_e32 v140, s59, v145
	ds_read_b128 v[154:157], v140
	ds_read_b128 v[158:161], v140 offset:1024
	ds_read_b128 v[162:165], v140 offset:2048
	ds_read_b128 v[166:169], v140 offset:3072
	v_add_u32_e32 v140, s60, v145
	s_add_u32 s69, s26, s86
	ds_read_b128 v[170:173], v140
	ds_read_b128 v[174:177], v140 offset:1024
	ds_read_b128 v[178:181], v140 offset:2048
	ds_read_b128 v[182:185], v140 offset:3072
	s_addc_u32 s70, s27, s87
	s_add_u32 s69, s69, 0x100
	s_addc_u32 s70, s70, 0
	s_add_u32 s71, s64, s86
	s_addc_u32 s72, s65, s87
	s_cmpk_eq_i32 s86, 0xf00
	s_cselect_b32 s91, s19, s70
	s_cselect_b32 s90, s66, s69
	s_cselect_b32 s89, s25, s72
	s_cselect_b32 s88, s67, s71
	v_lshl_add_u64 v[150:151], v[136:137], 0, s[86:87]
	s_add_i32 m0, s3, 0xc000
	ds_read_b128 v[186:189], v149
	ds_read_b128 v[190:193], v149 offset:1024
	ds_read_b128 v[194:197], v149 offset:2048
	ds_read_b128 v[198:201], v149 offset:3072
	ds_read_b128 v[202:205], v149 offset:4096
	ds_read_b128 v[206:209], v149 offset:5120
	ds_read_b128 v[210:213], v149 offset:6144
	ds_read_b128 v[214:217], v149 offset:7168
	global_load_lds_dwordx4 v[150:151], off
	v_lshl_add_u64 v[150:151], v[138:139], 0, s[86:87]
	s_add_i32 m0, s3, 0xe000
	s_nop 0
	global_load_lds_dwordx4 v[150:151], off
	s_waitcnt vmcnt(8)
	s_waitcnt lgkmcnt(0)
	s_barrier
	s_setprio 1
	s_waitcnt lgkmcnt(0)
	v_mfma_f32_16x16x32_bf16 v[124:127], v[154:157], v[186:189], v[124:127]
	v_mfma_f32_16x16x32_bf16 v[124:127], v[158:161], v[190:193], v[124:127]
	v_mfma_f32_16x16x32_bf16 v[120:123], v[166:169], v[190:193], v[120:123]
	v_mfma_f32_16x16x32_bf16 v[120:123], v[162:165], v[186:189], v[120:123]
	v_mfma_f32_16x16x32_bf16 v[112:115], v[162:165], v[194:197], v[112:115]
	v_mfma_f32_16x16x32_bf16 v[112:115], v[166:169], v[198:201], v[112:115]
	v_mfma_f32_16x16x32_bf16 v[116:119], v[158:161], v[198:201], v[116:119]
	v_mfma_f32_16x16x32_bf16 v[116:119], v[154:157], v[194:197], v[116:119]
	v_mfma_f32_16x16x32_bf16 v[108:111], v[154:157], v[202:205], v[108:111]
	v_mfma_f32_16x16x32_bf16 v[108:111], v[158:161], v[206:209], v[108:111]
	v_mfma_f32_16x16x32_bf16 v[104:107], v[166:169], v[206:209], v[104:107]
	v_mfma_f32_16x16x32_bf16 v[104:107], v[162:165], v[202:205], v[104:107]
	v_mfma_f32_16x16x32_bf16 v[96:99], v[162:165], v[210:213], v[96:99]
	v_mfma_f32_16x16x32_bf16 v[96:99], v[166:169], v[214:217], v[96:99]
	v_mfma_f32_16x16x32_bf16 v[100:103], v[158:161], v[214:217], v[100:103]
	v_mfma_f32_16x16x32_bf16 v[100:103], v[154:157], v[210:213], v[100:103]
	s_setprio 0
	s_setprio 1
	v_mfma_f32_16x16x32_bf16 v[92:95], v[170:173], v[186:189], v[92:95]
	v_mfma_f32_16x16x32_bf16 v[92:95], v[174:177], v[190:193], v[92:95]
	v_mfma_f32_16x16x32_bf16 v[88:91], v[182:185], v[190:193], v[88:91]
	v_mfma_f32_16x16x32_bf16 v[88:91], v[178:181], v[186:189], v[88:91]
	v_mfma_f32_16x16x32_bf16 v[80:83], v[178:181], v[194:197], v[80:83]
	v_mfma_f32_16x16x32_bf16 v[80:83], v[182:185], v[198:201], v[80:83]
	v_mfma_f32_16x16x32_bf16 v[84:87], v[174:177], v[198:201], v[84:87]
	v_mfma_f32_16x16x32_bf16 v[84:87], v[170:173], v[194:197], v[84:87]
	v_mfma_f32_16x16x32_bf16 v[76:79], v[170:173], v[202:205], v[76:79]
	v_mfma_f32_16x16x32_bf16 v[76:79], v[174:177], v[206:209], v[76:79]
	v_mfma_f32_16x16x32_bf16 v[72:75], v[182:185], v[206:209], v[72:75]
	v_mfma_f32_16x16x32_bf16 v[72:75], v[178:181], v[202:205], v[72:75]
	v_mfma_f32_16x16x32_bf16 v[64:67], v[178:181], v[210:213], v[64:67]
	v_mfma_f32_16x16x32_bf16 v[64:67], v[182:185], v[214:217], v[64:67]
	v_mfma_f32_16x16x32_bf16 v[68:71], v[174:177], v[214:217], v[68:71]
	v_mfma_f32_16x16x32_bf16 v[68:71], v[170:173], v[210:213], v[68:71]
	s_setprio 0
	s_barrier
	s_add_i32 s69, s59, s53
	v_lshl_add_u64 v[150:151], s[88:89], 0, v[130:131]
	s_mov_b32 m0, s69
	ds_read_b128 v[186:189], v149 offset:16384
	ds_read_b128 v[190:193], v149 offset:17408
	ds_read_b128 v[194:197], v149 offset:18432
	ds_read_b128 v[198:201], v149 offset:19456
	ds_read_b128 v[202:205], v149 offset:20480
	ds_read_b128 v[206:209], v149 offset:21504
	ds_read_b128 v[210:213], v149 offset:22528
	ds_read_b128 v[214:217], v149 offset:23552
	global_load_lds_dwordx4 v[150:151], off
	s_add_i32 m0, s69, 0x2000
	s_add_u32 s70, s88, 0x80000
	v_lshl_add_u64 v[218:219], s[88:89], 0, v[128:129]
	s_addc_u32 s71, s89, 0
	s_add_i32 s69, s60, s53
	global_load_lds_dwordx4 v[218:219], off
	v_lshl_add_u64 v[220:221], s[70:71], 0, v[130:131]
	s_mov_b32 m0, s69
	v_lshl_add_u64 v[222:223], s[90:91], 0, v[128:129]
	global_load_lds_dwordx4 v[220:221], off
	v_lshl_add_u64 v[220:221], s[70:71], 0, v[128:129]
	s_add_i32 m0, s69, 0x2000
	s_nop 0
	global_load_lds_dwordx4 v[220:221], off
	v_lshl_add_u64 v[220:221], s[90:91], 0, v[130:131]
	s_mov_b32 m0, s3
	s_nop 0
	global_load_lds_dwordx4 v[220:221], off
	s_mov_b32 m0, s7
	s_nop 0
	global_load_lds_dwordx4 v[222:223], off
	s_waitcnt vmcnt(8)
	s_waitcnt lgkmcnt(0)
	s_barrier
; #define PG8_STAGE(bufoff, gbase, voff) do { _Pragma("unroll") for (int _i = 0; _i < 2; ++_i) \
;         __builtin_amdgcn_global_load_lds((const unsigned*)((const char*)(gbase) + (voff)[_i]), (PG8_LAS unsigned*)(lds + (bufoff) + ldsw + _i * 8192), 16, 0, 0); } while (0)
; #define PG8_LDA(dst, b, h) do { _Pragma("unroll") for (int m = 0; m < 4; ++m) _Pragma("unroll") for (int k = 0; k < 2; ++k) dst[m][k] = *(const PG8_LAS bf16x8*)(lds + PG8_SA(b, h) + aoff + m * 2048 + k * 1024); } while (0)
; #define PG8_LDB(dst, b, h) do { _Pragma("unroll") for (int n = 0; n < 2; ++n) _Pragma("unroll") for (int k = 0; k < 2; ++k) dst[n][k] = *(const PG8_LAS bf16x8*)(lds + PG8_SB(b, h) + boff + n * 2048 + k * 1024); } while (0)
; #define PG8_MMA(ai, bj, At, Bt) do { __builtin_amdgcn_s_setprio(1); _Pragma("unroll") for (int m = 0; m < 4; ++m) _Pragma("unroll") for (int n = 0; n < 2; ++n) _Pragma("unroll") for (int k = 0; k < 2; ++k) \
;         acc[ai][bj][m][n] = __builtin_amdgcn_mfma_f32_16x16x32_bf16(Bt[n][k], At[m][k], acc[ai][bj][m][n], 0, 0, 0); __builtin_amdgcn_s_setprio(0); } while (0)
; #define PG8_WAIT_V(n) asm volatile("s_waitcnt vmcnt(" #n ")" ::: "memory")
; #define PG8_WAIT_L(n) asm volatile("s_waitcnt lgkmcnt(" #n ")" ::: "memory")
; #define PG8_BAR __builtin_amdgcn_s_barrier()
; #define PG8_SCHED __builtin_amdgcn_sched_barrier(0)
; template <class Epi, class Sched, bool ALIGN_EPI = false, bool SP2 = false, bool APERM = false  >
; __device__ __forceinline__ void gemm_phase(PG8_LAS unsigned char* lds, const Gemm g, const Sched& S, const Epi& E, const int wid  ) {
;     ...
;             PG8_WAIT_V(8); PG8_WAIT_L(0); PG8_BAR; PG8_MMA(1, 0, At, B0); PG8_MMA(1, 1, At, B1); PG8_BAR; PG8_SCHED;
;             PG8_LDB(B0, 1, 0); PG8_LDB(B1, 1, 1); PG8_SCHED; PG8_LDA(At, 1, 0); PG8_STAGE(PG8_SA(0, 1), a2 + hstep, voffA);
;             PG8_WAIT_V(8); PG8_WAIT_L(0); PG8_BAR; PG8_MMA(0, 0, At, B0); PG8_MMA(0, 1, At, B1); PG8_BAR; PG8_SCHED;
	s_setprio 1
	s_waitcnt lgkmcnt(0)
	v_mfma_f32_16x16x32_bf16 v[60:63], v[154:157], v[186:189], v[60:63]
	v_mfma_f32_16x16x32_bf16 v[60:63], v[158:161], v[190:193], v[60:63]
	v_mfma_f32_16x16x32_bf16 v[56:59], v[166:169], v[190:193], v[56:59]
	v_mfma_f32_16x16x32_bf16 v[56:59], v[162:165], v[186:189], v[56:59]
	v_mfma_f32_16x16x32_bf16 v[48:51], v[162:165], v[194:197], v[48:51]
	v_mfma_f32_16x16x32_bf16 v[48:51], v[166:169], v[198:201], v[48:51]
	v_mfma_f32_16x16x32_bf16 v[52:55], v[158:161], v[198:201], v[52:55]
	v_mfma_f32_16x16x32_bf16 v[52:55], v[154:157], v[194:197], v[52:55]
	v_mfma_f32_16x16x32_bf16 v[44:47], v[154:157], v[202:205], v[44:47]
	v_mfma_f32_16x16x32_bf16 v[44:47], v[158:161], v[206:209], v[44:47]
	v_mfma_f32_16x16x32_bf16 v[40:43], v[166:169], v[206:209], v[40:43]
	v_mfma_f32_16x16x32_bf16 v[40:43], v[162:165], v[202:205], v[40:43]
	v_mfma_f32_16x16x32_bf16 v[32:35], v[162:165], v[210:213], v[32:35]
	v_mfma_f32_16x16x32_bf16 v[32:35], v[166:169], v[214:217], v[32:35]
	v_mfma_f32_16x16x32_bf16 v[36:39], v[158:161], v[214:217], v[36:39]
	v_mfma_f32_16x16x32_bf16 v[36:39], v[154:157], v[210:213], v[36:39]
	s_setprio 0
	s_setprio 1
	v_mfma_f32_16x16x32_bf16 v[28:31], v[170:173], v[186:189], v[28:31]
	v_mfma_f32_16x16x32_bf16 v[28:31], v[174:177], v[190:193], v[28:31]
	v_mfma_f32_16x16x32_bf16 v[24:27], v[182:185], v[190:193], v[24:27]
	v_mfma_f32_16x16x32_bf16 v[24:27], v[178:181], v[186:189], v[24:27]
	v_mfma_f32_16x16x32_bf16 v[16:19], v[178:181], v[194:197], v[16:19]
	v_mfma_f32_16x16x32_bf16 v[16:19], v[182:185], v[198:201], v[16:19]
	v_mfma_f32_16x16x32_bf16 v[20:23], v[174:177], v[198:201], v[20:23]
	v_mfma_f32_16x16x32_bf16 v[20:23], v[170:173], v[194:197], v[20:23]
	v_mfma_f32_16x16x32_bf16 v[12:15], v[170:173], v[202:205], v[12:15]
	v_mfma_f32_16x16x32_bf16 v[12:15], v[174:177], v[206:209], v[12:15]
	v_mfma_f32_16x16x32_bf16 v[8:11], v[182:185], v[206:209], v[8:11]
	v_mfma_f32_16x16x32_bf16 v[8:11], v[178:181], v[202:205], v[8:11]
	v_mfma_f32_16x16x32_bf16 v[0:3], v[178:181], v[210:213], v[0:3]
	v_mfma_f32_16x16x32_bf16 v[0:3], v[182:185], v[214:217], v[0:3]
	v_mfma_f32_16x16x32_bf16 v[4:7], v[174:177], v[214:217], v[4:7]
	v_mfma_f32_16x16x32_bf16 v[4:7], v[170:173], v[210:213], v[4:7]
	s_setprio 0
	s_barrier
	s_add_i32 s69, 0, 0x18000
	v_add_u32_e32 v140, s69, v145
	s_add_i32 s72, 0, 0x1c000
	ds_read_b128 v[154:157], v140
	ds_read_b128 v[158:161], v140 offset:1024
	ds_read_b128 v[162:165], v140 offset:2048
	ds_read_b128 v[166:169], v140 offset:3072
	v_add_u32_e32 v140, s72, v145
	ds_read_b128 v[170:173], v140
	ds_read_b128 v[174:177], v140 offset:1024
	ds_read_b128 v[178:181], v140 offset:2048
	ds_read_b128 v[182:185], v140 offset:3072
	s_add_u32 s70, s90, 0x80000
	s_addc_u32 s71, s91, 0
	s_mov_b32 m0, s54
	v_lshl_add_u64 v[224:225], s[70:71], 0, v[130:131]
	ds_read_b128 v[186:189], v149 offset:32768
	ds_read_b128 v[190:193], v149 offset:33792
	ds_read_b128 v[194:197], v149 offset:34816
	ds_read_b128 v[198:201], v149 offset:35840
	ds_read_b128 v[202:205], v149 offset:36864
	ds_read_b128 v[206:209], v149 offset:37888
	ds_read_b128 v[210:213], v149 offset:38912
	ds_read_b128 v[214:217], v149 offset:39936
	global_load_lds_dwordx4 v[224:225], off
	v_lshl_add_u64 v[224:225], s[70:71], 0, v[128:129]
	s_mov_b32 m0, s55
	s_nop 0
	global_load_lds_dwordx4 v[224:225], off
	s_waitcnt vmcnt(8)
	s_waitcnt lgkmcnt(0)
	s_barrier
	s_setprio 1
	s_waitcnt lgkmcnt(0)
	v_mfma_f32_16x16x32_bf16 v[124:127], v[154:157], v[186:189], v[124:127]
	v_mfma_f32_16x16x32_bf16 v[124:127], v[158:161], v[190:193], v[124:127]
	v_mfma_f32_16x16x32_bf16 v[120:123], v[166:169], v[190:193], v[120:123]
	v_mfma_f32_16x16x32_bf16 v[120:123], v[162:165], v[186:189], v[120:123]
	v_mfma_f32_16x16x32_bf16 v[112:115], v[162:165], v[194:197], v[112:115]
	v_mfma_f32_16x16x32_bf16 v[112:115], v[166:169], v[198:201], v[112:115]
	v_mfma_f32_16x16x32_bf16 v[116:119], v[158:161], v[198:201], v[116:119]
	v_mfma_f32_16x16x32_bf16 v[116:119], v[154:157], v[194:197], v[116:119]
	v_mfma_f32_16x16x32_bf16 v[108:111], v[154:157], v[202:205], v[108:111]
	v_mfma_f32_16x16x32_bf16 v[108:111], v[158:161], v[206:209], v[108:111]
	v_mfma_f32_16x16x32_bf16 v[104:107], v[166:169], v[206:209], v[104:107]
	v_mfma_f32_16x16x32_bf16 v[104:107], v[162:165], v[202:205], v[104:107]
	v_mfma_f32_16x16x32_bf16 v[96:99], v[162:165], v[210:213], v[96:99]
	v_mfma_f32_16x16x32_bf16 v[96:99], v[166:169], v[214:217], v[96:99]
	v_mfma_f32_16x16x32_bf16 v[100:103], v[158:161], v[214:217], v[100:103]
	v_mfma_f32_16x16x32_bf16 v[100:103], v[154:157], v[210:213], v[100:103]
	s_setprio 0
	s_setprio 1
	v_mfma_f32_16x16x32_bf16 v[92:95], v[170:173], v[186:189], v[92:95]
	v_mfma_f32_16x16x32_bf16 v[92:95], v[174:177], v[190:193], v[92:95]
	v_mfma_f32_16x16x32_bf16 v[88:91], v[182:185], v[190:193], v[88:91]
	v_mfma_f32_16x16x32_bf16 v[88:91], v[178:181], v[186:189], v[88:91]
	v_mfma_f32_16x16x32_bf16 v[80:83], v[178:181], v[194:197], v[80:83]
	v_mfma_f32_16x16x32_bf16 v[80:83], v[182:185], v[198:201], v[80:83]
	v_mfma_f32_16x16x32_bf16 v[84:87], v[174:177], v[198:201], v[84:87]
	v_mfma_f32_16x16x32_bf16 v[84:87], v[170:173], v[194:197], v[84:87]
	v_mfma_f32_16x16x32_bf16 v[76:79], v[170:173], v[202:205], v[76:79]
	v_mfma_f32_16x16x32_bf16 v[76:79], v[174:177], v[206:209], v[76:79]
	v_mfma_f32_16x16x32_bf16 v[72:75], v[182:185], v[206:209], v[72:75]
	v_mfma_f32_16x16x32_bf16 v[72:75], v[178:181], v[202:205], v[72:75]
	v_mfma_f32_16x16x32_bf16 v[64:67], v[178:181], v[210:213], v[64:67]
	v_mfma_f32_16x16x32_bf16 v[64:67], v[182:185], v[214:217], v[64:67]
	v_mfma_f32_16x16x32_bf16 v[68:71], v[174:177], v[214:217], v[68:71]
	v_mfma_f32_16x16x32_bf16 v[68:71], v[170:173], v[210:213], v[68:71]
	s_setprio 0
	s_barrier
; #define PG8_STAGE(bufoff, gbase, voff) do { _Pragma("unroll") for (int _i = 0; _i < 2; ++_i) \
;         __builtin_amdgcn_global_load_lds((const unsigned*)((const char*)(gbase) + (voff)[_i]), (PG8_LAS unsigned*)(lds + (bufoff) + ldsw + _i * 8192), 16, 0, 0); } while (0)
; #define PG8_LDA(dst, b, h) do { _Pragma("unroll") for (int m = 0; m < 4; ++m) _Pragma("unroll") for (int k = 0; k < 2; ++k) dst[m][k] = *(const PG8_LAS bf16x8*)(lds + PG8_SA(b, h) + aoff + m * 2048 + k * 1024); } while (0)
; #define PG8_MMA(ai, bj, At, Bt) do { __builtin_amdgcn_s_setprio(1); _Pragma("unroll") for (int m = 0; m < 4; ++m) _Pragma("unroll") for (int n = 0; n < 2; ++n) _Pragma("unroll") for (int k = 0; k < 2; ++k) \
;         acc[ai][bj][m][n] = __builtin_amdgcn_mfma_f32_16x16x32_bf16(Bt[n][k], At[m][k], acc[ai][bj][m][n], 0, 0, 0); __builtin_amdgcn_s_setprio(0); } while (0)
; #define PG8_WAIT_V(n) asm volatile("s_waitcnt vmcnt(" #n ")" ::: "memory")
; #define PG8_WAIT_L(n) asm volatile("s_waitcnt lgkmcnt(" #n ")" ::: "memory")
; #define PG8_BAR __builtin_amdgcn_s_barrier()
; #define PG8_SCHED __builtin_amdgcn_sched_barrier(0)
; template <class Epi, class Sched, bool ALIGN_EPI = false, bool SP2 = false, bool APERM = false  >
; __device__ __forceinline__ void gemm_phase(PG8_LAS unsigned char* lds, const Gemm g, const Sched& S, const Epi& E, const int wid  ) {
;     ...
;             PG8_LDA(At, 1, 1); PG8_STAGE(PG8_SB(1, 0), b3, voffB); PG8_STAGE(PG8_SB(1, 1), b3 + hstep, voffB); PG8_STAGE(PG8_SA(1, 0), a3, voffA);
;             PG8_WAIT_V(8); PG8_WAIT_L(0); PG8_BAR; PG8_MMA(1, 0, At, B0); PG8_MMA(1, 1, At, B1); PG8_BAR; PG8_SCHED;
;     ...
;         if constexpr (ALIGN_EPI) { if (wr == 0) PG8_BAR; }
	s_add_i32 s69, s69, s53
	v_lshl_add_u64 v[150:151], v[150:151], 0, s[14:15]
	s_mov_b32 m0, s69
	ds_read_b128 v[186:189], v149 offset:49152
	ds_read_b128 v[190:193], v149 offset:50176
	ds_read_b128 v[194:197], v149 offset:51200
	ds_read_b128 v[198:201], v149 offset:52224
	ds_read_b128 v[202:205], v149 offset:53248
	ds_read_b128 v[206:209], v149 offset:54272
	ds_read_b128 v[210:213], v149 offset:55296
	ds_read_b128 v[214:217], v149 offset:56320
	global_load_lds_dwordx4 v[150:151], off
	s_add_i32 m0, s69, 0x2000
	s_add_u32 s70, s88, 0x80080
	v_lshl_add_u64 v[150:151], v[218:219], 0, s[14:15]
	s_addc_u32 s71, s89, 0
	s_add_i32 s69, s72, s53
	global_load_lds_dwordx4 v[150:151], off
	v_lshl_add_u64 v[150:151], s[70:71], 0, v[130:131]
	s_mov_b32 m0, s69
	s_nop 0
	global_load_lds_dwordx4 v[150:151], off
	v_lshl_add_u64 v[150:151], s[70:71], 0, v[128:129]
	s_add_i32 m0, s69, 0x2000
	s_nop 0
	global_load_lds_dwordx4 v[150:151], off
	v_lshl_add_u64 v[150:151], v[220:221], 0, s[14:15]
	s_mov_b32 m0, s57
	s_nop 0
	global_load_lds_dwordx4 v[150:151], off
	v_lshl_add_u64 v[150:151], v[222:223], 0, s[14:15]
	s_mov_b32 m0, s58
	s_nop 0
	global_load_lds_dwordx4 v[150:151], off
	s_waitcnt vmcnt(8)
	s_waitcnt lgkmcnt(0)
	s_barrier
	s_setprio 1
	s_waitcnt lgkmcnt(0)
	v_mfma_f32_16x16x32_bf16 v[60:63], v[154:157], v[186:189], v[60:63]
	v_mfma_f32_16x16x32_bf16 v[60:63], v[158:161], v[190:193], v[60:63]
	v_mfma_f32_16x16x32_bf16 v[56:59], v[166:169], v[190:193], v[56:59]
	v_mfma_f32_16x16x32_bf16 v[56:59], v[162:165], v[186:189], v[56:59]
	v_mfma_f32_16x16x32_bf16 v[48:51], v[162:165], v[194:197], v[48:51]
	v_mfma_f32_16x16x32_bf16 v[48:51], v[166:169], v[198:201], v[48:51]
	v_mfma_f32_16x16x32_bf16 v[52:55], v[158:161], v[198:201], v[52:55]
	v_mfma_f32_16x16x32_bf16 v[52:55], v[154:157], v[194:197], v[52:55]
	v_mfma_f32_16x16x32_bf16 v[44:47], v[154:157], v[202:205], v[44:47]
	v_mfma_f32_16x16x32_bf16 v[44:47], v[158:161], v[206:209], v[44:47]
	v_mfma_f32_16x16x32_bf16 v[40:43], v[166:169], v[206:209], v[40:43]
	v_mfma_f32_16x16x32_bf16 v[40:43], v[162:165], v[202:205], v[40:43]
	v_mfma_f32_16x16x32_bf16 v[32:35], v[162:165], v[210:213], v[32:35]
	v_mfma_f32_16x16x32_bf16 v[32:35], v[166:169], v[214:217], v[32:35]
	v_mfma_f32_16x16x32_bf16 v[36:39], v[158:161], v[214:217], v[36:39]
	v_mfma_f32_16x16x32_bf16 v[36:39], v[154:157], v[210:213], v[36:39]
	s_setprio 0
	s_setprio 1
	v_mfma_f32_16x16x32_bf16 v[28:31], v[170:173], v[186:189], v[28:31]
	v_mfma_f32_16x16x32_bf16 v[28:31], v[174:177], v[190:193], v[28:31]
	v_mfma_f32_16x16x32_bf16 v[24:27], v[182:185], v[190:193], v[24:27]
	v_mfma_f32_16x16x32_bf16 v[24:27], v[178:181], v[186:189], v[24:27]
	v_mfma_f32_16x16x32_bf16 v[16:19], v[178:181], v[194:197], v[16:19]
	v_mfma_f32_16x16x32_bf16 v[16:19], v[182:185], v[198:201], v[16:19]
	v_mfma_f32_16x16x32_bf16 v[20:23], v[174:177], v[198:201], v[20:23]
	v_mfma_f32_16x16x32_bf16 v[20:23], v[170:173], v[194:197], v[20:23]
	v_mfma_f32_16x16x32_bf16 v[12:15], v[170:173], v[202:205], v[12:15]
	v_mfma_f32_16x16x32_bf16 v[12:15], v[174:177], v[206:209], v[12:15]
	v_mfma_f32_16x16x32_bf16 v[8:11], v[182:185], v[206:209], v[8:11]
	v_mfma_f32_16x16x32_bf16 v[8:11], v[178:181], v[202:205], v[8:11]
	v_mfma_f32_16x16x32_bf16 v[0:3], v[178:181], v[210:213], v[0:3]
	v_mfma_f32_16x16x32_bf16 v[0:3], v[182:185], v[214:217], v[0:3]
	v_mfma_f32_16x16x32_bf16 v[4:7], v[174:177], v[214:217], v[4:7]
	v_mfma_f32_16x16x32_bf16 v[4:7], v[170:173], v[210:213], v[4:7]
	s_setprio 0
	s_barrier
	s_add_i32 s68, s68, 2
	s_add_u32 s86, s86, 0x100
	s_addc_u32 s87, s87, 0
	s_cmp_gt_u32 s68, 29
	s_cbranch_scc0 .LBB0_84
	s_and_b64 vcc, exec, s[16:17]
	s_cbranch_vccz .LBB0_87
	s_barrier

; #define PG8_STAGE(bufoff, gbase, voff) do { _Pragma("unroll") for (int _i = 0; _i < 2; ++_i) \
;         __builtin_amdgcn_global_load_lds((const unsigned*)((const char*)(gbase) + (voff)[_i]), (PG8_LAS unsigned*)(lds + (bufoff) + ldsw + _i * 8192), 16, 0, 0); } while (0)
; #define PG8_LDA(dst, b, h) do { _Pragma("unroll") for (int m = 0; m < 4; ++m) _Pragma("unroll") for (int k = 0; k < 2; ++k) dst[m][k] = *(const PG8_LAS bf16x8*)(lds + PG8_SA(b, h) + aoff + m * 2048 + k * 1024); } while (0)
; #define PG8_LDB(dst, b, h) do { _Pragma("unroll") for (int n = 0; n < 2; ++n) _Pragma("unroll") for (int k = 0; k < 2; ++k) dst[n][k] = *(const PG8_LAS bf16x8*)(lds + PG8_SB(b, h) + boff + n * 2048 + k * 1024); } while (0)
; #define PG8_MMA(ai, bj, At, Bt) do { __builtin_amdgcn_s_setprio(1); _Pragma("unroll") for (int m = 0; m < 4; ++m) _Pragma("unroll") for (int n = 0; n < 2; ++n) _Pragma("unroll") for (int k = 0; k < 2; ++k) \
;         acc[ai][bj][m][n] = __builtin_amdgcn_mfma_f32_16x16x32_bf16(Bt[n][k], At[m][k], acc[ai][bj][m][n], 0, 0, 0); __builtin_amdgcn_s_setprio(0); } while (0)
; #define PG8_WAIT_V(n) asm volatile("s_waitcnt vmcnt(" #n ")" ::: "memory")
; #define PG8_WAIT_L(n) asm volatile("s_waitcnt lgkmcnt(" #n ")" ::: "memory")
; #define PG8_BAR __builtin_amdgcn_s_barrier()
; #define PG8_SCHED __builtin_amdgcn_sched_barrier(0)
; template <class Epi, class Sched, bool ALIGN_EPI = false, bool SP2 = false, bool APERM = false  >
; __device__ __forceinline__ void gemm_phase(PG8_LAS unsigned char* lds, const Gemm g, const Sched& S, const Epi& E, const int wid  ) {
;     ...
;             const bool last = (t == nt - 2);
;             const char* a1 = cA + (size_t)(t + 1) * kstep;
;             const char* a2 = last ? nA : cA + (size_t)(t + 2) * kstep; const char* b2 = last ? nB : cB + (size_t)(t + 2) * kstep;
;             const char* a3 = a2 + kstep; const char* b3 = b2 + kstep;
;             if (last && has_next) S.a_ready(nxt);
;             if constexpr (SP2) {
;             PG8_LDB(B0, 0, 0); PG8_LDB(B1, 0, 1); PG8_SCHED; PG8_LDA(At, 0, 0); PG8_STAGE(PG8_SA(1, 1), a1 + hstep, voffA);
;             PG8_WAIT_V(8); PG8_WAIT_L(0); PG8_BAR; PG8_MMA(0, 0, At, B0); PG8_MMA(0, 1, At, B1); PG8_BAR; PG8_SCHED;
;             PG8_LDA(At, 0, 1); PG8_STAGE(PG8_SB(0, 0), b2, voffB); PG8_STAGE(PG8_SB(0, 1), b2 + hstep, voffB); PG8_STAGE(PG8_SA(0, 0), a2, voffA);
.LBB0_310:
	s_or_b32 s58, s55, 1
	v_add_u32_e32 v159, s96, v153
	s_lshl_b64 s[64:65], s[58:59], 7
	s_add_i32 s58, s55, 2
	s_waitcnt lgkmcnt(0)
	ds_read_b128 v[144:147], v159
	ds_read_b128 v[148:151], v159 offset:1024
	ds_read_b128 v[160:163], v159 offset:2048
	ds_read_b128 v[164:167], v159 offset:3072
	v_add_u32_e32 v159, s97, v153
	s_lshl_b64 s[68:69], s[58:59], 7
	ds_read_b128 v[168:171], v159
	ds_read_b128 v[172:175], v159 offset:1024
	ds_read_b128 v[176:179], v159 offset:2048
	ds_read_b128 v[180:183], v159 offset:3072
	s_add_u32 s78, s0, s68
	s_addc_u32 s79, s1, s69
	s_and_b64 s[76:77], s[72:73], exec
	s_cselect_b32 vcc_hi, s13, s79
	s_cselect_b32 vcc_lo, s33, s78
	s_add_u32 s76, s14, s68
	s_addc_u32 s77, s15, s69
	s_and_b64 s[68:69], s[72:73], exec
	s_cselect_b32 s73, s9, s77
	s_cselect_b32 s72, s52, s76
	s_add_u32 s64, s53, s64
	s_addc_u32 s65, s54, s65
	v_lshl_add_u64 v[216:217], s[64:65], 0, v[132:133]
	s_add_i32 m0, s29, 0xc000
	ds_read_b128 v[184:187], v158
	ds_read_b128 v[188:191], v158 offset:1024
	ds_read_b128 v[192:195], v158 offset:2048
	ds_read_b128 v[196:199], v158 offset:3072
	ds_read_b128 v[200:203], v158 offset:4096
	ds_read_b128 v[204:207], v158 offset:5120
	ds_read_b128 v[208:211], v158 offset:6144
	ds_read_b128 v[212:215], v158 offset:7168
	global_load_lds_dwordx4 v[216:217], off
	v_lshl_add_u64 v[216:217], s[64:65], 0, v[136:137]
	s_add_i32 m0, s29, 0xe000
	s_nop 0
	global_load_lds_dwordx4 v[216:217], off
	s_waitcnt vmcnt(8)
	s_waitcnt lgkmcnt(0)
	s_barrier
	s_setprio 1
	s_waitcnt lgkmcnt(0)
	v_mfma_f32_16x16x32_bf16 v[124:127], v[144:147], v[184:187], v[124:127]
	v_mfma_f32_16x16x32_bf16 v[124:127], v[148:151], v[188:191], v[124:127]
	v_mfma_f32_16x16x32_bf16 v[120:123], v[164:167], v[188:191], v[120:123]
	v_mfma_f32_16x16x32_bf16 v[120:123], v[160:163], v[184:187], v[120:123]
	v_mfma_f32_16x16x32_bf16 v[112:115], v[160:163], v[192:195], v[112:115]
	v_mfma_f32_16x16x32_bf16 v[112:115], v[164:167], v[196:199], v[112:115]
	v_mfma_f32_16x16x32_bf16 v[116:119], v[148:151], v[196:199], v[116:119]
	v_mfma_f32_16x16x32_bf16 v[116:119], v[144:147], v[192:195], v[116:119]
	v_mfma_f32_16x16x32_bf16 v[108:111], v[144:147], v[200:203], v[108:111]
	v_mfma_f32_16x16x32_bf16 v[108:111], v[148:151], v[204:207], v[108:111]
	v_mfma_f32_16x16x32_bf16 v[104:107], v[164:167], v[204:207], v[104:107]
	v_mfma_f32_16x16x32_bf16 v[104:107], v[160:163], v[200:203], v[104:107]
	v_mfma_f32_16x16x32_bf16 v[96:99], v[160:163], v[208:211], v[96:99]
	v_mfma_f32_16x16x32_bf16 v[96:99], v[164:167], v[212:215], v[96:99]
	v_mfma_f32_16x16x32_bf16 v[100:103], v[148:151], v[212:215], v[100:103]
	v_mfma_f32_16x16x32_bf16 v[100:103], v[144:147], v[208:211], v[100:103]
	s_setprio 0
	s_setprio 1
	v_mfma_f32_16x16x32_bf16 v[92:95], v[168:171], v[184:187], v[92:95]
	v_mfma_f32_16x16x32_bf16 v[92:95], v[172:175], v[188:191], v[92:95]
	v_mfma_f32_16x16x32_bf16 v[88:91], v[180:183], v[188:191], v[88:91]
	v_mfma_f32_16x16x32_bf16 v[88:91], v[176:179], v[184:187], v[88:91]
	v_mfma_f32_16x16x32_bf16 v[80:83], v[176:179], v[192:195], v[80:83]
	v_mfma_f32_16x16x32_bf16 v[80:83], v[180:183], v[196:199], v[80:83]
	v_mfma_f32_16x16x32_bf16 v[84:87], v[172:175], v[196:199], v[84:87]
	v_mfma_f32_16x16x32_bf16 v[84:87], v[168:171], v[192:195], v[84:87]
	v_mfma_f32_16x16x32_bf16 v[76:79], v[168:171], v[200:203], v[76:79]
	v_mfma_f32_16x16x32_bf16 v[76:79], v[172:175], v[204:207], v[76:79]
	v_mfma_f32_16x16x32_bf16 v[72:75], v[180:183], v[204:207], v[72:75]
	v_mfma_f32_16x16x32_bf16 v[72:75], v[176:179], v[200:203], v[72:75]
	v_mfma_f32_16x16x32_bf16 v[64:67], v[176:179], v[208:211], v[64:67]
	v_mfma_f32_16x16x32_bf16 v[64:67], v[180:183], v[212:215], v[64:67]
	v_mfma_f32_16x16x32_bf16 v[68:71], v[172:175], v[212:215], v[68:71]
	v_mfma_f32_16x16x32_bf16 v[68:71], v[168:171], v[208:211], v[68:71]
	s_setprio 0
	s_barrier
	s_add_i32 s64, s96, s91
	v_lshl_add_u64 v[216:217], s[72:73], 0, v[128:129]
	s_mov_b32 m0, s64
	ds_read_b128 v[184:187], v158 offset:16384
	ds_read_b128 v[188:191], v158 offset:17408
	ds_read_b128 v[192:195], v158 offset:18432
	ds_read_b128 v[196:199], v158 offset:19456
	ds_read_b128 v[200:203], v158 offset:20480
	ds_read_b128 v[204:207], v158 offset:21504
	ds_read_b128 v[208:211], v158 offset:22528
	ds_read_b128 v[212:215], v158 offset:23552
	global_load_lds_dwordx4 v[216:217], off
	s_add_i32 m0, s64, 0x2000
	s_add_u32 s64, s72, 0x80000
	v_lshl_add_u64 v[218:219], s[72:73], 0, v[130:131]
	s_addc_u32 s65, s73, 0
	s_add_i32 s68, s97, s91
	global_load_lds_dwordx4 v[218:219], off
	v_lshl_add_u64 v[220:221], s[64:65], 0, v[128:129]
	s_mov_b32 m0, s68
	v_lshl_add_u64 v[222:223], vcc, 0, v[136:137]
	global_load_lds_dwordx4 v[220:221], off
	v_lshl_add_u64 v[220:221], s[64:65], 0, v[130:131]
	s_add_i32 m0, s68, 0x2000
	s_nop 0
	global_load_lds_dwordx4 v[220:221], off
	v_lshl_add_u64 v[220:221], vcc, 0, v[132:133]
	s_mov_b32 m0, s29
	s_nop 0
	global_load_lds_dwordx4 v[220:221], off
	s_mov_b32 m0, s57
	s_nop 0
	global_load_lds_dwordx4 v[222:223], off
	s_waitcnt vmcnt(8)
	s_waitcnt lgkmcnt(0)
	s_barrier
; #define PG8_STAGE(bufoff, gbase, voff) do { _Pragma("unroll") for (int _i = 0; _i < 2; ++_i) \
;         __builtin_amdgcn_global_load_lds((const unsigned*)((const char*)(gbase) + (voff)[_i]), (PG8_LAS unsigned*)(lds + (bufoff) + ldsw + _i * 8192), 16, 0, 0); } while (0)
; #define PG8_LDA(dst, b, h) do { _Pragma("unroll") for (int m = 0; m < 4; ++m) _Pragma("unroll") for (int k = 0; k < 2; ++k) dst[m][k] = *(const PG8_LAS bf16x8*)(lds + PG8_SA(b, h) + aoff + m * 2048 + k * 1024); } while (0)
; #define PG8_LDB(dst, b, h) do { _Pragma("unroll") for (int n = 0; n < 2; ++n) _Pragma("unroll") for (int k = 0; k < 2; ++k) dst[n][k] = *(const PG8_LAS bf16x8*)(lds + PG8_SB(b, h) + boff + n * 2048 + k * 1024); } while (0)
; #define PG8_MMA(ai, bj, At, Bt) do { __builtin_amdgcn_s_setprio(1); _Pragma("unroll") for (int m = 0; m < 4; ++m) _Pragma("unroll") for (int n = 0; n < 2; ++n) _Pragma("unroll") for (int k = 0; k < 2; ++k) \
;         acc[ai][bj][m][n] = __builtin_amdgcn_mfma_f32_16x16x32_bf16(Bt[n][k], At[m][k], acc[ai][bj][m][n], 0, 0, 0); __builtin_amdgcn_s_setprio(0); } while (0)
; #define PG8_WAIT_V(n) asm volatile("s_waitcnt vmcnt(" #n ")" ::: "memory")
; #define PG8_WAIT_L(n) asm volatile("s_waitcnt lgkmcnt(" #n ")" ::: "memory")
; #define PG8_BAR __builtin_amdgcn_s_barrier()
; #define PG8_SCHED __builtin_amdgcn_sched_barrier(0)
; template <class Epi, class Sched, bool ALIGN_EPI = false, bool SP2 = false, bool APERM = false  >
; __device__ __forceinline__ void gemm_phase(PG8_LAS unsigned char* lds, const Gemm g, const Sched& S, const Epi& E, const int wid  ) {
;     ...
;             PG8_WAIT_V(8); PG8_WAIT_L(0); PG8_BAR; PG8_MMA(1, 0, At, B0); PG8_MMA(1, 1, At, B1); PG8_BAR; PG8_SCHED;
;             PG8_LDB(B0, 1, 0); PG8_LDB(B1, 1, 1); PG8_SCHED; PG8_LDA(At, 1, 0); PG8_STAGE(PG8_SA(0, 1), a2 + hstep, voffA);
;             PG8_WAIT_V(8); PG8_WAIT_L(0); PG8_BAR; PG8_MMA(0, 0, At, B0); PG8_MMA(0, 1, At, B1); PG8_BAR; PG8_SCHED;
	s_setprio 1
	s_waitcnt lgkmcnt(0)
	v_mfma_f32_16x16x32_bf16 v[60:63], v[144:147], v[184:187], v[60:63]
	v_mfma_f32_16x16x32_bf16 v[60:63], v[148:151], v[188:191], v[60:63]
	v_mfma_f32_16x16x32_bf16 v[56:59], v[164:167], v[188:191], v[56:59]
	v_mfma_f32_16x16x32_bf16 v[56:59], v[160:163], v[184:187], v[56:59]
	v_mfma_f32_16x16x32_bf16 v[48:51], v[160:163], v[192:195], v[48:51]
	v_mfma_f32_16x16x32_bf16 v[48:51], v[164:167], v[196:199], v[48:51]
	v_mfma_f32_16x16x32_bf16 v[52:55], v[148:151], v[196:199], v[52:55]
	v_mfma_f32_16x16x32_bf16 v[52:55], v[144:147], v[192:195], v[52:55]
	v_mfma_f32_16x16x32_bf16 v[44:47], v[144:147], v[200:203], v[44:47]
	v_mfma_f32_16x16x32_bf16 v[44:47], v[148:151], v[204:207], v[44:47]
	v_mfma_f32_16x16x32_bf16 v[40:43], v[164:167], v[204:207], v[40:43]
	v_mfma_f32_16x16x32_bf16 v[40:43], v[160:163], v[200:203], v[40:43]
	v_mfma_f32_16x16x32_bf16 v[32:35], v[160:163], v[208:211], v[32:35]
	v_mfma_f32_16x16x32_bf16 v[32:35], v[164:167], v[212:215], v[32:35]
	v_mfma_f32_16x16x32_bf16 v[36:39], v[148:151], v[212:215], v[36:39]
	v_mfma_f32_16x16x32_bf16 v[36:39], v[144:147], v[208:211], v[36:39]
	s_setprio 0
	s_setprio 1
	v_mfma_f32_16x16x32_bf16 v[28:31], v[168:171], v[184:187], v[28:31]
	v_mfma_f32_16x16x32_bf16 v[28:31], v[172:175], v[188:191], v[28:31]
	v_mfma_f32_16x16x32_bf16 v[24:27], v[180:183], v[188:191], v[24:27]
	v_mfma_f32_16x16x32_bf16 v[24:27], v[176:179], v[184:187], v[24:27]
	v_mfma_f32_16x16x32_bf16 v[16:19], v[176:179], v[192:195], v[16:19]
	v_mfma_f32_16x16x32_bf16 v[16:19], v[180:183], v[196:199], v[16:19]
	v_mfma_f32_16x16x32_bf16 v[20:23], v[172:175], v[196:199], v[20:23]
	v_mfma_f32_16x16x32_bf16 v[20:23], v[168:171], v[192:195], v[20:23]
	v_mfma_f32_16x16x32_bf16 v[12:15], v[168:171], v[200:203], v[12:15]
	v_mfma_f32_16x16x32_bf16 v[12:15], v[172:175], v[204:207], v[12:15]
	v_mfma_f32_16x16x32_bf16 v[8:11], v[180:183], v[204:207], v[8:11]
	v_mfma_f32_16x16x32_bf16 v[8:11], v[176:179], v[200:203], v[8:11]
	v_mfma_f32_16x16x32_bf16 v[0:3], v[176:179], v[208:211], v[0:3]
	v_mfma_f32_16x16x32_bf16 v[0:3], v[180:183], v[212:215], v[0:3]
	v_mfma_f32_16x16x32_bf16 v[4:7], v[172:175], v[212:215], v[4:7]
	v_mfma_f32_16x16x32_bf16 v[4:7], v[168:171], v[208:211], v[4:7]
	s_setprio 0
	s_barrier
	s_add_i32 s68, 0, 0x18000
	v_add_u32_e32 v159, s68, v153
	s_add_i32 s69, 0, 0x1c000
	ds_read_b128 v[144:147], v159
	ds_read_b128 v[148:151], v159 offset:1024
	ds_read_b128 v[160:163], v159 offset:2048
	ds_read_b128 v[164:167], v159 offset:3072
	v_add_u32_e32 v159, s69, v153
	ds_read_b128 v[168:171], v159
	ds_read_b128 v[172:175], v159 offset:1024
	ds_read_b128 v[176:179], v159 offset:2048
	ds_read_b128 v[180:183], v159 offset:3072
	s_add_u32 s64, vcc_lo, 0x80000
	s_addc_u32 s65, vcc_hi, 0
	s_mov_b32 m0, s92
	v_lshl_add_u64 v[224:225], s[64:65], 0, v[132:133]
	ds_read_b128 v[184:187], v158 offset:32768
	ds_read_b128 v[188:191], v158 offset:33792
	ds_read_b128 v[192:195], v158 offset:34816
	ds_read_b128 v[196:199], v158 offset:35840
	ds_read_b128 v[200:203], v158 offset:36864
	ds_read_b128 v[204:207], v158 offset:37888
	ds_read_b128 v[208:211], v158 offset:38912
	ds_read_b128 v[212:215], v158 offset:39936
	global_load_lds_dwordx4 v[224:225], off
	v_lshl_add_u64 v[224:225], s[64:65], 0, v[136:137]
	s_mov_b32 m0, s93
	s_nop 0
	global_load_lds_dwordx4 v[224:225], off
	s_waitcnt vmcnt(8)
	s_waitcnt lgkmcnt(0)
	s_barrier
	s_setprio 1
	s_waitcnt lgkmcnt(0)
	v_mfma_f32_16x16x32_bf16 v[124:127], v[144:147], v[184:187], v[124:127]
	v_mfma_f32_16x16x32_bf16 v[124:127], v[148:151], v[188:191], v[124:127]
	v_mfma_f32_16x16x32_bf16 v[120:123], v[164:167], v[188:191], v[120:123]
	v_mfma_f32_16x16x32_bf16 v[120:123], v[160:163], v[184:187], v[120:123]
	v_mfma_f32_16x16x32_bf16 v[112:115], v[160:163], v[192:195], v[112:115]
	v_mfma_f32_16x16x32_bf16 v[112:115], v[164:167], v[196:199], v[112:115]
	v_mfma_f32_16x16x32_bf16 v[116:119], v[148:151], v[196:199], v[116:119]
	v_mfma_f32_16x16x32_bf16 v[116:119], v[144:147], v[192:195], v[116:119]
	v_mfma_f32_16x16x32_bf16 v[108:111], v[144:147], v[200:203], v[108:111]
	v_mfma_f32_16x16x32_bf16 v[108:111], v[148:151], v[204:207], v[108:111]
	v_mfma_f32_16x16x32_bf16 v[104:107], v[164:167], v[204:207], v[104:107]
	v_mfma_f32_16x16x32_bf16 v[104:107], v[160:163], v[200:203], v[104:107]
	v_mfma_f32_16x16x32_bf16 v[96:99], v[160:163], v[208:211], v[96:99]
	v_mfma_f32_16x16x32_bf16 v[96:99], v[164:167], v[212:215], v[96:99]
	v_mfma_f32_16x16x32_bf16 v[100:103], v[148:151], v[212:215], v[100:103]
	v_mfma_f32_16x16x32_bf16 v[100:103], v[144:147], v[208:211], v[100:103]
	s_setprio 0
	s_setprio 1
	v_mfma_f32_16x16x32_bf16 v[92:95], v[168:171], v[184:187], v[92:95]
	v_mfma_f32_16x16x32_bf16 v[92:95], v[172:175], v[188:191], v[92:95]
	v_mfma_f32_16x16x32_bf16 v[88:91], v[180:183], v[188:191], v[88:91]
	v_mfma_f32_16x16x32_bf16 v[88:91], v[176:179], v[184:187], v[88:91]
	v_mfma_f32_16x16x32_bf16 v[80:83], v[176:179], v[192:195], v[80:83]
	v_mfma_f32_16x16x32_bf16 v[80:83], v[180:183], v[196:199], v[80:83]
	v_mfma_f32_16x16x32_bf16 v[84:87], v[172:175], v[196:199], v[84:87]
	v_mfma_f32_16x16x32_bf16 v[84:87], v[168:171], v[192:195], v[84:87]
	v_mfma_f32_16x16x32_bf16 v[76:79], v[168:171], v[200:203], v[76:79]
	v_mfma_f32_16x16x32_bf16 v[76:79], v[172:175], v[204:207], v[76:79]
	v_mfma_f32_16x16x32_bf16 v[72:75], v[180:183], v[204:207], v[72:75]
	v_mfma_f32_16x16x32_bf16 v[72:75], v[176:179], v[200:203], v[72:75]
	v_mfma_f32_16x16x32_bf16 v[64:67], v[176:179], v[208:211], v[64:67]
	v_mfma_f32_16x16x32_bf16 v[64:67], v[180:183], v[212:215], v[64:67]
	v_mfma_f32_16x16x32_bf16 v[68:71], v[172:175], v[212:215], v[68:71]
	v_mfma_f32_16x16x32_bf16 v[68:71], v[168:171], v[208:211], v[68:71]
	s_setprio 0
	s_barrier
; #define PG8_STAGE(bufoff, gbase, voff) do { _Pragma("unroll") for (int _i = 0; _i < 2; ++_i) \
;         __builtin_amdgcn_global_load_lds((const unsigned*)((const char*)(gbase) + (voff)[_i]), (PG8_LAS unsigned*)(lds + (bufoff) + ldsw + _i * 8192), 16, 0, 0); } while (0)
; #define PG8_LDA(dst, b, h) do { _Pragma("unroll") for (int m = 0; m < 4; ++m) _Pragma("unroll") for (int k = 0; k < 2; ++k) dst[m][k] = *(const PG8_LAS bf16x8*)(lds + PG8_SA(b, h) + aoff + m * 2048 + k * 1024); } while (0)
; #define PG8_MMA(ai, bj, At, Bt) do { __builtin_amdgcn_s_setprio(1); _Pragma("unroll") for (int m = 0; m < 4; ++m) _Pragma("unroll") for (int n = 0; n < 2; ++n) _Pragma("unroll") for (int k = 0; k < 2; ++k) \
;         acc[ai][bj][m][n] = __builtin_amdgcn_mfma_f32_16x16x32_bf16(Bt[n][k], At[m][k], acc[ai][bj][m][n], 0, 0, 0); __builtin_amdgcn_s_setprio(0); } while (0)
; #define PG8_WAIT_V(n) asm volatile("s_waitcnt vmcnt(" #n ")" ::: "memory")
; #define PG8_WAIT_L(n) asm volatile("s_waitcnt lgkmcnt(" #n ")" ::: "memory")
; #define PG8_BAR __builtin_amdgcn_s_barrier()
; #define PG8_SCHED __builtin_amdgcn_sched_barrier(0)
; template <class Epi, class Sched, bool ALIGN_EPI = false, bool SP2 = false, bool APERM = false  >
; __device__ __forceinline__ void gemm_phase(PG8_LAS unsigned char* lds, const Gemm g, const Sched& S, const Epi& E, const int wid  ) {
;     ...
;         for (int t = 0; t < nt; t += 2) {
;             const bool last = (t == nt - 2);
;             const char* a1 = cA + (size_t)(t + 1) * kstep;
;             const char* a2 = last ? nA : cA + (size_t)(t + 2) * kstep; const char* b2 = last ? nB : cB + (size_t)(t + 2) * kstep;
;     ...
;             PG8_LDA(At, 1, 1); PG8_STAGE(PG8_SB(1, 0), b3, voffB); PG8_STAGE(PG8_SB(1, 1), b3 + hstep, voffB); PG8_STAGE(PG8_SA(1, 0), a3, voffA);
;             PG8_WAIT_V(8); PG8_WAIT_L(0); PG8_BAR; PG8_MMA(1, 0, At, B0); PG8_MMA(1, 1, At, B1); PG8_BAR; PG8_SCHED;
	s_add_i32 s64, s68, s91
	v_lshl_add_u64 v[216:217], v[216:217], 0, s[60:61]
	s_mov_b32 m0, s64
	ds_read_b128 v[184:187], v158 offset:49152
	ds_read_b128 v[188:191], v158 offset:50176
	ds_read_b128 v[192:195], v158 offset:51200
	ds_read_b128 v[196:199], v158 offset:52224
	ds_read_b128 v[200:203], v158 offset:53248
	ds_read_b128 v[204:207], v158 offset:54272
	ds_read_b128 v[208:211], v158 offset:55296
	ds_read_b128 v[212:215], v158 offset:56320
	global_load_lds_dwordx4 v[216:217], off
	s_add_i32 m0, s64, 0x2000
	s_add_u32 s64, s72, 0x80080
	v_lshl_add_u64 v[216:217], v[218:219], 0, s[60:61]
	s_addc_u32 s65, s73, 0
	s_add_i32 s68, s69, s91
	global_load_lds_dwordx4 v[216:217], off
	v_lshl_add_u64 v[216:217], s[64:65], 0, v[128:129]
	s_mov_b32 m0, s68
	s_nop 0
	global_load_lds_dwordx4 v[216:217], off
	v_lshl_add_u64 v[216:217], s[64:65], 0, v[130:131]
	s_add_i32 m0, s68, 0x2000
	s_nop 0
	global_load_lds_dwordx4 v[216:217], off
	v_lshl_add_u64 v[216:217], v[220:221], 0, s[60:61]
	s_mov_b32 m0, s94
	s_nop 0
	global_load_lds_dwordx4 v[216:217], off
	v_lshl_add_u64 v[216:217], v[222:223], 0, s[60:61]
	s_mov_b32 m0, s95
	s_nop 0
	global_load_lds_dwordx4 v[216:217], off
	s_waitcnt vmcnt(8)
	s_waitcnt lgkmcnt(0)
	s_barrier
	s_setprio 1
	s_waitcnt lgkmcnt(0)
	v_mfma_f32_16x16x32_bf16 v[60:63], v[144:147], v[184:187], v[60:63]
	v_mfma_f32_16x16x32_bf16 v[60:63], v[148:151], v[188:191], v[60:63]
	v_mfma_f32_16x16x32_bf16 v[56:59], v[164:167], v[188:191], v[56:59]
	v_mfma_f32_16x16x32_bf16 v[56:59], v[160:163], v[184:187], v[56:59]
	v_mfma_f32_16x16x32_bf16 v[48:51], v[160:163], v[192:195], v[48:51]
	v_mfma_f32_16x16x32_bf16 v[48:51], v[164:167], v[196:199], v[48:51]
	v_mfma_f32_16x16x32_bf16 v[52:55], v[148:151], v[196:199], v[52:55]
	v_mfma_f32_16x16x32_bf16 v[52:55], v[144:147], v[192:195], v[52:55]
	v_mfma_f32_16x16x32_bf16 v[44:47], v[144:147], v[200:203], v[44:47]
	v_mfma_f32_16x16x32_bf16 v[44:47], v[148:151], v[204:207], v[44:47]
	v_mfma_f32_16x16x32_bf16 v[40:43], v[164:167], v[204:207], v[40:43]
	v_mfma_f32_16x16x32_bf16 v[40:43], v[160:163], v[200:203], v[40:43]
	v_mfma_f32_16x16x32_bf16 v[32:35], v[160:163], v[208:211], v[32:35]
	v_mfma_f32_16x16x32_bf16 v[32:35], v[164:167], v[212:215], v[32:35]
	v_mfma_f32_16x16x32_bf16 v[36:39], v[148:151], v[212:215], v[36:39]
	v_mfma_f32_16x16x32_bf16 v[36:39], v[144:147], v[208:211], v[36:39]
	s_setprio 0
	s_setprio 1
	v_mfma_f32_16x16x32_bf16 v[28:31], v[168:171], v[184:187], v[28:31]
	v_mfma_f32_16x16x32_bf16 v[28:31], v[172:175], v[188:191], v[28:31]
	v_mfma_f32_16x16x32_bf16 v[24:27], v[180:183], v[188:191], v[24:27]
	v_mfma_f32_16x16x32_bf16 v[24:27], v[176:179], v[184:187], v[24:27]
	v_mfma_f32_16x16x32_bf16 v[16:19], v[176:179], v[192:195], v[16:19]
	v_mfma_f32_16x16x32_bf16 v[16:19], v[180:183], v[196:199], v[16:19]
	v_mfma_f32_16x16x32_bf16 v[20:23], v[172:175], v[196:199], v[20:23]
	v_mfma_f32_16x16x32_bf16 v[20:23], v[168:171], v[192:195], v[20:23]
	v_mfma_f32_16x16x32_bf16 v[12:15], v[168:171], v[200:203], v[12:15]
	v_mfma_f32_16x16x32_bf16 v[12:15], v[172:175], v[204:207], v[12:15]
	v_mfma_f32_16x16x32_bf16 v[8:11], v[180:183], v[204:207], v[8:11]
	v_mfma_f32_16x16x32_bf16 v[8:11], v[176:179], v[200:203], v[8:11]
	v_mfma_f32_16x16x32_bf16 v[0:3], v[176:179], v[208:211], v[0:3]
	v_mfma_f32_16x16x32_bf16 v[0:3], v[180:183], v[212:215], v[0:3]
	v_mfma_f32_16x16x32_bf16 v[4:7], v[172:175], v[212:215], v[4:7]
	v_mfma_f32_16x16x32_bf16 v[4:7], v[168:171], v[208:211], v[4:7]
	s_setprio 0
	s_barrier
	s_cmp_gt_u32 s55, 29
	s_cbranch_scc1 .LBB0_312
	s_mov_b32 s55, s58
	s_branch .LBB0_293

; #define PG8_STAGE(bufoff, gbase, voff) do { _Pragma("unroll") for (int _i = 0; _i < 2; ++_i) \
;         __builtin_amdgcn_global_load_lds((const unsigned*)((const char*)(gbase) + (voff)[_i]), (PG8_LAS unsigned*)(lds + (bufoff) + ldsw + _i * 8192), 16, 0, 0); } while (0)
; #define PG8_LDA(dst, b, h) do { _Pragma("unroll") for (int m = 0; m < 4; ++m) _Pragma("unroll") for (int k = 0; k < 2; ++k) dst[m][k] = *(const PG8_LAS bf16x8*)(lds + PG8_SA(b, h) + aoff + m * 2048 + k * 1024); } while (0)
; #define PG8_LDB(dst, b, h) do { _Pragma("unroll") for (int n = 0; n < 2; ++n) _Pragma("unroll") for (int k = 0; k < 2; ++k) dst[n][k] = *(const PG8_LAS bf16x8*)(lds + PG8_SB(b, h) + boff + n * 2048 + k * 1024); } while (0)
; #define PG8_MMA(ai, bj, At, Bt) do { __builtin_amdgcn_s_setprio(1); _Pragma("unroll") for (int m = 0; m < 4; ++m) _Pragma("unroll") for (int n = 0; n < 2; ++n) _Pragma("unroll") for (int k = 0; k < 2; ++k) \
;         acc[ai][bj][m][n] = __builtin_amdgcn_mfma_f32_16x16x32_bf16(Bt[n][k], At[m][k], acc[ai][bj][m][n], 0, 0, 0); __builtin_amdgcn_s_setprio(0); } while (0)
; #define PG8_WAIT_V(n) asm volatile("s_waitcnt vmcnt(" #n ")" ::: "memory")
; #define PG8_WAIT_L(n) asm volatile("s_waitcnt lgkmcnt(" #n ")" ::: "memory")
; #define PG8_BAR __builtin_amdgcn_s_barrier()
; #define PG8_SCHED __builtin_amdgcn_sched_barrier(0)
; template <class Epi, class Sched, bool ALIGN_EPI = false, bool SP2 = false, bool APERM = false  >
; __device__ __forceinline__ void gemm_phase(PG8_LAS unsigned char* lds, const Gemm g, const Sched& S, const Epi& E, const int wid  ) {
;     ...
;             const bool last = (t == nt - 2);
;             const char* a1 = cA + (size_t)(t + 1) * kstep;
;             const char* a2 = last ? nA : cA + (size_t)(t + 2) * kstep; const char* b2 = last ? nB : cB + (size_t)(t + 2) * kstep;
;             const char* a3 = a2 + kstep; const char* b3 = b2 + kstep;
;             if (last && has_next) S.a_ready(nxt);
;             if constexpr (SP2) {
;             PG8_LDB(B0, 0, 0); PG8_LDB(B1, 0, 1); PG8_SCHED; PG8_LDA(At, 0, 0); PG8_STAGE(PG8_SA(1, 1), a1 + hstep, voffA);
;             PG8_WAIT_V(8); PG8_WAIT_L(0); PG8_BAR; PG8_MMA(0, 0, At, B0); PG8_MMA(0, 1, At, B1); PG8_BAR; PG8_SCHED;
;             PG8_LDA(At, 0, 1); PG8_STAGE(PG8_SB(0, 0), b2, voffB); PG8_STAGE(PG8_SB(0, 1), b2 + hstep, voffB); PG8_STAGE(PG8_SA(0, 0), a2, voffA);
.LBB0_390:
	s_lshl_b32 s6, s47, 7
	s_add_u32 s7, s60, s6
	s_addc_u32 s16, s61, 0
	s_add_u32 s14, s7, 0x100
	s_addc_u32 s15, s16, 0
	v_add_u32_e32 v140, s90, v230
	v_add_u32_e32 v156, s74, v230
	s_and_b64 s[0:1], s[12:13], exec
	ds_read_b128 v[128:131], v140
	ds_read_b128 v[132:135], v140 offset:1024
	ds_read_b128 v[136:139], v140 offset:2048
	ds_read_b128 v[140:143], v140 offset:3072
	ds_read_b128 v[144:147], v156
	ds_read_b128 v[148:151], v156 offset:1024
	ds_read_b128 v[152:155], v156 offset:2048
	ds_read_b128 v[156:159], v156 offset:3072
	s_cselect_b32 s15, s31, s15
	s_cselect_b32 s14, s33, s14
	s_add_u32 s0, s56, s6
	s_addc_u32 s1, s57, 0
	s_add_u32 s6, s0, 0x100
	s_addc_u32 s17, s1, 0
	s_and_b64 s[0:1], s[12:13], exec
	s_cselect_b32 s0, s46, s6
	s_cselect_b32 s1, s35, s17
	s_add_u32 s6, s7, 0x80080
	s_addc_u32 s7, s16, 0
	v_lshl_add_u64 v[206:207], s[6:7], 0, v[188:189]
	s_add_i32 m0, s5, 0xc000
	ds_read_b128 v[160:163], v243
	ds_read_b128 v[164:167], v243 offset:1024
	ds_read_b128 v[168:171], v243 offset:2048
	ds_read_b128 v[172:175], v243 offset:3072
	ds_read_b128 v[176:179], v243 offset:4096
	ds_read_b128 v[180:183], v243 offset:5120
	ds_read_b128 v[198:201], v243 offset:6144
	ds_read_b128 v[202:205], v243 offset:7168
	global_load_lds_dwordx4 v[206:207], off
	v_lshl_add_u64 v[206:207], s[6:7], 0, v[190:191]
	s_add_i32 m0, s5, 0xe000
	s_nop 0
	global_load_lds_dwordx4 v[206:207], off
	s_waitcnt vmcnt(8)
	s_waitcnt lgkmcnt(0)
	s_barrier
	s_setprio 1
	s_waitcnt lgkmcnt(0)
	v_mfma_f32_16x16x32_bf16 v[124:127], v[128:131], v[160:163], v[124:127]
	v_mfma_f32_16x16x32_bf16 v[124:127], v[132:135], v[164:167], v[124:127]
	v_mfma_f32_16x16x32_bf16 v[120:123], v[140:143], v[164:167], v[120:123]
	v_mfma_f32_16x16x32_bf16 v[120:123], v[136:139], v[160:163], v[120:123]
	v_mfma_f32_16x16x32_bf16 v[112:115], v[136:139], v[168:171], v[112:115]
	v_mfma_f32_16x16x32_bf16 v[112:115], v[140:143], v[172:175], v[112:115]
	v_mfma_f32_16x16x32_bf16 v[116:119], v[132:135], v[172:175], v[116:119]
	v_mfma_f32_16x16x32_bf16 v[116:119], v[128:131], v[168:171], v[116:119]
	v_mfma_f32_16x16x32_bf16 v[108:111], v[128:131], v[176:179], v[108:111]
	v_mfma_f32_16x16x32_bf16 v[108:111], v[132:135], v[180:183], v[108:111]
	v_mfma_f32_16x16x32_bf16 v[104:107], v[140:143], v[180:183], v[104:107]
	v_mfma_f32_16x16x32_bf16 v[104:107], v[136:139], v[176:179], v[104:107]
	v_mfma_f32_16x16x32_bf16 v[96:99], v[136:139], v[198:201], v[96:99]
	v_mfma_f32_16x16x32_bf16 v[96:99], v[140:143], v[202:205], v[96:99]
	v_mfma_f32_16x16x32_bf16 v[100:103], v[132:135], v[202:205], v[100:103]
	v_mfma_f32_16x16x32_bf16 v[100:103], v[128:131], v[198:201], v[100:103]
	s_setprio 0
	s_setprio 1
	v_mfma_f32_16x16x32_bf16 v[92:95], v[144:147], v[160:163], v[92:95]
	v_mfma_f32_16x16x32_bf16 v[92:95], v[148:151], v[164:167], v[92:95]
	v_mfma_f32_16x16x32_bf16 v[88:91], v[156:159], v[164:167], v[88:91]
	v_mfma_f32_16x16x32_bf16 v[88:91], v[152:155], v[160:163], v[88:91]
	v_mfma_f32_16x16x32_bf16 v[80:83], v[152:155], v[168:171], v[80:83]
	v_mfma_f32_16x16x32_bf16 v[80:83], v[156:159], v[172:175], v[80:83]
	v_mfma_f32_16x16x32_bf16 v[84:87], v[148:151], v[172:175], v[84:87]
	v_mfma_f32_16x16x32_bf16 v[84:87], v[144:147], v[168:171], v[84:87]
	v_mfma_f32_16x16x32_bf16 v[76:79], v[144:147], v[176:179], v[76:79]
	v_mfma_f32_16x16x32_bf16 v[76:79], v[148:151], v[180:183], v[76:79]
	v_mfma_f32_16x16x32_bf16 v[72:75], v[156:159], v[180:183], v[72:75]
	v_mfma_f32_16x16x32_bf16 v[72:75], v[152:155], v[176:179], v[72:75]
	v_mfma_f32_16x16x32_bf16 v[64:67], v[152:155], v[198:201], v[64:67]
	v_mfma_f32_16x16x32_bf16 v[64:67], v[156:159], v[202:205], v[64:67]
	v_mfma_f32_16x16x32_bf16 v[68:71], v[148:151], v[202:205], v[68:71]
	v_mfma_f32_16x16x32_bf16 v[68:71], v[144:147], v[198:201], v[68:71]
	s_setprio 0
	s_barrier
	s_add_i32 s6, s90, s63
	v_lshl_add_u64 v[206:207], s[0:1], 0, v[184:185]
	s_mov_b32 m0, s6
	ds_read_b128 v[160:163], v243 offset:16384
	ds_read_b128 v[164:167], v243 offset:17408
	ds_read_b128 v[168:171], v243 offset:18432
	ds_read_b128 v[172:175], v243 offset:19456
	ds_read_b128 v[176:179], v243 offset:20480
	ds_read_b128 v[180:183], v243 offset:21504
	ds_read_b128 v[198:201], v243 offset:22528
	ds_read_b128 v[202:205], v243 offset:23552
	global_load_lds_dwordx4 v[206:207], off
	s_add_i32 m0, s6, 0x2000
	s_add_u32 s6, s0, 0x80000
	v_lshl_add_u64 v[208:209], s[0:1], 0, v[186:187]
	s_addc_u32 s7, s1, 0
	s_add_i32 s12, s74, s63
	global_load_lds_dwordx4 v[208:209], off
	v_lshl_add_u64 v[210:211], s[6:7], 0, v[184:185]
	s_mov_b32 m0, s12
	v_lshl_add_u64 v[212:213], s[14:15], 0, v[190:191]
	global_load_lds_dwordx4 v[210:211], off
	v_lshl_add_u64 v[210:211], s[6:7], 0, v[186:187]
	s_add_i32 m0, s12, 0x2000
	s_nop 0
	global_load_lds_dwordx4 v[210:211], off
	v_lshl_add_u64 v[210:211], s[14:15], 0, v[188:189]
	s_mov_b32 m0, s5
	s_nop 0
	global_load_lds_dwordx4 v[210:211], off
	s_mov_b32 m0, s87
	s_nop 0
	global_load_lds_dwordx4 v[212:213], off
	s_waitcnt vmcnt(8)
	s_waitcnt lgkmcnt(0)
	s_barrier
; #define PG8_STAGE(bufoff, gbase, voff) do { _Pragma("unroll") for (int _i = 0; _i < 2; ++_i) \
;         __builtin_amdgcn_global_load_lds((const unsigned*)((const char*)(gbase) + (voff)[_i]), (PG8_LAS unsigned*)(lds + (bufoff) + ldsw + _i * 8192), 16, 0, 0); } while (0)
; #define PG8_LDA(dst, b, h) do { _Pragma("unroll") for (int m = 0; m < 4; ++m) _Pragma("unroll") for (int k = 0; k < 2; ++k) dst[m][k] = *(const PG8_LAS bf16x8*)(lds + PG8_SA(b, h) + aoff + m * 2048 + k * 1024); } while (0)
; #define PG8_LDB(dst, b, h) do { _Pragma("unroll") for (int n = 0; n < 2; ++n) _Pragma("unroll") for (int k = 0; k < 2; ++k) dst[n][k] = *(const PG8_LAS bf16x8*)(lds + PG8_SB(b, h) + boff + n * 2048 + k * 1024); } while (0)
; #define PG8_MMA(ai, bj, At, Bt) do { __builtin_amdgcn_s_setprio(1); _Pragma("unroll") for (int m = 0; m < 4; ++m) _Pragma("unroll") for (int n = 0; n < 2; ++n) _Pragma("unroll") for (int k = 0; k < 2; ++k) \
;         acc[ai][bj][m][n] = __builtin_amdgcn_mfma_f32_16x16x32_bf16(Bt[n][k], At[m][k], acc[ai][bj][m][n], 0, 0, 0); __builtin_amdgcn_s_setprio(0); } while (0)
; #define PG8_WAIT_V(n) asm volatile("s_waitcnt vmcnt(" #n ")" ::: "memory")
; #define PG8_WAIT_L(n) asm volatile("s_waitcnt lgkmcnt(" #n ")" ::: "memory")
; #define PG8_BAR __builtin_amdgcn_s_barrier()
; #define PG8_SCHED __builtin_amdgcn_sched_barrier(0)
; template <class Epi, class Sched, bool ALIGN_EPI = false, bool SP2 = false, bool APERM = false  >
; __device__ __forceinline__ void gemm_phase(PG8_LAS unsigned char* lds, const Gemm g, const Sched& S, const Epi& E, const int wid  ) {
;     ...
;             PG8_WAIT_V(8); PG8_WAIT_L(0); PG8_BAR; PG8_MMA(1, 0, At, B0); PG8_MMA(1, 1, At, B1); PG8_BAR; PG8_SCHED;
;             PG8_LDB(B0, 1, 0); PG8_LDB(B1, 1, 1); PG8_SCHED; PG8_LDA(At, 1, 0); PG8_STAGE(PG8_SA(0, 1), a2 + hstep, voffA);
;             PG8_WAIT_V(8); PG8_WAIT_L(0); PG8_BAR; PG8_MMA(0, 0, At, B0); PG8_MMA(0, 1, At, B1); PG8_BAR; PG8_SCHED;
	s_setprio 1
	s_waitcnt lgkmcnt(0)
	v_mfma_f32_16x16x32_bf16 v[60:63], v[128:131], v[160:163], v[60:63]
	v_mfma_f32_16x16x32_bf16 v[60:63], v[132:135], v[164:167], v[60:63]
	v_mfma_f32_16x16x32_bf16 v[56:59], v[140:143], v[164:167], v[56:59]
	v_mfma_f32_16x16x32_bf16 v[56:59], v[136:139], v[160:163], v[56:59]
	v_mfma_f32_16x16x32_bf16 v[48:51], v[136:139], v[168:171], v[48:51]
	v_mfma_f32_16x16x32_bf16 v[48:51], v[140:143], v[172:175], v[48:51]
	v_mfma_f32_16x16x32_bf16 v[52:55], v[132:135], v[172:175], v[52:55]
	v_mfma_f32_16x16x32_bf16 v[52:55], v[128:131], v[168:171], v[52:55]
	v_mfma_f32_16x16x32_bf16 v[44:47], v[128:131], v[176:179], v[44:47]
	v_mfma_f32_16x16x32_bf16 v[44:47], v[132:135], v[180:183], v[44:47]
	v_mfma_f32_16x16x32_bf16 v[40:43], v[140:143], v[180:183], v[40:43]
	v_mfma_f32_16x16x32_bf16 v[40:43], v[136:139], v[176:179], v[40:43]
	v_mfma_f32_16x16x32_bf16 v[32:35], v[136:139], v[198:201], v[32:35]
	v_mfma_f32_16x16x32_bf16 v[32:35], v[140:143], v[202:205], v[32:35]
	v_mfma_f32_16x16x32_bf16 v[36:39], v[132:135], v[202:205], v[36:39]
	v_mfma_f32_16x16x32_bf16 v[36:39], v[128:131], v[198:201], v[36:39]
	s_setprio 0
	s_setprio 1
	v_mfma_f32_16x16x32_bf16 v[28:31], v[144:147], v[160:163], v[28:31]
	v_mfma_f32_16x16x32_bf16 v[28:31], v[148:151], v[164:167], v[28:31]
	v_mfma_f32_16x16x32_bf16 v[24:27], v[156:159], v[164:167], v[24:27]
	v_mfma_f32_16x16x32_bf16 v[24:27], v[152:155], v[160:163], v[24:27]
	v_mfma_f32_16x16x32_bf16 v[16:19], v[152:155], v[168:171], v[16:19]
	v_mfma_f32_16x16x32_bf16 v[16:19], v[156:159], v[172:175], v[16:19]
	v_mfma_f32_16x16x32_bf16 v[20:23], v[148:151], v[172:175], v[20:23]
	v_mfma_f32_16x16x32_bf16 v[20:23], v[144:147], v[168:171], v[20:23]
	v_mfma_f32_16x16x32_bf16 v[12:15], v[144:147], v[176:179], v[12:15]
	v_mfma_f32_16x16x32_bf16 v[12:15], v[148:151], v[180:183], v[12:15]
	v_mfma_f32_16x16x32_bf16 v[8:11], v[156:159], v[180:183], v[8:11]
	v_mfma_f32_16x16x32_bf16 v[8:11], v[152:155], v[176:179], v[8:11]
	v_mfma_f32_16x16x32_bf16 v[0:3], v[152:155], v[198:201], v[0:3]
	v_mfma_f32_16x16x32_bf16 v[0:3], v[156:159], v[202:205], v[0:3]
	v_mfma_f32_16x16x32_bf16 v[4:7], v[148:151], v[202:205], v[4:7]
	v_mfma_f32_16x16x32_bf16 v[4:7], v[144:147], v[198:201], v[4:7]
	s_setprio 0
	s_barrier
	s_add_i32 s12, 0, 0x18000
	s_add_i32 s13, 0, 0x1c000
	v_add_u32_e32 v140, s12, v230
	v_add_u32_e32 v156, s13, v230
	ds_read_b128 v[128:131], v140
	ds_read_b128 v[132:135], v140 offset:1024
	ds_read_b128 v[136:139], v140 offset:2048
	ds_read_b128 v[140:143], v140 offset:3072
	ds_read_b128 v[144:147], v156
	ds_read_b128 v[148:151], v156 offset:1024
	ds_read_b128 v[152:155], v156 offset:2048
	ds_read_b128 v[156:159], v156 offset:3072
	s_add_u32 s6, s14, 0x80000
	s_addc_u32 s7, s15, 0
	s_mov_b32 m0, s10
	v_lshl_add_u64 v[214:215], s[6:7], 0, v[188:189]
	ds_read_b128 v[160:163], v243 offset:32768
	ds_read_b128 v[164:167], v243 offset:33792
	ds_read_b128 v[168:171], v243 offset:34816
	ds_read_b128 v[172:175], v243 offset:35840
	ds_read_b128 v[176:179], v243 offset:36864
	ds_read_b128 v[180:183], v243 offset:37888
	ds_read_b128 v[198:201], v243 offset:38912
	ds_read_b128 v[202:205], v243 offset:39936
	global_load_lds_dwordx4 v[214:215], off
	v_lshl_add_u64 v[214:215], s[6:7], 0, v[190:191]
	s_mov_b32 m0, s11
	s_nop 0
	global_load_lds_dwordx4 v[214:215], off
	s_waitcnt vmcnt(8)
	s_waitcnt lgkmcnt(0)
	s_barrier
	s_setprio 1
	s_waitcnt lgkmcnt(0)
	v_mfma_f32_16x16x32_bf16 v[124:127], v[128:131], v[160:163], v[124:127]
	v_mfma_f32_16x16x32_bf16 v[124:127], v[132:135], v[164:167], v[124:127]
	v_mfma_f32_16x16x32_bf16 v[120:123], v[140:143], v[164:167], v[120:123]
	v_mfma_f32_16x16x32_bf16 v[120:123], v[136:139], v[160:163], v[120:123]
	v_mfma_f32_16x16x32_bf16 v[112:115], v[136:139], v[168:171], v[112:115]
	v_mfma_f32_16x16x32_bf16 v[112:115], v[140:143], v[172:175], v[112:115]
	v_mfma_f32_16x16x32_bf16 v[116:119], v[132:135], v[172:175], v[116:119]
	v_mfma_f32_16x16x32_bf16 v[116:119], v[128:131], v[168:171], v[116:119]
	v_mfma_f32_16x16x32_bf16 v[108:111], v[128:131], v[176:179], v[108:111]
	v_mfma_f32_16x16x32_bf16 v[108:111], v[132:135], v[180:183], v[108:111]
	v_mfma_f32_16x16x32_bf16 v[104:107], v[140:143], v[180:183], v[104:107]
	v_mfma_f32_16x16x32_bf16 v[104:107], v[136:139], v[176:179], v[104:107]
	v_mfma_f32_16x16x32_bf16 v[96:99], v[136:139], v[198:201], v[96:99]
	v_mfma_f32_16x16x32_bf16 v[96:99], v[140:143], v[202:205], v[96:99]
	v_mfma_f32_16x16x32_bf16 v[100:103], v[132:135], v[202:205], v[100:103]
	v_mfma_f32_16x16x32_bf16 v[100:103], v[128:131], v[198:201], v[100:103]
	s_setprio 0
	s_setprio 1
	v_mfma_f32_16x16x32_bf16 v[92:95], v[144:147], v[160:163], v[92:95]
	v_mfma_f32_16x16x32_bf16 v[92:95], v[148:151], v[164:167], v[92:95]
	v_mfma_f32_16x16x32_bf16 v[88:91], v[156:159], v[164:167], v[88:91]
	v_mfma_f32_16x16x32_bf16 v[88:91], v[152:155], v[160:163], v[88:91]
	v_mfma_f32_16x16x32_bf16 v[80:83], v[152:155], v[168:171], v[80:83]
	v_mfma_f32_16x16x32_bf16 v[80:83], v[156:159], v[172:175], v[80:83]
	v_mfma_f32_16x16x32_bf16 v[84:87], v[148:151], v[172:175], v[84:87]
	v_mfma_f32_16x16x32_bf16 v[84:87], v[144:147], v[168:171], v[84:87]
	v_mfma_f32_16x16x32_bf16 v[76:79], v[144:147], v[176:179], v[76:79]
	v_mfma_f32_16x16x32_bf16 v[76:79], v[148:151], v[180:183], v[76:79]
	v_mfma_f32_16x16x32_bf16 v[72:75], v[156:159], v[180:183], v[72:75]
	v_mfma_f32_16x16x32_bf16 v[72:75], v[152:155], v[176:179], v[72:75]
	v_mfma_f32_16x16x32_bf16 v[64:67], v[152:155], v[198:201], v[64:67]
	v_mfma_f32_16x16x32_bf16 v[64:67], v[156:159], v[202:205], v[64:67]
	v_mfma_f32_16x16x32_bf16 v[68:71], v[148:151], v[202:205], v[68:71]
	v_mfma_f32_16x16x32_bf16 v[68:71], v[144:147], v[198:201], v[68:71]
	s_setprio 0
	s_barrier
; #define PG8_STAGE(bufoff, gbase, voff) do { _Pragma("unroll") for (int _i = 0; _i < 2; ++_i) \
;         __builtin_amdgcn_global_load_lds((const unsigned*)((const char*)(gbase) + (voff)[_i]), (PG8_LAS unsigned*)(lds + (bufoff) + ldsw + _i * 8192), 16, 0, 0); } while (0)
; #define PG8_LDA(dst, b, h) do { _Pragma("unroll") for (int m = 0; m < 4; ++m) _Pragma("unroll") for (int k = 0; k < 2; ++k) dst[m][k] = *(const PG8_LAS bf16x8*)(lds + PG8_SA(b, h) + aoff + m * 2048 + k * 1024); } while (0)
; #define PG8_MMA(ai, bj, At, Bt) do { __builtin_amdgcn_s_setprio(1); _Pragma("unroll") for (int m = 0; m < 4; ++m) _Pragma("unroll") for (int n = 0; n < 2; ++n) _Pragma("unroll") for (int k = 0; k < 2; ++k) \
;         acc[ai][bj][m][n] = __builtin_amdgcn_mfma_f32_16x16x32_bf16(Bt[n][k], At[m][k], acc[ai][bj][m][n], 0, 0, 0); __builtin_amdgcn_s_setprio(0); } while (0)
; #define PG8_WAIT_V(n) asm volatile("s_waitcnt vmcnt(" #n ")" ::: "memory")
; #define PG8_WAIT_L(n) asm volatile("s_waitcnt lgkmcnt(" #n ")" ::: "memory")
; #define PG8_BAR __builtin_amdgcn_s_barrier()
; #define PG8_SCHED __builtin_amdgcn_sched_barrier(0)
; template <class Epi, class Sched, bool ALIGN_EPI = false, bool SP2 = false, bool APERM = false  >
; __device__ __forceinline__ void gemm_phase(PG8_LAS unsigned char* lds, const Gemm g, const Sched& S, const Epi& E, const int wid  ) {
;     ...
;             PG8_LDA(At, 1, 1); PG8_STAGE(PG8_SB(1, 0), b3, voffB); PG8_STAGE(PG8_SB(1, 1), b3 + hstep, voffB); PG8_STAGE(PG8_SA(1, 0), a3, voffA);
;             PG8_WAIT_V(8); PG8_WAIT_L(0); PG8_BAR; PG8_MMA(1, 0, At, B0); PG8_MMA(1, 1, At, B1); PG8_BAR; PG8_SCHED;
	s_add_i32 s6, s12, s63
	v_lshl_add_u64 v[206:207], v[206:207], 0, s[72:73]
	s_mov_b32 m0, s6
	ds_read_b128 v[160:163], v243 offset:49152
	ds_read_b128 v[164:167], v243 offset:50176
	ds_read_b128 v[168:171], v243 offset:51200
	ds_read_b128 v[172:175], v243 offset:52224
	ds_read_b128 v[176:179], v243 offset:53248
	ds_read_b128 v[180:183], v243 offset:54272
	ds_read_b128 v[198:201], v243 offset:55296
	ds_read_b128 v[202:205], v243 offset:56320
	global_load_lds_dwordx4 v[206:207], off
	s_add_i32 m0, s6, 0x2000
	s_add_u32 s0, s0, 0x80080
	v_lshl_add_u64 v[206:207], v[208:209], 0, s[72:73]
	s_addc_u32 s1, s1, 0
	s_add_i32 s6, s13, s63
	global_load_lds_dwordx4 v[206:207], off
	v_lshl_add_u64 v[206:207], s[0:1], 0, v[184:185]
	s_mov_b32 m0, s6
	s_nop 0
	global_load_lds_dwordx4 v[206:207], off
	v_lshl_add_u64 v[206:207], s[0:1], 0, v[186:187]
	s_add_i32 m0, s6, 0x2000
	s_nop 0
	global_load_lds_dwordx4 v[206:207], off
	v_lshl_add_u64 v[206:207], v[210:211], 0, s[72:73]
	s_mov_b32 m0, s88
	s_nop 0
	global_load_lds_dwordx4 v[206:207], off
	v_lshl_add_u64 v[206:207], v[212:213], 0, s[72:73]
	s_mov_b32 m0, s89
	s_nop 0
	global_load_lds_dwordx4 v[206:207], off
	s_waitcnt vmcnt(8)
	s_waitcnt lgkmcnt(0)
	s_barrier
	s_setprio 1
	s_waitcnt lgkmcnt(0)
	v_mfma_f32_16x16x32_bf16 v[60:63], v[128:131], v[160:163], v[60:63]
	v_mfma_f32_16x16x32_bf16 v[60:63], v[132:135], v[164:167], v[60:63]
	v_mfma_f32_16x16x32_bf16 v[56:59], v[140:143], v[164:167], v[56:59]
	v_mfma_f32_16x16x32_bf16 v[56:59], v[136:139], v[160:163], v[56:59]
	v_mfma_f32_16x16x32_bf16 v[48:51], v[136:139], v[168:171], v[48:51]
	v_mfma_f32_16x16x32_bf16 v[48:51], v[140:143], v[172:175], v[48:51]
	v_mfma_f32_16x16x32_bf16 v[52:55], v[132:135], v[172:175], v[52:55]
	v_mfma_f32_16x16x32_bf16 v[52:55], v[128:131], v[168:171], v[52:55]
	v_mfma_f32_16x16x32_bf16 v[44:47], v[128:131], v[176:179], v[44:47]
	v_mfma_f32_16x16x32_bf16 v[44:47], v[132:135], v[180:183], v[44:47]
	v_mfma_f32_16x16x32_bf16 v[40:43], v[140:143], v[180:183], v[40:43]
	v_mfma_f32_16x16x32_bf16 v[40:43], v[136:139], v[176:179], v[40:43]
	v_mfma_f32_16x16x32_bf16 v[32:35], v[136:139], v[198:201], v[32:35]
	v_mfma_f32_16x16x32_bf16 v[32:35], v[140:143], v[202:205], v[32:35]
	v_mfma_f32_16x16x32_bf16 v[36:39], v[132:135], v[202:205], v[36:39]
	v_mfma_f32_16x16x32_bf16 v[36:39], v[128:131], v[198:201], v[36:39]
	s_setprio 0
	s_setprio 1
	v_mfma_f32_16x16x32_bf16 v[28:31], v[144:147], v[160:163], v[28:31]
	v_mfma_f32_16x16x32_bf16 v[28:31], v[148:151], v[164:167], v[28:31]
	v_mfma_f32_16x16x32_bf16 v[24:27], v[156:159], v[164:167], v[24:27]
	v_mfma_f32_16x16x32_bf16 v[24:27], v[152:155], v[160:163], v[24:27]
	v_mfma_f32_16x16x32_bf16 v[16:19], v[152:155], v[168:171], v[16:19]
	v_mfma_f32_16x16x32_bf16 v[16:19], v[156:159], v[172:175], v[16:19]
	v_mfma_f32_16x16x32_bf16 v[20:23], v[148:151], v[172:175], v[20:23]
	v_mfma_f32_16x16x32_bf16 v[20:23], v[144:147], v[168:171], v[20:23]
	v_mfma_f32_16x16x32_bf16 v[12:15], v[144:147], v[176:179], v[12:15]
	v_mfma_f32_16x16x32_bf16 v[12:15], v[148:151], v[180:183], v[12:15]
	v_mfma_f32_16x16x32_bf16 v[8:11], v[156:159], v[180:183], v[8:11]
	v_mfma_f32_16x16x32_bf16 v[8:11], v[152:155], v[176:179], v[8:11]
	v_mfma_f32_16x16x32_bf16 v[0:3], v[152:155], v[198:201], v[0:3]
	v_mfma_f32_16x16x32_bf16 v[0:3], v[156:159], v[202:205], v[0:3]
	v_mfma_f32_16x16x32_bf16 v[4:7], v[148:151], v[202:205], v[4:7]
	v_mfma_f32_16x16x32_bf16 v[4:7], v[144:147], v[198:201], v[4:7]
	s_setprio 0
	s_barrier
	s_add_i32 s0, s47, 2
	s_cmp_gt_u32 s47, 29
	s_cbranch_scc1 .LBB0_392
	s_mov_b32 s47, s0
	s_branch .LBB0_368

; #define PG8_STAGE(bufoff, gbase, voff) do { _Pragma("unroll") for (int _i = 0; _i < 2; ++_i) \
;         __builtin_amdgcn_global_load_lds((const unsigned*)((const char*)(gbase) + (voff)[_i]), (PG8_LAS unsigned*)(lds + (bufoff) + ldsw + _i * 8192), 16, 0, 0); } while (0)
; #define PG8_LDA(dst, b, h) do { _Pragma("unroll") for (int m = 0; m < 4; ++m) _Pragma("unroll") for (int k = 0; k < 2; ++k) dst[m][k] = *(const PG8_LAS bf16x8*)(lds + PG8_SA(b, h) + aoff + m * 2048 + k * 1024); } while (0)
; #define PG8_LDB(dst, b, h) do { _Pragma("unroll") for (int n = 0; n < 2; ++n) _Pragma("unroll") for (int k = 0; k < 2; ++k) dst[n][k] = *(const PG8_LAS bf16x8*)(lds + PG8_SB(b, h) + boff + n * 2048 + k * 1024); } while (0)
; #define PG8_MMA(ai, bj, At, Bt) do { __builtin_amdgcn_s_setprio(1); _Pragma("unroll") for (int m = 0; m < 4; ++m) _Pragma("unroll") for (int n = 0; n < 2; ++n) _Pragma("unroll") for (int k = 0; k < 2; ++k) \
;         acc[ai][bj][m][n] = __builtin_amdgcn_mfma_f32_16x16x32_bf16(Bt[n][k], At[m][k], acc[ai][bj][m][n], 0, 0, 0); __builtin_amdgcn_s_setprio(0); } while (0)
; #define PG8_WAIT_V(n) asm volatile("s_waitcnt vmcnt(" #n ")" ::: "memory")
; #define PG8_WAIT_L(n) asm volatile("s_waitcnt lgkmcnt(" #n ")" ::: "memory")
; template <class Epi, class Sched, bool ALIGN_EPI = false, bool SP2 = false, bool APERM = false  >
; __device__ __forceinline__ void gemm_phase(PG8_LAS unsigned char* lds, const Gemm g, const Sched& S, const Epi& E, const int wid  ) {
;     ...
;             const bool last = (t == nt - 2);
;             const char* a1 = cA + (size_t)(t + 1) * kstep;
;             const char* a2 = last ? nA : cA + (size_t)(t + 2) * kstep; const char* b2 = last ? nB : cB + (size_t)(t + 2) * kstep;
;             const char* a3 = a2 + kstep; const char* b3 = b2 + kstep;
;             if (last && has_next) S.a_ready(nxt);
;             if constexpr (SP2) {
;             PG8_LDB(B0, 0, 0); PG8_LDB(B1, 0, 1); PG8_SCHED; PG8_LDA(At, 0, 0); PG8_STAGE(PG8_SA(1, 1), a1 + hstep, voffA);
;             PG8_WAIT_V(8); PG8_WAIT_L(0); PG8_BAR; PG8_MMA(0, 0, At, B0); PG8_MMA(0, 1, At, B1); PG8_BAR; PG8_SCHED;
;             PG8_LDA(At, 0, 1); PG8_STAGE(PG8_SB(0, 0), b2, voffB); PG8_STAGE(PG8_SB(0, 1), b2 + hstep, voffB); PG8_STAGE(PG8_SA(0, 0), a2, voffA);
;             PG8_WAIT_V(8); PG8_WAIT_L(0); PG8_BAR; PG8_MMA(1, 0, At, B0); PG8_MMA(1, 1, At, B1); PG8_BAR; PG8_SCHED;
.LBB0_543:
	s_lshl_b32 s11, s10, 7
	s_add_u32 s46, s0, s11
	s_addc_u32 s47, s1, 0
	v_add_u32_e32 v146, s33, v150
	s_add_u32 s96, s46, 0x100
	s_waitcnt lgkmcnt(0)
	ds_read_b128 v[142:145], v146
	ds_read_b128 v[154:157], v146 offset:1024
	ds_read_b128 v[158:161], v146 offset:2048
	ds_read_b128 v[162:165], v146 offset:3072
	v_add_u32_e32 v146, s64, v150
	s_addc_u32 s97, s47, 0
	ds_read_b128 v[166:169], v146
	ds_read_b128 v[170:173], v146 offset:1024
	ds_read_b128 v[174:177], v146 offset:2048
	ds_read_b128 v[178:181], v146 offset:3072
	s_and_b64 s[8:9], s[94:95], exec
	s_cselect_b32 s97, s89, s97
	s_cselect_b32 s96, s88, s96
	s_add_u32 s8, s12, s11
	s_addc_u32 s9, s13, 0
	s_add_u32 s11, s8, 0x100
	s_addc_u32 vcc_lo, s9, 0
	s_and_b64 s[8:9], s[94:95], exec
	s_cselect_b32 s95, s91, vcc_lo
	s_cselect_b32 s94, s90, s11
	s_add_u32 s8, s46, 0x160080
	s_addc_u32 s9, s47, 0
	v_lshl_add_u64 v[146:147], s[8:9], 0, v[132:133]
	s_add_i32 m0, s76, 0xc000
	ds_read_b128 v[182:185], v153
	ds_read_b128 v[186:189], v153 offset:1024
	ds_read_b128 v[190:193], v153 offset:2048
	ds_read_b128 v[194:197], v153 offset:3072
	ds_read_b128 v[198:201], v153 offset:4096
	ds_read_b128 v[202:205], v153 offset:5120
	ds_read_b128 v[206:209], v153 offset:6144
	ds_read_b128 v[210:213], v153 offset:7168
	global_load_lds_dwordx4 v[146:147], off
	v_lshl_add_u64 v[146:147], s[8:9], 0, v[134:135]
	s_add_i32 m0, s76, 0xe000
	s_nop 0
	global_load_lds_dwordx4 v[146:147], off
	s_waitcnt vmcnt(8)
	s_waitcnt lgkmcnt(0)
	s_barrier
	s_setprio 1
	s_waitcnt lgkmcnt(0)
	v_mfma_f32_16x16x32_bf16 v[124:127], v[142:145], v[182:185], v[124:127]
	v_mfma_f32_16x16x32_bf16 v[124:127], v[154:157], v[186:189], v[124:127]
	v_mfma_f32_16x16x32_bf16 v[120:123], v[162:165], v[186:189], v[120:123]
	v_mfma_f32_16x16x32_bf16 v[120:123], v[158:161], v[182:185], v[120:123]
	v_mfma_f32_16x16x32_bf16 v[112:115], v[158:161], v[190:193], v[112:115]
	v_mfma_f32_16x16x32_bf16 v[112:115], v[162:165], v[194:197], v[112:115]
	v_mfma_f32_16x16x32_bf16 v[116:119], v[154:157], v[194:197], v[116:119]
	v_mfma_f32_16x16x32_bf16 v[116:119], v[142:145], v[190:193], v[116:119]
	v_mfma_f32_16x16x32_bf16 v[108:111], v[142:145], v[198:201], v[108:111]
	v_mfma_f32_16x16x32_bf16 v[108:111], v[154:157], v[202:205], v[108:111]
	v_mfma_f32_16x16x32_bf16 v[104:107], v[162:165], v[202:205], v[104:107]
	v_mfma_f32_16x16x32_bf16 v[104:107], v[158:161], v[198:201], v[104:107]
	v_mfma_f32_16x16x32_bf16 v[96:99], v[158:161], v[206:209], v[96:99]
	v_mfma_f32_16x16x32_bf16 v[96:99], v[162:165], v[210:213], v[96:99]
	v_mfma_f32_16x16x32_bf16 v[100:103], v[154:157], v[210:213], v[100:103]
	v_mfma_f32_16x16x32_bf16 v[100:103], v[142:145], v[206:209], v[100:103]
	s_setprio 0
	s_setprio 1
	v_mfma_f32_16x16x32_bf16 v[92:95], v[166:169], v[182:185], v[92:95]
	v_mfma_f32_16x16x32_bf16 v[92:95], v[170:173], v[186:189], v[92:95]
	v_mfma_f32_16x16x32_bf16 v[88:91], v[178:181], v[186:189], v[88:91]
	v_mfma_f32_16x16x32_bf16 v[88:91], v[174:177], v[182:185], v[88:91]
	v_mfma_f32_16x16x32_bf16 v[80:83], v[174:177], v[190:193], v[80:83]
	v_mfma_f32_16x16x32_bf16 v[80:83], v[178:181], v[194:197], v[80:83]
	v_mfma_f32_16x16x32_bf16 v[84:87], v[170:173], v[194:197], v[84:87]
	v_mfma_f32_16x16x32_bf16 v[84:87], v[166:169], v[190:193], v[84:87]
	v_mfma_f32_16x16x32_bf16 v[76:79], v[166:169], v[198:201], v[76:79]
	v_mfma_f32_16x16x32_bf16 v[76:79], v[170:173], v[202:205], v[76:79]
	v_mfma_f32_16x16x32_bf16 v[72:75], v[178:181], v[202:205], v[72:75]
	v_mfma_f32_16x16x32_bf16 v[72:75], v[174:177], v[198:201], v[72:75]
	v_mfma_f32_16x16x32_bf16 v[64:67], v[174:177], v[206:209], v[64:67]
	v_mfma_f32_16x16x32_bf16 v[64:67], v[178:181], v[210:213], v[64:67]
	v_mfma_f32_16x16x32_bf16 v[68:71], v[170:173], v[210:213], v[68:71]
	v_mfma_f32_16x16x32_bf16 v[68:71], v[166:169], v[206:209], v[68:71]
	s_setprio 0
	s_barrier
	s_add_i32 s8, s33, s16
	v_lshl_add_u64 v[146:147], s[94:95], 0, v[128:129]
	s_mov_b32 m0, s8
	ds_read_b128 v[182:185], v153 offset:16384
	ds_read_b128 v[186:189], v153 offset:17408
	ds_read_b128 v[190:193], v153 offset:18432
	ds_read_b128 v[194:197], v153 offset:19456
	ds_read_b128 v[198:201], v153 offset:20480
	ds_read_b128 v[202:205], v153 offset:21504
	ds_read_b128 v[206:209], v153 offset:22528
	ds_read_b128 v[210:213], v153 offset:23552
	global_load_lds_dwordx4 v[146:147], off
	s_add_i32 m0, s8, 0x2000
	s_add_u32 s8, s94, 0x160000
	v_lshl_add_u64 v[214:215], s[94:95], 0, v[130:131]
	s_addc_u32 s9, s95, 0
	s_add_i32 s11, s64, s16
	global_load_lds_dwordx4 v[214:215], off
	v_lshl_add_u64 v[216:217], s[8:9], 0, v[128:129]
	s_mov_b32 m0, s11
	v_lshl_add_u64 v[218:219], s[96:97], 0, v[134:135]
	global_load_lds_dwordx4 v[216:217], off
	v_lshl_add_u64 v[216:217], s[8:9], 0, v[130:131]
	s_add_i32 m0, s11, 0x2000
	s_nop 0
	global_load_lds_dwordx4 v[216:217], off
	v_lshl_add_u64 v[216:217], s[96:97], 0, v[132:133]
	s_mov_b32 m0, s76
	s_nop 0
	global_load_lds_dwordx4 v[216:217], off
	s_mov_b32 m0, s77
	s_nop 0
	global_load_lds_dwordx4 v[218:219], off
	s_waitcnt vmcnt(8)
	s_waitcnt lgkmcnt(0)
	s_barrier
; #define PG8_STAGE(bufoff, gbase, voff) do { _Pragma("unroll") for (int _i = 0; _i < 2; ++_i) \
;         __builtin_amdgcn_global_load_lds((const unsigned*)((const char*)(gbase) + (voff)[_i]), (PG8_LAS unsigned*)(lds + (bufoff) + ldsw + _i * 8192), 16, 0, 0); } while (0)
; #define PG8_LDA(dst, b, h) do { _Pragma("unroll") for (int m = 0; m < 4; ++m) _Pragma("unroll") for (int k = 0; k < 2; ++k) dst[m][k] = *(const PG8_LAS bf16x8*)(lds + PG8_SA(b, h) + aoff + m * 2048 + k * 1024); } while (0)
; #define PG8_LDB(dst, b, h) do { _Pragma("unroll") for (int n = 0; n < 2; ++n) _Pragma("unroll") for (int k = 0; k < 2; ++k) dst[n][k] = *(const PG8_LAS bf16x8*)(lds + PG8_SB(b, h) + boff + n * 2048 + k * 1024); } while (0)
; #define PG8_MMA(ai, bj, At, Bt) do { __builtin_amdgcn_s_setprio(1); _Pragma("unroll") for (int m = 0; m < 4; ++m) _Pragma("unroll") for (int n = 0; n < 2; ++n) _Pragma("unroll") for (int k = 0; k < 2; ++k) \
;         acc[ai][bj][m][n] = __builtin_amdgcn_mfma_f32_16x16x32_bf16(Bt[n][k], At[m][k], acc[ai][bj][m][n], 0, 0, 0); __builtin_amdgcn_s_setprio(0); } while (0)
; #define PG8_WAIT_V(n) asm volatile("s_waitcnt vmcnt(" #n ")" ::: "memory")
; #define PG8_WAIT_L(n) asm volatile("s_waitcnt lgkmcnt(" #n ")" ::: "memory")
; #define PG8_BAR __builtin_amdgcn_s_barrier()
; #define PG8_SCHED __builtin_amdgcn_sched_barrier(0)
; template <class Epi, class Sched, bool ALIGN_EPI = false, bool SP2 = false, bool APERM = false  >
; __device__ __forceinline__ void gemm_phase(PG8_LAS unsigned char* lds, const Gemm g, const Sched& S, const Epi& E, const int wid  ) {
;     ...
;             PG8_WAIT_V(8); PG8_WAIT_L(0); PG8_BAR; PG8_MMA(1, 0, At, B0); PG8_MMA(1, 1, At, B1); PG8_BAR; PG8_SCHED;
;             PG8_LDB(B0, 1, 0); PG8_LDB(B1, 1, 1); PG8_SCHED; PG8_LDA(At, 1, 0); PG8_STAGE(PG8_SA(0, 1), a2 + hstep, voffA);
;             PG8_WAIT_V(8); PG8_WAIT_L(0); PG8_BAR; PG8_MMA(0, 0, At, B0); PG8_MMA(0, 1, At, B1); PG8_BAR; PG8_SCHED;
	s_setprio 1
	s_waitcnt lgkmcnt(0)
	v_mfma_f32_16x16x32_bf16 v[60:63], v[142:145], v[182:185], v[60:63]
	v_mfma_f32_16x16x32_bf16 v[60:63], v[154:157], v[186:189], v[60:63]
	v_mfma_f32_16x16x32_bf16 v[56:59], v[162:165], v[186:189], v[56:59]
	v_mfma_f32_16x16x32_bf16 v[56:59], v[158:161], v[182:185], v[56:59]
	v_mfma_f32_16x16x32_bf16 v[48:51], v[158:161], v[190:193], v[48:51]
	v_mfma_f32_16x16x32_bf16 v[48:51], v[162:165], v[194:197], v[48:51]
	v_mfma_f32_16x16x32_bf16 v[52:55], v[154:157], v[194:197], v[52:55]
	v_mfma_f32_16x16x32_bf16 v[52:55], v[142:145], v[190:193], v[52:55]
	v_mfma_f32_16x16x32_bf16 v[44:47], v[142:145], v[198:201], v[44:47]
	v_mfma_f32_16x16x32_bf16 v[44:47], v[154:157], v[202:205], v[44:47]
	v_mfma_f32_16x16x32_bf16 v[40:43], v[162:165], v[202:205], v[40:43]
	v_mfma_f32_16x16x32_bf16 v[40:43], v[158:161], v[198:201], v[40:43]
	v_mfma_f32_16x16x32_bf16 v[32:35], v[158:161], v[206:209], v[32:35]
	v_mfma_f32_16x16x32_bf16 v[32:35], v[162:165], v[210:213], v[32:35]
	v_mfma_f32_16x16x32_bf16 v[36:39], v[154:157], v[210:213], v[36:39]
	v_mfma_f32_16x16x32_bf16 v[36:39], v[142:145], v[206:209], v[36:39]
	s_setprio 0
	s_setprio 1
	v_mfma_f32_16x16x32_bf16 v[28:31], v[166:169], v[182:185], v[28:31]
	v_mfma_f32_16x16x32_bf16 v[28:31], v[170:173], v[186:189], v[28:31]
	v_mfma_f32_16x16x32_bf16 v[24:27], v[178:181], v[186:189], v[24:27]
	v_mfma_f32_16x16x32_bf16 v[24:27], v[174:177], v[182:185], v[24:27]
	v_mfma_f32_16x16x32_bf16 v[16:19], v[174:177], v[190:193], v[16:19]
	v_mfma_f32_16x16x32_bf16 v[16:19], v[178:181], v[194:197], v[16:19]
	v_mfma_f32_16x16x32_bf16 v[20:23], v[170:173], v[194:197], v[20:23]
	v_mfma_f32_16x16x32_bf16 v[20:23], v[166:169], v[190:193], v[20:23]
	v_mfma_f32_16x16x32_bf16 v[12:15], v[166:169], v[198:201], v[12:15]
	v_mfma_f32_16x16x32_bf16 v[12:15], v[170:173], v[202:205], v[12:15]
	v_mfma_f32_16x16x32_bf16 v[8:11], v[178:181], v[202:205], v[8:11]
	v_mfma_f32_16x16x32_bf16 v[8:11], v[174:177], v[198:201], v[8:11]
	v_mfma_f32_16x16x32_bf16 v[0:3], v[174:177], v[206:209], v[0:3]
	v_mfma_f32_16x16x32_bf16 v[0:3], v[178:181], v[210:213], v[0:3]
	v_mfma_f32_16x16x32_bf16 v[4:7], v[170:173], v[210:213], v[4:7]
	v_mfma_f32_16x16x32_bf16 v[4:7], v[166:169], v[206:209], v[4:7]
	s_setprio 0
	s_barrier
	s_add_i32 s11, 0, 0x18000
	s_add_i32 s46, 0, 0x1c000
	v_add_u32_e32 v162, s11, v150
	v_add_u32_e32 v178, s46, v150
	ds_read_b128 v[142:145], v162
	ds_read_b128 v[154:157], v162 offset:1024
	ds_read_b128 v[158:161], v162 offset:2048
	ds_read_b128 v[162:165], v162 offset:3072
	ds_read_b128 v[166:169], v178
	ds_read_b128 v[170:173], v178 offset:1024
	ds_read_b128 v[174:177], v178 offset:2048
	ds_read_b128 v[178:181], v178 offset:3072
	s_add_u32 s8, s96, 0x160000
	s_addc_u32 s9, s97, 0
	s_mov_b32 m0, s74
	v_lshl_add_u64 v[220:221], s[8:9], 0, v[132:133]
	ds_read_b128 v[182:185], v153 offset:32768
	ds_read_b128 v[186:189], v153 offset:33792
	ds_read_b128 v[190:193], v153 offset:34816
	ds_read_b128 v[194:197], v153 offset:35840
	ds_read_b128 v[198:201], v153 offset:36864
	ds_read_b128 v[202:205], v153 offset:37888
	ds_read_b128 v[206:209], v153 offset:38912
	ds_read_b128 v[210:213], v153 offset:39936
	global_load_lds_dwordx4 v[220:221], off
	v_lshl_add_u64 v[220:221], s[8:9], 0, v[134:135]
	s_mov_b32 m0, s78
	s_nop 0
	global_load_lds_dwordx4 v[220:221], off
	s_waitcnt vmcnt(8)
	s_waitcnt lgkmcnt(0)
	s_barrier
	s_setprio 1
	s_waitcnt lgkmcnt(0)
	v_mfma_f32_16x16x32_bf16 v[124:127], v[142:145], v[182:185], v[124:127]
	v_mfma_f32_16x16x32_bf16 v[124:127], v[154:157], v[186:189], v[124:127]
	v_mfma_f32_16x16x32_bf16 v[120:123], v[162:165], v[186:189], v[120:123]
	v_mfma_f32_16x16x32_bf16 v[120:123], v[158:161], v[182:185], v[120:123]
	v_mfma_f32_16x16x32_bf16 v[112:115], v[158:161], v[190:193], v[112:115]
	v_mfma_f32_16x16x32_bf16 v[112:115], v[162:165], v[194:197], v[112:115]
	v_mfma_f32_16x16x32_bf16 v[116:119], v[154:157], v[194:197], v[116:119]
	v_mfma_f32_16x16x32_bf16 v[116:119], v[142:145], v[190:193], v[116:119]
	v_mfma_f32_16x16x32_bf16 v[108:111], v[142:145], v[198:201], v[108:111]
	v_mfma_f32_16x16x32_bf16 v[108:111], v[154:157], v[202:205], v[108:111]
	v_mfma_f32_16x16x32_bf16 v[104:107], v[162:165], v[202:205], v[104:107]
	v_mfma_f32_16x16x32_bf16 v[104:107], v[158:161], v[198:201], v[104:107]
	v_mfma_f32_16x16x32_bf16 v[96:99], v[158:161], v[206:209], v[96:99]
	v_mfma_f32_16x16x32_bf16 v[96:99], v[162:165], v[210:213], v[96:99]
	v_mfma_f32_16x16x32_bf16 v[100:103], v[154:157], v[210:213], v[100:103]
	v_mfma_f32_16x16x32_bf16 v[100:103], v[142:145], v[206:209], v[100:103]
	s_setprio 0
	s_setprio 1
	v_mfma_f32_16x16x32_bf16 v[92:95], v[166:169], v[182:185], v[92:95]
	v_mfma_f32_16x16x32_bf16 v[92:95], v[170:173], v[186:189], v[92:95]
	v_mfma_f32_16x16x32_bf16 v[88:91], v[178:181], v[186:189], v[88:91]
	v_mfma_f32_16x16x32_bf16 v[88:91], v[174:177], v[182:185], v[88:91]
	v_mfma_f32_16x16x32_bf16 v[80:83], v[174:177], v[190:193], v[80:83]
	v_mfma_f32_16x16x32_bf16 v[80:83], v[178:181], v[194:197], v[80:83]
	v_mfma_f32_16x16x32_bf16 v[84:87], v[170:173], v[194:197], v[84:87]
	v_mfma_f32_16x16x32_bf16 v[84:87], v[166:169], v[190:193], v[84:87]
	v_mfma_f32_16x16x32_bf16 v[76:79], v[166:169], v[198:201], v[76:79]
	v_mfma_f32_16x16x32_bf16 v[76:79], v[170:173], v[202:205], v[76:79]
	v_mfma_f32_16x16x32_bf16 v[72:75], v[178:181], v[202:205], v[72:75]
	v_mfma_f32_16x16x32_bf16 v[72:75], v[174:177], v[198:201], v[72:75]
	v_mfma_f32_16x16x32_bf16 v[64:67], v[174:177], v[206:209], v[64:67]
	v_mfma_f32_16x16x32_bf16 v[64:67], v[178:181], v[210:213], v[64:67]
	v_mfma_f32_16x16x32_bf16 v[68:71], v[170:173], v[210:213], v[68:71]
	v_mfma_f32_16x16x32_bf16 v[68:71], v[166:169], v[206:209], v[68:71]
	s_setprio 0
	s_barrier
; #define PG8_STAGE(bufoff, gbase, voff) do { _Pragma("unroll") for (int _i = 0; _i < 2; ++_i) \
;         __builtin_amdgcn_global_load_lds((const unsigned*)((const char*)(gbase) + (voff)[_i]), (PG8_LAS unsigned*)(lds + (bufoff) + ldsw + _i * 8192), 16, 0, 0); } while (0)
; #define PG8_LDA(dst, b, h) do { _Pragma("unroll") for (int m = 0; m < 4; ++m) _Pragma("unroll") for (int k = 0; k < 2; ++k) dst[m][k] = *(const PG8_LAS bf16x8*)(lds + PG8_SA(b, h) + aoff + m * 2048 + k * 1024); } while (0)
; #define PG8_MMA(ai, bj, At, Bt) do { __builtin_amdgcn_s_setprio(1); _Pragma("unroll") for (int m = 0; m < 4; ++m) _Pragma("unroll") for (int n = 0; n < 2; ++n) _Pragma("unroll") for (int k = 0; k < 2; ++k) \
;         acc[ai][bj][m][n] = __builtin_amdgcn_mfma_f32_16x16x32_bf16(Bt[n][k], At[m][k], acc[ai][bj][m][n], 0, 0, 0); __builtin_amdgcn_s_setprio(0); } while (0)
; #define PG8_WAIT_V(n) asm volatile("s_waitcnt vmcnt(" #n ")" ::: "memory")
; #define PG8_WAIT_L(n) asm volatile("s_waitcnt lgkmcnt(" #n ")" ::: "memory")
; #define PG8_BAR __builtin_amdgcn_s_barrier()
; #define PG8_SCHED __builtin_amdgcn_sched_barrier(0)
; template <class Epi, class Sched, bool ALIGN_EPI = false, bool SP2 = false, bool APERM = false  >
; __device__ __forceinline__ void gemm_phase(PG8_LAS unsigned char* lds, const Gemm g, const Sched& S, const Epi& E, const int wid  ) {
;     ...
;             PG8_LDA(At, 1, 1); PG8_STAGE(PG8_SB(1, 0), b3, voffB); PG8_STAGE(PG8_SB(1, 1), b3 + hstep, voffB); PG8_STAGE(PG8_SA(1, 0), a3, voffA);
;             PG8_WAIT_V(8); PG8_WAIT_L(0); PG8_BAR; PG8_MMA(1, 0, At, B0); PG8_MMA(1, 1, At, B1); PG8_BAR; PG8_SCHED;
	s_add_i32 s8, s11, s16
	v_lshl_add_u64 v[146:147], v[146:147], 0, s[24:25]
	s_mov_b32 m0, s8
	ds_read_b128 v[182:185], v153 offset:49152
	ds_read_b128 v[186:189], v153 offset:50176
	ds_read_b128 v[190:193], v153 offset:51200
	ds_read_b128 v[194:197], v153 offset:52224
	ds_read_b128 v[198:201], v153 offset:53248
	ds_read_b128 v[202:205], v153 offset:54272
	ds_read_b128 v[206:209], v153 offset:55296
	ds_read_b128 v[210:213], v153 offset:56320
	global_load_lds_dwordx4 v[146:147], off
	s_add_i32 m0, s8, 0x2000
	s_add_u32 s8, s94, 0x160080
	v_lshl_add_u64 v[146:147], v[214:215], 0, s[24:25]
	s_addc_u32 s9, s95, 0
	s_add_i32 s11, s46, s16
	global_load_lds_dwordx4 v[146:147], off
	v_lshl_add_u64 v[146:147], s[8:9], 0, v[128:129]
	s_mov_b32 m0, s11
	s_nop 0
	global_load_lds_dwordx4 v[146:147], off
	v_lshl_add_u64 v[146:147], s[8:9], 0, v[130:131]
	s_add_i32 m0, s11, 0x2000
	s_nop 0
	global_load_lds_dwordx4 v[146:147], off
	v_lshl_add_u64 v[146:147], v[216:217], 0, s[24:25]
	s_mov_b32 m0, s79
	s_nop 0
	global_load_lds_dwordx4 v[146:147], off
	v_lshl_add_u64 v[146:147], v[218:219], 0, s[24:25]
	s_mov_b32 m0, s75
	s_nop 0
	global_load_lds_dwordx4 v[146:147], off
	s_waitcnt vmcnt(8)
	s_waitcnt lgkmcnt(0)
	s_barrier
	s_setprio 1
	s_waitcnt lgkmcnt(0)
	v_mfma_f32_16x16x32_bf16 v[60:63], v[142:145], v[182:185], v[60:63]
	v_mfma_f32_16x16x32_bf16 v[60:63], v[154:157], v[186:189], v[60:63]
	v_mfma_f32_16x16x32_bf16 v[56:59], v[162:165], v[186:189], v[56:59]
	v_mfma_f32_16x16x32_bf16 v[56:59], v[158:161], v[182:185], v[56:59]
	v_mfma_f32_16x16x32_bf16 v[48:51], v[158:161], v[190:193], v[48:51]
	v_mfma_f32_16x16x32_bf16 v[48:51], v[162:165], v[194:197], v[48:51]
	v_mfma_f32_16x16x32_bf16 v[52:55], v[154:157], v[194:197], v[52:55]
	v_mfma_f32_16x16x32_bf16 v[52:55], v[142:145], v[190:193], v[52:55]
	v_mfma_f32_16x16x32_bf16 v[44:47], v[142:145], v[198:201], v[44:47]
	v_mfma_f32_16x16x32_bf16 v[44:47], v[154:157], v[202:205], v[44:47]
	v_mfma_f32_16x16x32_bf16 v[40:43], v[162:165], v[202:205], v[40:43]
	v_mfma_f32_16x16x32_bf16 v[40:43], v[158:161], v[198:201], v[40:43]
	v_mfma_f32_16x16x32_bf16 v[32:35], v[158:161], v[206:209], v[32:35]
	v_mfma_f32_16x16x32_bf16 v[32:35], v[162:165], v[210:213], v[32:35]
	v_mfma_f32_16x16x32_bf16 v[36:39], v[154:157], v[210:213], v[36:39]
	v_mfma_f32_16x16x32_bf16 v[36:39], v[142:145], v[206:209], v[36:39]
	s_setprio 0
	s_setprio 1
	v_mfma_f32_16x16x32_bf16 v[28:31], v[166:169], v[182:185], v[28:31]
	v_mfma_f32_16x16x32_bf16 v[28:31], v[170:173], v[186:189], v[28:31]
	v_mfma_f32_16x16x32_bf16 v[24:27], v[178:181], v[186:189], v[24:27]
	v_mfma_f32_16x16x32_bf16 v[24:27], v[174:177], v[182:185], v[24:27]
	v_mfma_f32_16x16x32_bf16 v[16:19], v[174:177], v[190:193], v[16:19]
	v_mfma_f32_16x16x32_bf16 v[16:19], v[178:181], v[194:197], v[16:19]
	v_mfma_f32_16x16x32_bf16 v[20:23], v[170:173], v[194:197], v[20:23]
	v_mfma_f32_16x16x32_bf16 v[20:23], v[166:169], v[190:193], v[20:23]
	v_mfma_f32_16x16x32_bf16 v[12:15], v[166:169], v[198:201], v[12:15]
	v_mfma_f32_16x16x32_bf16 v[12:15], v[170:173], v[202:205], v[12:15]
	v_mfma_f32_16x16x32_bf16 v[8:11], v[178:181], v[202:205], v[8:11]
	v_mfma_f32_16x16x32_bf16 v[8:11], v[174:177], v[198:201], v[8:11]
	v_mfma_f32_16x16x32_bf16 v[0:3], v[174:177], v[206:209], v[0:3]
	v_mfma_f32_16x16x32_bf16 v[0:3], v[178:181], v[210:213], v[0:3]
	v_mfma_f32_16x16x32_bf16 v[4:7], v[170:173], v[210:213], v[4:7]
	v_mfma_f32_16x16x32_bf16 v[4:7], v[166:169], v[206:209], v[4:7]
	s_setprio 0
	s_barrier
	s_add_i32 s8, s10, 2
	s_cmp_gt_u32 s10, 41
	s_cbranch_scc1 .LBB0_545
	s_mov_b32 s10, s8
	s_branch .LBB0_526

; #define PG8_STAGE(bufoff, gbase, voff) do { _Pragma("unroll") for (int _i = 0; _i < 2; ++_i) \
;         __builtin_amdgcn_global_load_lds((const unsigned*)((const char*)(gbase) + (voff)[_i]), (PG8_LAS unsigned*)(lds + (bufoff) + ldsw + _i * 8192), 16, 0, 0); } while (0)
; #define PG8_LDA(dst, b, h) do { _Pragma("unroll") for (int m = 0; m < 4; ++m) _Pragma("unroll") for (int k = 0; k < 2; ++k) dst[m][k] = *(const PG8_LAS bf16x8*)(lds + PG8_SA(b, h) + aoff + m * 2048 + k * 1024); } while (0)
; #define PG8_LDB(dst, b, h) do { _Pragma("unroll") for (int n = 0; n < 2; ++n) _Pragma("unroll") for (int k = 0; k < 2; ++k) dst[n][k] = *(const PG8_LAS bf16x8*)(lds + PG8_SB(b, h) + boff + n * 2048 + k * 1024); } while (0)
; #define PG8_MMA(ai, bj, At, Bt) do { __builtin_amdgcn_s_setprio(1); _Pragma("unroll") for (int m = 0; m < 4; ++m) _Pragma("unroll") for (int n = 0; n < 2; ++n) _Pragma("unroll") for (int k = 0; k < 2; ++k) \
;         acc[ai][bj][m][n] = __builtin_amdgcn_mfma_f32_16x16x32_bf16(Bt[n][k], At[m][k], acc[ai][bj][m][n], 0, 0, 0); __builtin_amdgcn_s_setprio(0); } while (0)
; #define PG8_WAIT_V(n) asm volatile("s_waitcnt vmcnt(" #n ")" ::: "memory")
; #define PG8_WAIT_L(n) asm volatile("s_waitcnt lgkmcnt(" #n ")" ::: "memory")
; template <class Epi, class Sched, bool ALIGN_EPI = false, bool SP2 = false, bool APERM = false  >
; __device__ __forceinline__ void gemm_phase(PG8_LAS unsigned char* lds, const Gemm g, const Sched& S, const Epi& E, const int wid  ) {
;     ...
;             const bool last = (t == nt - 2);
;             const char* a1 = cA + (size_t)(t + 1) * kstep;
;             const char* a2 = last ? nA : cA + (size_t)(t + 2) * kstep; const char* b2 = last ? nB : cB + (size_t)(t + 2) * kstep;
;             const char* a3 = a2 + kstep; const char* b3 = b2 + kstep;
;             if (last && has_next) S.a_ready(nxt);
;             if constexpr (SP2) {
;             PG8_LDB(B0, 0, 0); PG8_LDB(B1, 0, 1); PG8_SCHED; PG8_LDA(At, 0, 0); PG8_STAGE(PG8_SA(1, 1), a1 + hstep, voffA);
;             PG8_WAIT_V(8); PG8_WAIT_L(0); PG8_BAR; PG8_MMA(0, 0, At, B0); PG8_MMA(0, 1, At, B1); PG8_BAR; PG8_SCHED;
;             PG8_LDA(At, 0, 1); PG8_STAGE(PG8_SB(0, 0), b2, voffB); PG8_STAGE(PG8_SB(0, 1), b2 + hstep, voffB); PG8_STAGE(PG8_SA(0, 0), a2, voffA);
;             PG8_WAIT_V(8); PG8_WAIT_L(0); PG8_BAR; PG8_MMA(1, 0, At, B0); PG8_MMA(1, 1, At, B1); PG8_BAR; PG8_SCHED;
.LBB0_605:
	s_or_b32 s56, s65, 1
	v_add_u32_e32 v159, s88, v153
	s_lshl_b64 s[10:11], s[56:57], 7
	s_add_i32 s56, s65, 2
	s_waitcnt lgkmcnt(0)
	ds_read_b128 v[144:147], v159
	ds_read_b128 v[148:151], v159 offset:1024
	ds_read_b128 v[160:163], v159 offset:2048
	ds_read_b128 v[164:167], v159 offset:3072
	v_add_u32_e32 v159, s89, v153
	s_lshl_b64 s[46:47], s[56:57], 7
	ds_read_b128 v[168:171], v159
	ds_read_b128 v[172:175], v159 offset:1024
	ds_read_b128 v[176:179], v159 offset:2048
	ds_read_b128 v[180:183], v159 offset:3072
	s_add_u32 s68, s0, s46
	s_addc_u32 s69, s1, s47
	s_and_b64 s[52:53], s[30:31], exec
	s_cselect_b32 vcc_hi, s25, s69
	s_cselect_b32 vcc_lo, s24, s68
	s_add_u32 s46, s12, s46
	s_addc_u32 s47, s13, s47
	s_and_b64 s[30:31], s[30:31], exec
	s_cselect_b32 s31, s29, s47
	s_cselect_b32 s30, s28, s46
	s_add_u32 s10, s33, s10
	s_addc_u32 s11, s64, s11
	v_lshl_add_u64 v[216:217], s[10:11], 0, v[132:133]
	s_add_i32 m0, s70, 0xc000
	ds_read_b128 v[184:187], v158
	ds_read_b128 v[188:191], v158 offset:1024
	ds_read_b128 v[192:195], v158 offset:2048
	ds_read_b128 v[196:199], v158 offset:3072
	ds_read_b128 v[200:203], v158 offset:4096
	ds_read_b128 v[204:207], v158 offset:5120
	ds_read_b128 v[208:211], v158 offset:6144
	ds_read_b128 v[212:215], v158 offset:7168
	global_load_lds_dwordx4 v[216:217], off
	v_lshl_add_u64 v[216:217], s[10:11], 0, v[136:137]
	s_add_i32 m0, s70, 0xe000
	s_nop 0
	global_load_lds_dwordx4 v[216:217], off
	s_waitcnt vmcnt(8)
	s_waitcnt lgkmcnt(0)
	s_barrier
	s_setprio 1
	s_waitcnt lgkmcnt(0)
	v_mfma_f32_16x16x32_bf16 v[124:127], v[144:147], v[184:187], v[124:127]
	v_mfma_f32_16x16x32_bf16 v[124:127], v[148:151], v[188:191], v[124:127]
	v_mfma_f32_16x16x32_bf16 v[120:123], v[164:167], v[188:191], v[120:123]
	v_mfma_f32_16x16x32_bf16 v[120:123], v[160:163], v[184:187], v[120:123]
	v_mfma_f32_16x16x32_bf16 v[112:115], v[160:163], v[192:195], v[112:115]
	v_mfma_f32_16x16x32_bf16 v[112:115], v[164:167], v[196:199], v[112:115]
	v_mfma_f32_16x16x32_bf16 v[116:119], v[148:151], v[196:199], v[116:119]
	v_mfma_f32_16x16x32_bf16 v[116:119], v[144:147], v[192:195], v[116:119]
	v_mfma_f32_16x16x32_bf16 v[108:111], v[144:147], v[200:203], v[108:111]
	v_mfma_f32_16x16x32_bf16 v[108:111], v[148:151], v[204:207], v[108:111]
	v_mfma_f32_16x16x32_bf16 v[104:107], v[164:167], v[204:207], v[104:107]
	v_mfma_f32_16x16x32_bf16 v[104:107], v[160:163], v[200:203], v[104:107]
	v_mfma_f32_16x16x32_bf16 v[96:99], v[160:163], v[208:211], v[96:99]
	v_mfma_f32_16x16x32_bf16 v[96:99], v[164:167], v[212:215], v[96:99]
	v_mfma_f32_16x16x32_bf16 v[100:103], v[148:151], v[212:215], v[100:103]
	v_mfma_f32_16x16x32_bf16 v[100:103], v[144:147], v[208:211], v[100:103]
	s_setprio 0
	s_setprio 1
	v_mfma_f32_16x16x32_bf16 v[92:95], v[168:171], v[184:187], v[92:95]
	v_mfma_f32_16x16x32_bf16 v[92:95], v[172:175], v[188:191], v[92:95]
	v_mfma_f32_16x16x32_bf16 v[88:91], v[180:183], v[188:191], v[88:91]
	v_mfma_f32_16x16x32_bf16 v[88:91], v[176:179], v[184:187], v[88:91]
	v_mfma_f32_16x16x32_bf16 v[80:83], v[176:179], v[192:195], v[80:83]
	v_mfma_f32_16x16x32_bf16 v[80:83], v[180:183], v[196:199], v[80:83]
	v_mfma_f32_16x16x32_bf16 v[84:87], v[172:175], v[196:199], v[84:87]
	v_mfma_f32_16x16x32_bf16 v[84:87], v[168:171], v[192:195], v[84:87]
	v_mfma_f32_16x16x32_bf16 v[76:79], v[168:171], v[200:203], v[76:79]
	v_mfma_f32_16x16x32_bf16 v[76:79], v[172:175], v[204:207], v[76:79]
	v_mfma_f32_16x16x32_bf16 v[72:75], v[180:183], v[204:207], v[72:75]
	v_mfma_f32_16x16x32_bf16 v[72:75], v[176:179], v[200:203], v[72:75]
	v_mfma_f32_16x16x32_bf16 v[64:67], v[176:179], v[208:211], v[64:67]
	v_mfma_f32_16x16x32_bf16 v[64:67], v[180:183], v[212:215], v[64:67]
	v_mfma_f32_16x16x32_bf16 v[68:71], v[172:175], v[212:215], v[68:71]
	v_mfma_f32_16x16x32_bf16 v[68:71], v[168:171], v[208:211], v[68:71]
	s_setprio 0
	s_barrier
	s_add_i32 s10, s88, s16
	v_lshl_add_u64 v[216:217], s[30:31], 0, v[128:129]
	s_mov_b32 m0, s10
	ds_read_b128 v[184:187], v158 offset:16384
	ds_read_b128 v[188:191], v158 offset:17408
	ds_read_b128 v[192:195], v158 offset:18432
	ds_read_b128 v[196:199], v158 offset:19456
	ds_read_b128 v[200:203], v158 offset:20480
	ds_read_b128 v[204:207], v158 offset:21504
	ds_read_b128 v[208:211], v158 offset:22528
	ds_read_b128 v[212:215], v158 offset:23552
	global_load_lds_dwordx4 v[216:217], off
	s_add_i32 m0, s10, 0x2000
	s_add_u32 s10, s30, 0x160000
	v_lshl_add_u64 v[218:219], s[30:31], 0, v[130:131]
	s_addc_u32 s11, s31, 0
	s_add_i32 s46, s89, s16
	global_load_lds_dwordx4 v[218:219], off
	v_lshl_add_u64 v[220:221], s[10:11], 0, v[128:129]
	s_mov_b32 m0, s46
	v_lshl_add_u64 v[222:223], vcc, 0, v[136:137]
	global_load_lds_dwordx4 v[220:221], off
	v_lshl_add_u64 v[220:221], s[10:11], 0, v[130:131]
	s_add_i32 m0, s46, 0x2000
	s_nop 0
	global_load_lds_dwordx4 v[220:221], off
	v_lshl_add_u64 v[220:221], vcc, 0, v[132:133]
	s_mov_b32 m0, s70
	s_nop 0
	global_load_lds_dwordx4 v[220:221], off
	s_mov_b32 m0, s71
	s_nop 0
	global_load_lds_dwordx4 v[222:223], off
	s_waitcnt vmcnt(8)
	s_waitcnt lgkmcnt(0)
	s_barrier
; #define PG8_STAGE(bufoff, gbase, voff) do { _Pragma("unroll") for (int _i = 0; _i < 2; ++_i) \
;         __builtin_amdgcn_global_load_lds((const unsigned*)((const char*)(gbase) + (voff)[_i]), (PG8_LAS unsigned*)(lds + (bufoff) + ldsw + _i * 8192), 16, 0, 0); } while (0)
; #define PG8_LDA(dst, b, h) do { _Pragma("unroll") for (int m = 0; m < 4; ++m) _Pragma("unroll") for (int k = 0; k < 2; ++k) dst[m][k] = *(const PG8_LAS bf16x8*)(lds + PG8_SA(b, h) + aoff + m * 2048 + k * 1024); } while (0)
; #define PG8_LDB(dst, b, h) do { _Pragma("unroll") for (int n = 0; n < 2; ++n) _Pragma("unroll") for (int k = 0; k < 2; ++k) dst[n][k] = *(const PG8_LAS bf16x8*)(lds + PG8_SB(b, h) + boff + n * 2048 + k * 1024); } while (0)
; #define PG8_MMA(ai, bj, At, Bt) do { __builtin_amdgcn_s_setprio(1); _Pragma("unroll") for (int m = 0; m < 4; ++m) _Pragma("unroll") for (int n = 0; n < 2; ++n) _Pragma("unroll") for (int k = 0; k < 2; ++k) \
;         acc[ai][bj][m][n] = __builtin_amdgcn_mfma_f32_16x16x32_bf16(Bt[n][k], At[m][k], acc[ai][bj][m][n], 0, 0, 0); __builtin_amdgcn_s_setprio(0); } while (0)
; #define PG8_WAIT_V(n) asm volatile("s_waitcnt vmcnt(" #n ")" ::: "memory")
; #define PG8_WAIT_L(n) asm volatile("s_waitcnt lgkmcnt(" #n ")" ::: "memory")
; #define PG8_BAR __builtin_amdgcn_s_barrier()
; #define PG8_SCHED __builtin_amdgcn_sched_barrier(0)
; template <class Epi, class Sched, bool ALIGN_EPI = false, bool SP2 = false, bool APERM = false  >
; __device__ __forceinline__ void gemm_phase(PG8_LAS unsigned char* lds, const Gemm g, const Sched& S, const Epi& E, const int wid  ) {
;     ...
;             PG8_WAIT_V(8); PG8_WAIT_L(0); PG8_BAR; PG8_MMA(1, 0, At, B0); PG8_MMA(1, 1, At, B1); PG8_BAR; PG8_SCHED;
;             PG8_LDB(B0, 1, 0); PG8_LDB(B1, 1, 1); PG8_SCHED; PG8_LDA(At, 1, 0); PG8_STAGE(PG8_SA(0, 1), a2 + hstep, voffA);
;             PG8_WAIT_V(8); PG8_WAIT_L(0); PG8_BAR; PG8_MMA(0, 0, At, B0); PG8_MMA(0, 1, At, B1); PG8_BAR; PG8_SCHED;
	s_setprio 1
	s_waitcnt lgkmcnt(0)
	v_mfma_f32_16x16x32_bf16 v[60:63], v[144:147], v[184:187], v[60:63]
	v_mfma_f32_16x16x32_bf16 v[60:63], v[148:151], v[188:191], v[60:63]
	v_mfma_f32_16x16x32_bf16 v[56:59], v[164:167], v[188:191], v[56:59]
	v_mfma_f32_16x16x32_bf16 v[56:59], v[160:163], v[184:187], v[56:59]
	v_mfma_f32_16x16x32_bf16 v[48:51], v[160:163], v[192:195], v[48:51]
	v_mfma_f32_16x16x32_bf16 v[48:51], v[164:167], v[196:199], v[48:51]
	v_mfma_f32_16x16x32_bf16 v[52:55], v[148:151], v[196:199], v[52:55]
	v_mfma_f32_16x16x32_bf16 v[52:55], v[144:147], v[192:195], v[52:55]
	v_mfma_f32_16x16x32_bf16 v[44:47], v[144:147], v[200:203], v[44:47]
	v_mfma_f32_16x16x32_bf16 v[44:47], v[148:151], v[204:207], v[44:47]
	v_mfma_f32_16x16x32_bf16 v[40:43], v[164:167], v[204:207], v[40:43]
	v_mfma_f32_16x16x32_bf16 v[40:43], v[160:163], v[200:203], v[40:43]
	v_mfma_f32_16x16x32_bf16 v[32:35], v[160:163], v[208:211], v[32:35]
	v_mfma_f32_16x16x32_bf16 v[32:35], v[164:167], v[212:215], v[32:35]
	v_mfma_f32_16x16x32_bf16 v[36:39], v[148:151], v[212:215], v[36:39]
	v_mfma_f32_16x16x32_bf16 v[36:39], v[144:147], v[208:211], v[36:39]
	s_setprio 0
	s_setprio 1
	v_mfma_f32_16x16x32_bf16 v[28:31], v[168:171], v[184:187], v[28:31]
	v_mfma_f32_16x16x32_bf16 v[28:31], v[172:175], v[188:191], v[28:31]
	v_mfma_f32_16x16x32_bf16 v[24:27], v[180:183], v[188:191], v[24:27]
	v_mfma_f32_16x16x32_bf16 v[24:27], v[176:179], v[184:187], v[24:27]
	v_mfma_f32_16x16x32_bf16 v[16:19], v[176:179], v[192:195], v[16:19]
	v_mfma_f32_16x16x32_bf16 v[16:19], v[180:183], v[196:199], v[16:19]
	v_mfma_f32_16x16x32_bf16 v[20:23], v[172:175], v[196:199], v[20:23]
	v_mfma_f32_16x16x32_bf16 v[20:23], v[168:171], v[192:195], v[20:23]
	v_mfma_f32_16x16x32_bf16 v[12:15], v[168:171], v[200:203], v[12:15]
	v_mfma_f32_16x16x32_bf16 v[12:15], v[172:175], v[204:207], v[12:15]
	v_mfma_f32_16x16x32_bf16 v[8:11], v[180:183], v[204:207], v[8:11]
	v_mfma_f32_16x16x32_bf16 v[8:11], v[176:179], v[200:203], v[8:11]
	v_mfma_f32_16x16x32_bf16 v[0:3], v[176:179], v[208:211], v[0:3]
	v_mfma_f32_16x16x32_bf16 v[0:3], v[180:183], v[212:215], v[0:3]
	v_mfma_f32_16x16x32_bf16 v[4:7], v[172:175], v[212:215], v[4:7]
	v_mfma_f32_16x16x32_bf16 v[4:7], v[168:171], v[208:211], v[4:7]
	s_setprio 0
	s_barrier
	s_add_i32 s46, 0, 0x18000
	v_add_u32_e32 v159, s46, v153
	s_add_i32 s47, 0, 0x1c000
	ds_read_b128 v[144:147], v159
	ds_read_b128 v[148:151], v159 offset:1024
	ds_read_b128 v[160:163], v159 offset:2048
	ds_read_b128 v[164:167], v159 offset:3072
	v_add_u32_e32 v159, s47, v153
	ds_read_b128 v[168:171], v159
	ds_read_b128 v[172:175], v159 offset:1024
	ds_read_b128 v[176:179], v159 offset:2048
	ds_read_b128 v[180:183], v159 offset:3072
	s_add_u32 s10, vcc_lo, 0x160000
	s_addc_u32 s11, vcc_hi, 0
	s_mov_b32 m0, s72
	v_lshl_add_u64 v[224:225], s[10:11], 0, v[132:133]
	ds_read_b128 v[184:187], v158 offset:32768
	ds_read_b128 v[188:191], v158 offset:33792
	ds_read_b128 v[192:195], v158 offset:34816
	ds_read_b128 v[196:199], v158 offset:35840
	ds_read_b128 v[200:203], v158 offset:36864
	ds_read_b128 v[204:207], v158 offset:37888
	ds_read_b128 v[208:211], v158 offset:38912
	ds_read_b128 v[212:215], v158 offset:39936
	global_load_lds_dwordx4 v[224:225], off
	v_lshl_add_u64 v[224:225], s[10:11], 0, v[136:137]
	s_mov_b32 m0, s73
	s_nop 0
	global_load_lds_dwordx4 v[224:225], off
	s_waitcnt vmcnt(8)
	s_waitcnt lgkmcnt(0)
	s_barrier
	s_setprio 1
	s_waitcnt lgkmcnt(0)
	v_mfma_f32_16x16x32_bf16 v[124:127], v[144:147], v[184:187], v[124:127]
	v_mfma_f32_16x16x32_bf16 v[124:127], v[148:151], v[188:191], v[124:127]
	v_mfma_f32_16x16x32_bf16 v[120:123], v[164:167], v[188:191], v[120:123]
	v_mfma_f32_16x16x32_bf16 v[120:123], v[160:163], v[184:187], v[120:123]
	v_mfma_f32_16x16x32_bf16 v[112:115], v[160:163], v[192:195], v[112:115]
	v_mfma_f32_16x16x32_bf16 v[112:115], v[164:167], v[196:199], v[112:115]
	v_mfma_f32_16x16x32_bf16 v[116:119], v[148:151], v[196:199], v[116:119]
	v_mfma_f32_16x16x32_bf16 v[116:119], v[144:147], v[192:195], v[116:119]
	v_mfma_f32_16x16x32_bf16 v[108:111], v[144:147], v[200:203], v[108:111]
	v_mfma_f32_16x16x32_bf16 v[108:111], v[148:151], v[204:207], v[108:111]
	v_mfma_f32_16x16x32_bf16 v[104:107], v[164:167], v[204:207], v[104:107]
	v_mfma_f32_16x16x32_bf16 v[104:107], v[160:163], v[200:203], v[104:107]
	v_mfma_f32_16x16x32_bf16 v[96:99], v[160:163], v[208:211], v[96:99]
	v_mfma_f32_16x16x32_bf16 v[96:99], v[164:167], v[212:215], v[96:99]
	v_mfma_f32_16x16x32_bf16 v[100:103], v[148:151], v[212:215], v[100:103]
	v_mfma_f32_16x16x32_bf16 v[100:103], v[144:147], v[208:211], v[100:103]
	s_setprio 0
	s_setprio 1
	v_mfma_f32_16x16x32_bf16 v[92:95], v[168:171], v[184:187], v[92:95]
	v_mfma_f32_16x16x32_bf16 v[92:95], v[172:175], v[188:191], v[92:95]
	v_mfma_f32_16x16x32_bf16 v[88:91], v[180:183], v[188:191], v[88:91]
	v_mfma_f32_16x16x32_bf16 v[88:91], v[176:179], v[184:187], v[88:91]
	v_mfma_f32_16x16x32_bf16 v[80:83], v[176:179], v[192:195], v[80:83]
	v_mfma_f32_16x16x32_bf16 v[80:83], v[180:183], v[196:199], v[80:83]
	v_mfma_f32_16x16x32_bf16 v[84:87], v[172:175], v[196:199], v[84:87]
	v_mfma_f32_16x16x32_bf16 v[84:87], v[168:171], v[192:195], v[84:87]
	v_mfma_f32_16x16x32_bf16 v[76:79], v[168:171], v[200:203], v[76:79]
	v_mfma_f32_16x16x32_bf16 v[76:79], v[172:175], v[204:207], v[76:79]
	v_mfma_f32_16x16x32_bf16 v[72:75], v[180:183], v[204:207], v[72:75]
	v_mfma_f32_16x16x32_bf16 v[72:75], v[176:179], v[200:203], v[72:75]
	v_mfma_f32_16x16x32_bf16 v[64:67], v[176:179], v[208:211], v[64:67]
	v_mfma_f32_16x16x32_bf16 v[64:67], v[180:183], v[212:215], v[64:67]
	v_mfma_f32_16x16x32_bf16 v[68:71], v[172:175], v[212:215], v[68:71]
	v_mfma_f32_16x16x32_bf16 v[68:71], v[168:171], v[208:211], v[68:71]
	s_setprio 0
	s_barrier
; #define PG8_STAGE(bufoff, gbase, voff) do { _Pragma("unroll") for (int _i = 0; _i < 2; ++_i) \
;         __builtin_amdgcn_global_load_lds((const unsigned*)((const char*)(gbase) + (voff)[_i]), (PG8_LAS unsigned*)(lds + (bufoff) + ldsw + _i * 8192), 16, 0, 0); } while (0)
; #define PG8_LDA(dst, b, h) do { _Pragma("unroll") for (int m = 0; m < 4; ++m) _Pragma("unroll") for (int k = 0; k < 2; ++k) dst[m][k] = *(const PG8_LAS bf16x8*)(lds + PG8_SA(b, h) + aoff + m * 2048 + k * 1024); } while (0)
; #define PG8_MMA(ai, bj, At, Bt) do { __builtin_amdgcn_s_setprio(1); _Pragma("unroll") for (int m = 0; m < 4; ++m) _Pragma("unroll") for (int n = 0; n < 2; ++n) _Pragma("unroll") for (int k = 0; k < 2; ++k) \
;         acc[ai][bj][m][n] = __builtin_amdgcn_mfma_f32_16x16x32_bf16(Bt[n][k], At[m][k], acc[ai][bj][m][n], 0, 0, 0); __builtin_amdgcn_s_setprio(0); } while (0)
; #define PG8_WAIT_V(n) asm volatile("s_waitcnt vmcnt(" #n ")" ::: "memory")
; #define PG8_WAIT_L(n) asm volatile("s_waitcnt lgkmcnt(" #n ")" ::: "memory")
; #define PG8_BAR __builtin_amdgcn_s_barrier()
; #define PG8_SCHED __builtin_amdgcn_sched_barrier(0)
; template <class Epi, class Sched, bool ALIGN_EPI = false, bool SP2 = false, bool APERM = false  >
; __device__ __forceinline__ void gemm_phase(PG8_LAS unsigned char* lds, const Gemm g, const Sched& S, const Epi& E, const int wid  ) {
;     ...
;             PG8_LDA(At, 1, 1); PG8_STAGE(PG8_SB(1, 0), b3, voffB); PG8_STAGE(PG8_SB(1, 1), b3 + hstep, voffB); PG8_STAGE(PG8_SA(1, 0), a3, voffA);
;             PG8_WAIT_V(8); PG8_WAIT_L(0); PG8_BAR; PG8_MMA(1, 0, At, B0); PG8_MMA(1, 1, At, B1); PG8_BAR; PG8_SCHED;
	s_add_i32 s10, s46, s16
	v_lshl_add_u64 v[216:217], v[216:217], 0, s[58:59]
	s_mov_b32 m0, s10
	ds_read_b128 v[184:187], v158 offset:49152
	ds_read_b128 v[188:191], v158 offset:50176
	ds_read_b128 v[192:195], v158 offset:51200
	ds_read_b128 v[196:199], v158 offset:52224
	ds_read_b128 v[200:203], v158 offset:53248
	ds_read_b128 v[204:207], v158 offset:54272
	ds_read_b128 v[208:211], v158 offset:55296
	ds_read_b128 v[212:215], v158 offset:56320
	global_load_lds_dwordx4 v[216:217], off
	s_add_i32 m0, s10, 0x2000
	s_add_u32 s10, s30, 0x160080
	v_lshl_add_u64 v[216:217], v[218:219], 0, s[58:59]
	s_addc_u32 s11, s31, 0
	s_add_i32 s30, s47, s16
	global_load_lds_dwordx4 v[216:217], off
	v_lshl_add_u64 v[216:217], s[10:11], 0, v[128:129]
	s_mov_b32 m0, s30
	s_nop 0
	global_load_lds_dwordx4 v[216:217], off
	v_lshl_add_u64 v[216:217], s[10:11], 0, v[130:131]
	s_add_i32 m0, s30, 0x2000
	s_nop 0
	global_load_lds_dwordx4 v[216:217], off
	v_lshl_add_u64 v[216:217], v[220:221], 0, s[58:59]
	s_mov_b32 m0, s86
	s_nop 0
	global_load_lds_dwordx4 v[216:217], off
	v_lshl_add_u64 v[216:217], v[222:223], 0, s[58:59]
	s_mov_b32 m0, s87
	s_nop 0
	global_load_lds_dwordx4 v[216:217], off
	s_waitcnt vmcnt(8)
	s_waitcnt lgkmcnt(0)
	s_barrier
	s_setprio 1
	s_waitcnt lgkmcnt(0)
	v_mfma_f32_16x16x32_bf16 v[60:63], v[144:147], v[184:187], v[60:63]
	v_mfma_f32_16x16x32_bf16 v[60:63], v[148:151], v[188:191], v[60:63]
	v_mfma_f32_16x16x32_bf16 v[56:59], v[164:167], v[188:191], v[56:59]
	v_mfma_f32_16x16x32_bf16 v[56:59], v[160:163], v[184:187], v[56:59]
	v_mfma_f32_16x16x32_bf16 v[48:51], v[160:163], v[192:195], v[48:51]
	v_mfma_f32_16x16x32_bf16 v[48:51], v[164:167], v[196:199], v[48:51]
	v_mfma_f32_16x16x32_bf16 v[52:55], v[148:151], v[196:199], v[52:55]
	v_mfma_f32_16x16x32_bf16 v[52:55], v[144:147], v[192:195], v[52:55]
	v_mfma_f32_16x16x32_bf16 v[44:47], v[144:147], v[200:203], v[44:47]
	v_mfma_f32_16x16x32_bf16 v[44:47], v[148:151], v[204:207], v[44:47]
	v_mfma_f32_16x16x32_bf16 v[40:43], v[164:167], v[204:207], v[40:43]
	v_mfma_f32_16x16x32_bf16 v[40:43], v[160:163], v[200:203], v[40:43]
	v_mfma_f32_16x16x32_bf16 v[32:35], v[160:163], v[208:211], v[32:35]
	v_mfma_f32_16x16x32_bf16 v[32:35], v[164:167], v[212:215], v[32:35]
	v_mfma_f32_16x16x32_bf16 v[36:39], v[148:151], v[212:215], v[36:39]
	v_mfma_f32_16x16x32_bf16 v[36:39], v[144:147], v[208:211], v[36:39]
	s_setprio 0
	s_setprio 1
	v_mfma_f32_16x16x32_bf16 v[28:31], v[168:171], v[184:187], v[28:31]
	v_mfma_f32_16x16x32_bf16 v[28:31], v[172:175], v[188:191], v[28:31]
	v_mfma_f32_16x16x32_bf16 v[24:27], v[180:183], v[188:191], v[24:27]
	v_mfma_f32_16x16x32_bf16 v[24:27], v[176:179], v[184:187], v[24:27]
	v_mfma_f32_16x16x32_bf16 v[16:19], v[176:179], v[192:195], v[16:19]
	v_mfma_f32_16x16x32_bf16 v[16:19], v[180:183], v[196:199], v[16:19]
	v_mfma_f32_16x16x32_bf16 v[20:23], v[172:175], v[196:199], v[20:23]
	v_mfma_f32_16x16x32_bf16 v[20:23], v[168:171], v[192:195], v[20:23]
	v_mfma_f32_16x16x32_bf16 v[12:15], v[168:171], v[200:203], v[12:15]
	v_mfma_f32_16x16x32_bf16 v[12:15], v[172:175], v[204:207], v[12:15]
	v_mfma_f32_16x16x32_bf16 v[8:11], v[180:183], v[204:207], v[8:11]
	v_mfma_f32_16x16x32_bf16 v[8:11], v[176:179], v[200:203], v[8:11]
	v_mfma_f32_16x16x32_bf16 v[0:3], v[176:179], v[208:211], v[0:3]
	v_mfma_f32_16x16x32_bf16 v[0:3], v[180:183], v[212:215], v[0:3]
	v_mfma_f32_16x16x32_bf16 v[4:7], v[172:175], v[212:215], v[4:7]
	v_mfma_f32_16x16x32_bf16 v[4:7], v[168:171], v[208:211], v[4:7]
	s_setprio 0
	s_barrier
	s_cmp_gt_u32 s65, 41
	s_cbranch_scc1 .LBB0_607
	s_mov_b32 s65, s56
	s_branch .LBB0_588

; #define PG8_STAGE(bufoff, gbase, voff) do { _Pragma("unroll") for (int _i = 0; _i < 2; ++_i) \
;         __builtin_amdgcn_global_load_lds((const unsigned*)((const char*)(gbase) + (voff)[_i]), (PG8_LAS unsigned*)(lds + (bufoff) + ldsw + _i * 8192), 16, 0, 0); } while (0)
; #define PG8_LDA(dst, b, h) do { _Pragma("unroll") for (int m = 0; m < 4; ++m) _Pragma("unroll") for (int k = 0; k < 2; ++k) dst[m][k] = *(const PG8_LAS bf16x8*)(lds + PG8_SA(b, h) + aoff + m * 2048 + k * 1024); } while (0)
; #define PG8_LDB(dst, b, h) do { _Pragma("unroll") for (int n = 0; n < 2; ++n) _Pragma("unroll") for (int k = 0; k < 2; ++k) dst[n][k] = *(const PG8_LAS bf16x8*)(lds + PG8_SB(b, h) + boff + n * 2048 + k * 1024); } while (0)
; #define PG8_MMA(ai, bj, At, Bt) do { __builtin_amdgcn_s_setprio(1); _Pragma("unroll") for (int m = 0; m < 4; ++m) _Pragma("unroll") for (int n = 0; n < 2; ++n) _Pragma("unroll") for (int k = 0; k < 2; ++k) \
;         acc[ai][bj][m][n] = __builtin_amdgcn_mfma_f32_16x16x32_bf16(Bt[n][k], At[m][k], acc[ai][bj][m][n], 0, 0, 0); __builtin_amdgcn_s_setprio(0); } while (0)
; #define PG8_WAIT_V(n) asm volatile("s_waitcnt vmcnt(" #n ")" ::: "memory")
; #define PG8_WAIT_L(n) asm volatile("s_waitcnt lgkmcnt(" #n ")" ::: "memory")
; template <class Epi, class Sched, bool ALIGN_EPI = false, bool SP2 = false, bool APERM = false  >
; __device__ __forceinline__ void gemm_phase(PG8_LAS unsigned char* lds, const Gemm g, const Sched& S, const Epi& E, const int wid  ) {
;     ...
;             const bool last = (t == nt - 2);
;             const char* a1 = cA + (size_t)(t + 1) * kstep;
;             const char* a2 = last ? nA : cA + (size_t)(t + 2) * kstep; const char* b2 = last ? nB : cB + (size_t)(t + 2) * kstep;
;             const char* a3 = a2 + kstep; const char* b3 = b2 + kstep;
;             if (last && has_next) S.a_ready(nxt);
;             if constexpr (SP2) {
;             PG8_LDB(B0, 0, 0); PG8_LDB(B1, 0, 1); PG8_SCHED; PG8_LDA(At, 0, 0); PG8_STAGE(PG8_SA(1, 1), a1 + hstep, voffA);
;             PG8_WAIT_V(8); PG8_WAIT_L(0); PG8_BAR; PG8_MMA(0, 0, At, B0); PG8_MMA(0, 1, At, B1); PG8_BAR; PG8_SCHED;
;             PG8_LDA(At, 0, 1); PG8_STAGE(PG8_SB(0, 0), b2, voffB); PG8_STAGE(PG8_SB(0, 1), b2 + hstep, voffB); PG8_STAGE(PG8_SA(0, 0), a2, voffA);
;             PG8_WAIT_V(8); PG8_WAIT_L(0); PG8_BAR; PG8_MMA(1, 0, At, B0); PG8_MMA(1, 1, At, B1); PG8_BAR; PG8_SCHED;
.LBB0_669:
	v_add_u32_e32 v1, s70, v145
	ds_read_b128 v[152:155], v1
	ds_read_b128 v[156:159], v1 offset:1024
	ds_read_b128 v[160:163], v1 offset:2048
	ds_read_b128 v[164:167], v1 offset:3072
	v_add_u32_e32 v1, s71, v145
	ds_read_b128 v[168:171], v1
	ds_read_b128 v[172:175], v1 offset:1024
	ds_read_b128 v[176:179], v1 offset:2048
	ds_read_b128 v[180:183], v1 offset:3072
	s_add_i32 s80, s54, 2
	s_add_u32 s81, s34, 0x80
	s_addc_u32 s55, s35, 0
	s_cmp_eq_u32 s69, s54
	s_cselect_b32 s54, s28, s81
	s_cselect_b32 s55, s29, s55
	s_cselect_b32 s83, s31, s79
	s_cselect_b32 s82, s30, s78
	s_mov_b32 m0, s72
	v_lshl_add_u64 v[2:3], s[34:35], 0, v[140:141]
	ds_read_b128 v[184:187], v147
	ds_read_b128 v[188:191], v147 offset:1024
	ds_read_b128 v[192:195], v147 offset:2048
	ds_read_b128 v[196:199], v147 offset:3072
	ds_read_b128 v[200:203], v147 offset:4096
	ds_read_b128 v[204:207], v147 offset:5120
	ds_read_b128 v[208:211], v147 offset:6144
	ds_read_b128 v[212:215], v147 offset:7168
	global_load_lds_dwordx4 v[2:3], off
	v_lshl_add_u64 v[2:3], s[34:35], 0, v[142:143]
	s_mov_b32 m0, s73
	s_nop 0
	global_load_lds_dwordx4 v[2:3], off
	s_waitcnt vmcnt(8)
	s_waitcnt lgkmcnt(0)
	s_barrier
	s_setprio 1
	s_waitcnt lgkmcnt(0)
	v_mfma_f32_16x16x32_bf16 v[128:131], v[152:155], v[184:187], v[128:131]
	v_mfma_f32_16x16x32_bf16 v[128:131], v[156:159], v[188:191], v[128:131]
	v_mfma_f32_16x16x32_bf16 v[124:127], v[164:167], v[188:191], v[124:127]
	v_mfma_f32_16x16x32_bf16 v[124:127], v[160:163], v[184:187], v[124:127]
	v_mfma_f32_16x16x32_bf16 v[116:119], v[160:163], v[192:195], v[116:119]
	v_mfma_f32_16x16x32_bf16 v[116:119], v[164:167], v[196:199], v[116:119]
	v_mfma_f32_16x16x32_bf16 v[120:123], v[156:159], v[196:199], v[120:123]
	v_mfma_f32_16x16x32_bf16 v[120:123], v[152:155], v[192:195], v[120:123]
	v_mfma_f32_16x16x32_bf16 v[112:115], v[152:155], v[200:203], v[112:115]
	v_mfma_f32_16x16x32_bf16 v[112:115], v[156:159], v[204:207], v[112:115]
	v_mfma_f32_16x16x32_bf16 v[108:111], v[164:167], v[204:207], v[108:111]
	v_mfma_f32_16x16x32_bf16 v[108:111], v[160:163], v[200:203], v[108:111]
	v_mfma_f32_16x16x32_bf16 v[100:103], v[160:163], v[208:211], v[100:103]
	v_mfma_f32_16x16x32_bf16 v[100:103], v[164:167], v[212:215], v[100:103]
	v_mfma_f32_16x16x32_bf16 v[104:107], v[156:159], v[212:215], v[104:107]
	v_mfma_f32_16x16x32_bf16 v[104:107], v[152:155], v[208:211], v[104:107]
	s_setprio 0
	s_setprio 1
	v_mfma_f32_16x16x32_bf16 v[96:99], v[168:171], v[184:187], v[96:99]
	v_mfma_f32_16x16x32_bf16 v[96:99], v[172:175], v[188:191], v[96:99]
	v_mfma_f32_16x16x32_bf16 v[92:95], v[180:183], v[188:191], v[92:95]
	v_mfma_f32_16x16x32_bf16 v[92:95], v[176:179], v[184:187], v[92:95]
	v_mfma_f32_16x16x32_bf16 v[84:87], v[176:179], v[192:195], v[84:87]
	v_mfma_f32_16x16x32_bf16 v[84:87], v[180:183], v[196:199], v[84:87]
	v_mfma_f32_16x16x32_bf16 v[88:91], v[172:175], v[196:199], v[88:91]
	v_mfma_f32_16x16x32_bf16 v[88:91], v[168:171], v[192:195], v[88:91]
	v_mfma_f32_16x16x32_bf16 v[80:83], v[168:171], v[200:203], v[80:83]
	v_mfma_f32_16x16x32_bf16 v[80:83], v[172:175], v[204:207], v[80:83]
	v_mfma_f32_16x16x32_bf16 v[76:79], v[180:183], v[204:207], v[76:79]
	v_mfma_f32_16x16x32_bf16 v[76:79], v[176:179], v[200:203], v[76:79]
	v_mfma_f32_16x16x32_bf16 v[68:71], v[176:179], v[208:211], v[68:71]
	v_mfma_f32_16x16x32_bf16 v[68:71], v[180:183], v[212:215], v[68:71]
	v_mfma_f32_16x16x32_bf16 v[72:75], v[172:175], v[212:215], v[72:75]
	v_mfma_f32_16x16x32_bf16 v[72:75], v[168:171], v[208:211], v[72:75]
	s_setprio 0
	s_barrier
	s_add_i32 s81, s70, s46
	v_lshl_add_u64 v[148:149], s[82:83], 0, v[136:137]
	s_mov_b32 m0, s81
	ds_read_b128 v[184:187], v147 offset:16384
	ds_read_b128 v[188:191], v147 offset:17408
	ds_read_b128 v[192:195], v147 offset:18432
	ds_read_b128 v[196:199], v147 offset:19456
	ds_read_b128 v[200:203], v147 offset:20480
	ds_read_b128 v[204:207], v147 offset:21504
	ds_read_b128 v[208:211], v147 offset:22528
	ds_read_b128 v[212:215], v147 offset:23552
	global_load_lds_dwordx4 v[148:149], off
	s_add_i32 m0, s81, 0x2000
	v_lshl_add_u64 v[216:217], s[82:83], 0, v[132:133]
	s_add_u32 s82, s82, s4
	s_addc_u32 s83, s83, s5
	s_add_i32 s81, s71, s46
	global_load_lds_dwordx4 v[216:217], off
	v_lshl_add_u64 v[218:219], s[82:83], 0, v[136:137]
	s_mov_b32 m0, s81
	v_lshl_add_u64 v[220:221], s[82:83], 0, v[132:133]
	global_load_lds_dwordx4 v[218:219], off
	s_add_i32 m0, s81, 0x2000
	v_lshl_add_u64 v[222:223], s[54:55], 0, v[138:139]
	global_load_lds_dwordx4 v[220:221], off
	s_mov_b32 m0, s59
	v_lshl_add_u64 v[224:225], s[54:55], 0, v[134:135]
	global_load_lds_dwordx4 v[222:223], off
	s_mov_b32 m0, s63
	s_nop 0
	global_load_lds_dwordx4 v[224:225], off
	s_waitcnt vmcnt(8)
	s_waitcnt lgkmcnt(0)
	s_barrier
; #define PG8_STAGE(bufoff, gbase, voff) do { _Pragma("unroll") for (int _i = 0; _i < 2; ++_i) \
;         __builtin_amdgcn_global_load_lds((const unsigned*)((const char*)(gbase) + (voff)[_i]), (PG8_LAS unsigned*)(lds + (bufoff) + ldsw + _i * 8192), 16, 0, 0); } while (0)
; #define PG8_LDA(dst, b, h) do { _Pragma("unroll") for (int m = 0; m < 4; ++m) _Pragma("unroll") for (int k = 0; k < 2; ++k) dst[m][k] = *(const PG8_LAS bf16x8*)(lds + PG8_SA(b, h) + aoff + m * 2048 + k * 1024); } while (0)
; #define PG8_LDB(dst, b, h) do { _Pragma("unroll") for (int n = 0; n < 2; ++n) _Pragma("unroll") for (int k = 0; k < 2; ++k) dst[n][k] = *(const PG8_LAS bf16x8*)(lds + PG8_SB(b, h) + boff + n * 2048 + k * 1024); } while (0)
; #define PG8_MMA(ai, bj, At, Bt) do { __builtin_amdgcn_s_setprio(1); _Pragma("unroll") for (int m = 0; m < 4; ++m) _Pragma("unroll") for (int n = 0; n < 2; ++n) _Pragma("unroll") for (int k = 0; k < 2; ++k) \
;         acc[ai][bj][m][n] = __builtin_amdgcn_mfma_f32_16x16x32_bf16(Bt[n][k], At[m][k], acc[ai][bj][m][n], 0, 0, 0); __builtin_amdgcn_s_setprio(0); } while (0)
; #define PG8_WAIT_V(n) asm volatile("s_waitcnt vmcnt(" #n ")" ::: "memory")
; #define PG8_WAIT_L(n) asm volatile("s_waitcnt lgkmcnt(" #n ")" ::: "memory")
; #define PG8_BAR __builtin_amdgcn_s_barrier()
; #define PG8_SCHED __builtin_amdgcn_sched_barrier(0)
; template <class Epi, class Sched, bool ALIGN_EPI = false, bool SP2 = false, bool APERM = false  >
; __device__ __forceinline__ void gemm_phase(PG8_LAS unsigned char* lds, const Gemm g, const Sched& S, const Epi& E, const int wid  ) {
;     ...
;             PG8_WAIT_V(8); PG8_WAIT_L(0); PG8_BAR; PG8_MMA(1, 0, At, B0); PG8_MMA(1, 1, At, B1); PG8_BAR; PG8_SCHED;
;             PG8_LDB(B0, 1, 0); PG8_LDB(B1, 1, 1); PG8_SCHED; PG8_LDA(At, 1, 0); PG8_STAGE(PG8_SA(0, 1), a2 + hstep, voffA);
;             PG8_WAIT_V(8); PG8_WAIT_L(0); PG8_BAR; PG8_MMA(0, 0, At, B0); PG8_MMA(0, 1, At, B1); PG8_BAR; PG8_SCHED;
	s_setprio 1
	s_waitcnt lgkmcnt(0)
	v_mfma_f32_16x16x32_bf16 v[64:67], v[152:155], v[184:187], v[64:67]
	v_mfma_f32_16x16x32_bf16 v[64:67], v[156:159], v[188:191], v[64:67]
	v_mfma_f32_16x16x32_bf16 v[60:63], v[164:167], v[188:191], v[60:63]
	v_mfma_f32_16x16x32_bf16 v[60:63], v[160:163], v[184:187], v[60:63]
	v_mfma_f32_16x16x32_bf16 v[52:55], v[160:163], v[192:195], v[52:55]
	v_mfma_f32_16x16x32_bf16 v[52:55], v[164:167], v[196:199], v[52:55]
	v_mfma_f32_16x16x32_bf16 v[56:59], v[156:159], v[196:199], v[56:59]
	v_mfma_f32_16x16x32_bf16 v[56:59], v[152:155], v[192:195], v[56:59]
	v_mfma_f32_16x16x32_bf16 v[48:51], v[152:155], v[200:203], v[48:51]
	v_mfma_f32_16x16x32_bf16 v[48:51], v[156:159], v[204:207], v[48:51]
	v_mfma_f32_16x16x32_bf16 v[44:47], v[164:167], v[204:207], v[44:47]
	v_mfma_f32_16x16x32_bf16 v[44:47], v[160:163], v[200:203], v[44:47]
	v_mfma_f32_16x16x32_bf16 v[36:39], v[160:163], v[208:211], v[36:39]
	v_mfma_f32_16x16x32_bf16 v[36:39], v[164:167], v[212:215], v[36:39]
	v_mfma_f32_16x16x32_bf16 v[40:43], v[156:159], v[212:215], v[40:43]
	v_mfma_f32_16x16x32_bf16 v[40:43], v[152:155], v[208:211], v[40:43]
	s_setprio 0
	s_setprio 1
	v_mfma_f32_16x16x32_bf16 v[32:35], v[168:171], v[184:187], v[32:35]
	v_mfma_f32_16x16x32_bf16 v[32:35], v[172:175], v[188:191], v[32:35]
	v_mfma_f32_16x16x32_bf16 v[28:31], v[180:183], v[188:191], v[28:31]
	v_mfma_f32_16x16x32_bf16 v[28:31], v[176:179], v[184:187], v[28:31]
	v_mfma_f32_16x16x32_bf16 v[20:23], v[176:179], v[192:195], v[20:23]
	v_mfma_f32_16x16x32_bf16 v[20:23], v[180:183], v[196:199], v[20:23]
	v_mfma_f32_16x16x32_bf16 v[24:27], v[172:175], v[196:199], v[24:27]
	v_mfma_f32_16x16x32_bf16 v[24:27], v[168:171], v[192:195], v[24:27]
	v_mfma_f32_16x16x32_bf16 v[16:19], v[168:171], v[200:203], v[16:19]
	v_mfma_f32_16x16x32_bf16 v[16:19], v[172:175], v[204:207], v[16:19]
	v_mfma_f32_16x16x32_bf16 v[12:15], v[180:183], v[204:207], v[12:15]
	v_mfma_f32_16x16x32_bf16 v[12:15], v[176:179], v[200:203], v[12:15]
	v_mfma_f32_16x16x32_bf16 v[2:5], v[176:179], v[208:211], v[4:7]
	v_mfma_f32_16x16x32_bf16 v[2:5], v[180:183], v[212:215], v[2:5]
	v_mfma_f32_16x16x32_bf16 v[8:11], v[172:175], v[212:215], v[8:11]
	v_mfma_f32_16x16x32_bf16 v[8:11], v[168:171], v[208:211], v[8:11]
	s_setprio 0
	s_barrier
	s_add_i32 s81, 0, 0x18000
	v_add_u32_e32 v1, s81, v145
	s_add_i32 s82, 0, 0x1c000
	ds_read_b128 v[152:155], v1
	ds_read_b128 v[156:159], v1 offset:1024
	ds_read_b128 v[160:163], v1 offset:2048
	ds_read_b128 v[164:167], v1 offset:3072
	v_add_u32_e32 v1, s82, v145
	ds_read_b128 v[168:171], v1
	ds_read_b128 v[172:175], v1 offset:1024
	ds_read_b128 v[176:179], v1 offset:2048
	ds_read_b128 v[180:183], v1 offset:3072
	s_add_u32 s54, s54, s4
	s_addc_u32 s55, s55, s5
	s_mov_b32 m0, s64
	v_lshl_add_u64 v[6:7], s[54:55], 0, v[138:139]
	ds_read_b128 v[184:187], v147 offset:32768
	ds_read_b128 v[188:191], v147 offset:33792
	ds_read_b128 v[192:195], v147 offset:34816
	ds_read_b128 v[196:199], v147 offset:35840
	ds_read_b128 v[200:203], v147 offset:36864
	ds_read_b128 v[204:207], v147 offset:37888
	ds_read_b128 v[208:211], v147 offset:38912
	ds_read_b128 v[212:215], v147 offset:39936
	global_load_lds_dwordx4 v[6:7], off
	v_lshl_add_u64 v[6:7], s[54:55], 0, v[134:135]
	s_mov_b32 m0, s65
	s_nop 0
	global_load_lds_dwordx4 v[6:7], off
	s_waitcnt vmcnt(8)
	s_waitcnt lgkmcnt(0)
	s_barrier
	s_setprio 1
	s_waitcnt lgkmcnt(0)
	v_mfma_f32_16x16x32_bf16 v[128:131], v[152:155], v[184:187], v[128:131]
	v_mfma_f32_16x16x32_bf16 v[128:131], v[156:159], v[188:191], v[128:131]
	v_mfma_f32_16x16x32_bf16 v[124:127], v[164:167], v[188:191], v[124:127]
	v_mfma_f32_16x16x32_bf16 v[124:127], v[160:163], v[184:187], v[124:127]
	v_mfma_f32_16x16x32_bf16 v[116:119], v[160:163], v[192:195], v[116:119]
	v_mfma_f32_16x16x32_bf16 v[116:119], v[164:167], v[196:199], v[116:119]
	v_mfma_f32_16x16x32_bf16 v[120:123], v[156:159], v[196:199], v[120:123]
	v_mfma_f32_16x16x32_bf16 v[120:123], v[152:155], v[192:195], v[120:123]
	v_mfma_f32_16x16x32_bf16 v[112:115], v[152:155], v[200:203], v[112:115]
	v_mfma_f32_16x16x32_bf16 v[112:115], v[156:159], v[204:207], v[112:115]
	v_mfma_f32_16x16x32_bf16 v[108:111], v[164:167], v[204:207], v[108:111]
	v_mfma_f32_16x16x32_bf16 v[108:111], v[160:163], v[200:203], v[108:111]
	v_mfma_f32_16x16x32_bf16 v[100:103], v[160:163], v[208:211], v[100:103]
	v_mfma_f32_16x16x32_bf16 v[100:103], v[164:167], v[212:215], v[100:103]
	v_mfma_f32_16x16x32_bf16 v[104:107], v[156:159], v[212:215], v[104:107]
	v_mfma_f32_16x16x32_bf16 v[104:107], v[152:155], v[208:211], v[104:107]
	s_setprio 0
	s_setprio 1
	v_mfma_f32_16x16x32_bf16 v[96:99], v[168:171], v[184:187], v[96:99]
	v_mfma_f32_16x16x32_bf16 v[96:99], v[172:175], v[188:191], v[96:99]
	v_mfma_f32_16x16x32_bf16 v[92:95], v[180:183], v[188:191], v[92:95]
	v_mfma_f32_16x16x32_bf16 v[92:95], v[176:179], v[184:187], v[92:95]
	v_mfma_f32_16x16x32_bf16 v[84:87], v[176:179], v[192:195], v[84:87]
	v_mfma_f32_16x16x32_bf16 v[84:87], v[180:183], v[196:199], v[84:87]
	v_mfma_f32_16x16x32_bf16 v[88:91], v[172:175], v[196:199], v[88:91]
	v_mfma_f32_16x16x32_bf16 v[88:91], v[168:171], v[192:195], v[88:91]
	v_mfma_f32_16x16x32_bf16 v[80:83], v[168:171], v[200:203], v[80:83]
	v_mfma_f32_16x16x32_bf16 v[80:83], v[172:175], v[204:207], v[80:83]
	v_mfma_f32_16x16x32_bf16 v[76:79], v[180:183], v[204:207], v[76:79]
	v_mfma_f32_16x16x32_bf16 v[76:79], v[176:179], v[200:203], v[76:79]
	v_mfma_f32_16x16x32_bf16 v[68:71], v[176:179], v[208:211], v[68:71]
	v_mfma_f32_16x16x32_bf16 v[68:71], v[180:183], v[212:215], v[68:71]
	v_mfma_f32_16x16x32_bf16 v[72:75], v[172:175], v[212:215], v[72:75]
	v_mfma_f32_16x16x32_bf16 v[72:75], v[168:171], v[208:211], v[72:75]
	s_setprio 0
	s_barrier
; #define PG8_STAGE(bufoff, gbase, voff) do { _Pragma("unroll") for (int _i = 0; _i < 2; ++_i) \
;         __builtin_amdgcn_global_load_lds((const unsigned*)((const char*)(gbase) + (voff)[_i]), (PG8_LAS unsigned*)(lds + (bufoff) + ldsw + _i * 8192), 16, 0, 0); } while (0)
; #define PG8_LDA(dst, b, h) do { _Pragma("unroll") for (int m = 0; m < 4; ++m) _Pragma("unroll") for (int k = 0; k < 2; ++k) dst[m][k] = *(const PG8_LAS bf16x8*)(lds + PG8_SA(b, h) + aoff + m * 2048 + k * 1024); } while (0)
; #define PG8_MMA(ai, bj, At, Bt) do { __builtin_amdgcn_s_setprio(1); _Pragma("unroll") for (int m = 0; m < 4; ++m) _Pragma("unroll") for (int n = 0; n < 2; ++n) _Pragma("unroll") for (int k = 0; k < 2; ++k) \
;         acc[ai][bj][m][n] = __builtin_amdgcn_mfma_f32_16x16x32_bf16(Bt[n][k], At[m][k], acc[ai][bj][m][n], 0, 0, 0); __builtin_amdgcn_s_setprio(0); } while (0)
; #define PG8_WAIT_V(n) asm volatile("s_waitcnt vmcnt(" #n ")" ::: "memory")
; #define PG8_WAIT_L(n) asm volatile("s_waitcnt lgkmcnt(" #n ")" ::: "memory")
; #define PG8_BAR __builtin_amdgcn_s_barrier()
; #define PG8_SCHED __builtin_amdgcn_sched_barrier(0)
; template <class Epi, class Sched, bool ALIGN_EPI = false, bool SP2 = false, bool APERM = false  >
; __device__ __forceinline__ void gemm_phase(PG8_LAS unsigned char* lds, const Gemm g, const Sched& S, const Epi& E, const int wid  ) {
;     ...
;             PG8_LDA(At, 1, 1); PG8_STAGE(PG8_SB(1, 0), b3, voffB); PG8_STAGE(PG8_SB(1, 1), b3 + hstep, voffB); PG8_STAGE(PG8_SA(1, 0), a3, voffA);
;             PG8_WAIT_V(8); PG8_WAIT_L(0); PG8_BAR; PG8_MMA(1, 0, At, B0); PG8_MMA(1, 1, At, B1); PG8_BAR; PG8_SCHED;
	s_add_i32 s54, s81, s46
	v_lshl_add_u64 v[6:7], v[148:149], 0, s[16:17]
	s_mov_b32 m0, s54
	ds_read_b128 v[184:187], v147 offset:49152
	ds_read_b128 v[188:191], v147 offset:50176
	ds_read_b128 v[192:195], v147 offset:51200
	ds_read_b128 v[196:199], v147 offset:52224
	ds_read_b128 v[200:203], v147 offset:53248
	ds_read_b128 v[204:207], v147 offset:54272
	ds_read_b128 v[208:211], v147 offset:55296
	ds_read_b128 v[212:215], v147 offset:56320
	global_load_lds_dwordx4 v[6:7], off
	v_lshl_add_u64 v[6:7], v[216:217], 0, s[16:17]
	s_add_i32 m0, s54, 0x2000
	s_add_i32 s54, s82, s46
	global_load_lds_dwordx4 v[6:7], off
	v_lshl_add_u64 v[6:7], v[218:219], 0, s[16:17]
	s_mov_b32 m0, s54
	s_nop 0
	global_load_lds_dwordx4 v[6:7], off
	v_lshl_add_u64 v[6:7], v[220:221], 0, s[16:17]
	s_add_i32 m0, s54, 0x2000
	s_nop 0
	global_load_lds_dwordx4 v[6:7], off
	v_lshl_add_u64 v[6:7], v[222:223], 0, s[16:17]
	s_mov_b32 m0, s67
	s_nop 0
	global_load_lds_dwordx4 v[6:7], off
	v_lshl_add_u64 v[6:7], v[224:225], 0, s[16:17]
	s_mov_b32 m0, s68
	s_nop 0
	global_load_lds_dwordx4 v[6:7], off
	s_waitcnt vmcnt(8)
	s_waitcnt lgkmcnt(0)
	s_barrier
	s_setprio 1
	s_waitcnt lgkmcnt(0)
	v_mfma_f32_16x16x32_bf16 v[64:67], v[152:155], v[184:187], v[64:67]
	v_mfma_f32_16x16x32_bf16 v[64:67], v[156:159], v[188:191], v[64:67]
	v_mfma_f32_16x16x32_bf16 v[60:63], v[164:167], v[188:191], v[60:63]
	v_mfma_f32_16x16x32_bf16 v[60:63], v[160:163], v[184:187], v[60:63]
	v_mfma_f32_16x16x32_bf16 v[52:55], v[160:163], v[192:195], v[52:55]
	v_mfma_f32_16x16x32_bf16 v[52:55], v[164:167], v[196:199], v[52:55]
	v_mfma_f32_16x16x32_bf16 v[56:59], v[156:159], v[196:199], v[56:59]
	v_mfma_f32_16x16x32_bf16 v[56:59], v[152:155], v[192:195], v[56:59]
	v_mfma_f32_16x16x32_bf16 v[48:51], v[152:155], v[200:203], v[48:51]
	v_mfma_f32_16x16x32_bf16 v[48:51], v[156:159], v[204:207], v[48:51]
	v_mfma_f32_16x16x32_bf16 v[44:47], v[164:167], v[204:207], v[44:47]
	v_mfma_f32_16x16x32_bf16 v[44:47], v[160:163], v[200:203], v[44:47]
	v_mfma_f32_16x16x32_bf16 v[36:39], v[160:163], v[208:211], v[36:39]
	v_mfma_f32_16x16x32_bf16 v[36:39], v[164:167], v[212:215], v[36:39]
	v_mfma_f32_16x16x32_bf16 v[40:43], v[156:159], v[212:215], v[40:43]
	v_mfma_f32_16x16x32_bf16 v[40:43], v[152:155], v[208:211], v[40:43]
	s_setprio 0
	s_setprio 1
	v_mfma_f32_16x16x32_bf16 v[32:35], v[168:171], v[184:187], v[32:35]
	v_mfma_f32_16x16x32_bf16 v[28:31], v[176:179], v[184:187], v[28:31]
	v_mfma_f32_16x16x32_bf16 v[24:27], v[168:171], v[192:195], v[24:27]
	v_mfma_f32_16x16x32_bf16 v[20:23], v[176:179], v[192:195], v[20:23]
	v_mfma_f32_16x16x32_bf16 v[16:19], v[168:171], v[200:203], v[16:19]
	v_mfma_f32_16x16x32_bf16 v[12:15], v[176:179], v[200:203], v[12:15]
	v_mfma_f32_16x16x32_bf16 v[6:9], v[168:171], v[208:211], v[8:11]
	v_mfma_f32_16x16x32_bf16 v[2:5], v[176:179], v[208:211], v[2:5]
	v_mfma_f32_16x16x32_bf16 v[32:35], v[172:175], v[188:191], v[32:35]
	v_mfma_f32_16x16x32_bf16 v[28:31], v[180:183], v[188:191], v[28:31]
	v_mfma_f32_16x16x32_bf16 v[24:27], v[172:175], v[196:199], v[24:27]
	v_mfma_f32_16x16x32_bf16 v[20:23], v[180:183], v[196:199], v[20:23]
	v_mfma_f32_16x16x32_bf16 v[16:19], v[172:175], v[204:207], v[16:19]
	v_mfma_f32_16x16x32_bf16 v[12:15], v[180:183], v[204:207], v[12:15]
	v_mfma_f32_16x16x32_bf16 v[8:11], v[172:175], v[212:215], v[6:9]
	v_mfma_f32_16x16x32_bf16 v[4:7], v[180:183], v[212:215], v[2:5]
	s_setprio 0
	s_barrier
	s_add_u32 s34, s34, 0x100
	s_addc_u32 s35, s35, 0
	s_add_u32 s78, s78, 0x100
	s_addc_u32 s79, s79, 0
	s_cmp_ge_i32 s80, s66
	s_mov_b32 s54, s80
	s_cbranch_scc0 .LBB0_669
	v_readlane_b32 s80, v250, 61
	v_readlane_b32 s82, v249, 5
	v_readlane_b32 s81, v250, 62
	s_and_b64 vcc, exec, s[24:25]
	s_cbranch_vccnz .LBB0_662
	s_branch .LBB0_663

; #define PG8_STAGE(bufoff, gbase, voff) do { _Pragma("unroll") for (int _i = 0; _i < 2; ++_i) \
;         __builtin_amdgcn_global_load_lds((const unsigned*)((const char*)(gbase) + (voff)[_i]), (PG8_LAS unsigned*)(lds + (bufoff) + ldsw + _i * 8192), 16, 0, 0); } while (0)
; #define PG8_LDA(dst, b, h) do { _Pragma("unroll") for (int m = 0; m < 4; ++m) _Pragma("unroll") for (int k = 0; k < 2; ++k) dst[m][k] = *(const PG8_LAS bf16x8*)(lds + PG8_SA(b, h) + aoff + m * 2048 + k * 1024); } while (0)
; #define PG8_LDB(dst, b, h) do { _Pragma("unroll") for (int n = 0; n < 2; ++n) _Pragma("unroll") for (int k = 0; k < 2; ++k) dst[n][k] = *(const PG8_LAS bf16x8*)(lds + PG8_SB(b, h) + boff + n * 2048 + k * 1024); } while (0)
; #define PG8_MMA(ai, bj, At, Bt) do { __builtin_amdgcn_s_setprio(1); _Pragma("unroll") for (int m = 0; m < 4; ++m) _Pragma("unroll") for (int n = 0; n < 2; ++n) _Pragma("unroll") for (int k = 0; k < 2; ++k) \
;         acc[ai][bj][m][n] = __builtin_amdgcn_mfma_f32_16x16x32_bf16(Bt[n][k], At[m][k], acc[ai][bj][m][n], 0, 0, 0); __builtin_amdgcn_s_setprio(0); } while (0)
; #define PG8_WAIT_V(n) asm volatile("s_waitcnt vmcnt(" #n ")" ::: "memory")
; #define PG8_WAIT_L(n) asm volatile("s_waitcnt lgkmcnt(" #n ")" ::: "memory")
; template <class Epi, class Sched, bool ALIGN_EPI = false, bool SP2 = false, bool APERM = false  >
; __device__ __forceinline__ void gemm_phase(PG8_LAS unsigned char* lds, const Gemm g, const Sched& S, const Epi& E, const int wid  ) {
;     ...
;             const bool last = (t == nt - 2);
;             const char* a1 = cA + (size_t)(t + 1) * kstep;
;             const char* a2 = last ? nA : cA + (size_t)(t + 2) * kstep; const char* b2 = last ? nB : cB + (size_t)(t + 2) * kstep;
;             const char* a3 = a2 + kstep; const char* b3 = b2 + kstep;
;             if (last && has_next) S.a_ready(nxt);
;             if constexpr (SP2) {
;             PG8_LDB(B0, 0, 0); PG8_LDB(B1, 0, 1); PG8_SCHED; PG8_LDA(At, 0, 0); PG8_STAGE(PG8_SA(1, 1), a1 + hstep, voffA);
;             PG8_WAIT_V(8); PG8_WAIT_L(0); PG8_BAR; PG8_MMA(0, 0, At, B0); PG8_MMA(0, 1, At, B1); PG8_BAR; PG8_SCHED;
;             PG8_LDA(At, 0, 1); PG8_STAGE(PG8_SB(0, 0), b2, voffB); PG8_STAGE(PG8_SB(0, 1), b2 + hstep, voffB); PG8_STAGE(PG8_SA(0, 0), a2, voffA);
;             PG8_WAIT_V(8); PG8_WAIT_L(0); PG8_BAR; PG8_MMA(1, 0, At, B0); PG8_MMA(1, 1, At, B1); PG8_BAR; PG8_SCHED;
.LBB0_715:
	s_lshl_b32 s24, s71, 7
	s_add_u32 s25, s0, s24
	s_addc_u32 s26, s1, 0
	s_add_u32 s27, s25, 0x100
	v_add_u32_e32 v146, s94, v175
	s_addc_u32 s73, s26, 0
	s_waitcnt lgkmcnt(0)
	ds_read_b128 v[128:131], v146
	ds_read_b128 v[132:135], v146 offset:1024
	ds_read_b128 v[136:139], v146 offset:2048
	ds_read_b128 v[154:157], v146 offset:3072
	v_add_u32_e32 v146, s95, v175
	s_and_b64 s[18:19], s[16:17], exec
	ds_read_b128 v[158:161], v146
	ds_read_b128 v[162:165], v146 offset:1024
	ds_read_b128 v[166:169], v146 offset:2048
	ds_read_b128 v[170:173], v146 offset:3072
	s_cselect_b32 s19, s33, s73
	s_cselect_b32 s18, s52, s27
	s_add_u32 s24, s14, s24
	s_addc_u32 s27, s15, 0
	s_add_u32 s24, s24, 0x100
	s_addc_u32 s27, s27, 0
	s_and_b64 s[16:17], s[16:17], exec
	s_cselect_b32 s16, s65, s24
	s_cselect_b32 s17, s64, s27
	s_add_u32 s24, s25, 0x80080
	s_addc_u32 s25, s26, 0
	v_lshl_add_u64 v[214:215], s[24:25], 0, v[144:145]
	s_add_i32 m0, s11, 0xc000
	ds_read_b128 v[182:185], v180
	ds_read_b128 v[186:189], v180 offset:1024
	ds_read_b128 v[190:193], v180 offset:2048
	ds_read_b128 v[194:197], v180 offset:3072
	ds_read_b128 v[198:201], v180 offset:4096
	ds_read_b128 v[202:205], v180 offset:5120
	ds_read_b128 v[206:209], v180 offset:6144
	ds_read_b128 v[210:213], v180 offset:7168
	global_load_lds_dwordx4 v[214:215], off
	v_lshl_add_u64 v[214:215], s[24:25], 0, v[148:149]
	s_add_i32 m0, s11, 0xe000
	s_nop 0
	global_load_lds_dwordx4 v[214:215], off
	s_waitcnt vmcnt(8)
	s_waitcnt lgkmcnt(0)
	s_barrier
	s_setprio 1
	s_waitcnt lgkmcnt(0)
	v_mfma_f32_16x16x32_bf16 v[124:127], v[128:131], v[182:185], v[124:127]
	v_mfma_f32_16x16x32_bf16 v[124:127], v[132:135], v[186:189], v[124:127]
	v_mfma_f32_16x16x32_bf16 v[120:123], v[154:157], v[186:189], v[120:123]
	v_mfma_f32_16x16x32_bf16 v[120:123], v[136:139], v[182:185], v[120:123]
	v_mfma_f32_16x16x32_bf16 v[112:115], v[136:139], v[190:193], v[112:115]
	v_mfma_f32_16x16x32_bf16 v[112:115], v[154:157], v[194:197], v[112:115]
	v_mfma_f32_16x16x32_bf16 v[116:119], v[132:135], v[194:197], v[116:119]
	v_mfma_f32_16x16x32_bf16 v[116:119], v[128:131], v[190:193], v[116:119]
	v_mfma_f32_16x16x32_bf16 v[108:111], v[128:131], v[198:201], v[108:111]
	v_mfma_f32_16x16x32_bf16 v[108:111], v[132:135], v[202:205], v[108:111]
	v_mfma_f32_16x16x32_bf16 v[104:107], v[154:157], v[202:205], v[104:107]
	v_mfma_f32_16x16x32_bf16 v[104:107], v[136:139], v[198:201], v[104:107]
	v_mfma_f32_16x16x32_bf16 v[96:99], v[136:139], v[206:209], v[96:99]
	v_mfma_f32_16x16x32_bf16 v[96:99], v[154:157], v[210:213], v[96:99]
	v_mfma_f32_16x16x32_bf16 v[100:103], v[132:135], v[210:213], v[100:103]
	v_mfma_f32_16x16x32_bf16 v[100:103], v[128:131], v[206:209], v[100:103]
	s_setprio 0
	s_setprio 1
	v_mfma_f32_16x16x32_bf16 v[92:95], v[158:161], v[182:185], v[92:95]
	v_mfma_f32_16x16x32_bf16 v[92:95], v[162:165], v[186:189], v[92:95]
	v_mfma_f32_16x16x32_bf16 v[88:91], v[170:173], v[186:189], v[88:91]
	v_mfma_f32_16x16x32_bf16 v[88:91], v[166:169], v[182:185], v[88:91]
	v_mfma_f32_16x16x32_bf16 v[80:83], v[166:169], v[190:193], v[80:83]
	v_mfma_f32_16x16x32_bf16 v[80:83], v[170:173], v[194:197], v[80:83]
	v_mfma_f32_16x16x32_bf16 v[84:87], v[162:165], v[194:197], v[84:87]
	v_mfma_f32_16x16x32_bf16 v[84:87], v[158:161], v[190:193], v[84:87]
	v_mfma_f32_16x16x32_bf16 v[76:79], v[158:161], v[198:201], v[76:79]
	v_mfma_f32_16x16x32_bf16 v[76:79], v[162:165], v[202:205], v[76:79]
	v_mfma_f32_16x16x32_bf16 v[72:75], v[170:173], v[202:205], v[72:75]
	v_mfma_f32_16x16x32_bf16 v[72:75], v[166:169], v[198:201], v[72:75]
	v_mfma_f32_16x16x32_bf16 v[64:67], v[166:169], v[206:209], v[64:67]
	v_mfma_f32_16x16x32_bf16 v[64:67], v[170:173], v[210:213], v[64:67]
	v_mfma_f32_16x16x32_bf16 v[68:71], v[162:165], v[210:213], v[68:71]
	v_mfma_f32_16x16x32_bf16 v[68:71], v[158:161], v[206:209], v[68:71]
	s_setprio 0
	s_barrier
	s_add_i32 s24, s94, s46
	v_lshl_add_u64 v[214:215], s[16:17], 0, v[140:141]
	s_mov_b32 m0, s24
	ds_read_b128 v[182:185], v180 offset:16384
	ds_read_b128 v[186:189], v180 offset:17408
	ds_read_b128 v[190:193], v180 offset:18432
	ds_read_b128 v[194:197], v180 offset:19456
	ds_read_b128 v[198:201], v180 offset:20480
	ds_read_b128 v[202:205], v180 offset:21504
	ds_read_b128 v[206:209], v180 offset:22528
	ds_read_b128 v[210:213], v180 offset:23552
	global_load_lds_dwordx4 v[214:215], off
	s_add_i32 m0, s24, 0x2000
	s_add_u32 s24, s16, 0x80000
	v_lshl_add_u64 v[216:217], s[16:17], 0, v[142:143]
	s_addc_u32 s25, s17, 0
	s_add_i32 s26, s95, s46
	global_load_lds_dwordx4 v[216:217], off
	v_lshl_add_u64 v[218:219], s[24:25], 0, v[140:141]
	s_mov_b32 m0, s26
	v_lshl_add_u64 v[220:221], s[18:19], 0, v[148:149]
	global_load_lds_dwordx4 v[218:219], off
	v_lshl_add_u64 v[218:219], s[24:25], 0, v[142:143]
	s_add_i32 m0, s26, 0x2000
	s_nop 0
	global_load_lds_dwordx4 v[218:219], off
	v_lshl_add_u64 v[218:219], s[18:19], 0, v[144:145]
	s_mov_b32 m0, s11
	s_nop 0
	global_load_lds_dwordx4 v[218:219], off
	s_mov_b32 m0, s13
	s_nop 0
	global_load_lds_dwordx4 v[220:221], off
	s_waitcnt vmcnt(8)
	s_waitcnt lgkmcnt(0)
	s_barrier
; #define PG8_STAGE(bufoff, gbase, voff) do { _Pragma("unroll") for (int _i = 0; _i < 2; ++_i) \
;         __builtin_amdgcn_global_load_lds((const unsigned*)((const char*)(gbase) + (voff)[_i]), (PG8_LAS unsigned*)(lds + (bufoff) + ldsw + _i * 8192), 16, 0, 0); } while (0)
; #define PG8_LDA(dst, b, h) do { _Pragma("unroll") for (int m = 0; m < 4; ++m) _Pragma("unroll") for (int k = 0; k < 2; ++k) dst[m][k] = *(const PG8_LAS bf16x8*)(lds + PG8_SA(b, h) + aoff + m * 2048 + k * 1024); } while (0)
; #define PG8_LDB(dst, b, h) do { _Pragma("unroll") for (int n = 0; n < 2; ++n) _Pragma("unroll") for (int k = 0; k < 2; ++k) dst[n][k] = *(const PG8_LAS bf16x8*)(lds + PG8_SB(b, h) + boff + n * 2048 + k * 1024); } while (0)
; #define PG8_MMA(ai, bj, At, Bt) do { __builtin_amdgcn_s_setprio(1); _Pragma("unroll") for (int m = 0; m < 4; ++m) _Pragma("unroll") for (int n = 0; n < 2; ++n) _Pragma("unroll") for (int k = 0; k < 2; ++k) \
;         acc[ai][bj][m][n] = __builtin_amdgcn_mfma_f32_16x16x32_bf16(Bt[n][k], At[m][k], acc[ai][bj][m][n], 0, 0, 0); __builtin_amdgcn_s_setprio(0); } while (0)
; #define PG8_WAIT_V(n) asm volatile("s_waitcnt vmcnt(" #n ")" ::: "memory")
; #define PG8_WAIT_L(n) asm volatile("s_waitcnt lgkmcnt(" #n ")" ::: "memory")
; #define PG8_BAR __builtin_amdgcn_s_barrier()
; #define PG8_SCHED __builtin_amdgcn_sched_barrier(0)
; template <class Epi, class Sched, bool ALIGN_EPI = false, bool SP2 = false, bool APERM = false  >
; __device__ __forceinline__ void gemm_phase(PG8_LAS unsigned char* lds, const Gemm g, const Sched& S, const Epi& E, const int wid  ) {
;     ...
;             PG8_WAIT_V(8); PG8_WAIT_L(0); PG8_BAR; PG8_MMA(1, 0, At, B0); PG8_MMA(1, 1, At, B1); PG8_BAR; PG8_SCHED;
;             PG8_LDB(B0, 1, 0); PG8_LDB(B1, 1, 1); PG8_SCHED; PG8_LDA(At, 1, 0); PG8_STAGE(PG8_SA(0, 1), a2 + hstep, voffA);
;             PG8_WAIT_V(8); PG8_WAIT_L(0); PG8_BAR; PG8_MMA(0, 0, At, B0); PG8_MMA(0, 1, At, B1); PG8_BAR; PG8_SCHED;
	s_setprio 1
	s_waitcnt lgkmcnt(0)
	v_mfma_f32_16x16x32_bf16 v[60:63], v[128:131], v[182:185], v[60:63]
	v_mfma_f32_16x16x32_bf16 v[60:63], v[132:135], v[186:189], v[60:63]
	v_mfma_f32_16x16x32_bf16 v[56:59], v[154:157], v[186:189], v[56:59]
	v_mfma_f32_16x16x32_bf16 v[56:59], v[136:139], v[182:185], v[56:59]
	v_mfma_f32_16x16x32_bf16 v[48:51], v[136:139], v[190:193], v[48:51]
	v_mfma_f32_16x16x32_bf16 v[48:51], v[154:157], v[194:197], v[48:51]
	v_mfma_f32_16x16x32_bf16 v[52:55], v[132:135], v[194:197], v[52:55]
	v_mfma_f32_16x16x32_bf16 v[52:55], v[128:131], v[190:193], v[52:55]
	v_mfma_f32_16x16x32_bf16 v[44:47], v[128:131], v[198:201], v[44:47]
	v_mfma_f32_16x16x32_bf16 v[44:47], v[132:135], v[202:205], v[44:47]
	v_mfma_f32_16x16x32_bf16 v[40:43], v[154:157], v[202:205], v[40:43]
	v_mfma_f32_16x16x32_bf16 v[40:43], v[136:139], v[198:201], v[40:43]
	v_mfma_f32_16x16x32_bf16 v[32:35], v[136:139], v[206:209], v[32:35]
	v_mfma_f32_16x16x32_bf16 v[32:35], v[154:157], v[210:213], v[32:35]
	v_mfma_f32_16x16x32_bf16 v[36:39], v[132:135], v[210:213], v[36:39]
	v_mfma_f32_16x16x32_bf16 v[36:39], v[128:131], v[206:209], v[36:39]
	s_setprio 0
	s_setprio 1
	v_mfma_f32_16x16x32_bf16 v[28:31], v[158:161], v[182:185], v[28:31]
	v_mfma_f32_16x16x32_bf16 v[28:31], v[162:165], v[186:189], v[28:31]
	v_mfma_f32_16x16x32_bf16 v[24:27], v[170:173], v[186:189], v[24:27]
	v_mfma_f32_16x16x32_bf16 v[24:27], v[166:169], v[182:185], v[24:27]
	v_mfma_f32_16x16x32_bf16 v[16:19], v[166:169], v[190:193], v[16:19]
	v_mfma_f32_16x16x32_bf16 v[16:19], v[170:173], v[194:197], v[16:19]
	v_mfma_f32_16x16x32_bf16 v[20:23], v[162:165], v[194:197], v[20:23]
	v_mfma_f32_16x16x32_bf16 v[20:23], v[158:161], v[190:193], v[20:23]
	v_mfma_f32_16x16x32_bf16 v[12:15], v[158:161], v[198:201], v[12:15]
	v_mfma_f32_16x16x32_bf16 v[12:15], v[162:165], v[202:205], v[12:15]
	v_mfma_f32_16x16x32_bf16 v[8:11], v[170:173], v[202:205], v[8:11]
	v_mfma_f32_16x16x32_bf16 v[8:11], v[166:169], v[198:201], v[8:11]
	v_mfma_f32_16x16x32_bf16 v[0:3], v[166:169], v[206:209], v[0:3]
	v_mfma_f32_16x16x32_bf16 v[0:3], v[170:173], v[210:213], v[0:3]
	v_mfma_f32_16x16x32_bf16 v[4:7], v[162:165], v[210:213], v[4:7]
	v_mfma_f32_16x16x32_bf16 v[4:7], v[158:161], v[206:209], v[4:7]
	s_setprio 0
	s_barrier
	s_add_i32 s24, 0, 0x18000
	v_add_u32_e32 v146, s24, v175
	s_add_i32 s25, 0, 0x1c000
	ds_read_b128 v[128:131], v146
	ds_read_b128 v[132:135], v146 offset:1024
	ds_read_b128 v[136:139], v146 offset:2048
	ds_read_b128 v[154:157], v146 offset:3072
	v_add_u32_e32 v146, s25, v175
	ds_read_b128 v[158:161], v146
	ds_read_b128 v[162:165], v146 offset:1024
	ds_read_b128 v[166:169], v146 offset:2048
	ds_read_b128 v[170:173], v146 offset:3072
	s_add_u32 s18, s18, 0x80000
	s_addc_u32 s19, s19, 0
	s_mov_b32 m0, s30
	v_lshl_add_u64 v[222:223], s[18:19], 0, v[144:145]
	ds_read_b128 v[182:185], v180 offset:32768
	ds_read_b128 v[186:189], v180 offset:33792
	ds_read_b128 v[190:193], v180 offset:34816
	ds_read_b128 v[194:197], v180 offset:35840
	ds_read_b128 v[198:201], v180 offset:36864
	ds_read_b128 v[202:205], v180 offset:37888
	ds_read_b128 v[206:209], v180 offset:38912
	ds_read_b128 v[210:213], v180 offset:39936
	global_load_lds_dwordx4 v[222:223], off
	v_lshl_add_u64 v[222:223], s[18:19], 0, v[148:149]
	s_mov_b32 m0, s31
	s_nop 0
	global_load_lds_dwordx4 v[222:223], off
	s_waitcnt vmcnt(8)
	s_waitcnt lgkmcnt(0)
	s_barrier
	s_setprio 1
	s_waitcnt lgkmcnt(0)
	v_mfma_f32_16x16x32_bf16 v[124:127], v[128:131], v[182:185], v[124:127]
	v_mfma_f32_16x16x32_bf16 v[124:127], v[132:135], v[186:189], v[124:127]
	v_mfma_f32_16x16x32_bf16 v[120:123], v[154:157], v[186:189], v[120:123]
	v_mfma_f32_16x16x32_bf16 v[120:123], v[136:139], v[182:185], v[120:123]
	v_mfma_f32_16x16x32_bf16 v[112:115], v[136:139], v[190:193], v[112:115]
	v_mfma_f32_16x16x32_bf16 v[112:115], v[154:157], v[194:197], v[112:115]
	v_mfma_f32_16x16x32_bf16 v[116:119], v[132:135], v[194:197], v[116:119]
	v_mfma_f32_16x16x32_bf16 v[116:119], v[128:131], v[190:193], v[116:119]
	v_mfma_f32_16x16x32_bf16 v[108:111], v[128:131], v[198:201], v[108:111]
	v_mfma_f32_16x16x32_bf16 v[108:111], v[132:135], v[202:205], v[108:111]
	v_mfma_f32_16x16x32_bf16 v[104:107], v[154:157], v[202:205], v[104:107]
	v_mfma_f32_16x16x32_bf16 v[104:107], v[136:139], v[198:201], v[104:107]
	v_mfma_f32_16x16x32_bf16 v[96:99], v[136:139], v[206:209], v[96:99]
	v_mfma_f32_16x16x32_bf16 v[96:99], v[154:157], v[210:213], v[96:99]
	v_mfma_f32_16x16x32_bf16 v[100:103], v[132:135], v[210:213], v[100:103]
	v_mfma_f32_16x16x32_bf16 v[100:103], v[128:131], v[206:209], v[100:103]
	s_setprio 0
	s_setprio 1
	v_mfma_f32_16x16x32_bf16 v[92:95], v[158:161], v[182:185], v[92:95]
	v_mfma_f32_16x16x32_bf16 v[92:95], v[162:165], v[186:189], v[92:95]
	v_mfma_f32_16x16x32_bf16 v[88:91], v[170:173], v[186:189], v[88:91]
	v_mfma_f32_16x16x32_bf16 v[88:91], v[166:169], v[182:185], v[88:91]
	v_mfma_f32_16x16x32_bf16 v[80:83], v[166:169], v[190:193], v[80:83]
	v_mfma_f32_16x16x32_bf16 v[80:83], v[170:173], v[194:197], v[80:83]
	v_mfma_f32_16x16x32_bf16 v[84:87], v[162:165], v[194:197], v[84:87]
	v_mfma_f32_16x16x32_bf16 v[84:87], v[158:161], v[190:193], v[84:87]
	v_mfma_f32_16x16x32_bf16 v[76:79], v[158:161], v[198:201], v[76:79]
	v_mfma_f32_16x16x32_bf16 v[76:79], v[162:165], v[202:205], v[76:79]
	v_mfma_f32_16x16x32_bf16 v[72:75], v[170:173], v[202:205], v[72:75]
	v_mfma_f32_16x16x32_bf16 v[72:75], v[166:169], v[198:201], v[72:75]
	v_mfma_f32_16x16x32_bf16 v[64:67], v[166:169], v[206:209], v[64:67]
	v_mfma_f32_16x16x32_bf16 v[64:67], v[170:173], v[210:213], v[64:67]
	v_mfma_f32_16x16x32_bf16 v[68:71], v[162:165], v[210:213], v[68:71]
	v_mfma_f32_16x16x32_bf16 v[68:71], v[158:161], v[206:209], v[68:71]
	s_setprio 0
	s_barrier
; #define PG8_STAGE(bufoff, gbase, voff) do { _Pragma("unroll") for (int _i = 0; _i < 2; ++_i) \
;         __builtin_amdgcn_global_load_lds((const unsigned*)((const char*)(gbase) + (voff)[_i]), (PG8_LAS unsigned*)(lds + (bufoff) + ldsw + _i * 8192), 16, 0, 0); } while (0)
; #define PG8_LDA(dst, b, h) do { _Pragma("unroll") for (int m = 0; m < 4; ++m) _Pragma("unroll") for (int k = 0; k < 2; ++k) dst[m][k] = *(const PG8_LAS bf16x8*)(lds + PG8_SA(b, h) + aoff + m * 2048 + k * 1024); } while (0)
; #define PG8_MMA(ai, bj, At, Bt) do { __builtin_amdgcn_s_setprio(1); _Pragma("unroll") for (int m = 0; m < 4; ++m) _Pragma("unroll") for (int n = 0; n < 2; ++n) _Pragma("unroll") for (int k = 0; k < 2; ++k) \
;         acc[ai][bj][m][n] = __builtin_amdgcn_mfma_f32_16x16x32_bf16(Bt[n][k], At[m][k], acc[ai][bj][m][n], 0, 0, 0); __builtin_amdgcn_s_setprio(0); } while (0)
; #define PG8_WAIT_V(n) asm volatile("s_waitcnt vmcnt(" #n ")" ::: "memory")
; #define PG8_WAIT_L(n) asm volatile("s_waitcnt lgkmcnt(" #n ")" ::: "memory")
; #define PG8_BAR __builtin_amdgcn_s_barrier()
; #define PG8_SCHED __builtin_amdgcn_sched_barrier(0)
; template <class Epi, class Sched, bool ALIGN_EPI = false, bool SP2 = false, bool APERM = false  >
; __device__ __forceinline__ void gemm_phase(PG8_LAS unsigned char* lds, const Gemm g, const Sched& S, const Epi& E, const int wid  ) {
;     ...
;             PG8_LDA(At, 1, 1); PG8_STAGE(PG8_SB(1, 0), b3, voffB); PG8_STAGE(PG8_SB(1, 1), b3 + hstep, voffB); PG8_STAGE(PG8_SA(1, 0), a3, voffA);
;             PG8_WAIT_V(8); PG8_WAIT_L(0); PG8_BAR; PG8_MMA(1, 0, At, B0); PG8_MMA(1, 1, At, B1); PG8_BAR; PG8_SCHED;
	s_add_i32 s18, s24, s46
	v_lshl_add_u64 v[214:215], v[214:215], 0, s[62:63]
	s_mov_b32 m0, s18
	ds_read_b128 v[182:185], v180 offset:49152
	ds_read_b128 v[186:189], v180 offset:50176
	ds_read_b128 v[190:193], v180 offset:51200
	ds_read_b128 v[194:197], v180 offset:52224
	ds_read_b128 v[198:201], v180 offset:53248
	ds_read_b128 v[202:205], v180 offset:54272
	ds_read_b128 v[206:209], v180 offset:55296
	ds_read_b128 v[210:213], v180 offset:56320
	global_load_lds_dwordx4 v[214:215], off
	s_add_i32 m0, s18, 0x2000
	s_add_u32 s16, s16, 0x80080
	v_lshl_add_u64 v[214:215], v[216:217], 0, s[62:63]
	s_addc_u32 s17, s17, 0
	s_add_i32 s18, s25, s46
	global_load_lds_dwordx4 v[214:215], off
	v_lshl_add_u64 v[214:215], s[16:17], 0, v[140:141]
	s_mov_b32 m0, s18
	s_nop 0
	global_load_lds_dwordx4 v[214:215], off
	v_lshl_add_u64 v[214:215], s[16:17], 0, v[142:143]
	s_add_i32 m0, s18, 0x2000
	s_nop 0
	global_load_lds_dwordx4 v[214:215], off
	v_lshl_add_u64 v[214:215], v[218:219], 0, s[62:63]
	s_mov_b32 m0, s53
	s_nop 0
	global_load_lds_dwordx4 v[214:215], off
	v_lshl_add_u64 v[214:215], v[220:221], 0, s[62:63]
	s_mov_b32 m0, s85
	s_nop 0
	global_load_lds_dwordx4 v[214:215], off
	s_waitcnt vmcnt(8)
	s_waitcnt lgkmcnt(0)
	s_barrier
	s_setprio 1
	s_waitcnt lgkmcnt(0)
	v_mfma_f32_16x16x32_bf16 v[60:63], v[128:131], v[182:185], v[60:63]
	v_mfma_f32_16x16x32_bf16 v[60:63], v[132:135], v[186:189], v[60:63]
	v_mfma_f32_16x16x32_bf16 v[56:59], v[154:157], v[186:189], v[56:59]
	v_mfma_f32_16x16x32_bf16 v[56:59], v[136:139], v[182:185], v[56:59]
	v_mfma_f32_16x16x32_bf16 v[48:51], v[136:139], v[190:193], v[48:51]
	v_mfma_f32_16x16x32_bf16 v[48:51], v[154:157], v[194:197], v[48:51]
	v_mfma_f32_16x16x32_bf16 v[52:55], v[132:135], v[194:197], v[52:55]
	v_mfma_f32_16x16x32_bf16 v[52:55], v[128:131], v[190:193], v[52:55]
	v_mfma_f32_16x16x32_bf16 v[44:47], v[128:131], v[198:201], v[44:47]
	v_mfma_f32_16x16x32_bf16 v[44:47], v[132:135], v[202:205], v[44:47]
	v_mfma_f32_16x16x32_bf16 v[40:43], v[154:157], v[202:205], v[40:43]
	v_mfma_f32_16x16x32_bf16 v[40:43], v[136:139], v[198:201], v[40:43]
	v_mfma_f32_16x16x32_bf16 v[32:35], v[136:139], v[206:209], v[32:35]
	v_mfma_f32_16x16x32_bf16 v[32:35], v[154:157], v[210:213], v[32:35]
	v_mfma_f32_16x16x32_bf16 v[36:39], v[132:135], v[210:213], v[36:39]
	v_mfma_f32_16x16x32_bf16 v[36:39], v[128:131], v[206:209], v[36:39]
	s_setprio 0
	s_setprio 1
	v_mfma_f32_16x16x32_bf16 v[28:31], v[158:161], v[182:185], v[28:31]
	v_mfma_f32_16x16x32_bf16 v[28:31], v[162:165], v[186:189], v[28:31]
	v_mfma_f32_16x16x32_bf16 v[24:27], v[170:173], v[186:189], v[24:27]
	v_mfma_f32_16x16x32_bf16 v[24:27], v[166:169], v[182:185], v[24:27]
	v_mfma_f32_16x16x32_bf16 v[16:19], v[166:169], v[190:193], v[16:19]
	v_mfma_f32_16x16x32_bf16 v[16:19], v[170:173], v[194:197], v[16:19]
	v_mfma_f32_16x16x32_bf16 v[20:23], v[162:165], v[194:197], v[20:23]
	v_mfma_f32_16x16x32_bf16 v[20:23], v[158:161], v[190:193], v[20:23]
	v_mfma_f32_16x16x32_bf16 v[12:15], v[158:161], v[198:201], v[12:15]
	v_mfma_f32_16x16x32_bf16 v[12:15], v[162:165], v[202:205], v[12:15]
	v_mfma_f32_16x16x32_bf16 v[8:11], v[170:173], v[202:205], v[8:11]
	v_mfma_f32_16x16x32_bf16 v[8:11], v[166:169], v[198:201], v[8:11]
	v_mfma_f32_16x16x32_bf16 v[0:3], v[166:169], v[206:209], v[0:3]
	v_mfma_f32_16x16x32_bf16 v[0:3], v[170:173], v[210:213], v[0:3]
	v_mfma_f32_16x16x32_bf16 v[4:7], v[162:165], v[210:213], v[4:7]
	v_mfma_f32_16x16x32_bf16 v[4:7], v[158:161], v[206:209], v[4:7]
	s_setprio 0
	s_barrier
	s_add_i32 s16, s71, 2
	s_cmp_gt_u32 s71, 29
	s_cbranch_scc1 .LBB0_717
	s_mov_b32 s71, s16
	s_branch .LBB0_698

; #define PG8_STAGE(bufoff, gbase, voff) do { _Pragma("unroll") for (int _i = 0; _i < 2; ++_i) \
;         __builtin_amdgcn_global_load_lds((const unsigned*)((const char*)(gbase) + (voff)[_i]), (PG8_LAS unsigned*)(lds + (bufoff) + ldsw + _i * 8192), 16, 0, 0); } while (0)
; #define PG8_LDA(dst, b, h) do { _Pragma("unroll") for (int m = 0; m < 4; ++m) _Pragma("unroll") for (int k = 0; k < 2; ++k) dst[m][k] = *(const PG8_LAS bf16x8*)(lds + PG8_SA(b, h) + aoff + m * 2048 + k * 1024); } while (0)
; #define PG8_LDB(dst, b, h) do { _Pragma("unroll") for (int n = 0; n < 2; ++n) _Pragma("unroll") for (int k = 0; k < 2; ++k) dst[n][k] = *(const PG8_LAS bf16x8*)(lds + PG8_SB(b, h) + boff + n * 2048 + k * 1024); } while (0)
; #define PG8_MMA(ai, bj, At, Bt) do { __builtin_amdgcn_s_setprio(1); _Pragma("unroll") for (int m = 0; m < 4; ++m) _Pragma("unroll") for (int n = 0; n < 2; ++n) _Pragma("unroll") for (int k = 0; k < 2; ++k) \
;         acc[ai][bj][m][n] = __builtin_amdgcn_mfma_f32_16x16x32_bf16(Bt[n][k], At[m][k], acc[ai][bj][m][n], 0, 0, 0); __builtin_amdgcn_s_setprio(0); } while (0)
; #define PG8_WAIT_V(n) asm volatile("s_waitcnt vmcnt(" #n ")" ::: "memory")
; #define PG8_WAIT_L(n) asm volatile("s_waitcnt lgkmcnt(" #n ")" ::: "memory")
; template <class Epi, class Sched, bool ALIGN_EPI = false, bool SP2 = false, bool APERM = false  >
; __device__ __forceinline__ void gemm_phase(PG8_LAS unsigned char* lds, const Gemm g, const Sched& S, const Epi& E, const int wid  ) {
;     ...
;             const bool last = (t == nt - 2);
;             const char* a1 = cA + (size_t)(t + 1) * kstep;
;             const char* a2 = last ? nA : cA + (size_t)(t + 2) * kstep; const char* b2 = last ? nB : cB + (size_t)(t + 2) * kstep;
;             const char* a3 = a2 + kstep; const char* b3 = b2 + kstep;
;             if (last && has_next) S.a_ready(nxt);
;             if constexpr (SP2) {
;             PG8_LDB(B0, 0, 0); PG8_LDB(B1, 0, 1); PG8_SCHED; PG8_LDA(At, 0, 0); PG8_STAGE(PG8_SA(1, 1), a1 + hstep, voffA);
;             PG8_WAIT_V(8); PG8_WAIT_L(0); PG8_BAR; PG8_MMA(0, 0, At, B0); PG8_MMA(0, 1, At, B1); PG8_BAR; PG8_SCHED;
;             PG8_LDA(At, 0, 1); PG8_STAGE(PG8_SB(0, 0), b2, voffB); PG8_STAGE(PG8_SB(0, 1), b2 + hstep, voffB); PG8_STAGE(PG8_SA(0, 0), a2, voffA);
;             PG8_WAIT_V(8); PG8_WAIT_L(0); PG8_BAR; PG8_MMA(1, 0, At, B0); PG8_MMA(1, 1, At, B1); PG8_BAR; PG8_SCHED;
.LBB0_793:
	s_lshl_b32 s19, s74, 7
	s_add_u32 s24, s60, s19
	s_addc_u32 s25, s61, 0
	s_add_u32 s16, s24, 0x100
	v_add_u32_e32 v138, s55, v160
	s_addc_u32 s17, s25, 0
	s_waitcnt lgkmcnt(0)
	ds_read_b128 v[128:131], v138
	ds_read_b128 v[146:149], v138 offset:1024
	ds_read_b128 v[150:153], v138 offset:2048
	ds_read_b128 v[154:157], v138 offset:3072
	v_add_u32_e32 v138, s84, v160
	s_and_b64 s[0:1], s[6:7], exec
	ds_read_b128 v[168:171], v138
	ds_read_b128 v[172:175], v138 offset:1024
	ds_read_b128 v[176:179], v138 offset:2048
	ds_read_b128 v[180:183], v138 offset:3072
	s_cselect_b32 s17, s33, s17
	s_cselect_b32 s16, s52, s16
	s_add_u32 s0, s56, s19
	s_addc_u32 s1, s57, 0
	s_add_u32 s19, s0, 0x100
	s_addc_u32 s75, s1, 0
	s_and_b64 s[0:1], s[6:7], exec
	s_cselect_b32 s0, s65, s19
	s_cselect_b32 s1, s64, s75
	s_add_u32 s6, s24, 0x80080
	s_addc_u32 s7, s25, 0
	v_lshl_add_u64 v[216:217], s[6:7], 0, v[136:137]
	s_add_i32 m0, s15, 0xc000
	ds_read_b128 v[184:187], v165
	ds_read_b128 v[188:191], v165 offset:1024
	ds_read_b128 v[192:195], v165 offset:2048
	ds_read_b128 v[196:199], v165 offset:3072
	ds_read_b128 v[200:203], v165 offset:4096
	ds_read_b128 v[204:207], v165 offset:5120
	ds_read_b128 v[208:211], v165 offset:6144
	ds_read_b128 v[212:215], v165 offset:7168
	global_load_lds_dwordx4 v[216:217], off
	v_lshl_add_u64 v[216:217], s[6:7], 0, v[140:141]
	s_add_i32 m0, s15, 0xe000
	s_nop 0
	global_load_lds_dwordx4 v[216:217], off
	s_waitcnt vmcnt(8)
	s_waitcnt lgkmcnt(0)
	s_barrier
	s_setprio 1
	s_waitcnt lgkmcnt(0)
	v_mfma_f32_16x16x32_bf16 v[124:127], v[128:131], v[184:187], v[124:127]
	v_mfma_f32_16x16x32_bf16 v[124:127], v[146:149], v[188:191], v[124:127]
	v_mfma_f32_16x16x32_bf16 v[120:123], v[154:157], v[188:191], v[120:123]
	v_mfma_f32_16x16x32_bf16 v[120:123], v[150:153], v[184:187], v[120:123]
	v_mfma_f32_16x16x32_bf16 v[112:115], v[150:153], v[192:195], v[112:115]
	v_mfma_f32_16x16x32_bf16 v[112:115], v[154:157], v[196:199], v[112:115]
	v_mfma_f32_16x16x32_bf16 v[116:119], v[146:149], v[196:199], v[116:119]
	v_mfma_f32_16x16x32_bf16 v[116:119], v[128:131], v[192:195], v[116:119]
	v_mfma_f32_16x16x32_bf16 v[108:111], v[128:131], v[200:203], v[108:111]
	v_mfma_f32_16x16x32_bf16 v[108:111], v[146:149], v[204:207], v[108:111]
	v_mfma_f32_16x16x32_bf16 v[104:107], v[154:157], v[204:207], v[104:107]
	v_mfma_f32_16x16x32_bf16 v[104:107], v[150:153], v[200:203], v[104:107]
	v_mfma_f32_16x16x32_bf16 v[96:99], v[150:153], v[208:211], v[96:99]
	v_mfma_f32_16x16x32_bf16 v[96:99], v[154:157], v[212:215], v[96:99]
	v_mfma_f32_16x16x32_bf16 v[100:103], v[146:149], v[212:215], v[100:103]
	v_mfma_f32_16x16x32_bf16 v[100:103], v[128:131], v[208:211], v[100:103]
	s_setprio 0
	s_setprio 1
	v_mfma_f32_16x16x32_bf16 v[92:95], v[168:171], v[184:187], v[92:95]
	v_mfma_f32_16x16x32_bf16 v[92:95], v[172:175], v[188:191], v[92:95]
	v_mfma_f32_16x16x32_bf16 v[88:91], v[180:183], v[188:191], v[88:91]
	v_mfma_f32_16x16x32_bf16 v[88:91], v[176:179], v[184:187], v[88:91]
	v_mfma_f32_16x16x32_bf16 v[80:83], v[176:179], v[192:195], v[80:83]
	v_mfma_f32_16x16x32_bf16 v[80:83], v[180:183], v[196:199], v[80:83]
	v_mfma_f32_16x16x32_bf16 v[84:87], v[172:175], v[196:199], v[84:87]
	v_mfma_f32_16x16x32_bf16 v[84:87], v[168:171], v[192:195], v[84:87]
	v_mfma_f32_16x16x32_bf16 v[76:79], v[168:171], v[200:203], v[76:79]
	v_mfma_f32_16x16x32_bf16 v[76:79], v[172:175], v[204:207], v[76:79]
	v_mfma_f32_16x16x32_bf16 v[72:75], v[180:183], v[204:207], v[72:75]
	v_mfma_f32_16x16x32_bf16 v[72:75], v[176:179], v[200:203], v[72:75]
	v_mfma_f32_16x16x32_bf16 v[64:67], v[176:179], v[208:211], v[64:67]
	v_mfma_f32_16x16x32_bf16 v[64:67], v[180:183], v[212:215], v[64:67]
	v_mfma_f32_16x16x32_bf16 v[68:71], v[172:175], v[212:215], v[68:71]
	v_mfma_f32_16x16x32_bf16 v[68:71], v[168:171], v[208:211], v[68:71]
	s_setprio 0
	s_barrier
	s_add_i32 s6, s55, s29
	v_lshl_add_u64 v[216:217], s[0:1], 0, v[132:133]
	s_mov_b32 m0, s6
	ds_read_b128 v[184:187], v165 offset:16384
	ds_read_b128 v[188:191], v165 offset:17408
	ds_read_b128 v[192:195], v165 offset:18432
	ds_read_b128 v[196:199], v165 offset:19456
	ds_read_b128 v[200:203], v165 offset:20480
	ds_read_b128 v[204:207], v165 offset:21504
	ds_read_b128 v[208:211], v165 offset:22528
	ds_read_b128 v[212:215], v165 offset:23552
	global_load_lds_dwordx4 v[216:217], off
	s_add_i32 m0, s6, 0x2000
	s_add_u32 s6, s0, 0x80000
	v_lshl_add_u64 v[218:219], s[0:1], 0, v[134:135]
	s_addc_u32 s7, s1, 0
	s_add_i32 s19, s84, s29
	global_load_lds_dwordx4 v[218:219], off
	v_lshl_add_u64 v[220:221], s[6:7], 0, v[132:133]
	s_mov_b32 m0, s19
	v_lshl_add_u64 v[222:223], s[16:17], 0, v[140:141]
	global_load_lds_dwordx4 v[220:221], off
	v_lshl_add_u64 v[220:221], s[6:7], 0, v[134:135]
	s_add_i32 m0, s19, 0x2000
	s_nop 0
	global_load_lds_dwordx4 v[220:221], off
	v_lshl_add_u64 v[220:221], s[16:17], 0, v[136:137]
	s_mov_b32 m0, s15
	s_nop 0
	global_load_lds_dwordx4 v[220:221], off
	s_mov_b32 m0, s30
	s_nop 0
	global_load_lds_dwordx4 v[222:223], off
	s_waitcnt vmcnt(8)
	s_waitcnt lgkmcnt(0)
	s_barrier
; #define PG8_STAGE(bufoff, gbase, voff) do { _Pragma("unroll") for (int _i = 0; _i < 2; ++_i) \
;         __builtin_amdgcn_global_load_lds((const unsigned*)((const char*)(gbase) + (voff)[_i]), (PG8_LAS unsigned*)(lds + (bufoff) + ldsw + _i * 8192), 16, 0, 0); } while (0)
; #define PG8_LDA(dst, b, h) do { _Pragma("unroll") for (int m = 0; m < 4; ++m) _Pragma("unroll") for (int k = 0; k < 2; ++k) dst[m][k] = *(const PG8_LAS bf16x8*)(lds + PG8_SA(b, h) + aoff + m * 2048 + k * 1024); } while (0)
; #define PG8_LDB(dst, b, h) do { _Pragma("unroll") for (int n = 0; n < 2; ++n) _Pragma("unroll") for (int k = 0; k < 2; ++k) dst[n][k] = *(const PG8_LAS bf16x8*)(lds + PG8_SB(b, h) + boff + n * 2048 + k * 1024); } while (0)
; #define PG8_MMA(ai, bj, At, Bt) do { __builtin_amdgcn_s_setprio(1); _Pragma("unroll") for (int m = 0; m < 4; ++m) _Pragma("unroll") for (int n = 0; n < 2; ++n) _Pragma("unroll") for (int k = 0; k < 2; ++k) \
;         acc[ai][bj][m][n] = __builtin_amdgcn_mfma_f32_16x16x32_bf16(Bt[n][k], At[m][k], acc[ai][bj][m][n], 0, 0, 0); __builtin_amdgcn_s_setprio(0); } while (0)
; #define PG8_WAIT_V(n) asm volatile("s_waitcnt vmcnt(" #n ")" ::: "memory")
; #define PG8_WAIT_L(n) asm volatile("s_waitcnt lgkmcnt(" #n ")" ::: "memory")
; #define PG8_BAR __builtin_amdgcn_s_barrier()
; #define PG8_SCHED __builtin_amdgcn_sched_barrier(0)
; template <class Epi, class Sched, bool ALIGN_EPI = false, bool SP2 = false, bool APERM = false  >
; __device__ __forceinline__ void gemm_phase(PG8_LAS unsigned char* lds, const Gemm g, const Sched& S, const Epi& E, const int wid  ) {
;     ...
;             PG8_WAIT_V(8); PG8_WAIT_L(0); PG8_BAR; PG8_MMA(1, 0, At, B0); PG8_MMA(1, 1, At, B1); PG8_BAR; PG8_SCHED;
;             PG8_LDB(B0, 1, 0); PG8_LDB(B1, 1, 1); PG8_SCHED; PG8_LDA(At, 1, 0); PG8_STAGE(PG8_SA(0, 1), a2 + hstep, voffA);
;             PG8_WAIT_V(8); PG8_WAIT_L(0); PG8_BAR; PG8_MMA(0, 0, At, B0); PG8_MMA(0, 1, At, B1); PG8_BAR; PG8_SCHED;
	s_setprio 1
	s_waitcnt lgkmcnt(0)
	v_mfma_f32_16x16x32_bf16 v[60:63], v[128:131], v[184:187], v[60:63]
	v_mfma_f32_16x16x32_bf16 v[60:63], v[146:149], v[188:191], v[60:63]
	v_mfma_f32_16x16x32_bf16 v[56:59], v[154:157], v[188:191], v[56:59]
	v_mfma_f32_16x16x32_bf16 v[56:59], v[150:153], v[184:187], v[56:59]
	v_mfma_f32_16x16x32_bf16 v[48:51], v[150:153], v[192:195], v[48:51]
	v_mfma_f32_16x16x32_bf16 v[48:51], v[154:157], v[196:199], v[48:51]
	v_mfma_f32_16x16x32_bf16 v[52:55], v[146:149], v[196:199], v[52:55]
	v_mfma_f32_16x16x32_bf16 v[52:55], v[128:131], v[192:195], v[52:55]
	v_mfma_f32_16x16x32_bf16 v[44:47], v[128:131], v[200:203], v[44:47]
	v_mfma_f32_16x16x32_bf16 v[44:47], v[146:149], v[204:207], v[44:47]
	v_mfma_f32_16x16x32_bf16 v[40:43], v[154:157], v[204:207], v[40:43]
	v_mfma_f32_16x16x32_bf16 v[40:43], v[150:153], v[200:203], v[40:43]
	v_mfma_f32_16x16x32_bf16 v[32:35], v[150:153], v[208:211], v[32:35]
	v_mfma_f32_16x16x32_bf16 v[32:35], v[154:157], v[212:215], v[32:35]
	v_mfma_f32_16x16x32_bf16 v[36:39], v[146:149], v[212:215], v[36:39]
	v_mfma_f32_16x16x32_bf16 v[36:39], v[128:131], v[208:211], v[36:39]
	s_setprio 0
	s_setprio 1
	v_mfma_f32_16x16x32_bf16 v[28:31], v[168:171], v[184:187], v[28:31]
	v_mfma_f32_16x16x32_bf16 v[28:31], v[172:175], v[188:191], v[28:31]
	v_mfma_f32_16x16x32_bf16 v[24:27], v[180:183], v[188:191], v[24:27]
	v_mfma_f32_16x16x32_bf16 v[24:27], v[176:179], v[184:187], v[24:27]
	v_mfma_f32_16x16x32_bf16 v[16:19], v[176:179], v[192:195], v[16:19]
	v_mfma_f32_16x16x32_bf16 v[16:19], v[180:183], v[196:199], v[16:19]
	v_mfma_f32_16x16x32_bf16 v[20:23], v[172:175], v[196:199], v[20:23]
	v_mfma_f32_16x16x32_bf16 v[20:23], v[168:171], v[192:195], v[20:23]
	v_mfma_f32_16x16x32_bf16 v[12:15], v[168:171], v[200:203], v[12:15]
	v_mfma_f32_16x16x32_bf16 v[12:15], v[172:175], v[204:207], v[12:15]
	v_mfma_f32_16x16x32_bf16 v[8:11], v[180:183], v[204:207], v[8:11]
	v_mfma_f32_16x16x32_bf16 v[8:11], v[176:179], v[200:203], v[8:11]
	v_mfma_f32_16x16x32_bf16 v[0:3], v[176:179], v[208:211], v[0:3]
	v_mfma_f32_16x16x32_bf16 v[0:3], v[180:183], v[212:215], v[0:3]
	v_mfma_f32_16x16x32_bf16 v[4:7], v[172:175], v[212:215], v[4:7]
	v_mfma_f32_16x16x32_bf16 v[4:7], v[168:171], v[208:211], v[4:7]
	s_setprio 0
	s_barrier
	s_add_i32 s19, 0, 0x18000
	v_add_u32_e32 v138, s19, v160
	s_add_i32 s24, 0, 0x1c000
	ds_read_b128 v[128:131], v138
	ds_read_b128 v[146:149], v138 offset:1024
	ds_read_b128 v[150:153], v138 offset:2048
	ds_read_b128 v[154:157], v138 offset:3072
	v_add_u32_e32 v138, s24, v160
	ds_read_b128 v[168:171], v138
	ds_read_b128 v[172:175], v138 offset:1024
	ds_read_b128 v[176:179], v138 offset:2048
	ds_read_b128 v[180:183], v138 offset:3072
	s_add_u32 s6, s16, 0x80000
	s_addc_u32 s7, s17, 0
	s_mov_b32 m0, s31
	v_lshl_add_u64 v[224:225], s[6:7], 0, v[136:137]
	ds_read_b128 v[184:187], v165 offset:32768
	ds_read_b128 v[188:191], v165 offset:33792
	ds_read_b128 v[192:195], v165 offset:34816
	ds_read_b128 v[196:199], v165 offset:35840
	ds_read_b128 v[200:203], v165 offset:36864
	ds_read_b128 v[204:207], v165 offset:37888
	ds_read_b128 v[208:211], v165 offset:38912
	ds_read_b128 v[212:215], v165 offset:39936
	global_load_lds_dwordx4 v[224:225], off
	v_lshl_add_u64 v[224:225], s[6:7], 0, v[140:141]
	s_mov_b32 m0, s34
	s_nop 0
	global_load_lds_dwordx4 v[224:225], off
	s_waitcnt vmcnt(8)
	s_waitcnt lgkmcnt(0)
	s_barrier
	s_setprio 1
	s_waitcnt lgkmcnt(0)
	v_mfma_f32_16x16x32_bf16 v[124:127], v[128:131], v[184:187], v[124:127]
	v_mfma_f32_16x16x32_bf16 v[124:127], v[146:149], v[188:191], v[124:127]
	v_mfma_f32_16x16x32_bf16 v[120:123], v[154:157], v[188:191], v[120:123]
	v_mfma_f32_16x16x32_bf16 v[120:123], v[150:153], v[184:187], v[120:123]
	v_mfma_f32_16x16x32_bf16 v[112:115], v[150:153], v[192:195], v[112:115]
	v_mfma_f32_16x16x32_bf16 v[112:115], v[154:157], v[196:199], v[112:115]
	v_mfma_f32_16x16x32_bf16 v[116:119], v[146:149], v[196:199], v[116:119]
	v_mfma_f32_16x16x32_bf16 v[116:119], v[128:131], v[192:195], v[116:119]
	v_mfma_f32_16x16x32_bf16 v[108:111], v[128:131], v[200:203], v[108:111]
	v_mfma_f32_16x16x32_bf16 v[108:111], v[146:149], v[204:207], v[108:111]
	v_mfma_f32_16x16x32_bf16 v[104:107], v[154:157], v[204:207], v[104:107]
	v_mfma_f32_16x16x32_bf16 v[104:107], v[150:153], v[200:203], v[104:107]
	v_mfma_f32_16x16x32_bf16 v[96:99], v[150:153], v[208:211], v[96:99]
	v_mfma_f32_16x16x32_bf16 v[96:99], v[154:157], v[212:215], v[96:99]
	v_mfma_f32_16x16x32_bf16 v[100:103], v[146:149], v[212:215], v[100:103]
	v_mfma_f32_16x16x32_bf16 v[100:103], v[128:131], v[208:211], v[100:103]
	s_setprio 0
	s_setprio 1
	v_mfma_f32_16x16x32_bf16 v[92:95], v[168:171], v[184:187], v[92:95]
	v_mfma_f32_16x16x32_bf16 v[92:95], v[172:175], v[188:191], v[92:95]
	v_mfma_f32_16x16x32_bf16 v[88:91], v[180:183], v[188:191], v[88:91]
	v_mfma_f32_16x16x32_bf16 v[88:91], v[176:179], v[184:187], v[88:91]
	v_mfma_f32_16x16x32_bf16 v[80:83], v[176:179], v[192:195], v[80:83]
	v_mfma_f32_16x16x32_bf16 v[80:83], v[180:183], v[196:199], v[80:83]
	v_mfma_f32_16x16x32_bf16 v[84:87], v[172:175], v[196:199], v[84:87]
	v_mfma_f32_16x16x32_bf16 v[84:87], v[168:171], v[192:195], v[84:87]
	v_mfma_f32_16x16x32_bf16 v[76:79], v[168:171], v[200:203], v[76:79]
	v_mfma_f32_16x16x32_bf16 v[76:79], v[172:175], v[204:207], v[76:79]
	v_mfma_f32_16x16x32_bf16 v[72:75], v[180:183], v[204:207], v[72:75]
	v_mfma_f32_16x16x32_bf16 v[72:75], v[176:179], v[200:203], v[72:75]
	v_mfma_f32_16x16x32_bf16 v[64:67], v[176:179], v[208:211], v[64:67]
	v_mfma_f32_16x16x32_bf16 v[64:67], v[180:183], v[212:215], v[64:67]
	v_mfma_f32_16x16x32_bf16 v[68:71], v[172:175], v[212:215], v[68:71]
	v_mfma_f32_16x16x32_bf16 v[68:71], v[168:171], v[208:211], v[68:71]
	s_setprio 0
	s_barrier
; #define PG8_STAGE(bufoff, gbase, voff) do { _Pragma("unroll") for (int _i = 0; _i < 2; ++_i) \
;         __builtin_amdgcn_global_load_lds((const unsigned*)((const char*)(gbase) + (voff)[_i]), (PG8_LAS unsigned*)(lds + (bufoff) + ldsw + _i * 8192), 16, 0, 0); } while (0)
; #define PG8_LDA(dst, b, h) do { _Pragma("unroll") for (int m = 0; m < 4; ++m) _Pragma("unroll") for (int k = 0; k < 2; ++k) dst[m][k] = *(const PG8_LAS bf16x8*)(lds + PG8_SA(b, h) + aoff + m * 2048 + k * 1024); } while (0)
; #define PG8_MMA(ai, bj, At, Bt) do { __builtin_amdgcn_s_setprio(1); _Pragma("unroll") for (int m = 0; m < 4; ++m) _Pragma("unroll") for (int n = 0; n < 2; ++n) _Pragma("unroll") for (int k = 0; k < 2; ++k) \
;         acc[ai][bj][m][n] = __builtin_amdgcn_mfma_f32_16x16x32_bf16(Bt[n][k], At[m][k], acc[ai][bj][m][n], 0, 0, 0); __builtin_amdgcn_s_setprio(0); } while (0)
; #define PG8_WAIT_V(n) asm volatile("s_waitcnt vmcnt(" #n ")" ::: "memory")
; #define PG8_WAIT_L(n) asm volatile("s_waitcnt lgkmcnt(" #n ")" ::: "memory")
; #define PG8_BAR __builtin_amdgcn_s_barrier()
; #define PG8_SCHED __builtin_amdgcn_sched_barrier(0)
; template <class Epi, class Sched, bool ALIGN_EPI = false, bool SP2 = false, bool APERM = false  >
; __device__ __forceinline__ void gemm_phase(PG8_LAS unsigned char* lds, const Gemm g, const Sched& S, const Epi& E, const int wid  ) {
;     ...
;             PG8_LDA(At, 1, 1); PG8_STAGE(PG8_SB(1, 0), b3, voffB); PG8_STAGE(PG8_SB(1, 1), b3 + hstep, voffB); PG8_STAGE(PG8_SA(1, 0), a3, voffA);
;             PG8_WAIT_V(8); PG8_WAIT_L(0); PG8_BAR; PG8_MMA(1, 0, At, B0); PG8_MMA(1, 1, At, B1); PG8_BAR; PG8_SCHED;
	s_add_i32 s6, s19, s29
	v_lshl_add_u64 v[216:217], v[216:217], 0, s[70:71]
	s_mov_b32 m0, s6
	ds_read_b128 v[184:187], v165 offset:49152
	ds_read_b128 v[188:191], v165 offset:50176
	ds_read_b128 v[192:195], v165 offset:51200
	ds_read_b128 v[196:199], v165 offset:52224
	ds_read_b128 v[200:203], v165 offset:53248
	ds_read_b128 v[204:207], v165 offset:54272
	ds_read_b128 v[208:211], v165 offset:55296
	ds_read_b128 v[212:215], v165 offset:56320
	global_load_lds_dwordx4 v[216:217], off
	s_add_i32 m0, s6, 0x2000
	s_add_u32 s0, s0, 0x80080
	v_lshl_add_u64 v[216:217], v[218:219], 0, s[70:71]
	s_addc_u32 s1, s1, 0
	s_add_i32 s6, s24, s29
	global_load_lds_dwordx4 v[216:217], off
	v_lshl_add_u64 v[216:217], s[0:1], 0, v[132:133]
	s_mov_b32 m0, s6
	s_nop 0
	global_load_lds_dwordx4 v[216:217], off
	v_lshl_add_u64 v[216:217], s[0:1], 0, v[134:135]
	s_add_i32 m0, s6, 0x2000
	s_nop 0
	global_load_lds_dwordx4 v[216:217], off
	v_lshl_add_u64 v[216:217], v[220:221], 0, s[70:71]
	s_mov_b32 m0, s35
	s_nop 0
	global_load_lds_dwordx4 v[216:217], off
	v_lshl_add_u64 v[216:217], v[222:223], 0, s[70:71]
	s_mov_b32 m0, s47
	s_nop 0
	global_load_lds_dwordx4 v[216:217], off
	s_waitcnt vmcnt(8)
	s_waitcnt lgkmcnt(0)
	s_barrier
	s_setprio 1
	s_waitcnt lgkmcnt(0)
	v_mfma_f32_16x16x32_bf16 v[60:63], v[128:131], v[184:187], v[60:63]
	v_mfma_f32_16x16x32_bf16 v[60:63], v[146:149], v[188:191], v[60:63]
	v_mfma_f32_16x16x32_bf16 v[56:59], v[154:157], v[188:191], v[56:59]
	v_mfma_f32_16x16x32_bf16 v[56:59], v[150:153], v[184:187], v[56:59]
	v_mfma_f32_16x16x32_bf16 v[48:51], v[150:153], v[192:195], v[48:51]
	v_mfma_f32_16x16x32_bf16 v[48:51], v[154:157], v[196:199], v[48:51]
	v_mfma_f32_16x16x32_bf16 v[52:55], v[146:149], v[196:199], v[52:55]
	v_mfma_f32_16x16x32_bf16 v[52:55], v[128:131], v[192:195], v[52:55]
	v_mfma_f32_16x16x32_bf16 v[44:47], v[128:131], v[200:203], v[44:47]
	v_mfma_f32_16x16x32_bf16 v[44:47], v[146:149], v[204:207], v[44:47]
	v_mfma_f32_16x16x32_bf16 v[40:43], v[154:157], v[204:207], v[40:43]
	v_mfma_f32_16x16x32_bf16 v[40:43], v[150:153], v[200:203], v[40:43]
	v_mfma_f32_16x16x32_bf16 v[32:35], v[150:153], v[208:211], v[32:35]
	v_mfma_f32_16x16x32_bf16 v[32:35], v[154:157], v[212:215], v[32:35]
	v_mfma_f32_16x16x32_bf16 v[36:39], v[146:149], v[212:215], v[36:39]
	v_mfma_f32_16x16x32_bf16 v[36:39], v[128:131], v[208:211], v[36:39]
	s_setprio 0
	s_setprio 1
	v_mfma_f32_16x16x32_bf16 v[28:31], v[168:171], v[184:187], v[28:31]
	v_mfma_f32_16x16x32_bf16 v[28:31], v[172:175], v[188:191], v[28:31]
	v_mfma_f32_16x16x32_bf16 v[24:27], v[180:183], v[188:191], v[24:27]
	v_mfma_f32_16x16x32_bf16 v[24:27], v[176:179], v[184:187], v[24:27]
	v_mfma_f32_16x16x32_bf16 v[16:19], v[176:179], v[192:195], v[16:19]
	v_mfma_f32_16x16x32_bf16 v[16:19], v[180:183], v[196:199], v[16:19]
	v_mfma_f32_16x16x32_bf16 v[20:23], v[172:175], v[196:199], v[20:23]
	v_mfma_f32_16x16x32_bf16 v[20:23], v[168:171], v[192:195], v[20:23]
	v_mfma_f32_16x16x32_bf16 v[12:15], v[168:171], v[200:203], v[12:15]
	v_mfma_f32_16x16x32_bf16 v[12:15], v[172:175], v[204:207], v[12:15]
	v_mfma_f32_16x16x32_bf16 v[8:11], v[180:183], v[204:207], v[8:11]
	v_mfma_f32_16x16x32_bf16 v[8:11], v[176:179], v[200:203], v[8:11]
	v_mfma_f32_16x16x32_bf16 v[0:3], v[176:179], v[208:211], v[0:3]
	v_mfma_f32_16x16x32_bf16 v[0:3], v[180:183], v[212:215], v[0:3]
	v_mfma_f32_16x16x32_bf16 v[4:7], v[172:175], v[212:215], v[4:7]
	v_mfma_f32_16x16x32_bf16 v[4:7], v[168:171], v[208:211], v[4:7]
	s_setprio 0
	s_barrier
	s_add_i32 s0, s74, 2
	s_cmp_gt_u32 s74, 29
	s_cbranch_scc1 .LBB0_795
	s_mov_b32 s74, s0
	s_branch .LBB0_771

; #define PG8_STAGE(bufoff, gbase, voff) do { _Pragma("unroll") for (int _i = 0; _i < 2; ++_i) \
;         __builtin_amdgcn_global_load_lds((const unsigned*)((const char*)(gbase) + (voff)[_i]), (PG8_LAS unsigned*)(lds + (bufoff) + ldsw + _i * 8192), 16, 0, 0); } while (0)
; #define PG8_LDA(dst, b, h) do { _Pragma("unroll") for (int m = 0; m < 4; ++m) _Pragma("unroll") for (int k = 0; k < 2; ++k) dst[m][k] = *(const PG8_LAS bf16x8*)(lds + PG8_SA(b, h) + aoff + m * 2048 + k * 1024); } while (0)
; #define PG8_LDB(dst, b, h) do { _Pragma("unroll") for (int n = 0; n < 2; ++n) _Pragma("unroll") for (int k = 0; k < 2; ++k) dst[n][k] = *(const PG8_LAS bf16x8*)(lds + PG8_SB(b, h) + boff + n * 2048 + k * 1024); } while (0)
; #define PG8_MMA(ai, bj, At, Bt) do { __builtin_amdgcn_s_setprio(1); _Pragma("unroll") for (int m = 0; m < 4; ++m) _Pragma("unroll") for (int n = 0; n < 2; ++n) _Pragma("unroll") for (int k = 0; k < 2; ++k) \
;         acc[ai][bj][m][n] = __builtin_amdgcn_mfma_f32_16x16x32_bf16(Bt[n][k], At[m][k], acc[ai][bj][m][n], 0, 0, 0); __builtin_amdgcn_s_setprio(0); } while (0)
; #define PG8_WAIT_V(n) asm volatile("s_waitcnt vmcnt(" #n ")" ::: "memory")
; #define PG8_WAIT_L(n) asm volatile("s_waitcnt lgkmcnt(" #n ")" ::: "memory")
; template <class Epi, class Sched, bool ALIGN_EPI = false, bool SP2 = false, bool APERM = false  >
; __device__ __forceinline__ void gemm_phase(PG8_LAS unsigned char* lds, const Gemm g, const Sched& S, const Epi& E, const int wid  ) {
;     ...
;             const bool last = (t == nt - 2);
;             const char* a1 = cA + (size_t)(t + 1) * kstep;
;             const char* a2 = last ? nA : cA + (size_t)(t + 2) * kstep; const char* b2 = last ? nB : cB + (size_t)(t + 2) * kstep;
;             const char* a3 = a2 + kstep; const char* b3 = b2 + kstep;
;             if (last && has_next) S.a_ready(nxt);
;             if constexpr (SP2) {
;             PG8_LDB(B0, 0, 0); PG8_LDB(B1, 0, 1); PG8_SCHED; PG8_LDA(At, 0, 0); PG8_STAGE(PG8_SA(1, 1), a1 + hstep, voffA);
;             PG8_WAIT_V(8); PG8_WAIT_L(0); PG8_BAR; PG8_MMA(0, 0, At, B0); PG8_MMA(0, 1, At, B1); PG8_BAR; PG8_SCHED;
;             PG8_LDA(At, 0, 1); PG8_STAGE(PG8_SB(0, 0), b2, voffB); PG8_STAGE(PG8_SB(0, 1), b2 + hstep, voffB); PG8_STAGE(PG8_SA(0, 0), a2, voffA);
;             PG8_WAIT_V(8); PG8_WAIT_L(0); PG8_BAR; PG8_MMA(1, 0, At, B0); PG8_MMA(1, 1, At, B1); PG8_BAR; PG8_SCHED;
.LBB0_1019:
	v_add_u32_e32 v157, s92, v151
	ds_read_b128 v[146:149], v157
	ds_read_b128 v[158:161], v157 offset:1024
	ds_read_b128 v[162:165], v157 offset:2048
	ds_read_b128 v[166:169], v157 offset:3072
	v_add_u32_e32 v157, s93, v151
	s_add_u32 s65, s34, s78
	ds_read_b128 v[170:173], v157
	ds_read_b128 v[174:177], v157 offset:1024
	ds_read_b128 v[178:181], v157 offset:2048
	ds_read_b128 v[182:185], v157 offset:3072
	s_addc_u32 s73, s35, s79
	s_add_u32 s65, s65, 0x100
	s_addc_u32 s73, s73, 0
	s_add_u32 s80, s96, s78
	s_addc_u32 s81, s97, s79
	s_cmpk_eq_i32 s78, 0xf00
	s_cselect_b32 s83, s29, s73
	s_cselect_b32 s82, s33, s65
	s_cselect_b32 s81, s46, s81
	s_cselect_b32 s80, s47, s80
	v_lshl_add_u64 v[218:219], v[142:143], 0, s[78:79]
	s_add_i32 m0, s7, 0xc000
	ds_read_b128 v[186:189], v156
	ds_read_b128 v[190:193], v156 offset:1024
	ds_read_b128 v[194:197], v156 offset:2048
	ds_read_b128 v[198:201], v156 offset:3072
	ds_read_b128 v[202:205], v156 offset:4096
	ds_read_b128 v[206:209], v156 offset:5120
	ds_read_b128 v[210:213], v156 offset:6144
	ds_read_b128 v[214:217], v156 offset:7168
	global_load_lds_dwordx4 v[218:219], off
	v_lshl_add_u64 v[218:219], v[144:145], 0, s[78:79]
	s_add_i32 m0, s7, 0xe000
	s_nop 0
	global_load_lds_dwordx4 v[218:219], off
	s_waitcnt vmcnt(8)
	s_waitcnt lgkmcnt(0)
	s_barrier
	s_setprio 1
	s_waitcnt lgkmcnt(0)
	v_mfma_f32_16x16x32_bf16 v[124:127], v[146:149], v[186:189], v[124:127]
	v_mfma_f32_16x16x32_bf16 v[124:127], v[158:161], v[190:193], v[124:127]
	v_mfma_f32_16x16x32_bf16 v[120:123], v[166:169], v[190:193], v[120:123]
	v_mfma_f32_16x16x32_bf16 v[120:123], v[162:165], v[186:189], v[120:123]
	v_mfma_f32_16x16x32_bf16 v[112:115], v[162:165], v[194:197], v[112:115]
	v_mfma_f32_16x16x32_bf16 v[112:115], v[166:169], v[198:201], v[112:115]
	v_mfma_f32_16x16x32_bf16 v[116:119], v[158:161], v[198:201], v[116:119]
	v_mfma_f32_16x16x32_bf16 v[116:119], v[146:149], v[194:197], v[116:119]
	v_mfma_f32_16x16x32_bf16 v[108:111], v[146:149], v[202:205], v[108:111]
	v_mfma_f32_16x16x32_bf16 v[108:111], v[158:161], v[206:209], v[108:111]
	v_mfma_f32_16x16x32_bf16 v[104:107], v[166:169], v[206:209], v[104:107]
	v_mfma_f32_16x16x32_bf16 v[104:107], v[162:165], v[202:205], v[104:107]
	v_mfma_f32_16x16x32_bf16 v[96:99], v[162:165], v[210:213], v[96:99]
	v_mfma_f32_16x16x32_bf16 v[96:99], v[166:169], v[214:217], v[96:99]
	v_mfma_f32_16x16x32_bf16 v[100:103], v[158:161], v[214:217], v[100:103]
	v_mfma_f32_16x16x32_bf16 v[100:103], v[146:149], v[210:213], v[100:103]
	s_setprio 0
	s_setprio 1
	v_mfma_f32_16x16x32_bf16 v[92:95], v[170:173], v[186:189], v[92:95]
	v_mfma_f32_16x16x32_bf16 v[92:95], v[174:177], v[190:193], v[92:95]
	v_mfma_f32_16x16x32_bf16 v[88:91], v[182:185], v[190:193], v[88:91]
	v_mfma_f32_16x16x32_bf16 v[88:91], v[178:181], v[186:189], v[88:91]
	v_mfma_f32_16x16x32_bf16 v[80:83], v[178:181], v[194:197], v[80:83]
	v_mfma_f32_16x16x32_bf16 v[80:83], v[182:185], v[198:201], v[80:83]
	v_mfma_f32_16x16x32_bf16 v[84:87], v[174:177], v[198:201], v[84:87]
	v_mfma_f32_16x16x32_bf16 v[84:87], v[170:173], v[194:197], v[84:87]
	v_mfma_f32_16x16x32_bf16 v[76:79], v[170:173], v[202:205], v[76:79]
	v_mfma_f32_16x16x32_bf16 v[76:79], v[174:177], v[206:209], v[76:79]
	v_mfma_f32_16x16x32_bf16 v[72:75], v[182:185], v[206:209], v[72:75]
	v_mfma_f32_16x16x32_bf16 v[72:75], v[178:181], v[202:205], v[72:75]
	v_mfma_f32_16x16x32_bf16 v[64:67], v[178:181], v[210:213], v[64:67]
	v_mfma_f32_16x16x32_bf16 v[64:67], v[182:185], v[214:217], v[64:67]
	v_mfma_f32_16x16x32_bf16 v[68:71], v[174:177], v[214:217], v[68:71]
	v_mfma_f32_16x16x32_bf16 v[68:71], v[170:173], v[210:213], v[68:71]
	s_setprio 0
	s_barrier
	s_add_i32 s65, s92, s85
	v_lshl_add_u64 v[218:219], s[80:81], 0, v[130:131]
	s_mov_b32 m0, s65
	ds_read_b128 v[186:189], v156 offset:16384
	ds_read_b128 v[190:193], v156 offset:17408
	ds_read_b128 v[194:197], v156 offset:18432
	ds_read_b128 v[198:201], v156 offset:19456
	ds_read_b128 v[202:205], v156 offset:20480
	ds_read_b128 v[206:209], v156 offset:21504
	ds_read_b128 v[210:213], v156 offset:22528
	ds_read_b128 v[214:217], v156 offset:23552
	global_load_lds_dwordx4 v[218:219], off
	s_add_i32 m0, s65, 0x2000
	s_add_u32 vcc_lo, s80, 0x80000
	v_lshl_add_u64 v[220:221], s[80:81], 0, v[134:135]
	s_addc_u32 vcc_hi, s81, 0
	s_add_i32 s65, s93, s85
	global_load_lds_dwordx4 v[220:221], off
	v_lshl_add_u64 v[222:223], vcc, 0, v[130:131]
	s_mov_b32 m0, s65
	v_lshl_add_u64 v[224:225], s[82:83], 0, v[132:133]
	global_load_lds_dwordx4 v[222:223], off
	v_lshl_add_u64 v[222:223], vcc, 0, v[134:135]
	s_add_i32 m0, s65, 0x2000
	s_nop 0
	global_load_lds_dwordx4 v[222:223], off
	v_lshl_add_u64 v[222:223], s[82:83], 0, v[128:129]
	s_mov_b32 m0, s7
	s_nop 0
	global_load_lds_dwordx4 v[222:223], off
	s_mov_b32 m0, s9
	s_nop 0
	global_load_lds_dwordx4 v[224:225], off
	s_waitcnt vmcnt(8)
	s_waitcnt lgkmcnt(0)
	s_barrier
; #define PG8_STAGE(bufoff, gbase, voff) do { _Pragma("unroll") for (int _i = 0; _i < 2; ++_i) \
;         __builtin_amdgcn_global_load_lds((const unsigned*)((const char*)(gbase) + (voff)[_i]), (PG8_LAS unsigned*)(lds + (bufoff) + ldsw + _i * 8192), 16, 0, 0); } while (0)
; #define PG8_LDA(dst, b, h) do { _Pragma("unroll") for (int m = 0; m < 4; ++m) _Pragma("unroll") for (int k = 0; k < 2; ++k) dst[m][k] = *(const PG8_LAS bf16x8*)(lds + PG8_SA(b, h) + aoff + m * 2048 + k * 1024); } while (0)
; #define PG8_LDB(dst, b, h) do { _Pragma("unroll") for (int n = 0; n < 2; ++n) _Pragma("unroll") for (int k = 0; k < 2; ++k) dst[n][k] = *(const PG8_LAS bf16x8*)(lds + PG8_SB(b, h) + boff + n * 2048 + k * 1024); } while (0)
; #define PG8_MMA(ai, bj, At, Bt) do { __builtin_amdgcn_s_setprio(1); _Pragma("unroll") for (int m = 0; m < 4; ++m) _Pragma("unroll") for (int n = 0; n < 2; ++n) _Pragma("unroll") for (int k = 0; k < 2; ++k) \
;         acc[ai][bj][m][n] = __builtin_amdgcn_mfma_f32_16x16x32_bf16(Bt[n][k], At[m][k], acc[ai][bj][m][n], 0, 0, 0); __builtin_amdgcn_s_setprio(0); } while (0)
; #define PG8_WAIT_V(n) asm volatile("s_waitcnt vmcnt(" #n ")" ::: "memory")
; #define PG8_WAIT_L(n) asm volatile("s_waitcnt lgkmcnt(" #n ")" ::: "memory")
; #define PG8_BAR __builtin_amdgcn_s_barrier()
; #define PG8_SCHED __builtin_amdgcn_sched_barrier(0)
; template <class Epi, class Sched, bool ALIGN_EPI = false, bool SP2 = false, bool APERM = false  >
; __device__ __forceinline__ void gemm_phase(PG8_LAS unsigned char* lds, const Gemm g, const Sched& S, const Epi& E, const int wid  ) {
;     ...
;             PG8_WAIT_V(8); PG8_WAIT_L(0); PG8_BAR; PG8_MMA(1, 0, At, B0); PG8_MMA(1, 1, At, B1); PG8_BAR; PG8_SCHED;
;             PG8_LDB(B0, 1, 0); PG8_LDB(B1, 1, 1); PG8_SCHED; PG8_LDA(At, 1, 0); PG8_STAGE(PG8_SA(0, 1), a2 + hstep, voffA);
;             PG8_WAIT_V(8); PG8_WAIT_L(0); PG8_BAR; PG8_MMA(0, 0, At, B0); PG8_MMA(0, 1, At, B1); PG8_BAR; PG8_SCHED;
	s_setprio 1
	s_waitcnt lgkmcnt(0)
	v_mfma_f32_16x16x32_bf16 v[60:63], v[146:149], v[186:189], v[60:63]
	v_mfma_f32_16x16x32_bf16 v[60:63], v[158:161], v[190:193], v[60:63]
	v_mfma_f32_16x16x32_bf16 v[56:59], v[166:169], v[190:193], v[56:59]
	v_mfma_f32_16x16x32_bf16 v[56:59], v[162:165], v[186:189], v[56:59]
	v_mfma_f32_16x16x32_bf16 v[48:51], v[162:165], v[194:197], v[48:51]
	v_mfma_f32_16x16x32_bf16 v[48:51], v[166:169], v[198:201], v[48:51]
	v_mfma_f32_16x16x32_bf16 v[52:55], v[158:161], v[198:201], v[52:55]
	v_mfma_f32_16x16x32_bf16 v[52:55], v[146:149], v[194:197], v[52:55]
	v_mfma_f32_16x16x32_bf16 v[44:47], v[146:149], v[202:205], v[44:47]
	v_mfma_f32_16x16x32_bf16 v[44:47], v[158:161], v[206:209], v[44:47]
	v_mfma_f32_16x16x32_bf16 v[40:43], v[166:169], v[206:209], v[40:43]
	v_mfma_f32_16x16x32_bf16 v[40:43], v[162:165], v[202:205], v[40:43]
	v_mfma_f32_16x16x32_bf16 v[32:35], v[162:165], v[210:213], v[32:35]
	v_mfma_f32_16x16x32_bf16 v[32:35], v[166:169], v[214:217], v[32:35]
	v_mfma_f32_16x16x32_bf16 v[36:39], v[158:161], v[214:217], v[36:39]
	v_mfma_f32_16x16x32_bf16 v[36:39], v[146:149], v[210:213], v[36:39]
	s_setprio 0
	s_setprio 1
	v_mfma_f32_16x16x32_bf16 v[28:31], v[170:173], v[186:189], v[28:31]
	v_mfma_f32_16x16x32_bf16 v[28:31], v[174:177], v[190:193], v[28:31]
	v_mfma_f32_16x16x32_bf16 v[24:27], v[182:185], v[190:193], v[24:27]
	v_mfma_f32_16x16x32_bf16 v[24:27], v[178:181], v[186:189], v[24:27]
	v_mfma_f32_16x16x32_bf16 v[16:19], v[178:181], v[194:197], v[16:19]
	v_mfma_f32_16x16x32_bf16 v[16:19], v[182:185], v[198:201], v[16:19]
	v_mfma_f32_16x16x32_bf16 v[20:23], v[174:177], v[198:201], v[20:23]
	v_mfma_f32_16x16x32_bf16 v[20:23], v[170:173], v[194:197], v[20:23]
	v_mfma_f32_16x16x32_bf16 v[12:15], v[170:173], v[202:205], v[12:15]
	v_mfma_f32_16x16x32_bf16 v[12:15], v[174:177], v[206:209], v[12:15]
	v_mfma_f32_16x16x32_bf16 v[8:11], v[182:185], v[206:209], v[8:11]
	v_mfma_f32_16x16x32_bf16 v[8:11], v[178:181], v[202:205], v[8:11]
	v_mfma_f32_16x16x32_bf16 v[0:3], v[178:181], v[210:213], v[0:3]
	v_mfma_f32_16x16x32_bf16 v[0:3], v[182:185], v[214:217], v[0:3]
	v_mfma_f32_16x16x32_bf16 v[4:7], v[174:177], v[214:217], v[4:7]
	v_mfma_f32_16x16x32_bf16 v[4:7], v[170:173], v[210:213], v[4:7]
	s_setprio 0
	s_barrier
	s_add_i32 s65, 0, 0x18000
	v_add_u32_e32 v157, s65, v151
	s_add_i32 s73, 0, 0x1c000
	ds_read_b128 v[146:149], v157
	ds_read_b128 v[158:161], v157 offset:1024
	ds_read_b128 v[162:165], v157 offset:2048
	ds_read_b128 v[166:169], v157 offset:3072
	v_add_u32_e32 v157, s73, v151
	ds_read_b128 v[170:173], v157
	ds_read_b128 v[174:177], v157 offset:1024
	ds_read_b128 v[178:181], v157 offset:2048
	ds_read_b128 v[182:185], v157 offset:3072
	s_add_u32 s82, s82, 0x80000
	s_addc_u32 s83, s83, 0
	s_mov_b32 m0, s86
	v_lshl_add_u64 v[226:227], s[82:83], 0, v[128:129]
	ds_read_b128 v[186:189], v156 offset:32768
	ds_read_b128 v[190:193], v156 offset:33792
	ds_read_b128 v[194:197], v156 offset:34816
	ds_read_b128 v[198:201], v156 offset:35840
	ds_read_b128 v[202:205], v156 offset:36864
	ds_read_b128 v[206:209], v156 offset:37888
	ds_read_b128 v[210:213], v156 offset:38912
	ds_read_b128 v[214:217], v156 offset:39936
	global_load_lds_dwordx4 v[226:227], off
	v_lshl_add_u64 v[226:227], s[82:83], 0, v[132:133]
	s_mov_b32 m0, s87
	s_nop 0
	global_load_lds_dwordx4 v[226:227], off
	s_waitcnt vmcnt(8)
	s_waitcnt lgkmcnt(0)
	s_barrier
	s_setprio 1
	s_waitcnt lgkmcnt(0)
	v_mfma_f32_16x16x32_bf16 v[124:127], v[146:149], v[186:189], v[124:127]
	v_mfma_f32_16x16x32_bf16 v[124:127], v[158:161], v[190:193], v[124:127]
	v_mfma_f32_16x16x32_bf16 v[120:123], v[166:169], v[190:193], v[120:123]
	v_mfma_f32_16x16x32_bf16 v[120:123], v[162:165], v[186:189], v[120:123]
	v_mfma_f32_16x16x32_bf16 v[112:115], v[162:165], v[194:197], v[112:115]
	v_mfma_f32_16x16x32_bf16 v[112:115], v[166:169], v[198:201], v[112:115]
	v_mfma_f32_16x16x32_bf16 v[116:119], v[158:161], v[198:201], v[116:119]
	v_mfma_f32_16x16x32_bf16 v[116:119], v[146:149], v[194:197], v[116:119]
	v_mfma_f32_16x16x32_bf16 v[108:111], v[146:149], v[202:205], v[108:111]
	v_mfma_f32_16x16x32_bf16 v[108:111], v[158:161], v[206:209], v[108:111]
	v_mfma_f32_16x16x32_bf16 v[104:107], v[166:169], v[206:209], v[104:107]
	v_mfma_f32_16x16x32_bf16 v[104:107], v[162:165], v[202:205], v[104:107]
	v_mfma_f32_16x16x32_bf16 v[96:99], v[162:165], v[210:213], v[96:99]
	v_mfma_f32_16x16x32_bf16 v[96:99], v[166:169], v[214:217], v[96:99]
	v_mfma_f32_16x16x32_bf16 v[100:103], v[158:161], v[214:217], v[100:103]
	v_mfma_f32_16x16x32_bf16 v[100:103], v[146:149], v[210:213], v[100:103]
	s_setprio 0
	s_setprio 1
	v_mfma_f32_16x16x32_bf16 v[92:95], v[170:173], v[186:189], v[92:95]
	v_mfma_f32_16x16x32_bf16 v[92:95], v[174:177], v[190:193], v[92:95]
	v_mfma_f32_16x16x32_bf16 v[88:91], v[182:185], v[190:193], v[88:91]
	v_mfma_f32_16x16x32_bf16 v[88:91], v[178:181], v[186:189], v[88:91]
	v_mfma_f32_16x16x32_bf16 v[80:83], v[178:181], v[194:197], v[80:83]
	v_mfma_f32_16x16x32_bf16 v[80:83], v[182:185], v[198:201], v[80:83]
	v_mfma_f32_16x16x32_bf16 v[84:87], v[174:177], v[198:201], v[84:87]
	v_mfma_f32_16x16x32_bf16 v[84:87], v[170:173], v[194:197], v[84:87]
	v_mfma_f32_16x16x32_bf16 v[76:79], v[170:173], v[202:205], v[76:79]
	v_mfma_f32_16x16x32_bf16 v[76:79], v[174:177], v[206:209], v[76:79]
	v_mfma_f32_16x16x32_bf16 v[72:75], v[182:185], v[206:209], v[72:75]
	v_mfma_f32_16x16x32_bf16 v[72:75], v[178:181], v[202:205], v[72:75]
	v_mfma_f32_16x16x32_bf16 v[64:67], v[178:181], v[210:213], v[64:67]
	v_mfma_f32_16x16x32_bf16 v[64:67], v[182:185], v[214:217], v[64:67]
	v_mfma_f32_16x16x32_bf16 v[68:71], v[174:177], v[214:217], v[68:71]
	v_mfma_f32_16x16x32_bf16 v[68:71], v[170:173], v[210:213], v[68:71]
	s_setprio 0
	s_barrier
; #define PG8_STAGE(bufoff, gbase, voff) do { _Pragma("unroll") for (int _i = 0; _i < 2; ++_i) \
;         __builtin_amdgcn_global_load_lds((const unsigned*)((const char*)(gbase) + (voff)[_i]), (PG8_LAS unsigned*)(lds + (bufoff) + ldsw + _i * 8192), 16, 0, 0); } while (0)
; #define PG8_LDA(dst, b, h) do { _Pragma("unroll") for (int m = 0; m < 4; ++m) _Pragma("unroll") for (int k = 0; k < 2; ++k) dst[m][k] = *(const PG8_LAS bf16x8*)(lds + PG8_SA(b, h) + aoff + m * 2048 + k * 1024); } while (0)
; #define PG8_MMA(ai, bj, At, Bt) do { __builtin_amdgcn_s_setprio(1); _Pragma("unroll") for (int m = 0; m < 4; ++m) _Pragma("unroll") for (int n = 0; n < 2; ++n) _Pragma("unroll") for (int k = 0; k < 2; ++k) \
;         acc[ai][bj][m][n] = __builtin_amdgcn_mfma_f32_16x16x32_bf16(Bt[n][k], At[m][k], acc[ai][bj][m][n], 0, 0, 0); __builtin_amdgcn_s_setprio(0); } while (0)
; #define PG8_WAIT_V(n) asm volatile("s_waitcnt vmcnt(" #n ")" ::: "memory")
; #define PG8_WAIT_L(n) asm volatile("s_waitcnt lgkmcnt(" #n ")" ::: "memory")
; #define PG8_BAR __builtin_amdgcn_s_barrier()
; #define PG8_SCHED __builtin_amdgcn_sched_barrier(0)
; template <class Epi, class Sched, bool ALIGN_EPI = false, bool SP2 = false, bool APERM = false  >
; __device__ __forceinline__ void gemm_phase(PG8_LAS unsigned char* lds, const Gemm g, const Sched& S, const Epi& E, const int wid  ) {
;     ...
;             PG8_LDA(At, 1, 1); PG8_STAGE(PG8_SB(1, 0), b3, voffB); PG8_STAGE(PG8_SB(1, 1), b3 + hstep, voffB); PG8_STAGE(PG8_SA(1, 0), a3, voffA);
;             PG8_WAIT_V(8); PG8_WAIT_L(0); PG8_BAR; PG8_MMA(1, 0, At, B0); PG8_MMA(1, 1, At, B1); PG8_BAR; PG8_SCHED;
;     ...
;         if constexpr (ALIGN_EPI) { if (wr == 0) PG8_BAR; }
	s_add_i32 s65, s65, s85
	v_lshl_add_u64 v[218:219], v[218:219], 0, s[14:15]
	s_mov_b32 m0, s65
	ds_read_b128 v[186:189], v156 offset:49152
	ds_read_b128 v[190:193], v156 offset:50176
	ds_read_b128 v[194:197], v156 offset:51200
	ds_read_b128 v[198:201], v156 offset:52224
	ds_read_b128 v[202:205], v156 offset:53248
	ds_read_b128 v[206:209], v156 offset:54272
	ds_read_b128 v[210:213], v156 offset:55296
	ds_read_b128 v[214:217], v156 offset:56320
	global_load_lds_dwordx4 v[218:219], off
	s_add_i32 m0, s65, 0x2000
	s_add_u32 s80, s80, 0x80080
	v_lshl_add_u64 v[218:219], v[220:221], 0, s[14:15]
	s_addc_u32 s81, s81, 0
	s_add_i32 s65, s73, s85
	global_load_lds_dwordx4 v[218:219], off
	v_lshl_add_u64 v[218:219], s[80:81], 0, v[130:131]
	s_mov_b32 m0, s65
	s_nop 0
	global_load_lds_dwordx4 v[218:219], off
	v_lshl_add_u64 v[218:219], s[80:81], 0, v[134:135]
	s_add_i32 m0, s65, 0x2000
	s_nop 0
	global_load_lds_dwordx4 v[218:219], off
	v_lshl_add_u64 v[218:219], v[222:223], 0, s[14:15]
	s_mov_b32 m0, s90
	s_nop 0
	global_load_lds_dwordx4 v[218:219], off
	v_lshl_add_u64 v[218:219], v[224:225], 0, s[14:15]
	s_mov_b32 m0, s91
	s_nop 0
	global_load_lds_dwordx4 v[218:219], off
	s_waitcnt vmcnt(8)
	s_waitcnt lgkmcnt(0)
	s_barrier
	s_setprio 1
	s_waitcnt lgkmcnt(0)
	v_mfma_f32_16x16x32_bf16 v[60:63], v[146:149], v[186:189], v[60:63]
	v_mfma_f32_16x16x32_bf16 v[60:63], v[158:161], v[190:193], v[60:63]
	v_mfma_f32_16x16x32_bf16 v[56:59], v[166:169], v[190:193], v[56:59]
	v_mfma_f32_16x16x32_bf16 v[56:59], v[162:165], v[186:189], v[56:59]
	v_mfma_f32_16x16x32_bf16 v[48:51], v[162:165], v[194:197], v[48:51]
	v_mfma_f32_16x16x32_bf16 v[48:51], v[166:169], v[198:201], v[48:51]
	v_mfma_f32_16x16x32_bf16 v[52:55], v[158:161], v[198:201], v[52:55]
	v_mfma_f32_16x16x32_bf16 v[52:55], v[146:149], v[194:197], v[52:55]
	v_mfma_f32_16x16x32_bf16 v[44:47], v[146:149], v[202:205], v[44:47]
	v_mfma_f32_16x16x32_bf16 v[44:47], v[158:161], v[206:209], v[44:47]
	v_mfma_f32_16x16x32_bf16 v[40:43], v[166:169], v[206:209], v[40:43]
	v_mfma_f32_16x16x32_bf16 v[40:43], v[162:165], v[202:205], v[40:43]
	v_mfma_f32_16x16x32_bf16 v[32:35], v[162:165], v[210:213], v[32:35]
	v_mfma_f32_16x16x32_bf16 v[32:35], v[166:169], v[214:217], v[32:35]
	v_mfma_f32_16x16x32_bf16 v[36:39], v[158:161], v[214:217], v[36:39]
	v_mfma_f32_16x16x32_bf16 v[36:39], v[146:149], v[210:213], v[36:39]
	s_setprio 0
	s_setprio 1
	v_mfma_f32_16x16x32_bf16 v[28:31], v[170:173], v[186:189], v[28:31]
	v_mfma_f32_16x16x32_bf16 v[28:31], v[174:177], v[190:193], v[28:31]
	v_mfma_f32_16x16x32_bf16 v[24:27], v[182:185], v[190:193], v[24:27]
	v_mfma_f32_16x16x32_bf16 v[24:27], v[178:181], v[186:189], v[24:27]
	v_mfma_f32_16x16x32_bf16 v[16:19], v[178:181], v[194:197], v[16:19]
	v_mfma_f32_16x16x32_bf16 v[16:19], v[182:185], v[198:201], v[16:19]
	v_mfma_f32_16x16x32_bf16 v[20:23], v[174:177], v[198:201], v[20:23]
	v_mfma_f32_16x16x32_bf16 v[20:23], v[170:173], v[194:197], v[20:23]
	v_mfma_f32_16x16x32_bf16 v[12:15], v[170:173], v[202:205], v[12:15]
	v_mfma_f32_16x16x32_bf16 v[12:15], v[174:177], v[206:209], v[12:15]
	v_mfma_f32_16x16x32_bf16 v[8:11], v[182:185], v[206:209], v[8:11]
	v_mfma_f32_16x16x32_bf16 v[8:11], v[178:181], v[202:205], v[8:11]
	v_mfma_f32_16x16x32_bf16 v[0:3], v[178:181], v[210:213], v[0:3]
	v_mfma_f32_16x16x32_bf16 v[0:3], v[182:185], v[214:217], v[0:3]
	v_mfma_f32_16x16x32_bf16 v[4:7], v[174:177], v[214:217], v[4:7]
	v_mfma_f32_16x16x32_bf16 v[4:7], v[170:173], v[210:213], v[4:7]
	s_setprio 0
	s_barrier
	s_add_i32 s64, s64, 2
	s_add_u32 s78, s78, 0x100
	s_addc_u32 s79, s79, 0
	s_cmp_gt_u32 s64, 29
	s_cbranch_scc0 .LBB0_1019
	s_and_b64 vcc, exec, s[16:17]
	s_cbranch_vccz .LBB0_1022
	s_barrier

; #define PG8_STAGE(bufoff, gbase, voff) do { _Pragma("unroll") for (int _i = 0; _i < 2; ++_i) \
;         __builtin_amdgcn_global_load_lds((const unsigned*)((const char*)(gbase) + (voff)[_i]), (PG8_LAS unsigned*)(lds + (bufoff) + ldsw + _i * 8192), 16, 0, 0); } while (0)
; #define PG8_LDA(dst, b, h) do { _Pragma("unroll") for (int m = 0; m < 4; ++m) _Pragma("unroll") for (int k = 0; k < 2; ++k) dst[m][k] = *(const PG8_LAS bf16x8*)(lds + PG8_SA(b, h) + aoff + m * 2048 + k * 1024); } while (0)
; #define PG8_LDB(dst, b, h) do { _Pragma("unroll") for (int n = 0; n < 2; ++n) _Pragma("unroll") for (int k = 0; k < 2; ++k) dst[n][k] = *(const PG8_LAS bf16x8*)(lds + PG8_SB(b, h) + boff + n * 2048 + k * 1024); } while (0)
; #define PG8_MMA(ai, bj, At, Bt) do { __builtin_amdgcn_s_setprio(1); _Pragma("unroll") for (int m = 0; m < 4; ++m) _Pragma("unroll") for (int n = 0; n < 2; ++n) _Pragma("unroll") for (int k = 0; k < 2; ++k) \
;         acc[ai][bj][m][n] = __builtin_amdgcn_mfma_f32_16x16x32_bf16(Bt[n][k], At[m][k], acc[ai][bj][m][n], 0, 0, 0); __builtin_amdgcn_s_setprio(0); } while (0)
; #define PG8_WAIT_V(n) asm volatile("s_waitcnt vmcnt(" #n ")" ::: "memory")
; #define PG8_WAIT_L(n) asm volatile("s_waitcnt lgkmcnt(" #n ")" ::: "memory")
; template <class Epi, class Sched, bool ALIGN_EPI = false, bool SP2 = false, bool APERM = false  >
; __device__ __forceinline__ void gemm_phase(PG8_LAS unsigned char* lds, const Gemm g, const Sched& S, const Epi& E, const int wid  ) {
;     ...
;             const bool last = (t == nt - 2);
;             const char* a1 = cA + (size_t)(t + 1) * kstep;
;             const char* a2 = last ? nA : cA + (size_t)(t + 2) * kstep; const char* b2 = last ? nB : cB + (size_t)(t + 2) * kstep;
;             const char* a3 = a2 + kstep; const char* b3 = b2 + kstep;
;             if (last && has_next) S.a_ready(nxt);
;             if constexpr (SP2) {
;             PG8_LDB(B0, 0, 0); PG8_LDB(B1, 0, 1); PG8_SCHED; PG8_LDA(At, 0, 0); PG8_STAGE(PG8_SA(1, 1), a1 + hstep, voffA);
;             PG8_WAIT_V(8); PG8_WAIT_L(0); PG8_BAR; PG8_MMA(0, 0, At, B0); PG8_MMA(0, 1, At, B1); PG8_BAR; PG8_SCHED;
;             PG8_LDA(At, 0, 1); PG8_STAGE(PG8_SB(0, 0), b2, voffB); PG8_STAGE(PG8_SB(0, 1), b2 + hstep, voffB); PG8_STAGE(PG8_SA(0, 0), a2, voffA);
;             PG8_WAIT_V(8); PG8_WAIT_L(0); PG8_BAR; PG8_MMA(1, 0, At, B0); PG8_MMA(1, 1, At, B1); PG8_BAR; PG8_SCHED;
.LBB0_1099:
	s_lshl_b32 s30, s69, 7
	s_add_u32 s31, s44, s30
	s_addc_u32 s46, s45, 0
	s_add_u32 s14, s31, 0x100
	s_addc_u32 s15, s46, 0
	v_add_u32_e32 v140, s49, v235
	v_add_u32_e32 v156, s62, v235
	s_and_b64 s[10:11], s[12:13], exec
	ds_read_b128 v[128:131], v140
	ds_read_b128 v[132:135], v140 offset:1024
	ds_read_b128 v[136:139], v140 offset:2048
	ds_read_b128 v[140:143], v140 offset:3072
	ds_read_b128 v[144:147], v156
	ds_read_b128 v[148:151], v156 offset:1024
	ds_read_b128 v[152:155], v156 offset:2048
	ds_read_b128 v[156:159], v156 offset:3072
	s_cselect_b32 s15, s8, s15
	s_cselect_b32 s14, s9, s14
	s_add_u32 s10, s36, s30
	s_addc_u32 s11, s37, 0
	s_add_u32 s30, s10, 0x100
	s_addc_u32 s47, s11, 0
	s_and_b64 s[10:11], s[12:13], exec
	s_cselect_b32 s10, s68, s30
	s_cselect_b32 s11, s33, s47
	s_add_u32 s12, s31, 0x80080
	s_addc_u32 s13, s46, 0
	v_lshl_add_u64 v[206:207], s[12:13], 0, v[188:189]
	s_add_i32 m0, s35, 0xc000
	ds_read_b128 v[160:163], v247
	ds_read_b128 v[164:167], v247 offset:1024
	ds_read_b128 v[168:171], v247 offset:2048
	ds_read_b128 v[172:175], v247 offset:3072
	ds_read_b128 v[176:179], v247 offset:4096
	ds_read_b128 v[180:183], v247 offset:5120
	ds_read_b128 v[198:201], v247 offset:6144
	ds_read_b128 v[202:205], v247 offset:7168
	global_load_lds_dwordx4 v[206:207], off
	v_lshl_add_u64 v[206:207], s[12:13], 0, v[190:191]
	s_add_i32 m0, s35, 0xe000
	s_nop 0
	global_load_lds_dwordx4 v[206:207], off
	s_waitcnt vmcnt(8)
	s_waitcnt lgkmcnt(0)
	s_barrier
	s_setprio 1
	s_waitcnt lgkmcnt(0)
	v_mfma_f32_16x16x32_bf16 v[124:127], v[128:131], v[160:163], v[124:127]
	v_mfma_f32_16x16x32_bf16 v[124:127], v[132:135], v[164:167], v[124:127]
	v_mfma_f32_16x16x32_bf16 v[120:123], v[140:143], v[164:167], v[120:123]
	v_mfma_f32_16x16x32_bf16 v[120:123], v[136:139], v[160:163], v[120:123]
	v_mfma_f32_16x16x32_bf16 v[112:115], v[136:139], v[168:171], v[112:115]
	v_mfma_f32_16x16x32_bf16 v[112:115], v[140:143], v[172:175], v[112:115]
	v_mfma_f32_16x16x32_bf16 v[116:119], v[132:135], v[172:175], v[116:119]
	v_mfma_f32_16x16x32_bf16 v[116:119], v[128:131], v[168:171], v[116:119]
	v_mfma_f32_16x16x32_bf16 v[108:111], v[128:131], v[176:179], v[108:111]
	v_mfma_f32_16x16x32_bf16 v[108:111], v[132:135], v[180:183], v[108:111]
	v_mfma_f32_16x16x32_bf16 v[104:107], v[140:143], v[180:183], v[104:107]
	v_mfma_f32_16x16x32_bf16 v[104:107], v[136:139], v[176:179], v[104:107]
	v_mfma_f32_16x16x32_bf16 v[96:99], v[136:139], v[198:201], v[96:99]
	v_mfma_f32_16x16x32_bf16 v[96:99], v[140:143], v[202:205], v[96:99]
	v_mfma_f32_16x16x32_bf16 v[100:103], v[132:135], v[202:205], v[100:103]
	v_mfma_f32_16x16x32_bf16 v[100:103], v[128:131], v[198:201], v[100:103]
	s_setprio 0
	s_setprio 1
	v_mfma_f32_16x16x32_bf16 v[92:95], v[144:147], v[160:163], v[92:95]
	v_mfma_f32_16x16x32_bf16 v[92:95], v[148:151], v[164:167], v[92:95]
	v_mfma_f32_16x16x32_bf16 v[88:91], v[156:159], v[164:167], v[88:91]
	v_mfma_f32_16x16x32_bf16 v[88:91], v[152:155], v[160:163], v[88:91]
	v_mfma_f32_16x16x32_bf16 v[80:83], v[152:155], v[168:171], v[80:83]
	v_mfma_f32_16x16x32_bf16 v[80:83], v[156:159], v[172:175], v[80:83]
	v_mfma_f32_16x16x32_bf16 v[84:87], v[148:151], v[172:175], v[84:87]
	v_mfma_f32_16x16x32_bf16 v[84:87], v[144:147], v[168:171], v[84:87]
	v_mfma_f32_16x16x32_bf16 v[76:79], v[144:147], v[176:179], v[76:79]
	v_mfma_f32_16x16x32_bf16 v[76:79], v[148:151], v[180:183], v[76:79]
	v_mfma_f32_16x16x32_bf16 v[72:75], v[156:159], v[180:183], v[72:75]
	v_mfma_f32_16x16x32_bf16 v[72:75], v[152:155], v[176:179], v[72:75]
	v_mfma_f32_16x16x32_bf16 v[64:67], v[152:155], v[198:201], v[64:67]
	v_mfma_f32_16x16x32_bf16 v[64:67], v[156:159], v[202:205], v[64:67]
	v_mfma_f32_16x16x32_bf16 v[68:71], v[148:151], v[202:205], v[68:71]
	v_mfma_f32_16x16x32_bf16 v[68:71], v[144:147], v[198:201], v[68:71]
	s_setprio 0
	s_barrier
	s_add_i32 s12, s49, s96
	v_lshl_add_u64 v[206:207], s[10:11], 0, v[184:185]
	s_mov_b32 m0, s12
	ds_read_b128 v[160:163], v247 offset:16384
	ds_read_b128 v[164:167], v247 offset:17408
	ds_read_b128 v[168:171], v247 offset:18432
	ds_read_b128 v[172:175], v247 offset:19456
	ds_read_b128 v[176:179], v247 offset:20480
	ds_read_b128 v[180:183], v247 offset:21504
	ds_read_b128 v[198:201], v247 offset:22528
	ds_read_b128 v[202:205], v247 offset:23552
	global_load_lds_dwordx4 v[206:207], off
	s_add_i32 m0, s12, 0x2000
	s_add_u32 s12, s10, 0x80000
	v_lshl_add_u64 v[208:209], s[10:11], 0, v[186:187]
	s_addc_u32 s13, s11, 0
	s_add_i32 s30, s62, s96
	global_load_lds_dwordx4 v[208:209], off
	v_lshl_add_u64 v[210:211], s[12:13], 0, v[184:185]
	s_mov_b32 m0, s30
	v_lshl_add_u64 v[212:213], s[14:15], 0, v[190:191]
	global_load_lds_dwordx4 v[210:211], off
	v_lshl_add_u64 v[210:211], s[12:13], 0, v[186:187]
	s_add_i32 m0, s30, 0x2000
	s_nop 0
	global_load_lds_dwordx4 v[210:211], off
	v_lshl_add_u64 v[210:211], s[14:15], 0, v[188:189]
	s_mov_b32 m0, s35
	s_nop 0
	global_load_lds_dwordx4 v[210:211], off
	s_mov_b32 m0, s2
	s_nop 0
	global_load_lds_dwordx4 v[212:213], off
	s_waitcnt vmcnt(8)
	s_waitcnt lgkmcnt(0)
	s_barrier
; #define PG8_STAGE(bufoff, gbase, voff) do { _Pragma("unroll") for (int _i = 0; _i < 2; ++_i) \
;         __builtin_amdgcn_global_load_lds((const unsigned*)((const char*)(gbase) + (voff)[_i]), (PG8_LAS unsigned*)(lds + (bufoff) + ldsw + _i * 8192), 16, 0, 0); } while (0)
; #define PG8_LDA(dst, b, h) do { _Pragma("unroll") for (int m = 0; m < 4; ++m) _Pragma("unroll") for (int k = 0; k < 2; ++k) dst[m][k] = *(const PG8_LAS bf16x8*)(lds + PG8_SA(b, h) + aoff + m * 2048 + k * 1024); } while (0)
; #define PG8_LDB(dst, b, h) do { _Pragma("unroll") for (int n = 0; n < 2; ++n) _Pragma("unroll") for (int k = 0; k < 2; ++k) dst[n][k] = *(const PG8_LAS bf16x8*)(lds + PG8_SB(b, h) + boff + n * 2048 + k * 1024); } while (0)
; #define PG8_MMA(ai, bj, At, Bt) do { __builtin_amdgcn_s_setprio(1); _Pragma("unroll") for (int m = 0; m < 4; ++m) _Pragma("unroll") for (int n = 0; n < 2; ++n) _Pragma("unroll") for (int k = 0; k < 2; ++k) \
;         acc[ai][bj][m][n] = __builtin_amdgcn_mfma_f32_16x16x32_bf16(Bt[n][k], At[m][k], acc[ai][bj][m][n], 0, 0, 0); __builtin_amdgcn_s_setprio(0); } while (0)
; #define PG8_WAIT_V(n) asm volatile("s_waitcnt vmcnt(" #n ")" ::: "memory")
; #define PG8_WAIT_L(n) asm volatile("s_waitcnt lgkmcnt(" #n ")" ::: "memory")
; #define PG8_BAR __builtin_amdgcn_s_barrier()
; #define PG8_SCHED __builtin_amdgcn_sched_barrier(0)
; template <class Epi, class Sched, bool ALIGN_EPI = false, bool SP2 = false, bool APERM = false  >
; __device__ __forceinline__ void gemm_phase(PG8_LAS unsigned char* lds, const Gemm g, const Sched& S, const Epi& E, const int wid  ) {
;     ...
;             PG8_WAIT_V(8); PG8_WAIT_L(0); PG8_BAR; PG8_MMA(1, 0, At, B0); PG8_MMA(1, 1, At, B1); PG8_BAR; PG8_SCHED;
;             PG8_LDB(B0, 1, 0); PG8_LDB(B1, 1, 1); PG8_SCHED; PG8_LDA(At, 1, 0); PG8_STAGE(PG8_SA(0, 1), a2 + hstep, voffA);
;             PG8_WAIT_V(8); PG8_WAIT_L(0); PG8_BAR; PG8_MMA(0, 0, At, B0); PG8_MMA(0, 1, At, B1); PG8_BAR; PG8_SCHED;
	s_setprio 1
	s_waitcnt lgkmcnt(0)
	v_mfma_f32_16x16x32_bf16 v[60:63], v[128:131], v[160:163], v[60:63]
	v_mfma_f32_16x16x32_bf16 v[60:63], v[132:135], v[164:167], v[60:63]
	v_mfma_f32_16x16x32_bf16 v[56:59], v[140:143], v[164:167], v[56:59]
	v_mfma_f32_16x16x32_bf16 v[56:59], v[136:139], v[160:163], v[56:59]
	v_mfma_f32_16x16x32_bf16 v[48:51], v[136:139], v[168:171], v[48:51]
	v_mfma_f32_16x16x32_bf16 v[48:51], v[140:143], v[172:175], v[48:51]
	v_mfma_f32_16x16x32_bf16 v[52:55], v[132:135], v[172:175], v[52:55]
	v_mfma_f32_16x16x32_bf16 v[52:55], v[128:131], v[168:171], v[52:55]
	v_mfma_f32_16x16x32_bf16 v[44:47], v[128:131], v[176:179], v[44:47]
	v_mfma_f32_16x16x32_bf16 v[44:47], v[132:135], v[180:183], v[44:47]
	v_mfma_f32_16x16x32_bf16 v[40:43], v[140:143], v[180:183], v[40:43]
	v_mfma_f32_16x16x32_bf16 v[40:43], v[136:139], v[176:179], v[40:43]
	v_mfma_f32_16x16x32_bf16 v[32:35], v[136:139], v[198:201], v[32:35]
	v_mfma_f32_16x16x32_bf16 v[32:35], v[140:143], v[202:205], v[32:35]
	v_mfma_f32_16x16x32_bf16 v[36:39], v[132:135], v[202:205], v[36:39]
	v_mfma_f32_16x16x32_bf16 v[36:39], v[128:131], v[198:201], v[36:39]
	s_setprio 0
	s_setprio 1
	v_mfma_f32_16x16x32_bf16 v[28:31], v[144:147], v[160:163], v[28:31]
	v_mfma_f32_16x16x32_bf16 v[28:31], v[148:151], v[164:167], v[28:31]
	v_mfma_f32_16x16x32_bf16 v[24:27], v[156:159], v[164:167], v[24:27]
	v_mfma_f32_16x16x32_bf16 v[24:27], v[152:155], v[160:163], v[24:27]
	v_mfma_f32_16x16x32_bf16 v[16:19], v[152:155], v[168:171], v[16:19]
	v_mfma_f32_16x16x32_bf16 v[16:19], v[156:159], v[172:175], v[16:19]
	v_mfma_f32_16x16x32_bf16 v[20:23], v[148:151], v[172:175], v[20:23]
	v_mfma_f32_16x16x32_bf16 v[20:23], v[144:147], v[168:171], v[20:23]
	v_mfma_f32_16x16x32_bf16 v[12:15], v[144:147], v[176:179], v[12:15]
	v_mfma_f32_16x16x32_bf16 v[12:15], v[148:151], v[180:183], v[12:15]
	v_mfma_f32_16x16x32_bf16 v[8:11], v[156:159], v[180:183], v[8:11]
	v_mfma_f32_16x16x32_bf16 v[8:11], v[152:155], v[176:179], v[8:11]
	v_mfma_f32_16x16x32_bf16 v[0:3], v[152:155], v[198:201], v[0:3]
	v_mfma_f32_16x16x32_bf16 v[0:3], v[156:159], v[202:205], v[0:3]
	v_mfma_f32_16x16x32_bf16 v[4:7], v[148:151], v[202:205], v[4:7]
	v_mfma_f32_16x16x32_bf16 v[4:7], v[144:147], v[198:201], v[4:7]
	s_setprio 0
	s_barrier
	s_add_i32 s30, 0, 0x18000
	s_add_i32 s31, 0, 0x1c000
	v_add_u32_e32 v140, s30, v235
	v_add_u32_e32 v156, s31, v235
	ds_read_b128 v[128:131], v140
	ds_read_b128 v[132:135], v140 offset:1024
	ds_read_b128 v[136:139], v140 offset:2048
	ds_read_b128 v[140:143], v140 offset:3072
	ds_read_b128 v[144:147], v156
	ds_read_b128 v[148:151], v156 offset:1024
	ds_read_b128 v[152:155], v156 offset:2048
	ds_read_b128 v[156:159], v156 offset:3072
	s_add_u32 s12, s14, 0x80000
	s_addc_u32 s13, s15, 0
	s_mov_b32 m0, s3
	v_lshl_add_u64 v[214:215], s[12:13], 0, v[188:189]
	ds_read_b128 v[160:163], v247 offset:32768
	ds_read_b128 v[164:167], v247 offset:33792
	ds_read_b128 v[168:171], v247 offset:34816
	ds_read_b128 v[172:175], v247 offset:35840
	ds_read_b128 v[176:179], v247 offset:36864
	ds_read_b128 v[180:183], v247 offset:37888
	ds_read_b128 v[198:201], v247 offset:38912
	ds_read_b128 v[202:205], v247 offset:39936
	global_load_lds_dwordx4 v[214:215], off
	v_lshl_add_u64 v[214:215], s[12:13], 0, v[190:191]
	s_mov_b32 m0, s52
	s_nop 0
	global_load_lds_dwordx4 v[214:215], off
	s_waitcnt vmcnt(8)
	s_waitcnt lgkmcnt(0)
	s_barrier
	s_setprio 1
	s_waitcnt lgkmcnt(0)
	v_mfma_f32_16x16x32_bf16 v[124:127], v[128:131], v[160:163], v[124:127]
	v_mfma_f32_16x16x32_bf16 v[124:127], v[132:135], v[164:167], v[124:127]
	v_mfma_f32_16x16x32_bf16 v[120:123], v[140:143], v[164:167], v[120:123]
	v_mfma_f32_16x16x32_bf16 v[120:123], v[136:139], v[160:163], v[120:123]
	v_mfma_f32_16x16x32_bf16 v[112:115], v[136:139], v[168:171], v[112:115]
	v_mfma_f32_16x16x32_bf16 v[112:115], v[140:143], v[172:175], v[112:115]
	v_mfma_f32_16x16x32_bf16 v[116:119], v[132:135], v[172:175], v[116:119]
	v_mfma_f32_16x16x32_bf16 v[116:119], v[128:131], v[168:171], v[116:119]
	v_mfma_f32_16x16x32_bf16 v[108:111], v[128:131], v[176:179], v[108:111]
	v_mfma_f32_16x16x32_bf16 v[108:111], v[132:135], v[180:183], v[108:111]
	v_mfma_f32_16x16x32_bf16 v[104:107], v[140:143], v[180:183], v[104:107]
	v_mfma_f32_16x16x32_bf16 v[104:107], v[136:139], v[176:179], v[104:107]
	v_mfma_f32_16x16x32_bf16 v[96:99], v[136:139], v[198:201], v[96:99]
	v_mfma_f32_16x16x32_bf16 v[96:99], v[140:143], v[202:205], v[96:99]
	v_mfma_f32_16x16x32_bf16 v[100:103], v[132:135], v[202:205], v[100:103]
	v_mfma_f32_16x16x32_bf16 v[100:103], v[128:131], v[198:201], v[100:103]
	s_setprio 0
	s_setprio 1
	v_mfma_f32_16x16x32_bf16 v[92:95], v[144:147], v[160:163], v[92:95]
	v_mfma_f32_16x16x32_bf16 v[92:95], v[148:151], v[164:167], v[92:95]
	v_mfma_f32_16x16x32_bf16 v[88:91], v[156:159], v[164:167], v[88:91]
	v_mfma_f32_16x16x32_bf16 v[88:91], v[152:155], v[160:163], v[88:91]
	v_mfma_f32_16x16x32_bf16 v[80:83], v[152:155], v[168:171], v[80:83]
	v_mfma_f32_16x16x32_bf16 v[80:83], v[156:159], v[172:175], v[80:83]
	v_mfma_f32_16x16x32_bf16 v[84:87], v[148:151], v[172:175], v[84:87]
	v_mfma_f32_16x16x32_bf16 v[84:87], v[144:147], v[168:171], v[84:87]
	v_mfma_f32_16x16x32_bf16 v[76:79], v[144:147], v[176:179], v[76:79]
	v_mfma_f32_16x16x32_bf16 v[76:79], v[148:151], v[180:183], v[76:79]
	v_mfma_f32_16x16x32_bf16 v[72:75], v[156:159], v[180:183], v[72:75]
	v_mfma_f32_16x16x32_bf16 v[72:75], v[152:155], v[176:179], v[72:75]
	v_mfma_f32_16x16x32_bf16 v[64:67], v[152:155], v[198:201], v[64:67]
	v_mfma_f32_16x16x32_bf16 v[64:67], v[156:159], v[202:205], v[64:67]
	v_mfma_f32_16x16x32_bf16 v[68:71], v[148:151], v[202:205], v[68:71]
	v_mfma_f32_16x16x32_bf16 v[68:71], v[144:147], v[198:201], v[68:71]
	s_setprio 0
	s_barrier
; #define PG8_STAGE(bufoff, gbase, voff) do { _Pragma("unroll") for (int _i = 0; _i < 2; ++_i) \
;         __builtin_amdgcn_global_load_lds((const unsigned*)((const char*)(gbase) + (voff)[_i]), (PG8_LAS unsigned*)(lds + (bufoff) + ldsw + _i * 8192), 16, 0, 0); } while (0)
; #define PG8_LDA(dst, b, h) do { _Pragma("unroll") for (int m = 0; m < 4; ++m) _Pragma("unroll") for (int k = 0; k < 2; ++k) dst[m][k] = *(const PG8_LAS bf16x8*)(lds + PG8_SA(b, h) + aoff + m * 2048 + k * 1024); } while (0)
; #define PG8_MMA(ai, bj, At, Bt) do { __builtin_amdgcn_s_setprio(1); _Pragma("unroll") for (int m = 0; m < 4; ++m) _Pragma("unroll") for (int n = 0; n < 2; ++n) _Pragma("unroll") for (int k = 0; k < 2; ++k) \
;         acc[ai][bj][m][n] = __builtin_amdgcn_mfma_f32_16x16x32_bf16(Bt[n][k], At[m][k], acc[ai][bj][m][n], 0, 0, 0); __builtin_amdgcn_s_setprio(0); } while (0)
; #define PG8_WAIT_V(n) asm volatile("s_waitcnt vmcnt(" #n ")" ::: "memory")
; #define PG8_WAIT_L(n) asm volatile("s_waitcnt lgkmcnt(" #n ")" ::: "memory")
; #define PG8_BAR __builtin_amdgcn_s_barrier()
; #define PG8_SCHED __builtin_amdgcn_sched_barrier(0)
; template <class Epi, class Sched, bool ALIGN_EPI = false, bool SP2 = false, bool APERM = false  >
; __device__ __forceinline__ void gemm_phase(PG8_LAS unsigned char* lds, const Gemm g, const Sched& S, const Epi& E, const int wid  ) {
;     ...
;             PG8_LDA(At, 1, 1); PG8_STAGE(PG8_SB(1, 0), b3, voffB); PG8_STAGE(PG8_SB(1, 1), b3 + hstep, voffB); PG8_STAGE(PG8_SA(1, 0), a3, voffA);
;             PG8_WAIT_V(8); PG8_WAIT_L(0); PG8_BAR; PG8_MMA(1, 0, At, B0); PG8_MMA(1, 1, At, B1); PG8_BAR; PG8_SCHED;
	s_add_i32 s12, s30, s96
	v_lshl_add_u64 v[206:207], v[206:207], 0, s[64:65]
	s_mov_b32 m0, s12
	ds_read_b128 v[160:163], v247 offset:49152
	ds_read_b128 v[164:167], v247 offset:50176
	ds_read_b128 v[168:171], v247 offset:51200
	ds_read_b128 v[172:175], v247 offset:52224
	ds_read_b128 v[176:179], v247 offset:53248
	ds_read_b128 v[180:183], v247 offset:54272
	ds_read_b128 v[198:201], v247 offset:55296
	ds_read_b128 v[202:205], v247 offset:56320
	global_load_lds_dwordx4 v[206:207], off
	s_add_i32 m0, s12, 0x2000
	s_add_u32 s10, s10, 0x80080
	v_lshl_add_u64 v[206:207], v[208:209], 0, s[64:65]
	s_addc_u32 s11, s11, 0
	s_add_i32 s12, s31, s96
	global_load_lds_dwordx4 v[206:207], off
	v_lshl_add_u64 v[206:207], s[10:11], 0, v[184:185]
	s_mov_b32 m0, s12
	s_nop 0
	global_load_lds_dwordx4 v[206:207], off
	v_lshl_add_u64 v[206:207], s[10:11], 0, v[186:187]
	s_add_i32 m0, s12, 0x2000
	s_nop 0
	global_load_lds_dwordx4 v[206:207], off
	v_lshl_add_u64 v[206:207], v[210:211], 0, s[64:65]
	s_mov_b32 m0, s58
	s_nop 0
	global_load_lds_dwordx4 v[206:207], off
	v_lshl_add_u64 v[206:207], v[212:213], 0, s[64:65]
	s_mov_b32 m0, s59
	s_nop 0
	global_load_lds_dwordx4 v[206:207], off
	s_waitcnt vmcnt(8)
	s_waitcnt lgkmcnt(0)
	s_barrier
	s_setprio 1
	s_waitcnt lgkmcnt(0)
	v_mfma_f32_16x16x32_bf16 v[60:63], v[128:131], v[160:163], v[60:63]
	v_mfma_f32_16x16x32_bf16 v[60:63], v[132:135], v[164:167], v[60:63]
	v_mfma_f32_16x16x32_bf16 v[56:59], v[140:143], v[164:167], v[56:59]
	v_mfma_f32_16x16x32_bf16 v[56:59], v[136:139], v[160:163], v[56:59]
	v_mfma_f32_16x16x32_bf16 v[48:51], v[136:139], v[168:171], v[48:51]
	v_mfma_f32_16x16x32_bf16 v[48:51], v[140:143], v[172:175], v[48:51]
	v_mfma_f32_16x16x32_bf16 v[52:55], v[132:135], v[172:175], v[52:55]
	v_mfma_f32_16x16x32_bf16 v[52:55], v[128:131], v[168:171], v[52:55]
	v_mfma_f32_16x16x32_bf16 v[44:47], v[128:131], v[176:179], v[44:47]
	v_mfma_f32_16x16x32_bf16 v[44:47], v[132:135], v[180:183], v[44:47]
	v_mfma_f32_16x16x32_bf16 v[40:43], v[140:143], v[180:183], v[40:43]
	v_mfma_f32_16x16x32_bf16 v[40:43], v[136:139], v[176:179], v[40:43]
	v_mfma_f32_16x16x32_bf16 v[32:35], v[136:139], v[198:201], v[32:35]
	v_mfma_f32_16x16x32_bf16 v[32:35], v[140:143], v[202:205], v[32:35]
	v_mfma_f32_16x16x32_bf16 v[36:39], v[132:135], v[202:205], v[36:39]
	v_mfma_f32_16x16x32_bf16 v[36:39], v[128:131], v[198:201], v[36:39]
	s_setprio 0
	s_setprio 1
	v_mfma_f32_16x16x32_bf16 v[28:31], v[144:147], v[160:163], v[28:31]
	v_mfma_f32_16x16x32_bf16 v[28:31], v[148:151], v[164:167], v[28:31]
	v_mfma_f32_16x16x32_bf16 v[24:27], v[156:159], v[164:167], v[24:27]
	v_mfma_f32_16x16x32_bf16 v[24:27], v[152:155], v[160:163], v[24:27]
	v_mfma_f32_16x16x32_bf16 v[16:19], v[152:155], v[168:171], v[16:19]
	v_mfma_f32_16x16x32_bf16 v[16:19], v[156:159], v[172:175], v[16:19]
	v_mfma_f32_16x16x32_bf16 v[20:23], v[148:151], v[172:175], v[20:23]
	v_mfma_f32_16x16x32_bf16 v[20:23], v[144:147], v[168:171], v[20:23]
	v_mfma_f32_16x16x32_bf16 v[12:15], v[144:147], v[176:179], v[12:15]
	v_mfma_f32_16x16x32_bf16 v[12:15], v[148:151], v[180:183], v[12:15]
	v_mfma_f32_16x16x32_bf16 v[8:11], v[156:159], v[180:183], v[8:11]
	v_mfma_f32_16x16x32_bf16 v[8:11], v[152:155], v[176:179], v[8:11]
	v_mfma_f32_16x16x32_bf16 v[0:3], v[152:155], v[198:201], v[0:3]
	v_mfma_f32_16x16x32_bf16 v[0:3], v[156:159], v[202:205], v[0:3]
	v_mfma_f32_16x16x32_bf16 v[4:7], v[148:151], v[202:205], v[4:7]
	v_mfma_f32_16x16x32_bf16 v[4:7], v[144:147], v[198:201], v[4:7]
	s_setprio 0
	s_barrier
	s_add_i32 s10, s69, 2
	s_cmp_gt_u32 s69, 29
	s_cbranch_scc1 .LBB0_1101
	s_mov_b32 s69, s10
	s_branch .LBB0_1077

; #define PG8_STAGE(bufoff, gbase, voff) do { _Pragma("unroll") for (int _i = 0; _i < 2; ++_i) \
;         __builtin_amdgcn_global_load_lds((const unsigned*)((const char*)(gbase) + (voff)[_i]), (PG8_LAS unsigned*)(lds + (bufoff) + ldsw + _i * 8192), 16, 0, 0); } while (0)
; #define PG8_LDA(dst, b, h) do { _Pragma("unroll") for (int m = 0; m < 4; ++m) _Pragma("unroll") for (int k = 0; k < 2; ++k) dst[m][k] = *(const PG8_LAS bf16x8*)(lds + PG8_SA(b, h) + aoff + m * 2048 + k * 1024); } while (0)
; #define PG8_LDB(dst, b, h) do { _Pragma("unroll") for (int n = 0; n < 2; ++n) _Pragma("unroll") for (int k = 0; k < 2; ++k) dst[n][k] = *(const PG8_LAS bf16x8*)(lds + PG8_SB(b, h) + boff + n * 2048 + k * 1024); } while (0)
; #define PG8_MMA(ai, bj, At, Bt) do { __builtin_amdgcn_s_setprio(1); _Pragma("unroll") for (int m = 0; m < 4; ++m) _Pragma("unroll") for (int n = 0; n < 2; ++n) _Pragma("unroll") for (int k = 0; k < 2; ++k) \
;         acc[ai][bj][m][n] = __builtin_amdgcn_mfma_f32_16x16x32_bf16(Bt[n][k], At[m][k], acc[ai][bj][m][n], 0, 0, 0); __builtin_amdgcn_s_setprio(0); } while (0)
; #define PG8_WAIT_V(n) asm volatile("s_waitcnt vmcnt(" #n ")" ::: "memory")
; #define PG8_WAIT_L(n) asm volatile("s_waitcnt lgkmcnt(" #n ")" ::: "memory")
; template <class Epi, class Sched, bool ALIGN_EPI = false, bool SP2 = false, bool APERM = false  >
; __device__ __forceinline__ void gemm_phase(PG8_LAS unsigned char* lds, const Gemm g, const Sched& S, const Epi& E, const int wid  ) {
;     ...
;             const bool last = (t == nt - 2);
;             const char* a1 = cA + (size_t)(t + 1) * kstep;
;             const char* a2 = last ? nA : cA + (size_t)(t + 2) * kstep; const char* b2 = last ? nB : cB + (size_t)(t + 2) * kstep;
;             const char* a3 = a2 + kstep; const char* b3 = b2 + kstep;
;             if (last && has_next) S.a_ready(nxt);
;             if constexpr (SP2) {
;             PG8_LDB(B0, 0, 0); PG8_LDB(B1, 0, 1); PG8_SCHED; PG8_LDA(At, 0, 0); PG8_STAGE(PG8_SA(1, 1), a1 + hstep, voffA);
;             PG8_WAIT_V(8); PG8_WAIT_L(0); PG8_BAR; PG8_MMA(0, 0, At, B0); PG8_MMA(0, 1, At, B1); PG8_BAR; PG8_SCHED;
;             PG8_LDA(At, 0, 1); PG8_STAGE(PG8_SB(0, 0), b2, voffB); PG8_STAGE(PG8_SB(0, 1), b2 + hstep, voffB); PG8_STAGE(PG8_SA(0, 0), a2, voffA);
;             PG8_WAIT_V(8); PG8_WAIT_L(0); PG8_BAR; PG8_MMA(1, 0, At, B0); PG8_MMA(1, 1, At, B1); PG8_BAR; PG8_SCHED;
.LBB0_1252:
	s_lshl_b32 s74, s53, 7
	s_add_u32 s75, s14, s74
	s_addc_u32 s78, s15, 0
	v_add_u32_e32 v146, s33, v150
	s_add_u32 s72, s75, 0x100
	ds_read_b128 v[142:145], v146
	ds_read_b128 v[154:157], v146 offset:1024
	ds_read_b128 v[158:161], v146 offset:2048
	ds_read_b128 v[162:165], v146 offset:3072
	v_add_u32_e32 v146, s96, v150
	s_addc_u32 s73, s78, 0
	ds_read_b128 v[166:169], v146
	ds_read_b128 v[170:173], v146 offset:1024
	ds_read_b128 v[174:177], v146 offset:2048
	ds_read_b128 v[178:181], v146 offset:3072
	s_and_b64 s[46:47], s[70:71], exec
	s_cselect_b32 s73, s65, s73
	s_cselect_b32 s72, s64, s72
	s_add_u32 s46, s10, s74
	s_addc_u32 s47, s11, 0
	s_add_u32 s74, s46, 0x100
	s_addc_u32 vcc_lo, s47, 0
	s_and_b64 s[46:47], s[70:71], exec
	s_cselect_b32 s71, s67, vcc_lo
	s_cselect_b32 s70, s66, s74
	s_add_u32 s46, s75, 0x160080
	s_addc_u32 s47, s78, 0
	v_lshl_add_u64 v[146:147], s[46:47], 0, v[132:133]
	s_add_i32 m0, s87, 0xc000
	ds_read_b128 v[182:185], v153
	ds_read_b128 v[186:189], v153 offset:1024
	ds_read_b128 v[190:193], v153 offset:2048
	ds_read_b128 v[194:197], v153 offset:3072
	ds_read_b128 v[198:201], v153 offset:4096
	ds_read_b128 v[202:205], v153 offset:5120
	ds_read_b128 v[206:209], v153 offset:6144
	ds_read_b128 v[210:213], v153 offset:7168
	global_load_lds_dwordx4 v[146:147], off
	v_lshl_add_u64 v[146:147], s[46:47], 0, v[134:135]
	s_add_i32 m0, s87, 0xe000
	s_nop 0
	global_load_lds_dwordx4 v[146:147], off
	s_waitcnt vmcnt(8)
	s_waitcnt lgkmcnt(0)
	s_barrier
	s_setprio 1
	s_waitcnt lgkmcnt(0)
	v_mfma_f32_16x16x32_bf16 v[124:127], v[142:145], v[182:185], v[124:127]
	v_mfma_f32_16x16x32_bf16 v[124:127], v[154:157], v[186:189], v[124:127]
	v_mfma_f32_16x16x32_bf16 v[120:123], v[162:165], v[186:189], v[120:123]
	v_mfma_f32_16x16x32_bf16 v[120:123], v[158:161], v[182:185], v[120:123]
	v_mfma_f32_16x16x32_bf16 v[112:115], v[158:161], v[190:193], v[112:115]
	v_mfma_f32_16x16x32_bf16 v[112:115], v[162:165], v[194:197], v[112:115]
	v_mfma_f32_16x16x32_bf16 v[116:119], v[154:157], v[194:197], v[116:119]
	v_mfma_f32_16x16x32_bf16 v[116:119], v[142:145], v[190:193], v[116:119]
	v_mfma_f32_16x16x32_bf16 v[108:111], v[142:145], v[198:201], v[108:111]
	v_mfma_f32_16x16x32_bf16 v[108:111], v[154:157], v[202:205], v[108:111]
	v_mfma_f32_16x16x32_bf16 v[104:107], v[162:165], v[202:205], v[104:107]
	v_mfma_f32_16x16x32_bf16 v[104:107], v[158:161], v[198:201], v[104:107]
	v_mfma_f32_16x16x32_bf16 v[96:99], v[158:161], v[206:209], v[96:99]
	v_mfma_f32_16x16x32_bf16 v[96:99], v[162:165], v[210:213], v[96:99]
	v_mfma_f32_16x16x32_bf16 v[100:103], v[154:157], v[210:213], v[100:103]
	v_mfma_f32_16x16x32_bf16 v[100:103], v[142:145], v[206:209], v[100:103]
	s_setprio 0
	s_setprio 1
	v_mfma_f32_16x16x32_bf16 v[92:95], v[166:169], v[182:185], v[92:95]
	v_mfma_f32_16x16x32_bf16 v[92:95], v[170:173], v[186:189], v[92:95]
	v_mfma_f32_16x16x32_bf16 v[88:91], v[178:181], v[186:189], v[88:91]
	v_mfma_f32_16x16x32_bf16 v[88:91], v[174:177], v[182:185], v[88:91]
	v_mfma_f32_16x16x32_bf16 v[80:83], v[174:177], v[190:193], v[80:83]
	v_mfma_f32_16x16x32_bf16 v[80:83], v[178:181], v[194:197], v[80:83]
	v_mfma_f32_16x16x32_bf16 v[84:87], v[170:173], v[194:197], v[84:87]
	v_mfma_f32_16x16x32_bf16 v[84:87], v[166:169], v[190:193], v[84:87]
	v_mfma_f32_16x16x32_bf16 v[76:79], v[166:169], v[198:201], v[76:79]
	v_mfma_f32_16x16x32_bf16 v[76:79], v[170:173], v[202:205], v[76:79]
	v_mfma_f32_16x16x32_bf16 v[72:75], v[178:181], v[202:205], v[72:75]
	v_mfma_f32_16x16x32_bf16 v[72:75], v[174:177], v[198:201], v[72:75]
	v_mfma_f32_16x16x32_bf16 v[64:67], v[174:177], v[206:209], v[64:67]
	v_mfma_f32_16x16x32_bf16 v[64:67], v[178:181], v[210:213], v[64:67]
	v_mfma_f32_16x16x32_bf16 v[68:71], v[170:173], v[210:213], v[68:71]
	v_mfma_f32_16x16x32_bf16 v[68:71], v[166:169], v[206:209], v[68:71]
	s_setprio 0
	s_barrier
	s_add_i32 s46, s33, s79
	v_lshl_add_u64 v[146:147], s[70:71], 0, v[128:129]
	s_mov_b32 m0, s46
	ds_read_b128 v[182:185], v153 offset:16384
	ds_read_b128 v[186:189], v153 offset:17408
	ds_read_b128 v[190:193], v153 offset:18432
	ds_read_b128 v[194:197], v153 offset:19456
	ds_read_b128 v[198:201], v153 offset:20480
	ds_read_b128 v[202:205], v153 offset:21504
	ds_read_b128 v[206:209], v153 offset:22528
	ds_read_b128 v[210:213], v153 offset:23552
	global_load_lds_dwordx4 v[146:147], off
	s_add_i32 m0, s46, 0x2000
	s_add_u32 s46, s70, 0x160000
	v_lshl_add_u64 v[214:215], s[70:71], 0, v[130:131]
	s_addc_u32 s47, s71, 0
	s_add_i32 s74, s96, s79
	global_load_lds_dwordx4 v[214:215], off
	v_lshl_add_u64 v[216:217], s[46:47], 0, v[128:129]
	s_mov_b32 m0, s74
	v_lshl_add_u64 v[218:219], s[72:73], 0, v[134:135]
	global_load_lds_dwordx4 v[216:217], off
	v_lshl_add_u64 v[216:217], s[46:47], 0, v[130:131]
	s_add_i32 m0, s74, 0x2000
	s_nop 0
	global_load_lds_dwordx4 v[216:217], off
	v_lshl_add_u64 v[216:217], s[72:73], 0, v[132:133]
	s_mov_b32 m0, s87
	s_nop 0
	global_load_lds_dwordx4 v[216:217], off
	s_mov_b32 m0, s88
	s_nop 0
	global_load_lds_dwordx4 v[218:219], off
	s_waitcnt vmcnt(8)
	s_waitcnt lgkmcnt(0)
	s_barrier
; #define PG8_STAGE(bufoff, gbase, voff) do { _Pragma("unroll") for (int _i = 0; _i < 2; ++_i) \
;         __builtin_amdgcn_global_load_lds((const unsigned*)((const char*)(gbase) + (voff)[_i]), (PG8_LAS unsigned*)(lds + (bufoff) + ldsw + _i * 8192), 16, 0, 0); } while (0)
; #define PG8_LDA(dst, b, h) do { _Pragma("unroll") for (int m = 0; m < 4; ++m) _Pragma("unroll") for (int k = 0; k < 2; ++k) dst[m][k] = *(const PG8_LAS bf16x8*)(lds + PG8_SA(b, h) + aoff + m * 2048 + k * 1024); } while (0)
; #define PG8_LDB(dst, b, h) do { _Pragma("unroll") for (int n = 0; n < 2; ++n) _Pragma("unroll") for (int k = 0; k < 2; ++k) dst[n][k] = *(const PG8_LAS bf16x8*)(lds + PG8_SB(b, h) + boff + n * 2048 + k * 1024); } while (0)
; #define PG8_MMA(ai, bj, At, Bt) do { __builtin_amdgcn_s_setprio(1); _Pragma("unroll") for (int m = 0; m < 4; ++m) _Pragma("unroll") for (int n = 0; n < 2; ++n) _Pragma("unroll") for (int k = 0; k < 2; ++k) \
;         acc[ai][bj][m][n] = __builtin_amdgcn_mfma_f32_16x16x32_bf16(Bt[n][k], At[m][k], acc[ai][bj][m][n], 0, 0, 0); __builtin_amdgcn_s_setprio(0); } while (0)
; #define PG8_WAIT_V(n) asm volatile("s_waitcnt vmcnt(" #n ")" ::: "memory")
; #define PG8_WAIT_L(n) asm volatile("s_waitcnt lgkmcnt(" #n ")" ::: "memory")
; #define PG8_BAR __builtin_amdgcn_s_barrier()
; #define PG8_SCHED __builtin_amdgcn_sched_barrier(0)
; template <class Epi, class Sched, bool ALIGN_EPI = false, bool SP2 = false, bool APERM = false  >
; __device__ __forceinline__ void gemm_phase(PG8_LAS unsigned char* lds, const Gemm g, const Sched& S, const Epi& E, const int wid  ) {
;     ...
;             PG8_WAIT_V(8); PG8_WAIT_L(0); PG8_BAR; PG8_MMA(1, 0, At, B0); PG8_MMA(1, 1, At, B1); PG8_BAR; PG8_SCHED;
;             PG8_LDB(B0, 1, 0); PG8_LDB(B1, 1, 1); PG8_SCHED; PG8_LDA(At, 1, 0); PG8_STAGE(PG8_SA(0, 1), a2 + hstep, voffA);
;             PG8_WAIT_V(8); PG8_WAIT_L(0); PG8_BAR; PG8_MMA(0, 0, At, B0); PG8_MMA(0, 1, At, B1); PG8_BAR; PG8_SCHED;
	s_setprio 1
	s_waitcnt lgkmcnt(0)
	v_mfma_f32_16x16x32_bf16 v[60:63], v[142:145], v[182:185], v[60:63]
	v_mfma_f32_16x16x32_bf16 v[60:63], v[154:157], v[186:189], v[60:63]
	v_mfma_f32_16x16x32_bf16 v[56:59], v[162:165], v[186:189], v[56:59]
	v_mfma_f32_16x16x32_bf16 v[56:59], v[158:161], v[182:185], v[56:59]
	v_mfma_f32_16x16x32_bf16 v[48:51], v[158:161], v[190:193], v[48:51]
	v_mfma_f32_16x16x32_bf16 v[48:51], v[162:165], v[194:197], v[48:51]
	v_mfma_f32_16x16x32_bf16 v[52:55], v[154:157], v[194:197], v[52:55]
	v_mfma_f32_16x16x32_bf16 v[52:55], v[142:145], v[190:193], v[52:55]
	v_mfma_f32_16x16x32_bf16 v[44:47], v[142:145], v[198:201], v[44:47]
	v_mfma_f32_16x16x32_bf16 v[44:47], v[154:157], v[202:205], v[44:47]
	v_mfma_f32_16x16x32_bf16 v[40:43], v[162:165], v[202:205], v[40:43]
	v_mfma_f32_16x16x32_bf16 v[40:43], v[158:161], v[198:201], v[40:43]
	v_mfma_f32_16x16x32_bf16 v[32:35], v[158:161], v[206:209], v[32:35]
	v_mfma_f32_16x16x32_bf16 v[32:35], v[162:165], v[210:213], v[32:35]
	v_mfma_f32_16x16x32_bf16 v[36:39], v[154:157], v[210:213], v[36:39]
	v_mfma_f32_16x16x32_bf16 v[36:39], v[142:145], v[206:209], v[36:39]
	s_setprio 0
	s_setprio 1
	v_mfma_f32_16x16x32_bf16 v[28:31], v[166:169], v[182:185], v[28:31]
	v_mfma_f32_16x16x32_bf16 v[28:31], v[170:173], v[186:189], v[28:31]
	v_mfma_f32_16x16x32_bf16 v[24:27], v[178:181], v[186:189], v[24:27]
	v_mfma_f32_16x16x32_bf16 v[24:27], v[174:177], v[182:185], v[24:27]
	v_mfma_f32_16x16x32_bf16 v[16:19], v[174:177], v[190:193], v[16:19]
	v_mfma_f32_16x16x32_bf16 v[16:19], v[178:181], v[194:197], v[16:19]
	v_mfma_f32_16x16x32_bf16 v[20:23], v[170:173], v[194:197], v[20:23]
	v_mfma_f32_16x16x32_bf16 v[20:23], v[166:169], v[190:193], v[20:23]
	v_mfma_f32_16x16x32_bf16 v[12:15], v[166:169], v[198:201], v[12:15]
	v_mfma_f32_16x16x32_bf16 v[12:15], v[170:173], v[202:205], v[12:15]
	v_mfma_f32_16x16x32_bf16 v[8:11], v[178:181], v[202:205], v[8:11]
	v_mfma_f32_16x16x32_bf16 v[8:11], v[174:177], v[198:201], v[8:11]
	v_mfma_f32_16x16x32_bf16 v[0:3], v[174:177], v[206:209], v[0:3]
	v_mfma_f32_16x16x32_bf16 v[0:3], v[178:181], v[210:213], v[0:3]
	v_mfma_f32_16x16x32_bf16 v[4:7], v[170:173], v[210:213], v[4:7]
	v_mfma_f32_16x16x32_bf16 v[4:7], v[166:169], v[206:209], v[4:7]
	s_setprio 0
	s_barrier
	s_add_i32 s74, 0, 0x18000
	s_add_i32 s75, 0, 0x1c000
	v_add_u32_e32 v162, s74, v150
	v_add_u32_e32 v178, s75, v150
	ds_read_b128 v[142:145], v162
	ds_read_b128 v[154:157], v162 offset:1024
	ds_read_b128 v[158:161], v162 offset:2048
	ds_read_b128 v[162:165], v162 offset:3072
	ds_read_b128 v[166:169], v178
	ds_read_b128 v[170:173], v178 offset:1024
	ds_read_b128 v[174:177], v178 offset:2048
	ds_read_b128 v[178:181], v178 offset:3072
	s_add_u32 s46, s72, 0x160000
	s_addc_u32 s47, s73, 0
	s_mov_b32 m0, s89
	v_lshl_add_u64 v[220:221], s[46:47], 0, v[132:133]
	ds_read_b128 v[182:185], v153 offset:32768
	ds_read_b128 v[186:189], v153 offset:33792
	ds_read_b128 v[190:193], v153 offset:34816
	ds_read_b128 v[194:197], v153 offset:35840
	ds_read_b128 v[198:201], v153 offset:36864
	ds_read_b128 v[202:205], v153 offset:37888
	ds_read_b128 v[206:209], v153 offset:38912
	ds_read_b128 v[210:213], v153 offset:39936
	global_load_lds_dwordx4 v[220:221], off
	v_lshl_add_u64 v[220:221], s[46:47], 0, v[134:135]
	s_mov_b32 m0, s90
	s_nop 0
	global_load_lds_dwordx4 v[220:221], off
	s_waitcnt vmcnt(8)
	s_waitcnt lgkmcnt(0)
	s_barrier
	s_setprio 1
	s_waitcnt lgkmcnt(0)
	v_mfma_f32_16x16x32_bf16 v[124:127], v[142:145], v[182:185], v[124:127]
	v_mfma_f32_16x16x32_bf16 v[124:127], v[154:157], v[186:189], v[124:127]
	v_mfma_f32_16x16x32_bf16 v[120:123], v[162:165], v[186:189], v[120:123]
	v_mfma_f32_16x16x32_bf16 v[120:123], v[158:161], v[182:185], v[120:123]
	v_mfma_f32_16x16x32_bf16 v[112:115], v[158:161], v[190:193], v[112:115]
	v_mfma_f32_16x16x32_bf16 v[112:115], v[162:165], v[194:197], v[112:115]
	v_mfma_f32_16x16x32_bf16 v[116:119], v[154:157], v[194:197], v[116:119]
	v_mfma_f32_16x16x32_bf16 v[116:119], v[142:145], v[190:193], v[116:119]
	v_mfma_f32_16x16x32_bf16 v[108:111], v[142:145], v[198:201], v[108:111]
	v_mfma_f32_16x16x32_bf16 v[108:111], v[154:157], v[202:205], v[108:111]
	v_mfma_f32_16x16x32_bf16 v[104:107], v[162:165], v[202:205], v[104:107]
	v_mfma_f32_16x16x32_bf16 v[104:107], v[158:161], v[198:201], v[104:107]
	v_mfma_f32_16x16x32_bf16 v[96:99], v[158:161], v[206:209], v[96:99]
	v_mfma_f32_16x16x32_bf16 v[96:99], v[162:165], v[210:213], v[96:99]
	v_mfma_f32_16x16x32_bf16 v[100:103], v[154:157], v[210:213], v[100:103]
	v_mfma_f32_16x16x32_bf16 v[100:103], v[142:145], v[206:209], v[100:103]
	s_setprio 0
	s_setprio 1
	v_mfma_f32_16x16x32_bf16 v[92:95], v[166:169], v[182:185], v[92:95]
	v_mfma_f32_16x16x32_bf16 v[92:95], v[170:173], v[186:189], v[92:95]
	v_mfma_f32_16x16x32_bf16 v[88:91], v[178:181], v[186:189], v[88:91]
	v_mfma_f32_16x16x32_bf16 v[88:91], v[174:177], v[182:185], v[88:91]
	v_mfma_f32_16x16x32_bf16 v[80:83], v[174:177], v[190:193], v[80:83]
	v_mfma_f32_16x16x32_bf16 v[80:83], v[178:181], v[194:197], v[80:83]
	v_mfma_f32_16x16x32_bf16 v[84:87], v[170:173], v[194:197], v[84:87]
	v_mfma_f32_16x16x32_bf16 v[84:87], v[166:169], v[190:193], v[84:87]
	v_mfma_f32_16x16x32_bf16 v[76:79], v[166:169], v[198:201], v[76:79]
	v_mfma_f32_16x16x32_bf16 v[76:79], v[170:173], v[202:205], v[76:79]
	v_mfma_f32_16x16x32_bf16 v[72:75], v[178:181], v[202:205], v[72:75]
	v_mfma_f32_16x16x32_bf16 v[72:75], v[174:177], v[198:201], v[72:75]
	v_mfma_f32_16x16x32_bf16 v[64:67], v[174:177], v[206:209], v[64:67]
	v_mfma_f32_16x16x32_bf16 v[64:67], v[178:181], v[210:213], v[64:67]
	v_mfma_f32_16x16x32_bf16 v[68:71], v[170:173], v[210:213], v[68:71]
	v_mfma_f32_16x16x32_bf16 v[68:71], v[166:169], v[206:209], v[68:71]
	s_setprio 0
	s_barrier
; #define PG8_STAGE(bufoff, gbase, voff) do { _Pragma("unroll") for (int _i = 0; _i < 2; ++_i) \
;         __builtin_amdgcn_global_load_lds((const unsigned*)((const char*)(gbase) + (voff)[_i]), (PG8_LAS unsigned*)(lds + (bufoff) + ldsw + _i * 8192), 16, 0, 0); } while (0)
; #define PG8_LDA(dst, b, h) do { _Pragma("unroll") for (int m = 0; m < 4; ++m) _Pragma("unroll") for (int k = 0; k < 2; ++k) dst[m][k] = *(const PG8_LAS bf16x8*)(lds + PG8_SA(b, h) + aoff + m * 2048 + k * 1024); } while (0)
; #define PG8_MMA(ai, bj, At, Bt) do { __builtin_amdgcn_s_setprio(1); _Pragma("unroll") for (int m = 0; m < 4; ++m) _Pragma("unroll") for (int n = 0; n < 2; ++n) _Pragma("unroll") for (int k = 0; k < 2; ++k) \
;         acc[ai][bj][m][n] = __builtin_amdgcn_mfma_f32_16x16x32_bf16(Bt[n][k], At[m][k], acc[ai][bj][m][n], 0, 0, 0); __builtin_amdgcn_s_setprio(0); } while (0)
; #define PG8_WAIT_V(n) asm volatile("s_waitcnt vmcnt(" #n ")" ::: "memory")
; #define PG8_WAIT_L(n) asm volatile("s_waitcnt lgkmcnt(" #n ")" ::: "memory")
; #define PG8_BAR __builtin_amdgcn_s_barrier()
; #define PG8_SCHED __builtin_amdgcn_sched_barrier(0)
; template <class Epi, class Sched, bool ALIGN_EPI = false, bool SP2 = false, bool APERM = false  >
; __device__ __forceinline__ void gemm_phase(PG8_LAS unsigned char* lds, const Gemm g, const Sched& S, const Epi& E, const int wid  ) {
;     ...
;         for (int t = 0; t < nt; t += 2) {
;             const bool last = (t == nt - 2);
;     ...
;             PG8_LDA(At, 1, 1); PG8_STAGE(PG8_SB(1, 0), b3, voffB); PG8_STAGE(PG8_SB(1, 1), b3 + hstep, voffB); PG8_STAGE(PG8_SA(1, 0), a3, voffA);
;             PG8_WAIT_V(8); PG8_WAIT_L(0); PG8_BAR; PG8_MMA(1, 0, At, B0); PG8_MMA(1, 1, At, B1); PG8_BAR; PG8_SCHED;
	s_add_i32 s46, s74, s79
	v_lshl_add_u64 v[146:147], v[146:147], 0, s[24:25]
	s_mov_b32 m0, s46
	ds_read_b128 v[182:185], v153 offset:49152
	ds_read_b128 v[186:189], v153 offset:50176
	ds_read_b128 v[190:193], v153 offset:51200
	ds_read_b128 v[194:197], v153 offset:52224
	ds_read_b128 v[198:201], v153 offset:53248
	ds_read_b128 v[202:205], v153 offset:54272
	ds_read_b128 v[206:209], v153 offset:55296
	ds_read_b128 v[210:213], v153 offset:56320
	global_load_lds_dwordx4 v[146:147], off
	s_add_i32 m0, s46, 0x2000
	s_add_u32 s46, s70, 0x160080
	v_lshl_add_u64 v[146:147], v[214:215], 0, s[24:25]
	s_addc_u32 s47, s71, 0
	s_add_i32 s70, s75, s79
	global_load_lds_dwordx4 v[146:147], off
	v_lshl_add_u64 v[146:147], s[46:47], 0, v[128:129]
	s_mov_b32 m0, s70
	s_nop 0
	global_load_lds_dwordx4 v[146:147], off
	v_lshl_add_u64 v[146:147], s[46:47], 0, v[130:131]
	s_add_i32 m0, s70, 0x2000
	s_nop 0
	global_load_lds_dwordx4 v[146:147], off
	v_lshl_add_u64 v[146:147], v[216:217], 0, s[24:25]
	s_mov_b32 m0, s93
	s_nop 0
	global_load_lds_dwordx4 v[146:147], off
	v_lshl_add_u64 v[146:147], v[218:219], 0, s[24:25]
	s_mov_b32 m0, s95
	s_nop 0
	global_load_lds_dwordx4 v[146:147], off
	s_waitcnt vmcnt(8)
	s_waitcnt lgkmcnt(0)
	s_barrier
	s_setprio 1
	s_waitcnt lgkmcnt(0)
	v_mfma_f32_16x16x32_bf16 v[60:63], v[142:145], v[182:185], v[60:63]
	v_mfma_f32_16x16x32_bf16 v[60:63], v[154:157], v[186:189], v[60:63]
	v_mfma_f32_16x16x32_bf16 v[56:59], v[162:165], v[186:189], v[56:59]
	v_mfma_f32_16x16x32_bf16 v[56:59], v[158:161], v[182:185], v[56:59]
	v_mfma_f32_16x16x32_bf16 v[48:51], v[158:161], v[190:193], v[48:51]
	v_mfma_f32_16x16x32_bf16 v[48:51], v[162:165], v[194:197], v[48:51]
	v_mfma_f32_16x16x32_bf16 v[52:55], v[154:157], v[194:197], v[52:55]
	v_mfma_f32_16x16x32_bf16 v[52:55], v[142:145], v[190:193], v[52:55]
	v_mfma_f32_16x16x32_bf16 v[44:47], v[142:145], v[198:201], v[44:47]
	v_mfma_f32_16x16x32_bf16 v[44:47], v[154:157], v[202:205], v[44:47]
	v_mfma_f32_16x16x32_bf16 v[40:43], v[162:165], v[202:205], v[40:43]
	v_mfma_f32_16x16x32_bf16 v[40:43], v[158:161], v[198:201], v[40:43]
	v_mfma_f32_16x16x32_bf16 v[32:35], v[158:161], v[206:209], v[32:35]
	v_mfma_f32_16x16x32_bf16 v[32:35], v[162:165], v[210:213], v[32:35]
	v_mfma_f32_16x16x32_bf16 v[36:39], v[154:157], v[210:213], v[36:39]
	v_mfma_f32_16x16x32_bf16 v[36:39], v[142:145], v[206:209], v[36:39]
	s_setprio 0
	s_setprio 1
	v_mfma_f32_16x16x32_bf16 v[28:31], v[166:169], v[182:185], v[28:31]
	v_mfma_f32_16x16x32_bf16 v[28:31], v[170:173], v[186:189], v[28:31]
	v_mfma_f32_16x16x32_bf16 v[24:27], v[178:181], v[186:189], v[24:27]
	v_mfma_f32_16x16x32_bf16 v[24:27], v[174:177], v[182:185], v[24:27]
	v_mfma_f32_16x16x32_bf16 v[16:19], v[174:177], v[190:193], v[16:19]
	v_mfma_f32_16x16x32_bf16 v[16:19], v[178:181], v[194:197], v[16:19]
	v_mfma_f32_16x16x32_bf16 v[20:23], v[170:173], v[194:197], v[20:23]
	v_mfma_f32_16x16x32_bf16 v[20:23], v[166:169], v[190:193], v[20:23]
	v_mfma_f32_16x16x32_bf16 v[12:15], v[166:169], v[198:201], v[12:15]
	v_mfma_f32_16x16x32_bf16 v[12:15], v[170:173], v[202:205], v[12:15]
	v_mfma_f32_16x16x32_bf16 v[8:11], v[178:181], v[202:205], v[8:11]
	v_mfma_f32_16x16x32_bf16 v[8:11], v[174:177], v[198:201], v[8:11]
	v_mfma_f32_16x16x32_bf16 v[0:3], v[174:177], v[206:209], v[0:3]
	v_mfma_f32_16x16x32_bf16 v[0:3], v[178:181], v[210:213], v[0:3]
	v_mfma_f32_16x16x32_bf16 v[4:7], v[170:173], v[210:213], v[4:7]
	v_mfma_f32_16x16x32_bf16 v[4:7], v[166:169], v[206:209], v[4:7]
	s_setprio 0
	s_barrier
	s_add_i32 s46, s53, 2
	s_cmp_gt_u32 s53, 41
	s_cbranch_scc1 .LBB0_1254
	s_mov_b32 s53, s46
	s_branch .LBB0_1235

; #define PG8_STAGE(bufoff, gbase, voff) do { _Pragma("unroll") for (int _i = 0; _i < 2; ++_i) \
;         __builtin_amdgcn_global_load_lds((const unsigned*)((const char*)(gbase) + (voff)[_i]), (PG8_LAS unsigned*)(lds + (bufoff) + ldsw + _i * 8192), 16, 0, 0); } while (0)
; #define PG8_LDA(dst, b, h) do { _Pragma("unroll") for (int m = 0; m < 4; ++m) _Pragma("unroll") for (int k = 0; k < 2; ++k) dst[m][k] = *(const PG8_LAS bf16x8*)(lds + PG8_SA(b, h) + aoff + m * 2048 + k * 1024); } while (0)
; #define PG8_LDB(dst, b, h) do { _Pragma("unroll") for (int n = 0; n < 2; ++n) _Pragma("unroll") for (int k = 0; k < 2; ++k) dst[n][k] = *(const PG8_LAS bf16x8*)(lds + PG8_SB(b, h) + boff + n * 2048 + k * 1024); } while (0)
; #define PG8_MMA(ai, bj, At, Bt) do { __builtin_amdgcn_s_setprio(1); _Pragma("unroll") for (int m = 0; m < 4; ++m) _Pragma("unroll") for (int n = 0; n < 2; ++n) _Pragma("unroll") for (int k = 0; k < 2; ++k) \
;         acc[ai][bj][m][n] = __builtin_amdgcn_mfma_f32_16x16x32_bf16(Bt[n][k], At[m][k], acc[ai][bj][m][n], 0, 0, 0); __builtin_amdgcn_s_setprio(0); } while (0)
; #define PG8_WAIT_V(n) asm volatile("s_waitcnt vmcnt(" #n ")" ::: "memory")
; #define PG8_WAIT_L(n) asm volatile("s_waitcnt lgkmcnt(" #n ")" ::: "memory")
; template <class Epi, class Sched, bool ALIGN_EPI = false, bool SP2 = false, bool APERM = false  >
; __device__ __forceinline__ void gemm_phase(PG8_LAS unsigned char* lds, const Gemm g, const Sched& S, const Epi& E, const int wid  ) {
;     ...
;             const bool last = (t == nt - 2);
;             const char* a1 = cA + (size_t)(t + 1) * kstep;
;             const char* a2 = last ? nA : cA + (size_t)(t + 2) * kstep; const char* b2 = last ? nB : cB + (size_t)(t + 2) * kstep;
;             const char* a3 = a2 + kstep; const char* b3 = b2 + kstep;
;             if (last && has_next) S.a_ready(nxt);
;             if constexpr (SP2) {
;             PG8_LDB(B0, 0, 0); PG8_LDB(B1, 0, 1); PG8_SCHED; PG8_LDA(At, 0, 0); PG8_STAGE(PG8_SA(1, 1), a1 + hstep, voffA);
;             PG8_WAIT_V(8); PG8_WAIT_L(0); PG8_BAR; PG8_MMA(0, 0, At, B0); PG8_MMA(0, 1, At, B1); PG8_BAR; PG8_SCHED;
;             PG8_LDA(At, 0, 1); PG8_STAGE(PG8_SB(0, 0), b2, voffB); PG8_STAGE(PG8_SB(0, 1), b2 + hstep, voffB); PG8_STAGE(PG8_SA(0, 0), a2, voffA);
;             PG8_WAIT_V(8); PG8_WAIT_L(0); PG8_BAR; PG8_MMA(1, 0, At, B0); PG8_MMA(1, 1, At, B1); PG8_BAR; PG8_SCHED;
.LBB0_1314:
	s_or_b32 s36, s78, 1
	v_add_u32_e32 v159, s52, v153
	s_lshl_b64 s[74:75], s[36:37], 7
	s_add_i32 s36, s78, 2
	s_waitcnt lgkmcnt(0)
	ds_read_b128 v[144:147], v159
	ds_read_b128 v[148:151], v159 offset:1024
	ds_read_b128 v[160:163], v159 offset:2048
	ds_read_b128 v[164:167], v159 offset:3072
	v_add_u32_e32 v159, s95, v153
	s_lshl_b64 s[76:77], s[36:37], 7
	ds_read_b128 v[168:171], v159
	ds_read_b128 v[172:175], v159 offset:1024
	ds_read_b128 v[176:179], v159 offset:2048
	ds_read_b128 v[180:183], v159 offset:3072
	s_add_u32 vcc_lo, s14, s76
	s_addc_u32 vcc_hi, s15, s77
	s_and_b64 s[72:73], s[70:71], exec
	s_cselect_b32 s73, s25, vcc_hi
	s_cselect_b32 s72, s24, vcc_lo
	s_add_u32 s76, s10, s76
	s_addc_u32 s77, s11, s77
	s_and_b64 s[70:71], s[70:71], exec
	s_cselect_b32 s71, s29, s77
	s_cselect_b32 s70, s28, s76
	s_add_u32 s74, s33, s74
	s_addc_u32 s75, s53, s75
	v_lshl_add_u64 v[216:217], s[74:75], 0, v[132:133]
	s_add_i32 m0, s85, 0xc000
	ds_read_b128 v[184:187], v158
	ds_read_b128 v[188:191], v158 offset:1024
	ds_read_b128 v[192:195], v158 offset:2048
	ds_read_b128 v[196:199], v158 offset:3072
	ds_read_b128 v[200:203], v158 offset:4096
	ds_read_b128 v[204:207], v158 offset:5120
	ds_read_b128 v[208:211], v158 offset:6144
	ds_read_b128 v[212:215], v158 offset:7168
	global_load_lds_dwordx4 v[216:217], off
	v_lshl_add_u64 v[216:217], s[74:75], 0, v[136:137]
	s_add_i32 m0, s85, 0xe000
	s_nop 0
	global_load_lds_dwordx4 v[216:217], off
	s_waitcnt vmcnt(8)
	s_waitcnt lgkmcnt(0)
	s_barrier
	s_setprio 1
	s_waitcnt lgkmcnt(0)
	v_mfma_f32_16x16x32_bf16 v[124:127], v[144:147], v[184:187], v[124:127]
	v_mfma_f32_16x16x32_bf16 v[124:127], v[148:151], v[188:191], v[124:127]
	v_mfma_f32_16x16x32_bf16 v[120:123], v[164:167], v[188:191], v[120:123]
	v_mfma_f32_16x16x32_bf16 v[120:123], v[160:163], v[184:187], v[120:123]
	v_mfma_f32_16x16x32_bf16 v[112:115], v[160:163], v[192:195], v[112:115]
	v_mfma_f32_16x16x32_bf16 v[112:115], v[164:167], v[196:199], v[112:115]
	v_mfma_f32_16x16x32_bf16 v[116:119], v[148:151], v[196:199], v[116:119]
	v_mfma_f32_16x16x32_bf16 v[116:119], v[144:147], v[192:195], v[116:119]
	v_mfma_f32_16x16x32_bf16 v[108:111], v[144:147], v[200:203], v[108:111]
	v_mfma_f32_16x16x32_bf16 v[108:111], v[148:151], v[204:207], v[108:111]
	v_mfma_f32_16x16x32_bf16 v[104:107], v[164:167], v[204:207], v[104:107]
	v_mfma_f32_16x16x32_bf16 v[104:107], v[160:163], v[200:203], v[104:107]
	v_mfma_f32_16x16x32_bf16 v[96:99], v[160:163], v[208:211], v[96:99]
	v_mfma_f32_16x16x32_bf16 v[96:99], v[164:167], v[212:215], v[96:99]
	v_mfma_f32_16x16x32_bf16 v[100:103], v[148:151], v[212:215], v[100:103]
	v_mfma_f32_16x16x32_bf16 v[100:103], v[144:147], v[208:211], v[100:103]
	s_setprio 0
	s_setprio 1
	v_mfma_f32_16x16x32_bf16 v[92:95], v[168:171], v[184:187], v[92:95]
	v_mfma_f32_16x16x32_bf16 v[92:95], v[172:175], v[188:191], v[92:95]
	v_mfma_f32_16x16x32_bf16 v[88:91], v[180:183], v[188:191], v[88:91]
	v_mfma_f32_16x16x32_bf16 v[88:91], v[176:179], v[184:187], v[88:91]
	v_mfma_f32_16x16x32_bf16 v[80:83], v[176:179], v[192:195], v[80:83]
	v_mfma_f32_16x16x32_bf16 v[80:83], v[180:183], v[196:199], v[80:83]
	v_mfma_f32_16x16x32_bf16 v[84:87], v[172:175], v[196:199], v[84:87]
	v_mfma_f32_16x16x32_bf16 v[84:87], v[168:171], v[192:195], v[84:87]
	v_mfma_f32_16x16x32_bf16 v[76:79], v[168:171], v[200:203], v[76:79]
	v_mfma_f32_16x16x32_bf16 v[76:79], v[172:175], v[204:207], v[76:79]
	v_mfma_f32_16x16x32_bf16 v[72:75], v[180:183], v[204:207], v[72:75]
	v_mfma_f32_16x16x32_bf16 v[72:75], v[176:179], v[200:203], v[72:75]
	v_mfma_f32_16x16x32_bf16 v[64:67], v[176:179], v[208:211], v[64:67]
	v_mfma_f32_16x16x32_bf16 v[64:67], v[180:183], v[212:215], v[64:67]
	v_mfma_f32_16x16x32_bf16 v[68:71], v[172:175], v[212:215], v[68:71]
	v_mfma_f32_16x16x32_bf16 v[68:71], v[168:171], v[208:211], v[68:71]
	s_setprio 0
	s_barrier
	s_add_i32 s74, s52, s79
	v_lshl_add_u64 v[216:217], s[70:71], 0, v[128:129]
	s_mov_b32 m0, s74
	ds_read_b128 v[184:187], v158 offset:16384
	ds_read_b128 v[188:191], v158 offset:17408
	ds_read_b128 v[192:195], v158 offset:18432
	ds_read_b128 v[196:199], v158 offset:19456
	ds_read_b128 v[200:203], v158 offset:20480
	ds_read_b128 v[204:207], v158 offset:21504
	ds_read_b128 v[208:211], v158 offset:22528
	ds_read_b128 v[212:215], v158 offset:23552
	global_load_lds_dwordx4 v[216:217], off
	s_add_i32 m0, s74, 0x2000
	s_add_u32 s74, s70, 0x160000
	v_lshl_add_u64 v[218:219], s[70:71], 0, v[130:131]
	s_addc_u32 s75, s71, 0
	s_add_i32 s76, s95, s79
	global_load_lds_dwordx4 v[218:219], off
	v_lshl_add_u64 v[220:221], s[74:75], 0, v[128:129]
	s_mov_b32 m0, s76
	v_lshl_add_u64 v[222:223], s[72:73], 0, v[136:137]
	global_load_lds_dwordx4 v[220:221], off
	v_lshl_add_u64 v[220:221], s[74:75], 0, v[130:131]
	s_add_i32 m0, s76, 0x2000
	s_nop 0
	global_load_lds_dwordx4 v[220:221], off
	v_lshl_add_u64 v[220:221], s[72:73], 0, v[132:133]
	s_mov_b32 m0, s85
	s_nop 0
	global_load_lds_dwordx4 v[220:221], off
	s_mov_b32 m0, s88
	s_nop 0
	global_load_lds_dwordx4 v[222:223], off
	s_waitcnt vmcnt(8)
	s_waitcnt lgkmcnt(0)
	s_barrier
; #define PG8_STAGE(bufoff, gbase, voff) do { _Pragma("unroll") for (int _i = 0; _i < 2; ++_i) \
;         __builtin_amdgcn_global_load_lds((const unsigned*)((const char*)(gbase) + (voff)[_i]), (PG8_LAS unsigned*)(lds + (bufoff) + ldsw + _i * 8192), 16, 0, 0); } while (0)
; #define PG8_LDA(dst, b, h) do { _Pragma("unroll") for (int m = 0; m < 4; ++m) _Pragma("unroll") for (int k = 0; k < 2; ++k) dst[m][k] = *(const PG8_LAS bf16x8*)(lds + PG8_SA(b, h) + aoff + m * 2048 + k * 1024); } while (0)
; #define PG8_LDB(dst, b, h) do { _Pragma("unroll") for (int n = 0; n < 2; ++n) _Pragma("unroll") for (int k = 0; k < 2; ++k) dst[n][k] = *(const PG8_LAS bf16x8*)(lds + PG8_SB(b, h) + boff + n * 2048 + k * 1024); } while (0)
; #define PG8_MMA(ai, bj, At, Bt) do { __builtin_amdgcn_s_setprio(1); _Pragma("unroll") for (int m = 0; m < 4; ++m) _Pragma("unroll") for (int n = 0; n < 2; ++n) _Pragma("unroll") for (int k = 0; k < 2; ++k) \
;         acc[ai][bj][m][n] = __builtin_amdgcn_mfma_f32_16x16x32_bf16(Bt[n][k], At[m][k], acc[ai][bj][m][n], 0, 0, 0); __builtin_amdgcn_s_setprio(0); } while (0)
; #define PG8_WAIT_V(n) asm volatile("s_waitcnt vmcnt(" #n ")" ::: "memory")
; #define PG8_WAIT_L(n) asm volatile("s_waitcnt lgkmcnt(" #n ")" ::: "memory")
; #define PG8_BAR __builtin_amdgcn_s_barrier()
; #define PG8_SCHED __builtin_amdgcn_sched_barrier(0)
; template <class Epi, class Sched, bool ALIGN_EPI = false, bool SP2 = false, bool APERM = false  >
; __device__ __forceinline__ void gemm_phase(PG8_LAS unsigned char* lds, const Gemm g, const Sched& S, const Epi& E, const int wid  ) {
;     ...
;             PG8_WAIT_V(8); PG8_WAIT_L(0); PG8_BAR; PG8_MMA(1, 0, At, B0); PG8_MMA(1, 1, At, B1); PG8_BAR; PG8_SCHED;
;             PG8_LDB(B0, 1, 0); PG8_LDB(B1, 1, 1); PG8_SCHED; PG8_LDA(At, 1, 0); PG8_STAGE(PG8_SA(0, 1), a2 + hstep, voffA);
;             PG8_WAIT_V(8); PG8_WAIT_L(0); PG8_BAR; PG8_MMA(0, 0, At, B0); PG8_MMA(0, 1, At, B1); PG8_BAR; PG8_SCHED;
	s_setprio 1
	s_waitcnt lgkmcnt(0)
	v_mfma_f32_16x16x32_bf16 v[60:63], v[144:147], v[184:187], v[60:63]
	v_mfma_f32_16x16x32_bf16 v[60:63], v[148:151], v[188:191], v[60:63]
	v_mfma_f32_16x16x32_bf16 v[56:59], v[164:167], v[188:191], v[56:59]
	v_mfma_f32_16x16x32_bf16 v[56:59], v[160:163], v[184:187], v[56:59]
	v_mfma_f32_16x16x32_bf16 v[48:51], v[160:163], v[192:195], v[48:51]
	v_mfma_f32_16x16x32_bf16 v[48:51], v[164:167], v[196:199], v[48:51]
	v_mfma_f32_16x16x32_bf16 v[52:55], v[148:151], v[196:199], v[52:55]
	v_mfma_f32_16x16x32_bf16 v[52:55], v[144:147], v[192:195], v[52:55]
	v_mfma_f32_16x16x32_bf16 v[44:47], v[144:147], v[200:203], v[44:47]
	v_mfma_f32_16x16x32_bf16 v[44:47], v[148:151], v[204:207], v[44:47]
	v_mfma_f32_16x16x32_bf16 v[40:43], v[164:167], v[204:207], v[40:43]
	v_mfma_f32_16x16x32_bf16 v[40:43], v[160:163], v[200:203], v[40:43]
	v_mfma_f32_16x16x32_bf16 v[32:35], v[160:163], v[208:211], v[32:35]
	v_mfma_f32_16x16x32_bf16 v[32:35], v[164:167], v[212:215], v[32:35]
	v_mfma_f32_16x16x32_bf16 v[36:39], v[148:151], v[212:215], v[36:39]
	v_mfma_f32_16x16x32_bf16 v[36:39], v[144:147], v[208:211], v[36:39]
	s_setprio 0
	s_setprio 1
	v_mfma_f32_16x16x32_bf16 v[28:31], v[168:171], v[184:187], v[28:31]
	v_mfma_f32_16x16x32_bf16 v[28:31], v[172:175], v[188:191], v[28:31]
	v_mfma_f32_16x16x32_bf16 v[24:27], v[180:183], v[188:191], v[24:27]
	v_mfma_f32_16x16x32_bf16 v[24:27], v[176:179], v[184:187], v[24:27]
	v_mfma_f32_16x16x32_bf16 v[16:19], v[176:179], v[192:195], v[16:19]
	v_mfma_f32_16x16x32_bf16 v[16:19], v[180:183], v[196:199], v[16:19]
	v_mfma_f32_16x16x32_bf16 v[20:23], v[172:175], v[196:199], v[20:23]
	v_mfma_f32_16x16x32_bf16 v[20:23], v[168:171], v[192:195], v[20:23]
	v_mfma_f32_16x16x32_bf16 v[12:15], v[168:171], v[200:203], v[12:15]
	v_mfma_f32_16x16x32_bf16 v[12:15], v[172:175], v[204:207], v[12:15]
	v_mfma_f32_16x16x32_bf16 v[8:11], v[180:183], v[204:207], v[8:11]
	v_mfma_f32_16x16x32_bf16 v[8:11], v[176:179], v[200:203], v[8:11]
	v_mfma_f32_16x16x32_bf16 v[0:3], v[176:179], v[208:211], v[0:3]
	v_mfma_f32_16x16x32_bf16 v[0:3], v[180:183], v[212:215], v[0:3]
	v_mfma_f32_16x16x32_bf16 v[4:7], v[172:175], v[212:215], v[4:7]
	v_mfma_f32_16x16x32_bf16 v[4:7], v[168:171], v[208:211], v[4:7]
	s_setprio 0
	s_barrier
	s_add_i32 s74, 0, 0x18000
	v_add_u32_e32 v159, s74, v153
	s_add_i32 s75, 0, 0x1c000
	ds_read_b128 v[144:147], v159
	ds_read_b128 v[148:151], v159 offset:1024
	ds_read_b128 v[160:163], v159 offset:2048
	ds_read_b128 v[164:167], v159 offset:3072
	v_add_u32_e32 v159, s75, v153
	ds_read_b128 v[168:171], v159
	ds_read_b128 v[172:175], v159 offset:1024
	ds_read_b128 v[176:179], v159 offset:2048
	ds_read_b128 v[180:183], v159 offset:3072
	s_add_u32 s72, s72, 0x160000
	s_addc_u32 s73, s73, 0
	s_mov_b32 m0, s89
	v_lshl_add_u64 v[224:225], s[72:73], 0, v[132:133]
	ds_read_b128 v[184:187], v158 offset:32768
	ds_read_b128 v[188:191], v158 offset:33792
	ds_read_b128 v[192:195], v158 offset:34816
	ds_read_b128 v[196:199], v158 offset:35840
	ds_read_b128 v[200:203], v158 offset:36864
	ds_read_b128 v[204:207], v158 offset:37888
	ds_read_b128 v[208:211], v158 offset:38912
	ds_read_b128 v[212:215], v158 offset:39936
	global_load_lds_dwordx4 v[224:225], off
	v_lshl_add_u64 v[224:225], s[72:73], 0, v[136:137]
	s_mov_b32 m0, s90
	s_nop 0
	global_load_lds_dwordx4 v[224:225], off
	s_waitcnt vmcnt(8)
	s_waitcnt lgkmcnt(0)
	s_barrier
	s_setprio 1
	s_waitcnt lgkmcnt(0)
	v_mfma_f32_16x16x32_bf16 v[124:127], v[144:147], v[184:187], v[124:127]
	v_mfma_f32_16x16x32_bf16 v[124:127], v[148:151], v[188:191], v[124:127]
	v_mfma_f32_16x16x32_bf16 v[120:123], v[164:167], v[188:191], v[120:123]
	v_mfma_f32_16x16x32_bf16 v[120:123], v[160:163], v[184:187], v[120:123]
	v_mfma_f32_16x16x32_bf16 v[112:115], v[160:163], v[192:195], v[112:115]
	v_mfma_f32_16x16x32_bf16 v[112:115], v[164:167], v[196:199], v[112:115]
	v_mfma_f32_16x16x32_bf16 v[116:119], v[148:151], v[196:199], v[116:119]
	v_mfma_f32_16x16x32_bf16 v[116:119], v[144:147], v[192:195], v[116:119]
	v_mfma_f32_16x16x32_bf16 v[108:111], v[144:147], v[200:203], v[108:111]
	v_mfma_f32_16x16x32_bf16 v[108:111], v[148:151], v[204:207], v[108:111]
	v_mfma_f32_16x16x32_bf16 v[104:107], v[164:167], v[204:207], v[104:107]
	v_mfma_f32_16x16x32_bf16 v[104:107], v[160:163], v[200:203], v[104:107]
	v_mfma_f32_16x16x32_bf16 v[96:99], v[160:163], v[208:211], v[96:99]
	v_mfma_f32_16x16x32_bf16 v[96:99], v[164:167], v[212:215], v[96:99]
	v_mfma_f32_16x16x32_bf16 v[100:103], v[148:151], v[212:215], v[100:103]
	v_mfma_f32_16x16x32_bf16 v[100:103], v[144:147], v[208:211], v[100:103]
	s_setprio 0
	s_setprio 1
	v_mfma_f32_16x16x32_bf16 v[92:95], v[168:171], v[184:187], v[92:95]
	v_mfma_f32_16x16x32_bf16 v[92:95], v[172:175], v[188:191], v[92:95]
	v_mfma_f32_16x16x32_bf16 v[88:91], v[180:183], v[188:191], v[88:91]
	v_mfma_f32_16x16x32_bf16 v[88:91], v[176:179], v[184:187], v[88:91]
	v_mfma_f32_16x16x32_bf16 v[80:83], v[176:179], v[192:195], v[80:83]
	v_mfma_f32_16x16x32_bf16 v[80:83], v[180:183], v[196:199], v[80:83]
	v_mfma_f32_16x16x32_bf16 v[84:87], v[172:175], v[196:199], v[84:87]
	v_mfma_f32_16x16x32_bf16 v[84:87], v[168:171], v[192:195], v[84:87]
	v_mfma_f32_16x16x32_bf16 v[76:79], v[168:171], v[200:203], v[76:79]
	v_mfma_f32_16x16x32_bf16 v[76:79], v[172:175], v[204:207], v[76:79]
	v_mfma_f32_16x16x32_bf16 v[72:75], v[180:183], v[204:207], v[72:75]
	v_mfma_f32_16x16x32_bf16 v[72:75], v[176:179], v[200:203], v[72:75]
	v_mfma_f32_16x16x32_bf16 v[64:67], v[176:179], v[208:211], v[64:67]
	v_mfma_f32_16x16x32_bf16 v[64:67], v[180:183], v[212:215], v[64:67]
	v_mfma_f32_16x16x32_bf16 v[68:71], v[172:175], v[212:215], v[68:71]
	v_mfma_f32_16x16x32_bf16 v[68:71], v[168:171], v[208:211], v[68:71]
	s_setprio 0
	s_barrier
; #define PG8_STAGE(bufoff, gbase, voff) do { _Pragma("unroll") for (int _i = 0; _i < 2; ++_i) \
;         __builtin_amdgcn_global_load_lds((const unsigned*)((const char*)(gbase) + (voff)[_i]), (PG8_LAS unsigned*)(lds + (bufoff) + ldsw + _i * 8192), 16, 0, 0); } while (0)
; #define PG8_LDA(dst, b, h) do { _Pragma("unroll") for (int m = 0; m < 4; ++m) _Pragma("unroll") for (int k = 0; k < 2; ++k) dst[m][k] = *(const PG8_LAS bf16x8*)(lds + PG8_SA(b, h) + aoff + m * 2048 + k * 1024); } while (0)
; #define PG8_MMA(ai, bj, At, Bt) do { __builtin_amdgcn_s_setprio(1); _Pragma("unroll") for (int m = 0; m < 4; ++m) _Pragma("unroll") for (int n = 0; n < 2; ++n) _Pragma("unroll") for (int k = 0; k < 2; ++k) \
;         acc[ai][bj][m][n] = __builtin_amdgcn_mfma_f32_16x16x32_bf16(Bt[n][k], At[m][k], acc[ai][bj][m][n], 0, 0, 0); __builtin_amdgcn_s_setprio(0); } while (0)
; #define PG8_WAIT_V(n) asm volatile("s_waitcnt vmcnt(" #n ")" ::: "memory")
; #define PG8_WAIT_L(n) asm volatile("s_waitcnt lgkmcnt(" #n ")" ::: "memory")
; #define PG8_BAR __builtin_amdgcn_s_barrier()
; #define PG8_SCHED __builtin_amdgcn_sched_barrier(0)
; template <class Epi, class Sched, bool ALIGN_EPI = false, bool SP2 = false, bool APERM = false  >
; __device__ __forceinline__ void gemm_phase(PG8_LAS unsigned char* lds, const Gemm g, const Sched& S, const Epi& E, const int wid  ) {
;     ...
;         for (int t = 0; t < nt; t += 2) {
;             const bool last = (t == nt - 2);
;     ...
;             PG8_LDA(At, 1, 1); PG8_STAGE(PG8_SB(1, 0), b3, voffB); PG8_STAGE(PG8_SB(1, 1), b3 + hstep, voffB); PG8_STAGE(PG8_SA(1, 0), a3, voffA);
;             PG8_WAIT_V(8); PG8_WAIT_L(0); PG8_BAR; PG8_MMA(1, 0, At, B0); PG8_MMA(1, 1, At, B1); PG8_BAR; PG8_SCHED;
	s_add_i32 s72, s74, s79
	v_lshl_add_u64 v[216:217], v[216:217], 0, s[38:39]
	s_mov_b32 m0, s72
	ds_read_b128 v[184:187], v158 offset:49152
	ds_read_b128 v[188:191], v158 offset:50176
	ds_read_b128 v[192:195], v158 offset:51200
	ds_read_b128 v[196:199], v158 offset:52224
	ds_read_b128 v[200:203], v158 offset:53248
	ds_read_b128 v[204:207], v158 offset:54272
	ds_read_b128 v[208:211], v158 offset:55296
	ds_read_b128 v[212:215], v158 offset:56320
	global_load_lds_dwordx4 v[216:217], off
	s_add_i32 m0, s72, 0x2000
	s_add_u32 s70, s70, 0x160080
	v_lshl_add_u64 v[216:217], v[218:219], 0, s[38:39]
	s_addc_u32 s71, s71, 0
	s_add_i32 s72, s75, s79
	global_load_lds_dwordx4 v[216:217], off
	v_lshl_add_u64 v[216:217], s[70:71], 0, v[128:129]
	s_mov_b32 m0, s72
	s_nop 0
	global_load_lds_dwordx4 v[216:217], off
	v_lshl_add_u64 v[216:217], s[70:71], 0, v[130:131]
	s_add_i32 m0, s72, 0x2000
	s_nop 0
	global_load_lds_dwordx4 v[216:217], off
	v_lshl_add_u64 v[216:217], v[220:221], 0, s[38:39]
	s_mov_b32 m0, s93
	s_nop 0
	global_load_lds_dwordx4 v[216:217], off
	v_lshl_add_u64 v[216:217], v[222:223], 0, s[38:39]
	s_mov_b32 m0, s94
	s_nop 0
	global_load_lds_dwordx4 v[216:217], off
	s_waitcnt vmcnt(8)
	s_waitcnt lgkmcnt(0)
	s_barrier
	s_setprio 1
	s_waitcnt lgkmcnt(0)
	v_mfma_f32_16x16x32_bf16 v[60:63], v[144:147], v[184:187], v[60:63]
	v_mfma_f32_16x16x32_bf16 v[60:63], v[148:151], v[188:191], v[60:63]
	v_mfma_f32_16x16x32_bf16 v[56:59], v[164:167], v[188:191], v[56:59]
	v_mfma_f32_16x16x32_bf16 v[56:59], v[160:163], v[184:187], v[56:59]
	v_mfma_f32_16x16x32_bf16 v[48:51], v[160:163], v[192:195], v[48:51]
	v_mfma_f32_16x16x32_bf16 v[48:51], v[164:167], v[196:199], v[48:51]
	v_mfma_f32_16x16x32_bf16 v[52:55], v[148:151], v[196:199], v[52:55]
	v_mfma_f32_16x16x32_bf16 v[52:55], v[144:147], v[192:195], v[52:55]
	v_mfma_f32_16x16x32_bf16 v[44:47], v[144:147], v[200:203], v[44:47]
	v_mfma_f32_16x16x32_bf16 v[44:47], v[148:151], v[204:207], v[44:47]
	v_mfma_f32_16x16x32_bf16 v[40:43], v[164:167], v[204:207], v[40:43]
	v_mfma_f32_16x16x32_bf16 v[40:43], v[160:163], v[200:203], v[40:43]
	v_mfma_f32_16x16x32_bf16 v[32:35], v[160:163], v[208:211], v[32:35]
	v_mfma_f32_16x16x32_bf16 v[32:35], v[164:167], v[212:215], v[32:35]
	v_mfma_f32_16x16x32_bf16 v[36:39], v[148:151], v[212:215], v[36:39]
	v_mfma_f32_16x16x32_bf16 v[36:39], v[144:147], v[208:211], v[36:39]
	s_setprio 0
	s_setprio 1
	v_mfma_f32_16x16x32_bf16 v[28:31], v[168:171], v[184:187], v[28:31]
	v_mfma_f32_16x16x32_bf16 v[28:31], v[172:175], v[188:191], v[28:31]
	v_mfma_f32_16x16x32_bf16 v[24:27], v[180:183], v[188:191], v[24:27]
	v_mfma_f32_16x16x32_bf16 v[24:27], v[176:179], v[184:187], v[24:27]
	v_mfma_f32_16x16x32_bf16 v[16:19], v[176:179], v[192:195], v[16:19]
	v_mfma_f32_16x16x32_bf16 v[16:19], v[180:183], v[196:199], v[16:19]
	v_mfma_f32_16x16x32_bf16 v[20:23], v[172:175], v[196:199], v[20:23]
	v_mfma_f32_16x16x32_bf16 v[20:23], v[168:171], v[192:195], v[20:23]
	v_mfma_f32_16x16x32_bf16 v[12:15], v[168:171], v[200:203], v[12:15]
	v_mfma_f32_16x16x32_bf16 v[12:15], v[172:175], v[204:207], v[12:15]
	v_mfma_f32_16x16x32_bf16 v[8:11], v[180:183], v[204:207], v[8:11]
	v_mfma_f32_16x16x32_bf16 v[8:11], v[176:179], v[200:203], v[8:11]
	v_mfma_f32_16x16x32_bf16 v[0:3], v[176:179], v[208:211], v[0:3]
	v_mfma_f32_16x16x32_bf16 v[0:3], v[180:183], v[212:215], v[0:3]
	v_mfma_f32_16x16x32_bf16 v[4:7], v[172:175], v[212:215], v[4:7]
	v_mfma_f32_16x16x32_bf16 v[4:7], v[168:171], v[208:211], v[4:7]
	s_setprio 0
	s_barrier
	s_cmp_gt_u32 s78, 41
	s_cbranch_scc1 .LBB0_1316
	s_mov_b32 s78, s36
	s_branch .LBB0_1297

; #define PG8_STAGE(bufoff, gbase, voff) do { _Pragma("unroll") for (int _i = 0; _i < 2; ++_i) \
;         __builtin_amdgcn_global_load_lds((const unsigned*)((const char*)(gbase) + (voff)[_i]), (PG8_LAS unsigned*)(lds + (bufoff) + ldsw + _i * 8192), 16, 0, 0); } while (0)
; #define PG8_LDA(dst, b, h) do { _Pragma("unroll") for (int m = 0; m < 4; ++m) _Pragma("unroll") for (int k = 0; k < 2; ++k) dst[m][k] = *(const PG8_LAS bf16x8*)(lds + PG8_SA(b, h) + aoff + m * 2048 + k * 1024); } while (0)
; #define PG8_LDB(dst, b, h) do { _Pragma("unroll") for (int n = 0; n < 2; ++n) _Pragma("unroll") for (int k = 0; k < 2; ++k) dst[n][k] = *(const PG8_LAS bf16x8*)(lds + PG8_SB(b, h) + boff + n * 2048 + k * 1024); } while (0)
; #define PG8_MMA(ai, bj, At, Bt) do { __builtin_amdgcn_s_setprio(1); _Pragma("unroll") for (int m = 0; m < 4; ++m) _Pragma("unroll") for (int n = 0; n < 2; ++n) _Pragma("unroll") for (int k = 0; k < 2; ++k) \
;         acc[ai][bj][m][n] = __builtin_amdgcn_mfma_f32_16x16x32_bf16(Bt[n][k], At[m][k], acc[ai][bj][m][n], 0, 0, 0); __builtin_amdgcn_s_setprio(0); } while (0)
; #define PG8_WAIT_V(n) asm volatile("s_waitcnt vmcnt(" #n ")" ::: "memory")
; #define PG8_WAIT_L(n) asm volatile("s_waitcnt lgkmcnt(" #n ")" ::: "memory")
; template <class Epi, class Sched, bool ALIGN_EPI = false, bool SP2 = false, bool APERM = false  >
; __device__ __forceinline__ void gemm_phase(PG8_LAS unsigned char* lds, const Gemm g, const Sched& S, const Epi& E, const int wid  ) {
;     ...
;             const bool last = (t == nt - 2);
;             const char* a1 = cA + (size_t)(t + 1) * kstep;
;             const char* a2 = last ? nA : cA + (size_t)(t + 2) * kstep; const char* b2 = last ? nB : cB + (size_t)(t + 2) * kstep;
;             const char* a3 = a2 + kstep; const char* b3 = b2 + kstep;
;             if (last && has_next) S.a_ready(nxt);
;             if constexpr (SP2) {
;             PG8_LDB(B0, 0, 0); PG8_LDB(B1, 0, 1); PG8_SCHED; PG8_LDA(At, 0, 0); PG8_STAGE(PG8_SA(1, 1), a1 + hstep, voffA);
;             PG8_WAIT_V(8); PG8_WAIT_L(0); PG8_BAR; PG8_MMA(0, 0, At, B0); PG8_MMA(0, 1, At, B1); PG8_BAR; PG8_SCHED;
;             PG8_LDA(At, 0, 1); PG8_STAGE(PG8_SB(0, 0), b2, voffB); PG8_STAGE(PG8_SB(0, 1), b2 + hstep, voffB); PG8_STAGE(PG8_SA(0, 0), a2, voffA);
;             PG8_WAIT_V(8); PG8_WAIT_L(0); PG8_BAR; PG8_MMA(1, 0, At, B0); PG8_MMA(1, 1, At, B1); PG8_BAR; PG8_SCHED;
.LBB0_1373:
	v_add_u32_e32 v1, s78, v146
	ds_read_b128 v[150:153], v1
	ds_read_b128 v[154:157], v1 offset:1024
	ds_read_b128 v[158:161], v1 offset:2048
	ds_read_b128 v[162:165], v1 offset:3072
	v_add_u32_e32 v1, s79, v146
	ds_read_b128 v[166:169], v1
	ds_read_b128 v[170:173], v1 offset:1024
	ds_read_b128 v[174:177], v1 offset:2048
	ds_read_b128 v[178:181], v1 offset:3072
	s_add_i32 s88, s56, 2
	s_add_u32 s89, s54, 0x80
	s_addc_u32 s57, s55, 0
	s_cmp_eq_u32 s75, s56
	s_cselect_b32 s56, s48, s89
	s_cselect_b32 s57, s49, s57
	s_cselect_b32 s91, s53, s87
	s_cselect_b32 s90, s52, s86
	s_mov_b32 m0, s80
	v_lshl_add_u64 v[2:3], s[54:55], 0, v[140:141]
	ds_read_b128 v[182:185], v148
	ds_read_b128 v[186:189], v148 offset:1024
	ds_read_b128 v[190:193], v148 offset:2048
	ds_read_b128 v[194:197], v148 offset:3072
	ds_read_b128 v[198:201], v148 offset:4096
	ds_read_b128 v[202:205], v148 offset:5120
	ds_read_b128 v[206:209], v148 offset:6144
	ds_read_b128 v[210:213], v148 offset:7168
	global_load_lds_dwordx4 v[2:3], off
	v_lshl_add_u64 v[2:3], s[54:55], 0, v[142:143]
	s_mov_b32 m0, s81
	s_nop 0
	global_load_lds_dwordx4 v[2:3], off
	s_waitcnt vmcnt(8)
	s_waitcnt lgkmcnt(0)
	s_barrier
	s_setprio 1
	s_waitcnt lgkmcnt(0)
	v_mfma_f32_16x16x32_bf16 v[128:131], v[150:153], v[182:185], v[128:131]
	v_mfma_f32_16x16x32_bf16 v[128:131], v[154:157], v[186:189], v[128:131]
	v_mfma_f32_16x16x32_bf16 v[124:127], v[162:165], v[186:189], v[124:127]
	v_mfma_f32_16x16x32_bf16 v[124:127], v[158:161], v[182:185], v[124:127]
	v_mfma_f32_16x16x32_bf16 v[116:119], v[158:161], v[190:193], v[116:119]
	v_mfma_f32_16x16x32_bf16 v[116:119], v[162:165], v[194:197], v[116:119]
	v_mfma_f32_16x16x32_bf16 v[120:123], v[154:157], v[194:197], v[120:123]
	v_mfma_f32_16x16x32_bf16 v[120:123], v[150:153], v[190:193], v[120:123]
	v_mfma_f32_16x16x32_bf16 v[112:115], v[150:153], v[198:201], v[112:115]
	v_mfma_f32_16x16x32_bf16 v[112:115], v[154:157], v[202:205], v[112:115]
	v_mfma_f32_16x16x32_bf16 v[108:111], v[162:165], v[202:205], v[108:111]
	v_mfma_f32_16x16x32_bf16 v[108:111], v[158:161], v[198:201], v[108:111]
	v_mfma_f32_16x16x32_bf16 v[100:103], v[158:161], v[206:209], v[100:103]
	v_mfma_f32_16x16x32_bf16 v[100:103], v[162:165], v[210:213], v[100:103]
	v_mfma_f32_16x16x32_bf16 v[104:107], v[154:157], v[210:213], v[104:107]
	v_mfma_f32_16x16x32_bf16 v[104:107], v[150:153], v[206:209], v[104:107]
	s_setprio 0
	s_setprio 1
	v_mfma_f32_16x16x32_bf16 v[96:99], v[166:169], v[182:185], v[96:99]
	v_mfma_f32_16x16x32_bf16 v[96:99], v[170:173], v[186:189], v[96:99]
	v_mfma_f32_16x16x32_bf16 v[92:95], v[178:181], v[186:189], v[92:95]
	v_mfma_f32_16x16x32_bf16 v[92:95], v[174:177], v[182:185], v[92:95]
	v_mfma_f32_16x16x32_bf16 v[84:87], v[174:177], v[190:193], v[84:87]
	v_mfma_f32_16x16x32_bf16 v[84:87], v[178:181], v[194:197], v[84:87]
	v_mfma_f32_16x16x32_bf16 v[88:91], v[170:173], v[194:197], v[88:91]
	v_mfma_f32_16x16x32_bf16 v[88:91], v[166:169], v[190:193], v[88:91]
	v_mfma_f32_16x16x32_bf16 v[80:83], v[166:169], v[198:201], v[80:83]
	v_mfma_f32_16x16x32_bf16 v[80:83], v[170:173], v[202:205], v[80:83]
	v_mfma_f32_16x16x32_bf16 v[76:79], v[178:181], v[202:205], v[76:79]
	v_mfma_f32_16x16x32_bf16 v[76:79], v[174:177], v[198:201], v[76:79]
	v_mfma_f32_16x16x32_bf16 v[68:71], v[174:177], v[206:209], v[68:71]
	v_mfma_f32_16x16x32_bf16 v[68:71], v[178:181], v[210:213], v[68:71]
	v_mfma_f32_16x16x32_bf16 v[72:75], v[170:173], v[210:213], v[72:75]
	v_mfma_f32_16x16x32_bf16 v[72:75], v[166:169], v[206:209], v[72:75]
	s_setprio 0
	s_barrier
	s_add_i32 s89, s78, s76
	v_lshl_add_u64 v[214:215], s[90:91], 0, v[136:137]
	s_mov_b32 m0, s89
	ds_read_b128 v[182:185], v148 offset:16384
	ds_read_b128 v[186:189], v148 offset:17408
	ds_read_b128 v[190:193], v148 offset:18432
	ds_read_b128 v[194:197], v148 offset:19456
	ds_read_b128 v[198:201], v148 offset:20480
	ds_read_b128 v[202:205], v148 offset:21504
	ds_read_b128 v[206:209], v148 offset:22528
	ds_read_b128 v[210:213], v148 offset:23552
	global_load_lds_dwordx4 v[214:215], off
	s_add_i32 m0, s89, 0x2000
	v_lshl_add_u64 v[216:217], s[90:91], 0, v[132:133]
	s_add_u32 s90, s90, s4
	s_addc_u32 s91, s91, s5
	s_add_i32 s89, s79, s76
	global_load_lds_dwordx4 v[216:217], off
	v_lshl_add_u64 v[218:219], s[90:91], 0, v[136:137]
	s_mov_b32 m0, s89
	v_lshl_add_u64 v[220:221], s[90:91], 0, v[132:133]
	global_load_lds_dwordx4 v[218:219], off
	s_add_i32 m0, s89, 0x2000
	v_lshl_add_u64 v[222:223], s[56:57], 0, v[138:139]
	global_load_lds_dwordx4 v[220:221], off
	s_mov_b32 m0, s66
	v_lshl_add_u64 v[224:225], s[56:57], 0, v[134:135]
	global_load_lds_dwordx4 v[222:223], off
	s_mov_b32 m0, s69
	s_nop 0
	global_load_lds_dwordx4 v[224:225], off
	s_waitcnt vmcnt(8)
	s_waitcnt lgkmcnt(0)
	s_barrier
; #define PG8_STAGE(bufoff, gbase, voff) do { _Pragma("unroll") for (int _i = 0; _i < 2; ++_i) \
;         __builtin_amdgcn_global_load_lds((const unsigned*)((const char*)(gbase) + (voff)[_i]), (PG8_LAS unsigned*)(lds + (bufoff) + ldsw + _i * 8192), 16, 0, 0); } while (0)
; #define PG8_LDA(dst, b, h) do { _Pragma("unroll") for (int m = 0; m < 4; ++m) _Pragma("unroll") for (int k = 0; k < 2; ++k) dst[m][k] = *(const PG8_LAS bf16x8*)(lds + PG8_SA(b, h) + aoff + m * 2048 + k * 1024); } while (0)
; #define PG8_LDB(dst, b, h) do { _Pragma("unroll") for (int n = 0; n < 2; ++n) _Pragma("unroll") for (int k = 0; k < 2; ++k) dst[n][k] = *(const PG8_LAS bf16x8*)(lds + PG8_SB(b, h) + boff + n * 2048 + k * 1024); } while (0)
; #define PG8_MMA(ai, bj, At, Bt) do { __builtin_amdgcn_s_setprio(1); _Pragma("unroll") for (int m = 0; m < 4; ++m) _Pragma("unroll") for (int n = 0; n < 2; ++n) _Pragma("unroll") for (int k = 0; k < 2; ++k) \
;         acc[ai][bj][m][n] = __builtin_amdgcn_mfma_f32_16x16x32_bf16(Bt[n][k], At[m][k], acc[ai][bj][m][n], 0, 0, 0); __builtin_amdgcn_s_setprio(0); } while (0)
; #define PG8_WAIT_V(n) asm volatile("s_waitcnt vmcnt(" #n ")" ::: "memory")
; #define PG8_WAIT_L(n) asm volatile("s_waitcnt lgkmcnt(" #n ")" ::: "memory")
; #define PG8_BAR __builtin_amdgcn_s_barrier()
; #define PG8_SCHED __builtin_amdgcn_sched_barrier(0)
; template <class Epi, class Sched, bool ALIGN_EPI = false, bool SP2 = false, bool APERM = false  >
; __device__ __forceinline__ void gemm_phase(PG8_LAS unsigned char* lds, const Gemm g, const Sched& S, const Epi& E, const int wid  ) {
;     ...
;             PG8_WAIT_V(8); PG8_WAIT_L(0); PG8_BAR; PG8_MMA(1, 0, At, B0); PG8_MMA(1, 1, At, B1); PG8_BAR; PG8_SCHED;
;             PG8_LDB(B0, 1, 0); PG8_LDB(B1, 1, 1); PG8_SCHED; PG8_LDA(At, 1, 0); PG8_STAGE(PG8_SA(0, 1), a2 + hstep, voffA);
;             PG8_WAIT_V(8); PG8_WAIT_L(0); PG8_BAR; PG8_MMA(0, 0, At, B0); PG8_MMA(0, 1, At, B1); PG8_BAR; PG8_SCHED;
	s_setprio 1
	s_waitcnt lgkmcnt(0)
	v_mfma_f32_16x16x32_bf16 v[64:67], v[150:153], v[182:185], v[64:67]
	v_mfma_f32_16x16x32_bf16 v[64:67], v[154:157], v[186:189], v[64:67]
	v_mfma_f32_16x16x32_bf16 v[60:63], v[162:165], v[186:189], v[60:63]
	v_mfma_f32_16x16x32_bf16 v[60:63], v[158:161], v[182:185], v[60:63]
	v_mfma_f32_16x16x32_bf16 v[52:55], v[158:161], v[190:193], v[52:55]
	v_mfma_f32_16x16x32_bf16 v[52:55], v[162:165], v[194:197], v[52:55]
	v_mfma_f32_16x16x32_bf16 v[56:59], v[154:157], v[194:197], v[56:59]
	v_mfma_f32_16x16x32_bf16 v[56:59], v[150:153], v[190:193], v[56:59]
	v_mfma_f32_16x16x32_bf16 v[48:51], v[150:153], v[198:201], v[48:51]
	v_mfma_f32_16x16x32_bf16 v[48:51], v[154:157], v[202:205], v[48:51]
	v_mfma_f32_16x16x32_bf16 v[44:47], v[162:165], v[202:205], v[44:47]
	v_mfma_f32_16x16x32_bf16 v[44:47], v[158:161], v[198:201], v[44:47]
	v_mfma_f32_16x16x32_bf16 v[36:39], v[158:161], v[206:209], v[36:39]
	v_mfma_f32_16x16x32_bf16 v[36:39], v[162:165], v[210:213], v[36:39]
	v_mfma_f32_16x16x32_bf16 v[40:43], v[154:157], v[210:213], v[40:43]
	v_mfma_f32_16x16x32_bf16 v[40:43], v[150:153], v[206:209], v[40:43]
	s_setprio 0
	s_setprio 1
	v_mfma_f32_16x16x32_bf16 v[32:35], v[166:169], v[182:185], v[32:35]
	v_mfma_f32_16x16x32_bf16 v[32:35], v[170:173], v[186:189], v[32:35]
	v_mfma_f32_16x16x32_bf16 v[28:31], v[178:181], v[186:189], v[28:31]
	v_mfma_f32_16x16x32_bf16 v[28:31], v[174:177], v[182:185], v[28:31]
	v_mfma_f32_16x16x32_bf16 v[20:23], v[174:177], v[190:193], v[20:23]
	v_mfma_f32_16x16x32_bf16 v[20:23], v[178:181], v[194:197], v[20:23]
	v_mfma_f32_16x16x32_bf16 v[24:27], v[170:173], v[194:197], v[24:27]
	v_mfma_f32_16x16x32_bf16 v[24:27], v[166:169], v[190:193], v[24:27]
	v_mfma_f32_16x16x32_bf16 v[16:19], v[166:169], v[198:201], v[16:19]
	v_mfma_f32_16x16x32_bf16 v[16:19], v[170:173], v[202:205], v[16:19]
	v_mfma_f32_16x16x32_bf16 v[12:15], v[178:181], v[202:205], v[12:15]
	v_mfma_f32_16x16x32_bf16 v[12:15], v[174:177], v[198:201], v[12:15]
	v_mfma_f32_16x16x32_bf16 v[2:5], v[174:177], v[206:209], v[4:7]
	v_mfma_f32_16x16x32_bf16 v[2:5], v[178:181], v[210:213], v[2:5]
	v_mfma_f32_16x16x32_bf16 v[8:11], v[170:173], v[210:213], v[8:11]
	v_mfma_f32_16x16x32_bf16 v[8:11], v[166:169], v[206:209], v[8:11]
	s_setprio 0
	s_barrier
	s_add_i32 s89, 0, 0x18000
	v_add_u32_e32 v1, s89, v146
	s_add_i32 s90, 0, 0x1c000
	ds_read_b128 v[150:153], v1
	ds_read_b128 v[154:157], v1 offset:1024
	ds_read_b128 v[158:161], v1 offset:2048
	ds_read_b128 v[162:165], v1 offset:3072
	v_add_u32_e32 v1, s90, v146
	ds_read_b128 v[166:169], v1
	ds_read_b128 v[170:173], v1 offset:1024
	ds_read_b128 v[174:177], v1 offset:2048
	ds_read_b128 v[178:181], v1 offset:3072
	s_add_u32 s56, s56, s4
	s_addc_u32 s57, s57, s5
	s_mov_b32 m0, s70
	v_lshl_add_u64 v[6:7], s[56:57], 0, v[138:139]
	ds_read_b128 v[182:185], v148 offset:32768
	ds_read_b128 v[186:189], v148 offset:33792
	ds_read_b128 v[190:193], v148 offset:34816
	ds_read_b128 v[194:197], v148 offset:35840
	ds_read_b128 v[198:201], v148 offset:36864
	ds_read_b128 v[202:205], v148 offset:37888
	ds_read_b128 v[206:209], v148 offset:38912
	ds_read_b128 v[210:213], v148 offset:39936
	global_load_lds_dwordx4 v[6:7], off
	v_lshl_add_u64 v[6:7], s[56:57], 0, v[134:135]
	s_mov_b32 m0, s71
	s_nop 0
	global_load_lds_dwordx4 v[6:7], off
	s_waitcnt vmcnt(8)
	s_waitcnt lgkmcnt(0)
	s_barrier
	s_setprio 1
	s_waitcnt lgkmcnt(0)
	v_mfma_f32_16x16x32_bf16 v[128:131], v[150:153], v[182:185], v[128:131]
	v_mfma_f32_16x16x32_bf16 v[128:131], v[154:157], v[186:189], v[128:131]
	v_mfma_f32_16x16x32_bf16 v[124:127], v[162:165], v[186:189], v[124:127]
	v_mfma_f32_16x16x32_bf16 v[124:127], v[158:161], v[182:185], v[124:127]
	v_mfma_f32_16x16x32_bf16 v[116:119], v[158:161], v[190:193], v[116:119]
	v_mfma_f32_16x16x32_bf16 v[116:119], v[162:165], v[194:197], v[116:119]
	v_mfma_f32_16x16x32_bf16 v[120:123], v[154:157], v[194:197], v[120:123]
	v_mfma_f32_16x16x32_bf16 v[120:123], v[150:153], v[190:193], v[120:123]
	v_mfma_f32_16x16x32_bf16 v[112:115], v[150:153], v[198:201], v[112:115]
	v_mfma_f32_16x16x32_bf16 v[112:115], v[154:157], v[202:205], v[112:115]
	v_mfma_f32_16x16x32_bf16 v[108:111], v[162:165], v[202:205], v[108:111]
	v_mfma_f32_16x16x32_bf16 v[108:111], v[158:161], v[198:201], v[108:111]
	v_mfma_f32_16x16x32_bf16 v[100:103], v[158:161], v[206:209], v[100:103]
	v_mfma_f32_16x16x32_bf16 v[100:103], v[162:165], v[210:213], v[100:103]
	v_mfma_f32_16x16x32_bf16 v[104:107], v[154:157], v[210:213], v[104:107]
	v_mfma_f32_16x16x32_bf16 v[104:107], v[150:153], v[206:209], v[104:107]
	s_setprio 0
	s_setprio 1
	v_mfma_f32_16x16x32_bf16 v[96:99], v[166:169], v[182:185], v[96:99]
	v_mfma_f32_16x16x32_bf16 v[96:99], v[170:173], v[186:189], v[96:99]
	v_mfma_f32_16x16x32_bf16 v[92:95], v[178:181], v[186:189], v[92:95]
	v_mfma_f32_16x16x32_bf16 v[92:95], v[174:177], v[182:185], v[92:95]
	v_mfma_f32_16x16x32_bf16 v[84:87], v[174:177], v[190:193], v[84:87]
	v_mfma_f32_16x16x32_bf16 v[84:87], v[178:181], v[194:197], v[84:87]
	v_mfma_f32_16x16x32_bf16 v[88:91], v[170:173], v[194:197], v[88:91]
	v_mfma_f32_16x16x32_bf16 v[88:91], v[166:169], v[190:193], v[88:91]
	v_mfma_f32_16x16x32_bf16 v[80:83], v[166:169], v[198:201], v[80:83]
	v_mfma_f32_16x16x32_bf16 v[80:83], v[170:173], v[202:205], v[80:83]
	v_mfma_f32_16x16x32_bf16 v[76:79], v[178:181], v[202:205], v[76:79]
	v_mfma_f32_16x16x32_bf16 v[76:79], v[174:177], v[198:201], v[76:79]
	v_mfma_f32_16x16x32_bf16 v[68:71], v[174:177], v[206:209], v[68:71]
	v_mfma_f32_16x16x32_bf16 v[68:71], v[178:181], v[210:213], v[68:71]
	v_mfma_f32_16x16x32_bf16 v[72:75], v[170:173], v[210:213], v[72:75]
	v_mfma_f32_16x16x32_bf16 v[72:75], v[166:169], v[206:209], v[72:75]
	s_setprio 0
	s_barrier
; #define PG8_STAGE(bufoff, gbase, voff) do { _Pragma("unroll") for (int _i = 0; _i < 2; ++_i) \
;         __builtin_amdgcn_global_load_lds((const unsigned*)((const char*)(gbase) + (voff)[_i]), (PG8_LAS unsigned*)(lds + (bufoff) + ldsw + _i * 8192), 16, 0, 0); } while (0)
; #define PG8_LDA(dst, b, h) do { _Pragma("unroll") for (int m = 0; m < 4; ++m) _Pragma("unroll") for (int k = 0; k < 2; ++k) dst[m][k] = *(const PG8_LAS bf16x8*)(lds + PG8_SA(b, h) + aoff + m * 2048 + k * 1024); } while (0)
; #define PG8_MMA(ai, bj, At, Bt) do { __builtin_amdgcn_s_setprio(1); _Pragma("unroll") for (int m = 0; m < 4; ++m) _Pragma("unroll") for (int n = 0; n < 2; ++n) _Pragma("unroll") for (int k = 0; k < 2; ++k) \
;         acc[ai][bj][m][n] = __builtin_amdgcn_mfma_f32_16x16x32_bf16(Bt[n][k], At[m][k], acc[ai][bj][m][n], 0, 0, 0); __builtin_amdgcn_s_setprio(0); } while (0)
; #define PG8_WAIT_V(n) asm volatile("s_waitcnt vmcnt(" #n ")" ::: "memory")
; #define PG8_WAIT_L(n) asm volatile("s_waitcnt lgkmcnt(" #n ")" ::: "memory")
; #define PG8_BAR __builtin_amdgcn_s_barrier()
; #define PG8_SCHED __builtin_amdgcn_sched_barrier(0)
; template <class Epi, class Sched, bool ALIGN_EPI = false, bool SP2 = false, bool APERM = false  >
; __device__ __forceinline__ void gemm_phase(PG8_LAS unsigned char* lds, const Gemm g, const Sched& S, const Epi& E, const int wid  ) {
;     ...
;         for (int t = 0; t < nt; t += 2) {
;             const bool last = (t == nt - 2);
;     ...
;             PG8_LDA(At, 1, 1); PG8_STAGE(PG8_SB(1, 0), b3, voffB); PG8_STAGE(PG8_SB(1, 1), b3 + hstep, voffB); PG8_STAGE(PG8_SA(1, 0), a3, voffA);
;             PG8_WAIT_V(8); PG8_WAIT_L(0); PG8_BAR; PG8_MMA(1, 0, At, B0); PG8_MMA(1, 1, At, B1); PG8_BAR; PG8_SCHED;
	s_add_i32 s56, s89, s76
	v_lshl_add_u64 v[6:7], v[214:215], 0, s[16:17]
	s_mov_b32 m0, s56
	ds_read_b128 v[182:185], v148 offset:49152
	ds_read_b128 v[186:189], v148 offset:50176
	ds_read_b128 v[190:193], v148 offset:51200
	ds_read_b128 v[194:197], v148 offset:52224
	ds_read_b128 v[198:201], v148 offset:53248
	ds_read_b128 v[202:205], v148 offset:54272
	ds_read_b128 v[206:209], v148 offset:55296
	ds_read_b128 v[210:213], v148 offset:56320
	global_load_lds_dwordx4 v[6:7], off
	v_lshl_add_u64 v[6:7], v[216:217], 0, s[16:17]
	s_add_i32 m0, s56, 0x2000
	s_add_i32 s56, s90, s76
	global_load_lds_dwordx4 v[6:7], off
	v_lshl_add_u64 v[6:7], v[218:219], 0, s[16:17]
	s_mov_b32 m0, s56
	s_nop 0
	global_load_lds_dwordx4 v[6:7], off
	v_lshl_add_u64 v[6:7], v[220:221], 0, s[16:17]
	s_add_i32 m0, s56, 0x2000
	s_nop 0
	global_load_lds_dwordx4 v[6:7], off
	v_lshl_add_u64 v[6:7], v[222:223], 0, s[16:17]
	s_mov_b32 m0, s73
	s_nop 0
	global_load_lds_dwordx4 v[6:7], off
	v_lshl_add_u64 v[6:7], v[224:225], 0, s[16:17]
	s_mov_b32 m0, s74
	s_nop 0
	global_load_lds_dwordx4 v[6:7], off
	s_waitcnt vmcnt(8)
	s_waitcnt lgkmcnt(0)
	s_barrier
	s_setprio 1
	s_waitcnt lgkmcnt(0)
	v_mfma_f32_16x16x32_bf16 v[64:67], v[150:153], v[182:185], v[64:67]
	v_mfma_f32_16x16x32_bf16 v[64:67], v[154:157], v[186:189], v[64:67]
	v_mfma_f32_16x16x32_bf16 v[60:63], v[162:165], v[186:189], v[60:63]
	v_mfma_f32_16x16x32_bf16 v[60:63], v[158:161], v[182:185], v[60:63]
	v_mfma_f32_16x16x32_bf16 v[52:55], v[158:161], v[190:193], v[52:55]
	v_mfma_f32_16x16x32_bf16 v[52:55], v[162:165], v[194:197], v[52:55]
	v_mfma_f32_16x16x32_bf16 v[56:59], v[154:157], v[194:197], v[56:59]
	v_mfma_f32_16x16x32_bf16 v[56:59], v[150:153], v[190:193], v[56:59]
	v_mfma_f32_16x16x32_bf16 v[48:51], v[150:153], v[198:201], v[48:51]
	v_mfma_f32_16x16x32_bf16 v[48:51], v[154:157], v[202:205], v[48:51]
	v_mfma_f32_16x16x32_bf16 v[44:47], v[162:165], v[202:205], v[44:47]
	v_mfma_f32_16x16x32_bf16 v[44:47], v[158:161], v[198:201], v[44:47]
	v_mfma_f32_16x16x32_bf16 v[36:39], v[158:161], v[206:209], v[36:39]
	v_mfma_f32_16x16x32_bf16 v[36:39], v[162:165], v[210:213], v[36:39]
	v_mfma_f32_16x16x32_bf16 v[40:43], v[154:157], v[210:213], v[40:43]
	v_mfma_f32_16x16x32_bf16 v[40:43], v[150:153], v[206:209], v[40:43]
	s_setprio 0
	s_setprio 1
	v_mfma_f32_16x16x32_bf16 v[32:35], v[166:169], v[182:185], v[32:35]
	v_mfma_f32_16x16x32_bf16 v[28:31], v[174:177], v[182:185], v[28:31]
	v_mfma_f32_16x16x32_bf16 v[24:27], v[166:169], v[190:193], v[24:27]
	v_mfma_f32_16x16x32_bf16 v[20:23], v[174:177], v[190:193], v[20:23]
	v_mfma_f32_16x16x32_bf16 v[16:19], v[166:169], v[198:201], v[16:19]
	v_mfma_f32_16x16x32_bf16 v[12:15], v[174:177], v[198:201], v[12:15]
	v_mfma_f32_16x16x32_bf16 v[6:9], v[166:169], v[206:209], v[8:11]
	v_mfma_f32_16x16x32_bf16 v[2:5], v[174:177], v[206:209], v[2:5]
	v_mfma_f32_16x16x32_bf16 v[32:35], v[170:173], v[186:189], v[32:35]
	v_mfma_f32_16x16x32_bf16 v[28:31], v[178:181], v[186:189], v[28:31]
	v_mfma_f32_16x16x32_bf16 v[24:27], v[170:173], v[194:197], v[24:27]
	v_mfma_f32_16x16x32_bf16 v[20:23], v[178:181], v[194:197], v[20:23]
	v_mfma_f32_16x16x32_bf16 v[16:19], v[170:173], v[202:205], v[16:19]
	v_mfma_f32_16x16x32_bf16 v[12:15], v[178:181], v[202:205], v[12:15]
	v_mfma_f32_16x16x32_bf16 v[8:11], v[170:173], v[210:213], v[6:9]
	v_mfma_f32_16x16x32_bf16 v[4:7], v[178:181], v[210:213], v[2:5]
	s_setprio 0
	s_barrier
	s_add_u32 s54, s54, 0x100
	s_addc_u32 s55, s55, 0
	s_add_u32 s86, s86, 0x100
	s_addc_u32 s87, s87, 0
	s_cmp_ge_i32 s88, s72
	s_mov_b32 s56, s88
	s_cbranch_scc0 .LBB0_1373

; #define PG8_STAGE(bufoff, gbase, voff) do { _Pragma("unroll") for (int _i = 0; _i < 2; ++_i) \
;         __builtin_amdgcn_global_load_lds((const unsigned*)((const char*)(gbase) + (voff)[_i]), (PG8_LAS unsigned*)(lds + (bufoff) + ldsw + _i * 8192), 16, 0, 0); } while (0)
; #define PG8_LDA(dst, b, h) do { _Pragma("unroll") for (int m = 0; m < 4; ++m) _Pragma("unroll") for (int k = 0; k < 2; ++k) dst[m][k] = *(const PG8_LAS bf16x8*)(lds + PG8_SA(b, h) + aoff + m * 2048 + k * 1024); } while (0)
; #define PG8_LDB(dst, b, h) do { _Pragma("unroll") for (int n = 0; n < 2; ++n) _Pragma("unroll") for (int k = 0; k < 2; ++k) dst[n][k] = *(const PG8_LAS bf16x8*)(lds + PG8_SB(b, h) + boff + n * 2048 + k * 1024); } while (0)
; #define PG8_MMA(ai, bj, At, Bt) do { __builtin_amdgcn_s_setprio(1); _Pragma("unroll") for (int m = 0; m < 4; ++m) _Pragma("unroll") for (int n = 0; n < 2; ++n) _Pragma("unroll") for (int k = 0; k < 2; ++k) \
;         acc[ai][bj][m][n] = __builtin_amdgcn_mfma_f32_16x16x32_bf16(Bt[n][k], At[m][k], acc[ai][bj][m][n], 0, 0, 0); __builtin_amdgcn_s_setprio(0); } while (0)
; #define PG8_WAIT_V(n) asm volatile("s_waitcnt vmcnt(" #n ")" ::: "memory")
; #define PG8_WAIT_L(n) asm volatile("s_waitcnt lgkmcnt(" #n ")" ::: "memory")
; template <class Epi, class Sched, bool ALIGN_EPI = false, bool SP2 = false, bool APERM = false  >
; __device__ __forceinline__ void gemm_phase(PG8_LAS unsigned char* lds, const Gemm g, const Sched& S, const Epi& E, const int wid  ) {
;     ...
;             const bool last = (t == nt - 2);
;             const char* a1 = cA + (size_t)(t + 1) * kstep;
;             const char* a2 = last ? nA : cA + (size_t)(t + 2) * kstep; const char* b2 = last ? nB : cB + (size_t)(t + 2) * kstep;
;             const char* a3 = a2 + kstep; const char* b3 = b2 + kstep;
;             if (last && has_next) S.a_ready(nxt);
;             if constexpr (SP2) {
;             PG8_LDB(B0, 0, 0); PG8_LDB(B1, 0, 1); PG8_SCHED; PG8_LDA(At, 0, 0); PG8_STAGE(PG8_SA(1, 1), a1 + hstep, voffA);
;             PG8_WAIT_V(8); PG8_WAIT_L(0); PG8_BAR; PG8_MMA(0, 0, At, B0); PG8_MMA(0, 1, At, B1); PG8_BAR; PG8_SCHED;
;             PG8_LDA(At, 0, 1); PG8_STAGE(PG8_SB(0, 0), b2, voffB); PG8_STAGE(PG8_SB(0, 1), b2 + hstep, voffB); PG8_STAGE(PG8_SA(0, 0), a2, voffA);
;             PG8_WAIT_V(8); PG8_WAIT_L(0); PG8_BAR; PG8_MMA(1, 0, At, B0); PG8_MMA(1, 1, At, B1); PG8_BAR; PG8_SCHED;
.LBB0_1423:
	s_lshl_b32 s24, s89, 7
	s_add_u32 s25, s30, s24
	s_addc_u32 s26, s31, 0
	s_add_u32 s27, s25, 0x100
	s_addc_u32 s90, s26, 0
	v_add_u32_e32 v140, s85, v173
	v_add_u32_e32 v154, s86, v173
	s_and_b64 s[18:19], s[6:7], exec
	s_waitcnt lgkmcnt(0)
	ds_read_b128 v[128:131], v140
	ds_read_b128 v[132:135], v140 offset:1024
	ds_read_b128 v[136:139], v140 offset:2048
	ds_read_b128 v[140:143], v140 offset:3072
	ds_read_b128 v[144:147], v154
	ds_read_b128 v[162:165], v154 offset:1024
	ds_read_b128 v[166:169], v154 offset:2048
	ds_read_b128 v[180:183], v154 offset:3072
	s_cselect_b32 s19, s33, s90
	s_cselect_b32 s18, s65, s27
	s_add_u32 s24, s14, s24
	s_addc_u32 s27, s15, 0
	s_add_u32 s24, s24, 0x100
	s_addc_u32 s27, s27, 0
	s_and_b64 s[6:7], s[6:7], exec
	s_cselect_b32 s6, s88, s24
	s_cselect_b32 s7, s67, s27
	s_add_u32 s24, s25, 0x80080
	s_addc_u32 s25, s26, 0
	v_lshl_add_u64 v[170:171], s[24:25], 0, v[152:153]
	s_add_i32 m0, s11, 0xc000
	ds_read_b128 v[184:187], v178
	ds_read_b128 v[188:191], v178 offset:1024
	ds_read_b128 v[192:195], v178 offset:2048
	ds_read_b128 v[196:199], v178 offset:3072
	ds_read_b128 v[200:203], v178 offset:4096
	ds_read_b128 v[204:207], v178 offset:5120
	ds_read_b128 v[208:211], v178 offset:6144
	ds_read_b128 v[212:215], v178 offset:7168
	global_load_lds_dwordx4 v[170:171], off
	v_lshl_add_u64 v[170:171], s[24:25], 0, v[156:157]
	s_add_i32 m0, s11, 0xe000
	s_nop 0
	global_load_lds_dwordx4 v[170:171], off
	s_waitcnt vmcnt(8)
	s_waitcnt lgkmcnt(0)
	s_barrier
	s_setprio 1
	s_waitcnt lgkmcnt(0)
	v_mfma_f32_16x16x32_bf16 v[124:127], v[128:131], v[184:187], v[124:127]
	v_mfma_f32_16x16x32_bf16 v[124:127], v[132:135], v[188:191], v[124:127]
	v_mfma_f32_16x16x32_bf16 v[120:123], v[140:143], v[188:191], v[120:123]
	v_mfma_f32_16x16x32_bf16 v[120:123], v[136:139], v[184:187], v[120:123]
	v_mfma_f32_16x16x32_bf16 v[112:115], v[136:139], v[192:195], v[112:115]
	v_mfma_f32_16x16x32_bf16 v[112:115], v[140:143], v[196:199], v[112:115]
	v_mfma_f32_16x16x32_bf16 v[116:119], v[132:135], v[196:199], v[116:119]
	v_mfma_f32_16x16x32_bf16 v[116:119], v[128:131], v[192:195], v[116:119]
	v_mfma_f32_16x16x32_bf16 v[108:111], v[128:131], v[200:203], v[108:111]
	v_mfma_f32_16x16x32_bf16 v[108:111], v[132:135], v[204:207], v[108:111]
	v_mfma_f32_16x16x32_bf16 v[104:107], v[140:143], v[204:207], v[104:107]
	v_mfma_f32_16x16x32_bf16 v[104:107], v[136:139], v[200:203], v[104:107]
	v_mfma_f32_16x16x32_bf16 v[96:99], v[136:139], v[208:211], v[96:99]
	v_mfma_f32_16x16x32_bf16 v[96:99], v[140:143], v[212:215], v[96:99]
	v_mfma_f32_16x16x32_bf16 v[100:103], v[132:135], v[212:215], v[100:103]
	v_mfma_f32_16x16x32_bf16 v[100:103], v[128:131], v[208:211], v[100:103]
	s_setprio 0
	s_setprio 1
	v_mfma_f32_16x16x32_bf16 v[92:95], v[144:147], v[184:187], v[92:95]
	v_mfma_f32_16x16x32_bf16 v[92:95], v[162:165], v[188:191], v[92:95]
	v_mfma_f32_16x16x32_bf16 v[88:91], v[180:183], v[188:191], v[88:91]
	v_mfma_f32_16x16x32_bf16 v[88:91], v[166:169], v[184:187], v[88:91]
	v_mfma_f32_16x16x32_bf16 v[80:83], v[166:169], v[192:195], v[80:83]
	v_mfma_f32_16x16x32_bf16 v[80:83], v[180:183], v[196:199], v[80:83]
	v_mfma_f32_16x16x32_bf16 v[84:87], v[162:165], v[196:199], v[84:87]
	v_mfma_f32_16x16x32_bf16 v[84:87], v[144:147], v[192:195], v[84:87]
	v_mfma_f32_16x16x32_bf16 v[76:79], v[144:147], v[200:203], v[76:79]
	v_mfma_f32_16x16x32_bf16 v[76:79], v[162:165], v[204:207], v[76:79]
	v_mfma_f32_16x16x32_bf16 v[72:75], v[180:183], v[204:207], v[72:75]
	v_mfma_f32_16x16x32_bf16 v[72:75], v[166:169], v[200:203], v[72:75]
	v_mfma_f32_16x16x32_bf16 v[64:67], v[166:169], v[208:211], v[64:67]
	v_mfma_f32_16x16x32_bf16 v[64:67], v[180:183], v[212:215], v[64:67]
	v_mfma_f32_16x16x32_bf16 v[68:71], v[162:165], v[212:215], v[68:71]
	v_mfma_f32_16x16x32_bf16 v[68:71], v[144:147], v[208:211], v[68:71]
	s_setprio 0
	s_barrier
	s_add_i32 s24, s85, s76
	v_lshl_add_u64 v[170:171], s[6:7], 0, v[148:149]
	s_mov_b32 m0, s24
	ds_read_b128 v[184:187], v178 offset:16384
	ds_read_b128 v[188:191], v178 offset:17408
	ds_read_b128 v[192:195], v178 offset:18432
	ds_read_b128 v[196:199], v178 offset:19456
	ds_read_b128 v[200:203], v178 offset:20480
	ds_read_b128 v[204:207], v178 offset:21504
	ds_read_b128 v[208:211], v178 offset:22528
	ds_read_b128 v[212:215], v178 offset:23552
	global_load_lds_dwordx4 v[170:171], off
	s_add_i32 m0, s24, 0x2000
	s_add_u32 s24, s6, 0x80000
	v_lshl_add_u64 v[216:217], s[6:7], 0, v[150:151]
	s_addc_u32 s25, s7, 0
	s_add_i32 s26, s86, s76
	global_load_lds_dwordx4 v[216:217], off
	v_lshl_add_u64 v[218:219], s[24:25], 0, v[148:149]
	s_mov_b32 m0, s26
	v_lshl_add_u64 v[220:221], s[18:19], 0, v[156:157]
	global_load_lds_dwordx4 v[218:219], off
	v_lshl_add_u64 v[218:219], s[24:25], 0, v[150:151]
	s_add_i32 m0, s26, 0x2000
	s_nop 0
	global_load_lds_dwordx4 v[218:219], off
	v_lshl_add_u64 v[218:219], s[18:19], 0, v[152:153]
	s_mov_b32 m0, s11
	s_nop 0
	global_load_lds_dwordx4 v[218:219], off
	s_mov_b32 m0, s13
	s_nop 0
	global_load_lds_dwordx4 v[220:221], off
	s_waitcnt vmcnt(8)
	s_waitcnt lgkmcnt(0)
	s_barrier
; #define PG8_STAGE(bufoff, gbase, voff) do { _Pragma("unroll") for (int _i = 0; _i < 2; ++_i) \
;         __builtin_amdgcn_global_load_lds((const unsigned*)((const char*)(gbase) + (voff)[_i]), (PG8_LAS unsigned*)(lds + (bufoff) + ldsw + _i * 8192), 16, 0, 0); } while (0)
; #define PG8_LDA(dst, b, h) do { _Pragma("unroll") for (int m = 0; m < 4; ++m) _Pragma("unroll") for (int k = 0; k < 2; ++k) dst[m][k] = *(const PG8_LAS bf16x8*)(lds + PG8_SA(b, h) + aoff + m * 2048 + k * 1024); } while (0)
; #define PG8_LDB(dst, b, h) do { _Pragma("unroll") for (int n = 0; n < 2; ++n) _Pragma("unroll") for (int k = 0; k < 2; ++k) dst[n][k] = *(const PG8_LAS bf16x8*)(lds + PG8_SB(b, h) + boff + n * 2048 + k * 1024); } while (0)
; #define PG8_MMA(ai, bj, At, Bt) do { __builtin_amdgcn_s_setprio(1); _Pragma("unroll") for (int m = 0; m < 4; ++m) _Pragma("unroll") for (int n = 0; n < 2; ++n) _Pragma("unroll") for (int k = 0; k < 2; ++k) \
;         acc[ai][bj][m][n] = __builtin_amdgcn_mfma_f32_16x16x32_bf16(Bt[n][k], At[m][k], acc[ai][bj][m][n], 0, 0, 0); __builtin_amdgcn_s_setprio(0); } while (0)
; #define PG8_WAIT_V(n) asm volatile("s_waitcnt vmcnt(" #n ")" ::: "memory")
; #define PG8_WAIT_L(n) asm volatile("s_waitcnt lgkmcnt(" #n ")" ::: "memory")
; #define PG8_BAR __builtin_amdgcn_s_barrier()
; #define PG8_SCHED __builtin_amdgcn_sched_barrier(0)
; template <class Epi, class Sched, bool ALIGN_EPI = false, bool SP2 = false, bool APERM = false  >
; __device__ __forceinline__ void gemm_phase(PG8_LAS unsigned char* lds, const Gemm g, const Sched& S, const Epi& E, const int wid  ) {
;     ...
;             PG8_WAIT_V(8); PG8_WAIT_L(0); PG8_BAR; PG8_MMA(1, 0, At, B0); PG8_MMA(1, 1, At, B1); PG8_BAR; PG8_SCHED;
;             PG8_LDB(B0, 1, 0); PG8_LDB(B1, 1, 1); PG8_SCHED; PG8_LDA(At, 1, 0); PG8_STAGE(PG8_SA(0, 1), a2 + hstep, voffA);
;             PG8_WAIT_V(8); PG8_WAIT_L(0); PG8_BAR; PG8_MMA(0, 0, At, B0); PG8_MMA(0, 1, At, B1); PG8_BAR; PG8_SCHED;
	s_setprio 1
	s_waitcnt lgkmcnt(0)
	v_mfma_f32_16x16x32_bf16 v[60:63], v[128:131], v[184:187], v[60:63]
	v_mfma_f32_16x16x32_bf16 v[60:63], v[132:135], v[188:191], v[60:63]
	v_mfma_f32_16x16x32_bf16 v[56:59], v[140:143], v[188:191], v[56:59]
	v_mfma_f32_16x16x32_bf16 v[56:59], v[136:139], v[184:187], v[56:59]
	v_mfma_f32_16x16x32_bf16 v[48:51], v[136:139], v[192:195], v[48:51]
	v_mfma_f32_16x16x32_bf16 v[48:51], v[140:143], v[196:199], v[48:51]
	v_mfma_f32_16x16x32_bf16 v[52:55], v[132:135], v[196:199], v[52:55]
	v_mfma_f32_16x16x32_bf16 v[52:55], v[128:131], v[192:195], v[52:55]
	v_mfma_f32_16x16x32_bf16 v[44:47], v[128:131], v[200:203], v[44:47]
	v_mfma_f32_16x16x32_bf16 v[44:47], v[132:135], v[204:207], v[44:47]
	v_mfma_f32_16x16x32_bf16 v[40:43], v[140:143], v[204:207], v[40:43]
	v_mfma_f32_16x16x32_bf16 v[40:43], v[136:139], v[200:203], v[40:43]
	v_mfma_f32_16x16x32_bf16 v[32:35], v[136:139], v[208:211], v[32:35]
	v_mfma_f32_16x16x32_bf16 v[32:35], v[140:143], v[212:215], v[32:35]
	v_mfma_f32_16x16x32_bf16 v[36:39], v[132:135], v[212:215], v[36:39]
	v_mfma_f32_16x16x32_bf16 v[36:39], v[128:131], v[208:211], v[36:39]
	s_setprio 0
	s_setprio 1
	v_mfma_f32_16x16x32_bf16 v[28:31], v[144:147], v[184:187], v[28:31]
	v_mfma_f32_16x16x32_bf16 v[28:31], v[162:165], v[188:191], v[28:31]
	v_mfma_f32_16x16x32_bf16 v[24:27], v[180:183], v[188:191], v[24:27]
	v_mfma_f32_16x16x32_bf16 v[24:27], v[166:169], v[184:187], v[24:27]
	v_mfma_f32_16x16x32_bf16 v[16:19], v[166:169], v[192:195], v[16:19]
	v_mfma_f32_16x16x32_bf16 v[16:19], v[180:183], v[196:199], v[16:19]
	v_mfma_f32_16x16x32_bf16 v[20:23], v[162:165], v[196:199], v[20:23]
	v_mfma_f32_16x16x32_bf16 v[20:23], v[144:147], v[192:195], v[20:23]
	v_mfma_f32_16x16x32_bf16 v[12:15], v[144:147], v[200:203], v[12:15]
	v_mfma_f32_16x16x32_bf16 v[12:15], v[162:165], v[204:207], v[12:15]
	v_mfma_f32_16x16x32_bf16 v[8:11], v[180:183], v[204:207], v[8:11]
	v_mfma_f32_16x16x32_bf16 v[8:11], v[166:169], v[200:203], v[8:11]
	v_mfma_f32_16x16x32_bf16 v[0:3], v[166:169], v[208:211], v[0:3]
	v_mfma_f32_16x16x32_bf16 v[0:3], v[180:183], v[212:215], v[0:3]
	v_mfma_f32_16x16x32_bf16 v[4:7], v[162:165], v[212:215], v[4:7]
	v_mfma_f32_16x16x32_bf16 v[4:7], v[144:147], v[208:211], v[4:7]
	s_setprio 0
	s_barrier
	s_add_i32 s24, 0, 0x18000
	s_add_i32 s25, 0, 0x1c000
	v_add_u32_e32 v140, s24, v173
	v_add_u32_e32 v154, s25, v173
	ds_read_b128 v[128:131], v140
	ds_read_b128 v[132:135], v140 offset:1024
	ds_read_b128 v[136:139], v140 offset:2048
	ds_read_b128 v[140:143], v140 offset:3072
	ds_read_b128 v[144:147], v154
	ds_read_b128 v[162:165], v154 offset:1024
	ds_read_b128 v[166:169], v154 offset:2048
	ds_read_b128 v[180:183], v154 offset:3072
	s_add_u32 s18, s18, 0x80000
	s_addc_u32 s19, s19, 0
	s_mov_b32 m0, s78
	v_lshl_add_u64 v[222:223], s[18:19], 0, v[152:153]
	ds_read_b128 v[184:187], v178 offset:32768
	ds_read_b128 v[188:191], v178 offset:33792
	ds_read_b128 v[192:195], v178 offset:34816
	ds_read_b128 v[196:199], v178 offset:35840
	ds_read_b128 v[200:203], v178 offset:36864
	ds_read_b128 v[204:207], v178 offset:37888
	ds_read_b128 v[208:211], v178 offset:38912
	ds_read_b128 v[212:215], v178 offset:39936
	global_load_lds_dwordx4 v[222:223], off
	v_lshl_add_u64 v[222:223], s[18:19], 0, v[156:157]
	s_mov_b32 m0, s79
	s_nop 0
	global_load_lds_dwordx4 v[222:223], off
	s_waitcnt vmcnt(8)
	s_waitcnt lgkmcnt(0)
	s_barrier
	s_setprio 1
	s_waitcnt lgkmcnt(0)
	v_mfma_f32_16x16x32_bf16 v[124:127], v[128:131], v[184:187], v[124:127]
	v_mfma_f32_16x16x32_bf16 v[124:127], v[132:135], v[188:191], v[124:127]
	v_mfma_f32_16x16x32_bf16 v[120:123], v[140:143], v[188:191], v[120:123]
	v_mfma_f32_16x16x32_bf16 v[120:123], v[136:139], v[184:187], v[120:123]
	v_mfma_f32_16x16x32_bf16 v[112:115], v[136:139], v[192:195], v[112:115]
	v_mfma_f32_16x16x32_bf16 v[112:115], v[140:143], v[196:199], v[112:115]
	v_mfma_f32_16x16x32_bf16 v[116:119], v[132:135], v[196:199], v[116:119]
	v_mfma_f32_16x16x32_bf16 v[116:119], v[128:131], v[192:195], v[116:119]
	v_mfma_f32_16x16x32_bf16 v[108:111], v[128:131], v[200:203], v[108:111]
	v_mfma_f32_16x16x32_bf16 v[108:111], v[132:135], v[204:207], v[108:111]
	v_mfma_f32_16x16x32_bf16 v[104:107], v[140:143], v[204:207], v[104:107]
	v_mfma_f32_16x16x32_bf16 v[104:107], v[136:139], v[200:203], v[104:107]
	v_mfma_f32_16x16x32_bf16 v[96:99], v[136:139], v[208:211], v[96:99]
	v_mfma_f32_16x16x32_bf16 v[96:99], v[140:143], v[212:215], v[96:99]
	v_mfma_f32_16x16x32_bf16 v[100:103], v[132:135], v[212:215], v[100:103]
	v_mfma_f32_16x16x32_bf16 v[100:103], v[128:131], v[208:211], v[100:103]
	s_setprio 0
	s_setprio 1
	v_mfma_f32_16x16x32_bf16 v[92:95], v[144:147], v[184:187], v[92:95]
	v_mfma_f32_16x16x32_bf16 v[92:95], v[162:165], v[188:191], v[92:95]
	v_mfma_f32_16x16x32_bf16 v[88:91], v[180:183], v[188:191], v[88:91]
	v_mfma_f32_16x16x32_bf16 v[88:91], v[166:169], v[184:187], v[88:91]
	v_mfma_f32_16x16x32_bf16 v[80:83], v[166:169], v[192:195], v[80:83]
	v_mfma_f32_16x16x32_bf16 v[80:83], v[180:183], v[196:199], v[80:83]
	v_mfma_f32_16x16x32_bf16 v[84:87], v[162:165], v[196:199], v[84:87]
	v_mfma_f32_16x16x32_bf16 v[84:87], v[144:147], v[192:195], v[84:87]
	v_mfma_f32_16x16x32_bf16 v[76:79], v[144:147], v[200:203], v[76:79]
	v_mfma_f32_16x16x32_bf16 v[76:79], v[162:165], v[204:207], v[76:79]
	v_mfma_f32_16x16x32_bf16 v[72:75], v[180:183], v[204:207], v[72:75]
	v_mfma_f32_16x16x32_bf16 v[72:75], v[166:169], v[200:203], v[72:75]
	v_mfma_f32_16x16x32_bf16 v[64:67], v[166:169], v[208:211], v[64:67]
	v_mfma_f32_16x16x32_bf16 v[64:67], v[180:183], v[212:215], v[64:67]
	v_mfma_f32_16x16x32_bf16 v[68:71], v[162:165], v[212:215], v[68:71]
	v_mfma_f32_16x16x32_bf16 v[68:71], v[144:147], v[208:211], v[68:71]
	s_setprio 0
	s_barrier
; #define PG8_STAGE(bufoff, gbase, voff) do { _Pragma("unroll") for (int _i = 0; _i < 2; ++_i) \
;         __builtin_amdgcn_global_load_lds((const unsigned*)((const char*)(gbase) + (voff)[_i]), (PG8_LAS unsigned*)(lds + (bufoff) + ldsw + _i * 8192), 16, 0, 0); } while (0)
; #define PG8_LDA(dst, b, h) do { _Pragma("unroll") for (int m = 0; m < 4; ++m) _Pragma("unroll") for (int k = 0; k < 2; ++k) dst[m][k] = *(const PG8_LAS bf16x8*)(lds + PG8_SA(b, h) + aoff + m * 2048 + k * 1024); } while (0)
; #define PG8_MMA(ai, bj, At, Bt) do { __builtin_amdgcn_s_setprio(1); _Pragma("unroll") for (int m = 0; m < 4; ++m) _Pragma("unroll") for (int n = 0; n < 2; ++n) _Pragma("unroll") for (int k = 0; k < 2; ++k) \
;         acc[ai][bj][m][n] = __builtin_amdgcn_mfma_f32_16x16x32_bf16(Bt[n][k], At[m][k], acc[ai][bj][m][n], 0, 0, 0); __builtin_amdgcn_s_setprio(0); } while (0)
; #define PG8_WAIT_V(n) asm volatile("s_waitcnt vmcnt(" #n ")" ::: "memory")
; #define PG8_WAIT_L(n) asm volatile("s_waitcnt lgkmcnt(" #n ")" ::: "memory")
; #define PG8_BAR __builtin_amdgcn_s_barrier()
; #define PG8_SCHED __builtin_amdgcn_sched_barrier(0)
; template <class Epi, class Sched, bool ALIGN_EPI = false, bool SP2 = false, bool APERM = false  >
; __device__ __forceinline__ void gemm_phase(PG8_LAS unsigned char* lds, const Gemm g, const Sched& S, const Epi& E, const int wid  ) {
;     ...
;         for (int t = 0; t < nt; t += 2) {
;             const bool last = (t == nt - 2);
;     ...
;             PG8_LDA(At, 1, 1); PG8_STAGE(PG8_SB(1, 0), b3, voffB); PG8_STAGE(PG8_SB(1, 1), b3 + hstep, voffB); PG8_STAGE(PG8_SA(1, 0), a3, voffA);
;             PG8_WAIT_V(8); PG8_WAIT_L(0); PG8_BAR; PG8_MMA(1, 0, At, B0); PG8_MMA(1, 1, At, B1); PG8_BAR; PG8_SCHED;
	s_add_i32 s18, s24, s76
	v_lshl_add_u64 v[170:171], v[170:171], 0, s[40:41]
	s_mov_b32 m0, s18
	ds_read_b128 v[184:187], v178 offset:49152
	ds_read_b128 v[188:191], v178 offset:50176
	ds_read_b128 v[192:195], v178 offset:51200
	ds_read_b128 v[196:199], v178 offset:52224
	ds_read_b128 v[200:203], v178 offset:53248
	ds_read_b128 v[204:207], v178 offset:54272
	ds_read_b128 v[208:211], v178 offset:55296
	ds_read_b128 v[212:215], v178 offset:56320
	global_load_lds_dwordx4 v[170:171], off
	s_add_i32 m0, s18, 0x2000
	s_add_u32 s6, s6, 0x80080
	v_lshl_add_u64 v[170:171], v[216:217], 0, s[40:41]
	s_addc_u32 s7, s7, 0
	s_add_i32 s18, s25, s76
	global_load_lds_dwordx4 v[170:171], off
	v_lshl_add_u64 v[170:171], s[6:7], 0, v[148:149]
	s_mov_b32 m0, s18
	s_nop 0
	global_load_lds_dwordx4 v[170:171], off
	v_lshl_add_u64 v[170:171], s[6:7], 0, v[150:151]
	s_add_i32 m0, s18, 0x2000
	s_nop 0
	global_load_lds_dwordx4 v[170:171], off
	v_lshl_add_u64 v[170:171], v[218:219], 0, s[40:41]
	s_mov_b32 m0, s82
	s_nop 0
	global_load_lds_dwordx4 v[170:171], off
	v_lshl_add_u64 v[170:171], v[220:221], 0, s[40:41]
	s_mov_b32 m0, s84
	s_nop 0
	global_load_lds_dwordx4 v[170:171], off
	s_waitcnt vmcnt(8)
	s_waitcnt lgkmcnt(0)
	s_barrier
	s_setprio 1
	s_waitcnt lgkmcnt(0)
	v_mfma_f32_16x16x32_bf16 v[60:63], v[128:131], v[184:187], v[60:63]
	v_mfma_f32_16x16x32_bf16 v[60:63], v[132:135], v[188:191], v[60:63]
	v_mfma_f32_16x16x32_bf16 v[56:59], v[140:143], v[188:191], v[56:59]
	v_mfma_f32_16x16x32_bf16 v[56:59], v[136:139], v[184:187], v[56:59]
	v_mfma_f32_16x16x32_bf16 v[48:51], v[136:139], v[192:195], v[48:51]
	v_mfma_f32_16x16x32_bf16 v[48:51], v[140:143], v[196:199], v[48:51]
	v_mfma_f32_16x16x32_bf16 v[52:55], v[132:135], v[196:199], v[52:55]
	v_mfma_f32_16x16x32_bf16 v[52:55], v[128:131], v[192:195], v[52:55]
	v_mfma_f32_16x16x32_bf16 v[44:47], v[128:131], v[200:203], v[44:47]
	v_mfma_f32_16x16x32_bf16 v[44:47], v[132:135], v[204:207], v[44:47]
	v_mfma_f32_16x16x32_bf16 v[40:43], v[140:143], v[204:207], v[40:43]
	v_mfma_f32_16x16x32_bf16 v[40:43], v[136:139], v[200:203], v[40:43]
	v_mfma_f32_16x16x32_bf16 v[32:35], v[136:139], v[208:211], v[32:35]
	v_mfma_f32_16x16x32_bf16 v[32:35], v[140:143], v[212:215], v[32:35]
	v_mfma_f32_16x16x32_bf16 v[36:39], v[132:135], v[212:215], v[36:39]
	v_mfma_f32_16x16x32_bf16 v[36:39], v[128:131], v[208:211], v[36:39]
	s_setprio 0
	s_setprio 1
	v_mfma_f32_16x16x32_bf16 v[28:31], v[144:147], v[184:187], v[28:31]
	v_mfma_f32_16x16x32_bf16 v[28:31], v[162:165], v[188:191], v[28:31]
	v_mfma_f32_16x16x32_bf16 v[24:27], v[180:183], v[188:191], v[24:27]
	v_mfma_f32_16x16x32_bf16 v[24:27], v[166:169], v[184:187], v[24:27]
	v_mfma_f32_16x16x32_bf16 v[16:19], v[166:169], v[192:195], v[16:19]
	v_mfma_f32_16x16x32_bf16 v[16:19], v[180:183], v[196:199], v[16:19]
	v_mfma_f32_16x16x32_bf16 v[20:23], v[162:165], v[196:199], v[20:23]
	v_mfma_f32_16x16x32_bf16 v[20:23], v[144:147], v[192:195], v[20:23]
	v_mfma_f32_16x16x32_bf16 v[12:15], v[144:147], v[200:203], v[12:15]
	v_mfma_f32_16x16x32_bf16 v[12:15], v[162:165], v[204:207], v[12:15]
	v_mfma_f32_16x16x32_bf16 v[8:11], v[180:183], v[204:207], v[8:11]
	v_mfma_f32_16x16x32_bf16 v[8:11], v[166:169], v[200:203], v[8:11]
	v_mfma_f32_16x16x32_bf16 v[0:3], v[166:169], v[208:211], v[0:3]
	v_mfma_f32_16x16x32_bf16 v[0:3], v[180:183], v[212:215], v[0:3]
	v_mfma_f32_16x16x32_bf16 v[4:7], v[162:165], v[212:215], v[4:7]
	v_mfma_f32_16x16x32_bf16 v[4:7], v[144:147], v[208:211], v[4:7]
	s_setprio 0
	s_barrier
	s_add_i32 s6, s89, 2
	s_cmp_gt_u32 s89, 29
	s_cbranch_scc1 .LBB0_1425
	s_mov_b32 s89, s6
	s_branch .LBB0_1406
